# v2 + all flat_* memory ops converted to global_* (lgkmcnt waits no longer cover them)
# speedup vs baseline: 1.0164x; 1.0029x over previous
_Z14fwd_megakernel6Params:
	s_mov_b32 s80, s2
	s_load_dword s2, s[0:1], 0xd8
	s_load_dwordx4 s[4:7], s[0:1], 0xc0
	s_load_dwordx2 s[82:83], s[0:1], 0xd0
	s_add_u32 s36, s0, 0xd0
	v_and_b32_e32 v83, 0x3ff, v0
	s_waitcnt lgkmcnt(0)
	v_writelane_b32 v254, s2, 0
	s_addc_u32 s37, s1, 0
	v_readfirstlane_b32 s90, v83
	v_writelane_b32 v254, s4, 1
	s_cmp_lt_u32 s90, 64
	s_cselect_b64 s[88:89], -1, 0
	v_writelane_b32 v254, s5, 2
	v_writelane_b32 v254, s6, 3
	s_cmp_gt_u32 s90, 63
	v_writelane_b32 v254, s7, 4
	s_cselect_b64 s[2:3], -1, 0
	v_writelane_b32 v254, s2, 5
	s_mov_b64 s[4:5], s[6:7]
	s_and_b64 vcc, exec, s[2:3]
	v_writelane_b32 v254, s3, 6
	s_cbranch_vccnz .LBB0_4
	v_mbcnt_lo_u32_b32 v1, -1, 0
	v_mbcnt_hi_u32_b32 v1, -1, v1
	s_nop 0
	v_cmp_eq_u32_e32 vcc, 0, v1
	s_and_saveexec_b64 s[6:7], vcc
	s_cbranch_execz .LBB0_3
	s_add_i32 s2, 0, 0x25ff0
	v_mov_b32_e32 v1, 0
	v_mov_b32_e32 v2, s2
	s_add_i32 s2, 0, 0x25ff4
	ds_write_b32 v2, v1
	v_mov_b32_e32 v2, s2
	ds_write_b32 v2, v1
	s_getreg_b32 s2, hwreg(HW_REG_XCC_ID, 0, 4)
	s_lshl_b32 s2, s2, 8
	s_and_b32 s2, s2, 0xf00
	s_add_u32 s2, s4, s2
	s_addc_u32 s3, s5, 0
	v_mov_b32_e32 v1, s2
	v_add_co_u32_e32 v2, vcc, 0x100000, v1
	v_mov_b32_e32 v1, s3
	s_nop 0
	v_addc_co_u32_e32 v3, vcc, 0, v1, vcc
	v_mov_b32_e32 v1, 1
	global_atomic_add v[2:3], v1, off offset:1024

.LBB0_7:
	v_add_u32_e32 v9, -2, v9
	v_ashrrev_i32_e32 v11, 31, v7
	v_mov_b32_e32 v10, v7
	v_ashrrev_i32_e32 v13, 31, v6
	v_mov_b32_e32 v12, v6
	v_cmp_eq_u32_e32 vcc, 0, v9
	v_add_u32_e32 v7, s3, v7
	v_add_u32_e32 v6, s2, v6
	v_lshl_add_u64 v[12:13], v[12:13], 2, s[8:9]
	v_lshl_add_u64 v[10:11], v[10:11], 2, s[8:9]
	s_or_b64 s[12:13], vcc, s[12:13]
	global_store_dword v[12:13], v8, off
	global_store_dword v[10:11], v8, off
	s_andn2_b64 exec, exec, s[12:13]
	s_cbranch_execnz .LBB0_7
	s_or_b64 exec, exec, s[12:13]
	v_cmp_ne_u32_e32 vcc, v1, v3
	v_mad_u64_u32 v[4:5], s[2:3], v3, s10, v[4:5]
	s_orn2_b64 s[12:13], vcc, exec

.LBB0_11:
	v_add_u32_e32 v4, s10, v4
	v_cmp_lt_i32_e32 vcc, s2, v4
	global_store_dword v[6:7], v1, off
	s_or_b64 s[12:13], vcc, s[12:13]
	v_lshl_add_u64 v[6:7], v[6:7], 0, s[4:5]
	s_andn2_b64 exec, exec, s[12:13]
	s_cbranch_execnz .LBB0_11
.LBB0_12:
	s_or_b64 exec, exec, s[6:7]
	s_load_dwordx16 s[12:27], s[0:1], 0x40
	s_cmp_eq_u32 s80, 0
	s_movk_i32 s4, 0x80
	s_cselect_b64 s[2:3], -1, 0
	v_cmp_gt_i32_e32 vcc, s4, v2
	s_waitcnt lgkmcnt(0)
	v_writelane_b32 v254, s12, 24
	s_and_b64 s[2:3], s[2:3], vcc
	s_nop 0
	v_writelane_b32 v254, s13, 25
	v_writelane_b32 v254, s14, 26
	v_writelane_b32 v254, s15, 27
	v_writelane_b32 v254, s16, 28
	v_writelane_b32 v254, s17, 29
	v_writelane_b32 v254, s18, 30
	v_writelane_b32 v254, s19, 31
	v_writelane_b32 v254, s20, 32
	v_writelane_b32 v254, s21, 33
	v_writelane_b32 v254, s22, 34
	v_writelane_b32 v254, s23, 35
	v_writelane_b32 v254, s24, 36
	v_writelane_b32 v254, s25, 37
	v_writelane_b32 v254, s26, 38
	v_writelane_b32 v254, s27, 39
	s_load_dwordx16 s[12:27], s[0:1], 0x80
	s_waitcnt lgkmcnt(0)
	v_writelane_b32 v254, s12, 40
	s_nop 1
	v_writelane_b32 v254, s13, 41
	v_writelane_b32 v254, s14, 42
	v_writelane_b32 v254, s15, 43
	v_writelane_b32 v254, s16, 44
	v_writelane_b32 v254, s17, 45
	v_writelane_b32 v254, s18, 46
	v_writelane_b32 v254, s19, 47
	v_writelane_b32 v254, s20, 48
	v_writelane_b32 v254, s21, 49
	v_writelane_b32 v254, s22, 50
	v_writelane_b32 v254, s23, 51
	v_writelane_b32 v254, s24, 52
	v_writelane_b32 v254, s25, 53
	v_writelane_b32 v254, s26, 54
	v_writelane_b32 v254, s27, 55
	s_and_saveexec_b64 s[4:5], s[2:3]
	s_cbranch_execz .LBB0_14
	s_load_dwordx16 s[12:27], s[0:1], 0x40
	v_ashrrev_i32_e32 v3, 31, v2
	v_lshlrev_b64 v[2:3], 2, v[2:3]
	s_mov_b64 s[2:3], 0xf0000
	s_waitcnt lgkmcnt(0)
	v_lshl_add_u64 v[4:5], s[20:21], 0, v[2:3]
	global_load_dword v1, v[4:5], off
	v_lshl_add_u64 v[4:5], s[8:9], 0, v[2:3]
	v_add_co_u32_e32 v8, vcc, 0xf0000, v4
	v_lshl_add_u64 v[6:7], s[22:23], 0, v[2:3]
	s_nop 0
	v_addc_co_u32_e32 v9, vcc, 0, v5, vcc
	v_lshl_add_u64 v[4:5], v[4:5], 0, s[2:3]
	s_waitcnt vmcnt(0)
	v_mul_f32_e32 v1, 0x3e0293ee, v1
	global_store_dword v[8:9], v1, off
	global_load_dword v1, v[6:7], off
	v_lshl_add_u64 v[6:7], s[24:25], 0, v[2:3]
	s_waitcnt vmcnt(0)
	global_store_dword v[4:5], v1, off offset:512
	global_load_dword v1, v[6:7], off
	v_lshl_add_u64 v[6:7], s[26:27], 0, v[2:3]
	s_load_dwordx16 s[12:27], s[0:1], 0x80
	s_waitcnt lgkmcnt(0)
	v_lshl_add_u64 v[2:3], s[14:15], 0, v[2:3]
	s_waitcnt vmcnt(0)
	v_mul_f32_e32 v1, 0x3e0293ee, v1
	global_store_dword v[4:5], v1, off offset:1024
	global_load_dword v1, v[6:7], off
	s_waitcnt vmcnt(0)
	global_store_dword v[4:5], v1, off offset:1536
	global_load_dword v1, v[2:3], off
	s_waitcnt vmcnt(0)
	v_mul_f32_e32 v1, 0x3e0293ee, v1
	global_store_dword v[4:5], v1, off offset:2048

.LBB0_123:
	ds_read_b32 v72, v87
	ds_read_b32 v98, v87 offset:132
	ds_read_b32 v73, v87 offset:264
	ds_read_b32 v99, v87 offset:396
	ds_read_b32 v100, v87 offset:528
	ds_read_b32 v102, v87 offset:660
	ds_read_b32 v101, v87 offset:792
	ds_read_b32 v103, v87 offset:924
	s_waitcnt lgkmcnt(0)
	v_pk_mul_f32 v[72:73], v[70:71], v[72:73]
	v_pk_mul_f32 v[98:99], v[68:69], v[98:99]
	v_pk_mul_f32 v[100:101], v[66:67], v[100:101]
	v_pk_mul_f32 v[102:103], v[94:95], v[102:103]
	v_bfe_u32 v104, v99, 16, 1
	v_bfe_u32 v89, v103, 16, 1
	v_bfe_u32 v97, v102, 16, 1
	v_add3_u32 v97, v102, v97, s55
	v_add3_u32 v89, v103, v89, s55
	v_bfe_u32 v102, v72, 16, 1
	v_bfe_u32 v103, v73, 16, 1
	v_bfe_u32 v105, v98, 16, 1
	v_add3_u32 v73, v73, v103, s55
	v_add3_u32 v72, v72, v102, s55
	v_add3_u32 v98, v98, v105, s55
	v_add3_u32 v99, v99, v104, s55
	v_lshrrev_b32_e32 v72, 16, v72
	v_lshrrev_b32_e32 v73, 16, v73
	v_and_or_b32 v99, v99, s80, v73
	v_and_or_b32 v98, v98, s80, v72
	v_mad_u64_u32 v[72:73], s[24:25], s82, v80, 0
	v_bfe_u32 v105, v101, 16, 1
	v_mov_b32_e32 v102, v73
	v_bfe_u32 v104, v100, 16, 1
	v_add3_u32 v101, v101, v105, s55
	v_mad_u64_u32 v[102:103], s[24:25], s82, v65, v[102:103]
	v_add3_u32 v100, v100, v104, s55
	v_lshrrev_b32_e32 v101, 16, v101
	v_mov_b32_e32 v73, v102
	v_lshrrev_b32_e32 v100, 16, v100
	v_and_or_b32 v101, v89, s80, v101
	v_lshl_add_u64 v[72:73], v[72:73], 1, v[92:93]
	v_mov_b32_e32 v89, v77
	v_and_or_b32 v100, v97, s80, v100
	v_lshl_add_u64 v[72:73], v[72:73], 0, v[88:89]
	global_store_dwordx4 v[72:73], v[98:101], off
	ds_read_b32 v72, v87 offset:32
	ds_read_b32 v98, v87 offset:164
	ds_read_b32 v73, v87 offset:296
	ds_read_b32 v99, v87 offset:428
	ds_read_b32 v100, v87 offset:560
	ds_read_b32 v102, v87 offset:692
	ds_read_b32 v101, v87 offset:824
	ds_read_b32 v103, v87 offset:956
	s_waitcnt lgkmcnt(0)
	v_pk_mul_f32 v[72:73], v[70:71], v[72:73]
	v_pk_mul_f32 v[98:99], v[68:69], v[98:99]
	v_pk_mul_f32 v[100:101], v[66:67], v[100:101]
	v_pk_mul_f32 v[102:103], v[94:95], v[102:103]
	v_bfe_u32 v105, v99, 16, 1
	v_bfe_u32 v97, v103, 16, 1
	v_bfe_u32 v104, v102, 16, 1
	v_add3_u32 v102, v102, v104, s55
	v_add3_u32 v97, v103, v97, s55
	v_bfe_u32 v103, v72, 16, 1
	v_bfe_u32 v104, v73, 16, 1
	v_bfe_u32 v106, v98, 16, 1
	v_add3_u32 v99, v99, v105, s55
	v_bfe_u32 v105, v100, 16, 1
	v_add3_u32 v73, v73, v104, s55
	v_add3_u32 v72, v72, v103, s55
	v_add3_u32 v98, v98, v106, s55
	v_add3_u32 v100, v100, v105, s55
	v_lshrrev_b32_e32 v72, 16, v72
	v_lshrrev_b32_e32 v73, 16, v73
	v_lshrrev_b32_e32 v100, 16, v100
	v_and_or_b32 v99, v99, s80, v73
	v_and_or_b32 v98, v98, s80, v72
	v_mad_u64_u32 v[72:73], s[24:25], s82, v82, 0
	v_and_or_b32 v100, v102, s80, v100
	v_mov_b32_e32 v102, v73
	v_bfe_u32 v106, v101, 16, 1
	v_mad_u64_u32 v[102:103], s[24:25], s82, v75, v[102:103]
	v_add3_u32 v101, v101, v106, s55
	v_mov_b32_e32 v73, v102
	v_lshrrev_b32_e32 v101, 16, v101
	v_lshl_add_u64 v[72:73], v[72:73], 1, v[92:93]
	v_and_or_b32 v101, v97, s80, v101
	v_lshl_add_u64 v[72:73], v[72:73], 0, v[88:89]
	global_store_dwordx4 v[72:73], v[98:101], off
	ds_read_b32 v72, v87 offset:64
	ds_read_b32 v98, v87 offset:196
	ds_read_b32 v73, v87 offset:328
	ds_read_b32 v99, v87 offset:460
	ds_read_b32 v100, v87 offset:592
	ds_read_b32 v102, v87 offset:724
	ds_read_b32 v101, v87 offset:856
	ds_read_b32 v103, v87 offset:988
	s_waitcnt lgkmcnt(0)
	v_pk_mul_f32 v[72:73], v[70:71], v[72:73]
	v_pk_mul_f32 v[98:99], v[68:69], v[98:99]
	v_pk_mul_f32 v[100:101], v[66:67], v[100:101]
	v_pk_mul_f32 v[102:103], v[94:95], v[102:103]
	v_bfe_u32 v105, v99, 16, 1
	v_bfe_u32 v97, v103, 16, 1
	v_bfe_u32 v104, v102, 16, 1
	v_add3_u32 v102, v102, v104, s55
	v_add3_u32 v97, v103, v97, s55
	v_bfe_u32 v103, v72, 16, 1
	v_bfe_u32 v104, v73, 16, 1
	v_bfe_u32 v106, v98, 16, 1
	v_add3_u32 v99, v99, v105, s55
	v_bfe_u32 v105, v100, 16, 1
	v_add3_u32 v73, v73, v104, s55
	v_add3_u32 v72, v72, v103, s55
	v_add3_u32 v98, v98, v106, s55
	v_add3_u32 v100, v100, v105, s55
	v_lshrrev_b32_e32 v72, 16, v72
	v_lshrrev_b32_e32 v73, 16, v73
	v_lshrrev_b32_e32 v100, 16, v100
	v_and_or_b32 v99, v99, s80, v73
	v_and_or_b32 v98, v98, s80, v72
	v_mad_u64_u32 v[72:73], s[24:25], s82, v84, 0
	v_and_or_b32 v100, v102, s80, v100
	v_mov_b32_e32 v102, v73
	v_bfe_u32 v106, v101, 16, 1
	v_mad_u64_u32 v[102:103], s[24:25], s82, v79, v[102:103]
	v_add3_u32 v101, v101, v106, s55
	v_mov_b32_e32 v73, v102
	v_lshrrev_b32_e32 v101, 16, v101
	v_lshl_add_u64 v[72:73], v[72:73], 1, v[92:93]
	v_and_or_b32 v101, v97, s80, v101
	v_lshl_add_u64 v[72:73], v[72:73], 0, v[88:89]
	global_store_dwordx4 v[72:73], v[98:101], off
	ds_read_b32 v72, v87 offset:96
	ds_read_b32 v98, v87 offset:228
	ds_read_b32 v73, v87 offset:360
	ds_read_b32 v99, v87 offset:492
	ds_read_b32 v100, v87 offset:624
	ds_read_b32 v102, v87 offset:756
	ds_read_b32 v101, v87 offset:888
	ds_read_b32 v103, v87 offset:1020
	s_waitcnt lgkmcnt(0)
	v_pk_mul_f32 v[70:71], v[70:71], v[72:73]
	v_pk_mul_f32 v[68:69], v[68:69], v[98:99]
	v_pk_mul_f32 v[66:67], v[66:67], v[100:101]
	v_pk_mul_f32 v[72:73], v[94:95], v[102:103]
	v_bfe_u32 v97, v69, 16, 1
	v_bfe_u32 v94, v73, 16, 1
	v_bfe_u32 v95, v72, 16, 1
	v_bfe_u32 v98, v68, 16, 1
	v_add3_u32 v98, v68, v98, s55
	v_add3_u32 v97, v69, v97, s55
	v_add3_u32 v68, v72, v95, s55
	v_add3_u32 v69, v73, v94, s55
	v_bfe_u32 v72, v70, 16, 1
	v_bfe_u32 v73, v71, 16, 1
	v_bfe_u32 v94, v66, 16, 1
	v_bfe_u32 v95, v67, 16, 1
	v_add3_u32 v67, v67, v95, s55
	v_add3_u32 v66, v66, v94, s55
	v_add3_u32 v71, v71, v73, s55
	v_add3_u32 v70, v70, v72, s55
	v_lshrrev_b32_e32 v70, 16, v70
	v_lshrrev_b32_e32 v71, 16, v71
	v_lshrrev_b32_e32 v66, 16, v66
	v_lshrrev_b32_e32 v67, 16, v67
	v_and_or_b32 v69, v69, s80, v67
	v_and_or_b32 v68, v68, s80, v66
	v_and_or_b32 v67, v97, s80, v71
	v_and_or_b32 v66, v98, s80, v70
	v_mad_u64_u32 v[70:71], s[24:25], s82, v86, 0
	v_mov_b32_e32 v72, v71
	v_mad_u64_u32 v[72:73], s[24:25], s82, v81, v[72:73]
	v_mov_b32_e32 v71, v72
	v_lshl_add_u64 v[70:71], v[70:71], 1, v[92:93]
	v_lshl_add_u64 v[70:71], v[70:71], 0, v[88:89]
	global_store_dwordx4 v[70:71], v[66:69], off
	s_waitcnt lgkmcnt(0)

.LBB0_230:
	ds_read_b32 v72, v87
	ds_read_b32 v104, v87 offset:132
	ds_read_b32 v73, v87 offset:264
	ds_read_b32 v105, v87 offset:396
	ds_read_b32 v106, v87 offset:528
	ds_read_b32 v108, v87 offset:660
	ds_read_b32 v107, v87 offset:792
	ds_read_b32 v109, v87 offset:924
	s_waitcnt lgkmcnt(0)
	v_pk_mul_f32 v[72:73], v[70:71], v[72:73]
	s_waitcnt lgkmcnt(4)
	v_pk_mul_f32 v[104:105], v[68:69], v[104:105]
	s_andn2_b64 vcc, exec, s[26:27]
	s_waitcnt lgkmcnt(1)
	v_pk_mul_f32 v[106:107], v[66:67], v[106:107]
	s_waitcnt lgkmcnt(0)
	v_pk_mul_f32 v[108:109], v[94:95], v[108:109]
	v_bfe_u32 v111, v105, 16, 1
	v_bfe_u32 v89, v109, 16, 1
	v_bfe_u32 v110, v108, 16, 1
	v_add3_u32 v108, v108, v110, s55
	v_add3_u32 v89, v109, v89, s55
	v_bfe_u32 v109, v72, 16, 1
	v_bfe_u32 v110, v73, 16, 1
	v_bfe_u32 v112, v104, 16, 1
	v_add3_u32 v105, v105, v111, s55
	v_bfe_u32 v111, v106, 16, 1
	v_add3_u32 v73, v73, v110, s55
	v_add3_u32 v72, v72, v109, s55
	v_add3_u32 v104, v104, v112, s55
	v_add3_u32 v106, v106, v111, s55
	v_lshrrev_b32_e32 v72, 16, v72
	v_lshrrev_b32_e32 v73, 16, v73
	v_lshrrev_b32_e32 v106, 16, v106
	v_and_or_b32 v105, v105, s80, v73
	v_and_or_b32 v104, v104, s80, v72
	v_mad_u64_u32 v[72:73], s[28:29], s44, v80, 0
	v_bfe_u32 v112, v107, 16, 1
	v_and_or_b32 v106, v108, s80, v106
	v_mov_b32_e32 v108, v73
	v_add3_u32 v107, v107, v112, s55
	v_mad_u64_u32 v[108:109], s[28:29], s44, v65, v[108:109]
	v_lshrrev_b32_e32 v107, 16, v107
	v_mov_b32_e32 v73, v108
	v_and_or_b32 v107, v89, s80, v107
	v_lshl_add_u64 v[72:73], v[72:73], 1, v[90:91]
	v_mov_b32_e32 v89, v77
	v_lshl_add_u64 v[72:73], v[72:73], 0, v[88:89]
	global_store_dwordx4 v[72:73], v[104:107], off
	ds_read_b32 v72, v87 offset:32
	ds_read_b32 v104, v87 offset:164
	ds_read_b32 v73, v87 offset:296
	ds_read_b32 v105, v87 offset:428
	ds_read_b32 v106, v87 offset:560
	ds_read_b32 v108, v87 offset:692
	ds_read_b32 v107, v87 offset:824
	ds_read_b32 v109, v87 offset:956
	s_waitcnt lgkmcnt(0)
	v_pk_mul_f32 v[72:73], v[70:71], v[72:73]
	v_pk_mul_f32 v[104:105], v[68:69], v[104:105]
	v_pk_mul_f32 v[106:107], v[66:67], v[106:107]
	v_pk_mul_f32 v[108:109], v[94:95], v[108:109]
	v_bfe_u32 v112, v105, 16, 1
	v_bfe_u32 v110, v109, 16, 1
	v_bfe_u32 v111, v108, 16, 1
	v_add3_u32 v108, v108, v111, s55
	v_add3_u32 v109, v109, v110, s55
	v_bfe_u32 v110, v72, 16, 1
	v_bfe_u32 v111, v73, 16, 1
	v_bfe_u32 v113, v104, 16, 1
	v_add3_u32 v105, v105, v112, s55
	v_bfe_u32 v112, v106, 16, 1
	v_add3_u32 v73, v73, v111, s55
	v_add3_u32 v72, v72, v110, s55
	v_add3_u32 v104, v104, v113, s55
	v_bfe_u32 v113, v107, 16, 1
	v_add3_u32 v106, v106, v112, s55
	v_lshrrev_b32_e32 v72, 16, v72
	v_lshrrev_b32_e32 v73, 16, v73
	v_add3_u32 v107, v107, v113, s55
	v_lshrrev_b32_e32 v106, 16, v106
	v_and_or_b32 v105, v105, s80, v73
	v_and_or_b32 v104, v104, s80, v72
	v_mad_u64_u32 v[72:73], s[28:29], s44, v82, 0
	v_lshrrev_b32_e32 v107, 16, v107
	v_and_or_b32 v106, v108, s80, v106
	v_mov_b32_e32 v108, v73
	v_and_or_b32 v107, v109, s80, v107
	v_mad_u64_u32 v[108:109], s[28:29], s44, v75, v[108:109]
	v_mov_b32_e32 v73, v108
	v_lshl_add_u64 v[72:73], v[72:73], 1, v[90:91]
	v_lshl_add_u64 v[72:73], v[72:73], 0, v[88:89]
	global_store_dwordx4 v[72:73], v[104:107], off
	ds_read_b32 v72, v87 offset:64
	ds_read_b32 v104, v87 offset:196
	ds_read_b32 v73, v87 offset:328
	ds_read_b32 v105, v87 offset:460
	ds_read_b32 v106, v87 offset:592
	ds_read_b32 v108, v87 offset:724
	ds_read_b32 v107, v87 offset:856
	ds_read_b32 v109, v87 offset:988
	s_waitcnt lgkmcnt(0)
	v_pk_mul_f32 v[72:73], v[70:71], v[72:73]
	v_pk_mul_f32 v[104:105], v[68:69], v[104:105]
	v_pk_mul_f32 v[106:107], v[66:67], v[106:107]
	v_pk_mul_f32 v[108:109], v[94:95], v[108:109]
	v_bfe_u32 v112, v105, 16, 1
	v_bfe_u32 v110, v109, 16, 1
	v_bfe_u32 v111, v108, 16, 1
	v_add3_u32 v108, v108, v111, s55
	v_add3_u32 v109, v109, v110, s55
	v_bfe_u32 v110, v72, 16, 1
	v_bfe_u32 v111, v73, 16, 1
	v_bfe_u32 v113, v104, 16, 1
	v_add3_u32 v105, v105, v112, s55
	v_bfe_u32 v112, v106, 16, 1
	v_add3_u32 v73, v73, v111, s55
	v_add3_u32 v72, v72, v110, s55
	v_add3_u32 v104, v104, v113, s55
	v_bfe_u32 v113, v107, 16, 1
	v_add3_u32 v106, v106, v112, s55
	v_lshrrev_b32_e32 v72, 16, v72
	v_lshrrev_b32_e32 v73, 16, v73
	v_add3_u32 v107, v107, v113, s55
	v_lshrrev_b32_e32 v106, 16, v106
	v_and_or_b32 v105, v105, s80, v73
	v_and_or_b32 v104, v104, s80, v72
	v_mad_u64_u32 v[72:73], s[28:29], s44, v84, 0
	v_lshrrev_b32_e32 v107, 16, v107
	v_and_or_b32 v106, v108, s80, v106
	v_mov_b32_e32 v108, v73
	v_and_or_b32 v107, v109, s80, v107
	v_mad_u64_u32 v[108:109], s[28:29], s44, v79, v[108:109]
	v_mov_b32_e32 v73, v108
	v_lshl_add_u64 v[72:73], v[72:73], 1, v[90:91]
	v_lshl_add_u64 v[72:73], v[72:73], 0, v[88:89]
	global_store_dwordx4 v[72:73], v[104:107], off
	ds_read_b32 v72, v87 offset:96
	ds_read_b32 v104, v87 offset:228
	ds_read_b32 v73, v87 offset:360
	ds_read_b32 v105, v87 offset:492
	ds_read_b32 v106, v87 offset:624
	ds_read_b32 v108, v87 offset:756
	ds_read_b32 v107, v87 offset:888
	ds_read_b32 v109, v87 offset:1020
	s_waitcnt lgkmcnt(0)
	v_pk_mul_f32 v[70:71], v[70:71], v[72:73]
	v_pk_mul_f32 v[68:69], v[68:69], v[104:105]
	v_pk_mul_f32 v[66:67], v[66:67], v[106:107]
	v_pk_mul_f32 v[72:73], v[94:95], v[108:109]
	v_bfe_u32 v104, v69, 16, 1
	v_bfe_u32 v94, v73, 16, 1
	v_bfe_u32 v95, v72, 16, 1
	v_bfe_u32 v105, v68, 16, 1
	v_add3_u32 v105, v68, v105, s55
	v_add3_u32 v104, v69, v104, s55
	v_add3_u32 v68, v72, v95, s55
	v_add3_u32 v69, v73, v94, s55
	v_bfe_u32 v72, v70, 16, 1
	v_bfe_u32 v73, v71, 16, 1
	v_bfe_u32 v94, v66, 16, 1
	v_bfe_u32 v95, v67, 16, 1
	v_add3_u32 v67, v67, v95, s55
	v_add3_u32 v66, v66, v94, s55
	v_add3_u32 v71, v71, v73, s55
	v_add3_u32 v70, v70, v72, s55
	v_lshrrev_b32_e32 v70, 16, v70
	v_lshrrev_b32_e32 v71, 16, v71
	v_lshrrev_b32_e32 v66, 16, v66
	v_lshrrev_b32_e32 v67, 16, v67
	v_and_or_b32 v69, v69, s80, v67
	v_and_or_b32 v68, v68, s80, v66
	v_and_or_b32 v67, v104, s80, v71
	v_and_or_b32 v66, v105, s80, v70
	v_mad_u64_u32 v[70:71], s[28:29], s44, v86, 0
	v_mov_b32_e32 v72, v71
	v_mad_u64_u32 v[72:73], s[28:29], s44, v81, v[72:73]
	v_mov_b32_e32 v71, v72
	v_lshl_add_u64 v[70:71], v[70:71], 1, v[90:91]
	v_lshl_add_u64 v[70:71], v[70:71], 0, v[88:89]
	global_store_dwordx4 v[70:71], v[66:69], off
	s_waitcnt lgkmcnt(0)
	s_cbranch_vccnz .LBB0_124
	s_add_i32 s38, s45, s83
	s_cmp_gt_i32 s38, 0xa01f
	s_cbranch_scc1 .LBB0_121
	s_cmpk_gt_i32 s38, 0x15ff
	s_cbranch_scc0 .LBB0_244
	s_cmpk_gt_u32 s38, 0x2bff
	s_cbranch_scc0 .LBB0_245
	s_cmpk_gt_u32 s38, 0x41ff
	s_cbranch_scc0 .LBB0_246
	s_mov_b64 s[30:31], -1
	s_cmpk_gt_u32 s38, 0x521f
	s_mov_b64 s[34:35], -1
	s_cbranch_scc0 .LBB0_263
	s_cmpk_gt_u32 s38, 0x541f
	s_cbranch_scc0 .LBB0_247
	s_cmpk_gt_u32 s38, 0x561f
	s_cbranch_scc0 .LBB0_248
	s_cmpk_gt_u32 s38, 0x5e1f
	s_cbranch_scc0 .LBB0_249
	s_cmpk_gt_u32 s38, 0x741f
	s_cbranch_scc0 .LBB0_251
	s_cmpk_gt_u32 s38, 0x8a1f
	s_mov_b64 s[20:21], -1
	s_cbranch_scc0 .LBB0_242
	s_add_i32 s21, s46, s47
	s_add_i32 s21, s21, 0xffeebc00
	s_add_i32 s20, s38, 0xffff75e0
	s_and_b32 s28, s21, 0x7e0
	s_and_b32 s22, s20, 0xffffffc0
	s_mul_i32 s20, s28, 0x2c00
	s_add_u32 s26, s16, s20
	v_add_u32_e32 v2, s22, v85
	s_addc_u32 s27, s17, 0
	s_lshl_b64 s[20:21], s[22:23], 1
	v_ashrrev_i32_e32 v3, 31, v2
	v_readlane_b32 s56, v254, 40
	s_add_u32 s26, s26, s20
	v_lshlrev_b64 v[2:3], 13, v[2:3]
	v_readlane_b32 s70, v254, 54
	v_readlane_b32 s71, v254, 55
	s_addc_u32 s27, s27, s21
	s_lshl_b32 s22, s28, 2
	v_lshl_add_u64 v[2:3], s[70:71], 0, v[2:3]
	v_readlane_b32 s57, v254, 41
	v_readlane_b32 s58, v254, 42
	v_readlane_b32 s59, v254, 43
	v_readlane_b32 s60, v254, 44
	v_readlane_b32 s61, v254, 45
	v_readlane_b32 s62, v254, 46
	v_readlane_b32 s63, v254, 47
	v_readlane_b32 s64, v254, 48
	v_readlane_b32 s65, v254, 49
	v_readlane_b32 s66, v254, 50
	v_readlane_b32 s67, v254, 51
	v_readlane_b32 s68, v254, 52
	v_readlane_b32 s69, v254, 53
	v_lshl_add_u64 v[66:67], v[2:3], 0, s[22:23]
	s_mov_b64 s[20:21], 0

.LBB0_338:
	v_bfe_u32 v6, v2, 16, 1
	v_add3_u32 v2, v2, v6, s5
	v_bfe_u32 v6, v3, 16, 1
	v_lshrrev_b32_e32 v2, 16, v2
	v_add3_u32 v3, v3, v6, s5
	v_and_or_b32 v2, v3, s7, v2
	v_bfe_u32 v3, v4, 16, 1
	v_add3_u32 v3, v4, v3, s5
	v_bfe_u32 v4, v5, 16, 1
	v_lshrrev_b32_e32 v3, 16, v3
	v_add3_u32 v4, v5, v4, s5
	s_add_i32 s4, s4, s6
	v_and_or_b32 v3, v4, s7, v3
	v_lshl_add_u64 v[58:59], v[58:59], 0, s[10:11]
	s_cmpk_gt_i32 s4, 0x43ff
	v_lshl_add_u64 v[60:61], v[60:61], 0, s[8:9]
	global_store_dwordx2 v[62:63], v[2:3], off offset:3584
	s_cbranch_scc1 .LBB0_343
.LBB0_339:
	s_cmpk_gt_i32 s4, 0x3fff
	s_mov_b64 s[0:1], -1
	s_cbranch_scc0 .LBB0_341
	s_add_i32 s12, s4, 0xffffc000
	s_lshl_b64 s[0:1], s[12:13], 13
	v_lshl_add_u64 v[2:3], v[34:35], 0, s[0:1]
	global_load_dwordx4 v[30:33], v[2:3], off
	global_load_dwordx4 v[26:29], v[2:3], off offset:1024
	global_load_dwordx4 v[22:25], v[2:3], off offset:2048
	global_load_dwordx4 v[18:21], v[2:3], off offset:3072
	v_add_co_u32_e32 v62, vcc, s2, v2
	s_lshl_b64 s[14:15], s[12:13], 12
	s_nop 0
	v_addc_co_u32_e32 v63, vcc, 0, v3, vcc
	global_load_dwordx4 v[14:17], v[62:63], off
	global_load_dwordx4 v[10:13], v[62:63], off offset:1024
	global_load_dwordx4 v[2:5], v[62:63], off offset:3072
	global_load_dwordx4 v[6:9], v[62:63], off offset:2048
	global_load_dwordx4 v[74:77], v[38:39], off
	v_cmp_lt_i32_e32 vcc, v67, v66
	s_waitcnt vmcnt(0)
	v_mov_b32_e32 v78, v31
	v_cndmask_b32_e32 v62, v65, v67, vcc
	v_mov_b32_e32 v79, v27
	v_mov_b32_e32 v84, v33
	v_mov_b32_e32 v85, v29
	v_lshlrev_b32_e32 v73, 2, v62
	v_mov_b32_e32 v62, v30
	v_mov_b32_e32 v63, v26
	v_mov_b32_e32 v80, v32
	v_mov_b32_e32 v81, v28
	v_pk_mul_f32 v[86:87], v[24:25], v[24:25]
	v_pk_mul_f32 v[88:89], v[22:23], v[22:23]
	v_pk_mul_f32 v[78:79], v[78:79], v[78:79]
	v_pk_mul_f32 v[84:85], v[84:85], v[84:85]
	v_pk_mov_b32 v[92:93], v[88:89], v[86:87] op_sel:[1,0]
	v_mov_b32_e32 v89, v87
	v_pk_fma_f32 v[62:63], v[62:63], v[62:63], v[78:79]
	v_pk_fma_f32 v[78:79], v[80:81], v[80:81], v[84:85]
	v_mul_f32_e32 v82, v19, v19
	v_mul_f32_e32 v90, v21, v21
	v_pk_add_f32 v[80:81], v[92:93], v[88:89]
	v_pk_add_f32 v[62:63], v[62:63], v[78:79]
	v_mul_f32_e32 v99, v14, v14
	v_mul_f32_e32 v100, v15, v15
	v_mul_f32_e32 v101, v16, v16
	v_mul_f32_e32 v102, v17, v17
	v_pk_fma_f32 v[86:87], v[18:19], v[18:19], v[82:83] op_sel_hi:[1,1,0]
	v_pk_fma_f32 v[90:91], v[20:21], v[20:21], v[90:91] op_sel_hi:[1,1,0]
	v_pk_add_f32 v[78:79], v[80:81], v[80:81] op_sel:[0,1] op_sel_hi:[1,0]
	v_pk_add_f32 v[62:63], v[62:63], v[62:63] op_sel:[0,1] op_sel_hi:[1,0]
	v_pk_mul_f32 v[94:95], v[12:13], v[12:13]
	v_pk_mul_f32 v[96:97], v[10:11], v[10:11]
	v_mov_b32_e32 v87, v101
	v_mov_b32_e32 v91, v102
	v_mov_b32_e32 v79, v100
	v_mov_b32_e32 v63, v99
	v_pk_mov_b32 v[84:85], v[96:97], v[94:95] op_sel:[1,0]
	v_mov_b32_e32 v97, v95
	v_pk_add_f32 v[80:81], v[86:87], v[90:91]
	v_pk_add_f32 v[62:63], v[62:63], v[78:79]
	v_mul_f32_e32 v82, v7, v7
	v_mul_f32_e32 v98, v9, v9
	v_pk_add_f32 v[84:85], v[84:85], v[96:97]
	v_pk_add_f32 v[62:63], v[62:63], v[80:81]
	v_mul_f32_e32 v103, v2, v2
	v_mul_f32_e32 v104, v3, v3
	v_mul_f32_e32 v105, v4, v4
	v_mul_f32_e32 v106, v5, v5
	v_pk_fma_f32 v[88:89], v[6:7], v[6:7], v[82:83] op_sel_hi:[1,1,0]
	v_pk_fma_f32 v[92:93], v[8:9], v[8:9], v[98:99] op_sel_hi:[1,1,0]
	v_pk_add_f32 v[84:85], v[84:85], v[84:85] op_sel:[0,1] op_sel_hi:[1,0]
	v_pk_add_f32 v[62:63], v[62:63], v[62:63] op_sel:[0,1] op_sel_hi:[1,0]
	v_mov_b32_e32 v89, v105
	v_mov_b32_e32 v93, v106
	v_mov_b32_e32 v85, v104
	v_mov_b32_e32 v63, v103
	v_pk_add_f32 v[86:87], v[88:89], v[92:93]
	v_pk_add_f32 v[62:63], v[62:63], v[84:85]
	v_cmp_lt_i32_e32 vcc, v68, v66
	v_pk_add_f32 v[62:63], v[62:63], v[86:87]
	s_nop 0
	v_add_f32_e32 v62, v62, v63
	ds_bpermute_b32 v63, v73, v62
	v_cndmask_b32_e32 v73, v65, v68, vcc
	v_lshlrev_b32_e32 v73, 2, v73
	v_cmp_lt_i32_e32 vcc, v69, v66
	s_waitcnt lgkmcnt(0)
	v_add_f32_e32 v62, v62, v63
	ds_bpermute_b32 v63, v73, v62
	v_cndmask_b32_e32 v73, v65, v69, vcc
	v_lshlrev_b32_e32 v73, 2, v73
	v_cmp_lt_i32_e32 vcc, v70, v66
	s_waitcnt lgkmcnt(0)
	v_add_f32_e32 v62, v62, v63
	ds_bpermute_b32 v63, v73, v62
	v_cndmask_b32_e32 v73, v65, v70, vcc
	v_lshlrev_b32_e32 v73, 2, v73
	v_cmp_lt_i32_e32 vcc, v71, v66
	s_waitcnt lgkmcnt(0)
	v_add_f32_e32 v62, v62, v63
	ds_bpermute_b32 v63, v73, v62
	v_cndmask_b32_e32 v73, v65, v71, vcc
	v_lshlrev_b32_e32 v73, 2, v73
	v_cmp_lt_i32_e32 vcc, v72, v66
	s_waitcnt lgkmcnt(0)
	v_add_f32_e32 v62, v62, v63
	ds_bpermute_b32 v63, v73, v62
	v_cndmask_b32_e32 v73, v65, v72, vcc
	v_lshlrev_b32_e32 v73, 2, v73
	s_waitcnt lgkmcnt(0)
	v_add_f32_e32 v62, v62, v63
	ds_bpermute_b32 v63, v73, v62
	s_waitcnt lgkmcnt(0)
	v_add_f32_e32 v62, v62, v63
	v_fmamk_f32 v62, v62, 0x3a000000, v1
	v_mul_f32_e32 v63, 0x4f800000, v62
	v_cmp_gt_f32_e32 vcc, s3, v62
	s_nop 1
	v_cndmask_b32_e32 v62, v62, v63, vcc
	v_sqrt_f32_e32 v63, v62
	s_nop 0
	v_add_u32_e32 v73, -1, v63
	v_add_u32_e32 v78, 1, v63
	v_fma_f32 v79, -v73, v63, v62
	v_fma_f32 v80, -v78, v63, v62
	v_cmp_ge_f32_e64 s[0:1], 0, v79
	s_nop 1
	v_cndmask_b32_e64 v63, v63, v73, s[0:1]
	v_cmp_lt_f32_e64 s[0:1], 0, v80
	s_nop 1
	v_cndmask_b32_e64 v63, v63, v78, s[0:1]
	v_mul_f32_e32 v73, 0x37800000, v63
	v_cndmask_b32_e32 v63, v63, v73, vcc
	v_cmp_class_f32_e32 vcc, v62, v64
	s_nop 1
	v_cndmask_b32_e32 v73, v63, v62, vcc
	v_div_scale_f32 v78, s[0:1], v73, v73, 1.0
	v_rcp_f32_e32 v79, v78
	v_div_scale_f32 v80, vcc, 1.0, v73, 1.0
	v_lshl_add_u64 v[62:63], v[36:37], 0, s[14:15]
	v_fma_f32 v81, -v78, v79, 1.0
	v_fmac_f32_e32 v79, v81, v79
	v_mul_f32_e32 v81, v80, v79
	v_fma_f32 v82, -v78, v81, v80
	v_fmac_f32_e32 v81, v82, v79
	v_fma_f32 v78, -v78, v81, v80
	v_div_fmas_f32 v78, v78, v79, v81
	v_div_fixup_f32 v78, v78, v73, 1.0
	v_pk_mul_f32 v[30:31], v[30:31], v[78:79] op_sel_hi:[1,0]
	v_pk_mul_f32 v[32:33], v[32:33], v[78:79] op_sel_hi:[1,0]
	v_pk_mul_f32 v[30:31], v[74:75], v[30:31]
	v_pk_mul_f32 v[32:33], v[76:77], v[32:33]
	v_bfe_u32 v73, v30, 16, 1
	v_bfe_u32 v75, v32, 16, 1
	v_bfe_u32 v74, v31, 16, 1
	v_bfe_u32 v76, v33, 16, 1
	v_add3_u32 v30, v30, v73, s5
	v_add3_u32 v32, v32, v75, s5
	v_add3_u32 v31, v31, v74, s5
	v_add3_u32 v33, v33, v76, s5
	v_lshrrev_b32_e32 v30, 16, v30
	v_lshrrev_b32_e32 v32, 16, v32
	v_and_or_b32 v30, v31, s7, v30
	v_and_or_b32 v31, v33, s7, v32
	global_store_dwordx2 v[62:63], v[30:31], off
	global_load_dwordx4 v[30:33], v[38:39], off offset:1024
	v_pk_mul_f32 v[26:27], v[26:27], v[78:79] op_sel_hi:[1,0]
	v_pk_mul_f32 v[28:29], v[28:29], v[78:79] op_sel_hi:[1,0]
	v_pk_mul_f32 v[22:23], v[22:23], v[78:79] op_sel_hi:[1,0]
	v_pk_mul_f32 v[24:25], v[24:25], v[78:79] op_sel_hi:[1,0]
	v_pk_mul_f32 v[18:19], v[18:19], v[78:79] op_sel_hi:[1,0]
	v_pk_mul_f32 v[20:21], v[20:21], v[78:79] op_sel_hi:[1,0]
	v_pk_mul_f32 v[14:15], v[14:15], v[78:79] op_sel_hi:[1,0]
	v_pk_mul_f32 v[16:17], v[16:17], v[78:79] op_sel_hi:[1,0]
	v_pk_mul_f32 v[10:11], v[10:11], v[78:79] op_sel_hi:[1,0]
	v_pk_mul_f32 v[12:13], v[12:13], v[78:79] op_sel_hi:[1,0]
	v_pk_mul_f32 v[6:7], v[6:7], v[78:79] op_sel_hi:[1,0]
	v_pk_mul_f32 v[8:9], v[8:9], v[78:79] op_sel_hi:[1,0]
	v_pk_mul_f32 v[4:5], v[4:5], v[78:79] op_sel_hi:[1,0]
	v_pk_mul_f32 v[2:3], v[2:3], v[78:79] op_sel_hi:[1,0]
	s_mov_b64 s[0:1], 0
	s_waitcnt vmcnt(0)
	v_pk_mul_f32 v[28:29], v[32:33], v[28:29]
	v_pk_mul_f32 v[26:27], v[30:31], v[26:27]
	v_bfe_u32 v32, v28, 16, 1
	v_bfe_u32 v30, v26, 16, 1
	v_bfe_u32 v31, v27, 16, 1
	v_bfe_u32 v33, v29, 16, 1
	v_add3_u32 v26, v26, v30, s5
	v_add3_u32 v28, v28, v32, s5
	v_add3_u32 v27, v27, v31, s5
	v_add3_u32 v29, v29, v33, s5
	v_lshrrev_b32_e32 v26, 16, v26
	v_lshrrev_b32_e32 v28, 16, v28
	v_and_or_b32 v26, v27, s7, v26
	v_and_or_b32 v27, v29, s7, v28
	global_store_dwordx2 v[62:63], v[26:27], off offset:512
	global_load_dwordx4 v[26:29], v[38:39], off offset:2048
	s_waitcnt vmcnt(0)
	v_pk_mul_f32 v[24:25], v[28:29], v[24:25]
	v_pk_mul_f32 v[22:23], v[26:27], v[22:23]
	v_bfe_u32 v28, v24, 16, 1
	v_bfe_u32 v26, v22, 16, 1
	v_bfe_u32 v27, v23, 16, 1
	v_bfe_u32 v29, v25, 16, 1
	v_add3_u32 v22, v22, v26, s5
	v_add3_u32 v24, v24, v28, s5
	v_add3_u32 v23, v23, v27, s5
	v_add3_u32 v25, v25, v29, s5
	v_lshrrev_b32_e32 v22, 16, v22
	v_lshrrev_b32_e32 v24, 16, v24
	v_and_or_b32 v22, v23, s7, v22
	v_and_or_b32 v23, v25, s7, v24
	global_store_dwordx2 v[62:63], v[22:23], off offset:1024
	global_load_dwordx4 v[22:25], v[38:39], off offset:3072
	s_waitcnt vmcnt(0)
	v_pk_mul_f32 v[20:21], v[24:25], v[20:21]
	v_pk_mul_f32 v[18:19], v[22:23], v[18:19]
	v_bfe_u32 v24, v20, 16, 1
	v_bfe_u32 v22, v18, 16, 1
	v_bfe_u32 v23, v19, 16, 1
	v_bfe_u32 v25, v21, 16, 1
	v_add3_u32 v18, v18, v22, s5
	v_add3_u32 v20, v20, v24, s5
	v_add3_u32 v19, v19, v23, s5
	v_add3_u32 v21, v21, v25, s5
	v_lshrrev_b32_e32 v18, 16, v18
	v_lshrrev_b32_e32 v20, 16, v20
	v_and_or_b32 v18, v19, s7, v18
	v_and_or_b32 v19, v21, s7, v20
	global_store_dwordx2 v[62:63], v[18:19], off offset:1536
	global_load_dwordx4 v[18:21], v[40:41], off
	s_waitcnt vmcnt(0)
	v_pk_mul_f32 v[16:17], v[20:21], v[16:17]
	v_pk_mul_f32 v[14:15], v[18:19], v[14:15]
	v_bfe_u32 v20, v16, 16, 1
	v_bfe_u32 v18, v14, 16, 1
	v_bfe_u32 v19, v15, 16, 1
	v_bfe_u32 v21, v17, 16, 1
	v_add3_u32 v14, v14, v18, s5
	v_add3_u32 v16, v16, v20, s5
	v_add3_u32 v15, v15, v19, s5
	v_add3_u32 v17, v17, v21, s5
	v_lshrrev_b32_e32 v14, 16, v14
	v_lshrrev_b32_e32 v16, 16, v16
	v_and_or_b32 v14, v15, s7, v14
	v_and_or_b32 v15, v17, s7, v16
	global_store_dwordx2 v[62:63], v[14:15], off offset:2048
	global_load_dwordx4 v[14:17], v[42:43], off
	s_waitcnt vmcnt(0)
	v_pk_mul_f32 v[12:13], v[12:13], v[16:17]
	v_pk_mul_f32 v[10:11], v[10:11], v[14:15]
	v_bfe_u32 v16, v12, 16, 1
	v_bfe_u32 v14, v10, 16, 1
	v_bfe_u32 v15, v11, 16, 1
	v_bfe_u32 v17, v13, 16, 1
	v_add3_u32 v10, v10, v14, s5
	v_add3_u32 v12, v12, v16, s5
	v_add3_u32 v11, v11, v15, s5
	v_add3_u32 v13, v13, v17, s5
	v_lshrrev_b32_e32 v10, 16, v10
	v_lshrrev_b32_e32 v12, 16, v12
	v_and_or_b32 v10, v11, s7, v10
	v_and_or_b32 v11, v13, s7, v12
	global_store_dwordx2 v[62:63], v[10:11], off offset:2560
	global_load_dwordx4 v[10:13], v[44:45], off
	s_waitcnt vmcnt(0)
	v_pk_mul_f32 v[8:9], v[8:9], v[12:13]
	v_pk_mul_f32 v[6:7], v[6:7], v[10:11]
	v_bfe_u32 v12, v8, 16, 1
	v_bfe_u32 v10, v6, 16, 1
	v_bfe_u32 v11, v7, 16, 1
	v_bfe_u32 v13, v9, 16, 1
	v_add3_u32 v6, v6, v10, s5
	v_add3_u32 v8, v8, v12, s5
	v_add3_u32 v7, v7, v11, s5
	v_add3_u32 v9, v9, v13, s5
	v_lshrrev_b32_e32 v6, 16, v6
	v_lshrrev_b32_e32 v8, 16, v8
	v_and_or_b32 v6, v7, s7, v6
	v_and_or_b32 v7, v9, s7, v8
	global_store_dwordx2 v[62:63], v[6:7], off offset:3072
	global_load_dwordx4 v[6:9], v[46:47], off
	s_waitcnt vmcnt(0)
	v_pk_mul_f32 v[2:3], v[2:3], v[6:7]
	v_pk_mul_f32 v[4:5], v[4:5], v[8:9]
.LBB0_341:
	s_andn2_b64 vcc, exec, s[0:1]
	s_cbranch_vccnz .LBB0_338
	global_load_dwordx4 v[30:33], v[58:59], off offset:-4096
	global_load_dwordx4 v[26:29], v[58:59], off offset:-3072
	global_load_dwordx4 v[22:25], v[58:59], off offset:-2048
	global_load_dwordx4 v[14:17], v[58:59], off
	global_load_dwordx4 v[18:21], v[58:59], off offset:-1024
	global_load_dwordx4 v[10:13], v[58:59], off offset:1024
	global_load_dwordx4 v[2:5], v[58:59], off offset:3072
	global_load_dwordx4 v[6:9], v[58:59], off offset:2048
	global_load_dwordx4 v[74:77], v[48:49], off
	v_cmp_lt_i32_e32 vcc, v67, v66
	s_waitcnt vmcnt(0)
	v_mov_b32_e32 v78, v31
	v_cndmask_b32_e32 v62, v65, v67, vcc
	v_mov_b32_e32 v79, v27
	v_mov_b32_e32 v84, v33
	v_mov_b32_e32 v85, v29
	v_lshlrev_b32_e32 v73, 2, v62
	v_mov_b32_e32 v62, v30
	v_mov_b32_e32 v63, v26
	v_mov_b32_e32 v80, v32
	v_mov_b32_e32 v81, v28
	v_pk_mul_f32 v[86:87], v[24:25], v[24:25]
	v_pk_mul_f32 v[88:89], v[22:23], v[22:23]
	v_pk_mul_f32 v[78:79], v[78:79], v[78:79]
	v_pk_mul_f32 v[84:85], v[84:85], v[84:85]
	v_pk_mov_b32 v[100:101], v[88:89], v[86:87] op_sel:[1,0]
	v_mov_b32_e32 v89, v87
	v_pk_fma_f32 v[62:63], v[62:63], v[62:63], v[78:79]
	v_pk_fma_f32 v[78:79], v[80:81], v[80:81], v[84:85]
	v_mul_f32_e32 v82, v19, v19
	v_mul_f32_e32 v90, v21, v21
	v_pk_add_f32 v[80:81], v[100:101], v[88:89]
	v_pk_add_f32 v[62:63], v[62:63], v[78:79]
	v_mul_f32_e32 v99, v14, v14
	v_mul_f32_e32 v104, v15, v15
	v_mul_f32_e32 v105, v16, v16
	v_mul_f32_e32 v106, v17, v17
	v_pk_fma_f32 v[86:87], v[18:19], v[18:19], v[82:83] op_sel_hi:[1,1,0]
	v_pk_fma_f32 v[90:91], v[20:21], v[20:21], v[90:91] op_sel_hi:[1,1,0]
	v_pk_add_f32 v[78:79], v[80:81], v[80:81] op_sel:[0,1] op_sel_hi:[1,0]
	v_pk_add_f32 v[62:63], v[62:63], v[62:63] op_sel:[0,1] op_sel_hi:[1,0]
	v_pk_mul_f32 v[92:93], v[12:13], v[12:13]
	v_pk_mul_f32 v[94:95], v[10:11], v[10:11]
	v_mov_b32_e32 v87, v105
	v_mov_b32_e32 v91, v106
	v_mov_b32_e32 v79, v104
	v_mov_b32_e32 v63, v99
	v_pk_mov_b32 v[102:103], v[94:95], v[92:93] op_sel:[1,0]
	v_mov_b32_e32 v95, v93
	v_pk_add_f32 v[80:81], v[86:87], v[90:91]
	v_pk_add_f32 v[62:63], v[62:63], v[78:79]
	v_mul_f32_e32 v96, v7, v7
	v_mul_f32_e32 v98, v9, v9
	v_pk_add_f32 v[84:85], v[102:103], v[94:95]
	v_pk_add_f32 v[62:63], v[62:63], v[80:81]
	v_mul_f32_e32 v107, v2, v2
	v_mul_f32_e32 v108, v3, v3
	v_mul_f32_e32 v109, v4, v4
	v_mul_f32_e32 v110, v5, v5
	v_pk_fma_f32 v[92:93], v[6:7], v[6:7], v[96:97] op_sel_hi:[1,1,0]
	v_pk_fma_f32 v[96:97], v[8:9], v[8:9], v[98:99] op_sel_hi:[1,1,0]
	v_pk_add_f32 v[84:85], v[84:85], v[84:85] op_sel:[0,1] op_sel_hi:[1,0]
	v_pk_add_f32 v[62:63], v[62:63], v[62:63] op_sel:[0,1] op_sel_hi:[1,0]
	v_mov_b32_e32 v93, v109
	v_mov_b32_e32 v97, v110
	v_mov_b32_e32 v85, v108
	v_mov_b32_e32 v63, v107
	v_pk_add_f32 v[86:87], v[92:93], v[96:97]
	v_pk_add_f32 v[62:63], v[62:63], v[84:85]
	v_cmp_lt_i32_e32 vcc, v68, v66
	v_pk_add_f32 v[62:63], v[62:63], v[86:87]
	s_nop 0
	v_add_f32_e32 v62, v62, v63
	ds_bpermute_b32 v63, v73, v62
	v_cndmask_b32_e32 v73, v65, v68, vcc
	v_lshlrev_b32_e32 v73, 2, v73
	v_cmp_lt_i32_e32 vcc, v69, v66
	s_waitcnt lgkmcnt(0)
	v_add_f32_e32 v62, v62, v63
	ds_bpermute_b32 v63, v73, v62
	v_cndmask_b32_e32 v73, v65, v69, vcc
	v_lshlrev_b32_e32 v73, 2, v73
	v_cmp_lt_i32_e32 vcc, v70, v66
	s_waitcnt lgkmcnt(0)
	v_add_f32_e32 v62, v62, v63
	ds_bpermute_b32 v63, v73, v62
	v_cndmask_b32_e32 v73, v65, v70, vcc
	v_lshlrev_b32_e32 v73, 2, v73
	v_cmp_lt_i32_e32 vcc, v71, v66
	s_waitcnt lgkmcnt(0)
	v_add_f32_e32 v62, v62, v63
	ds_bpermute_b32 v63, v73, v62
	v_cndmask_b32_e32 v73, v65, v71, vcc
	v_lshlrev_b32_e32 v73, 2, v73
	v_cmp_lt_i32_e32 vcc, v72, v66
	s_waitcnt lgkmcnt(0)
	v_add_f32_e32 v62, v62, v63
	ds_bpermute_b32 v63, v73, v62
	v_cndmask_b32_e32 v73, v65, v72, vcc
	v_lshlrev_b32_e32 v73, 2, v73
	s_waitcnt lgkmcnt(0)
	v_add_f32_e32 v62, v62, v63
	ds_bpermute_b32 v63, v73, v62
	s_waitcnt lgkmcnt(0)
	v_add_f32_e32 v62, v62, v63
	v_fmamk_f32 v62, v62, 0x3a000000, v1
	v_mul_f32_e32 v63, 0x4f800000, v62
	v_cmp_gt_f32_e32 vcc, s3, v62
	s_nop 1
	v_cndmask_b32_e32 v62, v62, v63, vcc
	v_sqrt_f32_e32 v63, v62
	s_nop 0
	v_add_u32_e32 v73, -1, v63
	v_add_u32_e32 v78, 1, v63
	v_fma_f32 v79, -v73, v63, v62
	v_fma_f32 v80, -v78, v63, v62
	v_cmp_ge_f32_e64 s[0:1], 0, v79
	s_nop 1
	v_cndmask_b32_e64 v63, v63, v73, s[0:1]
	v_cmp_lt_f32_e64 s[0:1], 0, v80
	s_nop 1
	v_cndmask_b32_e64 v63, v63, v78, s[0:1]
	v_mul_f32_e32 v73, 0x37800000, v63
	v_cndmask_b32_e32 v63, v63, v73, vcc
	v_cmp_class_f32_e32 vcc, v62, v64
	s_nop 1
	v_cndmask_b32_e32 v62, v63, v62, vcc
	v_div_scale_f32 v63, s[0:1], v62, v62, 1.0
	v_rcp_f32_e32 v73, v63
	v_div_scale_f32 v78, vcc, 1.0, v62, 1.0
	v_fma_f32 v79, -v63, v73, 1.0
	v_fmac_f32_e32 v73, v79, v73
	v_mul_f32_e32 v79, v78, v73
	v_fma_f32 v80, -v63, v79, v78
	v_fmac_f32_e32 v79, v80, v73
	v_fma_f32 v63, -v63, v79, v78
	v_div_fmas_f32 v63, v63, v73, v79
	v_div_fixup_f32 v62, v63, v62, 1.0
	v_pk_mul_f32 v[30:31], v[30:31], v[62:63] op_sel_hi:[1,0]
	v_pk_mul_f32 v[32:33], v[32:33], v[62:63] op_sel_hi:[1,0]
	v_pk_mul_f32 v[30:31], v[74:75], v[30:31]
	v_pk_mul_f32 v[32:33], v[76:77], v[32:33]
	v_bfe_u32 v63, v30, 16, 1
	v_bfe_u32 v74, v32, 16, 1
	v_bfe_u32 v73, v31, 16, 1
	v_bfe_u32 v75, v33, 16, 1
	v_add3_u32 v30, v30, v63, s5
	v_add3_u32 v32, v32, v74, s5
	v_add3_u32 v31, v31, v73, s5
	v_add3_u32 v33, v33, v75, s5
	v_lshrrev_b32_e32 v30, 16, v30
	v_lshrrev_b32_e32 v32, 16, v32
	v_and_or_b32 v30, v31, s7, v30
	v_and_or_b32 v31, v33, s7, v32
	global_store_dwordx2 v[60:61], v[30:31], off
	global_load_dwordx4 v[30:33], v[48:49], off offset:1024
	v_pk_mul_f32 v[26:27], v[26:27], v[62:63] op_sel_hi:[1,0]
	v_pk_mul_f32 v[28:29], v[28:29], v[62:63] op_sel_hi:[1,0]
	v_pk_mul_f32 v[22:23], v[22:23], v[62:63] op_sel_hi:[1,0]
	v_pk_mul_f32 v[24:25], v[24:25], v[62:63] op_sel_hi:[1,0]
	v_pk_mul_f32 v[18:19], v[18:19], v[62:63] op_sel_hi:[1,0]
	v_pk_mul_f32 v[20:21], v[20:21], v[62:63] op_sel_hi:[1,0]
	v_pk_mul_f32 v[14:15], v[14:15], v[62:63] op_sel_hi:[1,0]
	v_pk_mul_f32 v[16:17], v[16:17], v[62:63] op_sel_hi:[1,0]
	v_pk_mul_f32 v[10:11], v[10:11], v[62:63] op_sel_hi:[1,0]
	v_pk_mul_f32 v[12:13], v[12:13], v[62:63] op_sel_hi:[1,0]
	v_pk_mul_f32 v[6:7], v[6:7], v[62:63] op_sel_hi:[1,0]
	v_pk_mul_f32 v[8:9], v[8:9], v[62:63] op_sel_hi:[1,0]
	v_pk_mul_f32 v[4:5], v[4:5], v[62:63] op_sel_hi:[1,0]
	v_pk_mul_f32 v[2:3], v[2:3], v[62:63] op_sel_hi:[1,0]
	v_mov_b64_e32 v[62:63], v[60:61]
	s_waitcnt vmcnt(0)
	v_pk_mul_f32 v[28:29], v[32:33], v[28:29]
	v_pk_mul_f32 v[26:27], v[30:31], v[26:27]
	v_bfe_u32 v32, v28, 16, 1
	v_bfe_u32 v30, v26, 16, 1
	v_bfe_u32 v31, v27, 16, 1
	v_bfe_u32 v33, v29, 16, 1
	v_add3_u32 v26, v26, v30, s5
	v_add3_u32 v28, v28, v32, s5
	v_add3_u32 v27, v27, v31, s5
	v_add3_u32 v29, v29, v33, s5
	v_lshrrev_b32_e32 v26, 16, v26
	v_lshrrev_b32_e32 v28, 16, v28
	v_and_or_b32 v26, v27, s7, v26
	v_and_or_b32 v27, v29, s7, v28
	global_store_dwordx2 v[60:61], v[26:27], off offset:512
	global_load_dwordx4 v[26:29], v[48:49], off offset:2048
	s_waitcnt vmcnt(0)
	v_pk_mul_f32 v[24:25], v[28:29], v[24:25]
	v_pk_mul_f32 v[22:23], v[26:27], v[22:23]
	v_bfe_u32 v28, v24, 16, 1
	v_bfe_u32 v26, v22, 16, 1
	v_bfe_u32 v27, v23, 16, 1
	v_bfe_u32 v29, v25, 16, 1
	v_add3_u32 v22, v22, v26, s5
	v_add3_u32 v24, v24, v28, s5
	v_add3_u32 v23, v23, v27, s5
	v_add3_u32 v25, v25, v29, s5
	v_lshrrev_b32_e32 v22, 16, v22
	v_lshrrev_b32_e32 v24, 16, v24
	v_and_or_b32 v22, v23, s7, v22
	v_and_or_b32 v23, v25, s7, v24
	global_store_dwordx2 v[60:61], v[22:23], off offset:1024
	global_load_dwordx4 v[22:25], v[48:49], off offset:3072
	s_waitcnt vmcnt(0)
	v_pk_mul_f32 v[20:21], v[24:25], v[20:21]
	v_pk_mul_f32 v[18:19], v[22:23], v[18:19]
	v_bfe_u32 v24, v20, 16, 1
	v_bfe_u32 v22, v18, 16, 1
	v_bfe_u32 v23, v19, 16, 1
	v_bfe_u32 v25, v21, 16, 1
	v_add3_u32 v18, v18, v22, s5
	v_add3_u32 v20, v20, v24, s5
	v_add3_u32 v19, v19, v23, s5
	v_add3_u32 v21, v21, v25, s5
	v_lshrrev_b32_e32 v18, 16, v18
	v_lshrrev_b32_e32 v20, 16, v20
	v_and_or_b32 v18, v19, s7, v18
	v_and_or_b32 v19, v21, s7, v20
	global_store_dwordx2 v[60:61], v[18:19], off offset:1536
	global_load_dwordx4 v[18:21], v[50:51], off
	s_waitcnt vmcnt(0)
	v_pk_mul_f32 v[16:17], v[20:21], v[16:17]
	v_pk_mul_f32 v[14:15], v[18:19], v[14:15]
	v_bfe_u32 v20, v16, 16, 1
	v_bfe_u32 v18, v14, 16, 1
	v_bfe_u32 v19, v15, 16, 1
	v_bfe_u32 v21, v17, 16, 1
	v_add3_u32 v14, v14, v18, s5
	v_add3_u32 v16, v16, v20, s5
	v_add3_u32 v15, v15, v19, s5
	v_add3_u32 v17, v17, v21, s5
	v_lshrrev_b32_e32 v14, 16, v14
	v_lshrrev_b32_e32 v16, 16, v16
	v_and_or_b32 v14, v15, s7, v14
	v_and_or_b32 v15, v17, s7, v16
	global_store_dwordx2 v[60:61], v[14:15], off offset:2048
	global_load_dwordx4 v[14:17], v[52:53], off
	s_waitcnt vmcnt(0)
	v_pk_mul_f32 v[12:13], v[12:13], v[16:17]
	v_pk_mul_f32 v[10:11], v[10:11], v[14:15]
	v_bfe_u32 v16, v12, 16, 1
	v_bfe_u32 v14, v10, 16, 1
	v_bfe_u32 v15, v11, 16, 1
	v_bfe_u32 v17, v13, 16, 1
	v_add3_u32 v10, v10, v14, s5
	v_add3_u32 v12, v12, v16, s5
	v_add3_u32 v11, v11, v15, s5
	v_add3_u32 v13, v13, v17, s5
	v_lshrrev_b32_e32 v10, 16, v10
	v_lshrrev_b32_e32 v12, 16, v12
	v_and_or_b32 v10, v11, s7, v10
	v_and_or_b32 v11, v13, s7, v12
	global_store_dwordx2 v[60:61], v[10:11], off offset:2560
	global_load_dwordx4 v[10:13], v[54:55], off
	s_waitcnt vmcnt(0)
	v_pk_mul_f32 v[8:9], v[8:9], v[12:13]
	v_pk_mul_f32 v[6:7], v[6:7], v[10:11]
	v_bfe_u32 v12, v8, 16, 1
	v_bfe_u32 v10, v6, 16, 1
	v_bfe_u32 v11, v7, 16, 1
	v_bfe_u32 v13, v9, 16, 1
	v_add3_u32 v6, v6, v10, s5
	v_add3_u32 v8, v8, v12, s5
	v_add3_u32 v7, v7, v11, s5
	v_add3_u32 v9, v9, v13, s5
	v_lshrrev_b32_e32 v6, 16, v6
	v_lshrrev_b32_e32 v8, 16, v8
	v_and_or_b32 v6, v7, s7, v6
	v_and_or_b32 v7, v9, s7, v8
	global_store_dwordx2 v[60:61], v[6:7], off offset:3072
	global_load_dwordx4 v[6:9], v[56:57], off
	s_waitcnt vmcnt(0)
	v_pk_mul_f32 v[2:3], v[2:3], v[6:7]
	v_pk_mul_f32 v[4:5], v[4:5], v[8:9]
	s_branch .LBB0_338

.LBB0_349:
	global_load_dword v48, v[2:3], off sc1
	global_load_dword v1, v[4:5], off sc1
	global_load_dword v34, v[6:7], off sc1
	global_load_dword v35, v[8:9], off sc1
	global_load_dword v36, v[10:11], off sc1
	global_load_dword v37, v[12:13], off sc1
	global_load_dword v38, v[14:15], off sc1
	global_load_dword v39, v[16:17], off sc1
	global_load_dword v40, v[18:19], off sc1
	global_load_dword v41, v[20:21], off sc1
	global_load_dword v42, v[22:23], off sc1
	global_load_dword v43, v[24:25], off sc1
	global_load_dword v44, v[26:27], off sc1
	global_load_dword v45, v[28:29], off sc1
	global_load_dword v46, v[30:31], off sc1
	global_load_dword v47, v[32:33], off sc1
	s_or_b64 s[10:11], s[10:11], exec
	s_or_b64 s[8:9], s[8:9], exec
	s_waitcnt vmcnt(0) lgkmcnt(0)
	v_add_u32_e32 v49, v1, v48
	v_add_u32_e32 v49, v49, v34
	v_add_u32_e32 v49, v49, v35
	v_add_u32_e32 v49, v49, v36
	v_add_u32_e32 v49, v49, v37
	v_add_u32_e32 v49, v49, v38
	v_add_u32_e32 v49, v49, v39
	v_add_u32_e32 v49, v49, v40
	v_add_u32_e32 v49, v49, v41
	v_add_u32_e32 v49, v49, v42
	v_add_u32_e32 v49, v49, v43
	v_add_u32_e32 v49, v49, v44
	v_add_u32_e32 v49, v49, v45
	v_add_u32_e32 v49, v49, v46
	v_add_u32_e32 v49, v49, v47
	v_cmp_ne_u32_e32 vcc, s3, v49
	s_and_saveexec_b64 s[12:13], vcc
	s_cbranch_execz .LBB0_348
	s_and_b32 s15, s14, 0xff
	s_mov_b64 s[16:17], -1
	s_cmp_eq_u32 s15, 0
	s_mov_b64 s[20:21], -1
	s_mov_b64 s[18:19], -1
	s_sleep 1
	s_cbranch_scc1 .LBB0_352
	s_and_saveexec_b64 s[22:23], s[20:21]
	s_cbranch_execz .LBB0_347
	s_branch .LBB0_355
.LBB0_352:
	v_mov_b64_e32 v[50:51], s[0:1]
	global_load_dword v49, v[50:51], off sc1
	s_mov_b64 s[20:21], 0
	s_waitcnt vmcnt(0) lgkmcnt(0)
	v_cmp_eq_u32_e32 vcc, 0, v49
	s_and_saveexec_b64 s[22:23], vcc
	s_cmp_lt_u32 s14, 0x40001
	s_cselect_b64 s[20:21], -1, 0
	s_xor_b64 s[18:19], exec, -1
	s_and_b64 s[20:21], s[20:21], exec
	s_or_b64 exec, exec, s[22:23]
	s_and_saveexec_b64 s[22:23], s[20:21]
	s_cbranch_execz .LBB0_347

.LBB0_356:
	s_or_b64 exec, exec, s[4:5]
	s_xor_b64 s[4:5], s[6:7], -1
	s_and_saveexec_b64 s[6:7], s[4:5]
	s_xor_b64 s[4:5], exec, s[6:7]
	s_cbranch_execz .LBB0_358
	v_mov_b32_e32 v4, 1
	v_mov_b64_e32 v[2:3], s[0:1]
	global_atomic_add v[2:3], v4, off

.LBB0_359:
	s_lshl_b32 s0, s2, 8
	s_add_u32 s0, s42, s0
	s_addc_u32 s1, s43, 0
	v_mov_b32_e32 v1, s0
	v_add_co_u32_e32 v6, vcc, 0x101000, v1
	v_mov_b32_e32 v1, s1
	s_nop 0
	v_addc_co_u32_e32 v7, vcc, 0, v1, vcc
	v_mov_b32_e32 v1, 1
	global_atomic_add v1, v[6:7], v1, off offset:1024 sc0
	v_cvt_f32_u32_e32 v3, v4
	v_sub_u32_e32 v5, 0, v4
	s_add_u32 s3, s0, 0x100000
	s_addc_u32 s2, s1, 0
	v_rcp_iflag_f32_e32 v3, v3
	s_waitcnt vmcnt(0) lgkmcnt(0)
	v_add_u32_e32 v6, 1, v1
	v_mul_f32_e32 v3, 0x4f7ffffe, v3
	v_cvt_u32_f32_e32 v3, v3
	v_mul_lo_u32 v5, v5, v3
	v_mul_hi_u32 v5, v3, v5
	v_add_u32_e32 v3, v3, v5
	v_mul_hi_u32 v3, v1, v3
	v_mul_lo_u32 v5, v3, v4
	v_sub_u32_e32 v1, v1, v5
	v_add_u32_e32 v7, 1, v3
	v_cmp_ge_u32_e32 vcc, v1, v4
	v_sub_u32_e32 v5, v1, v4
	s_nop 0
	v_cndmask_b32_e32 v3, v3, v7, vcc
	v_cndmask_b32_e32 v1, v1, v5, vcc
	v_add_u32_e32 v5, 1, v3
	v_cmp_ge_u32_e32 vcc, v1, v4
	s_nop 1
	v_cndmask_b32_e32 v1, v3, v5, vcc
	v_mad_u64_u32 v[4:5], s[0:1], v4, v1, v[4:5]
	v_cmp_ne_u32_e32 vcc, v6, v4
	s_and_saveexec_b64 s[0:1], vcc
	s_xor_b64 s[0:1], exec, s[0:1]
	s_cbranch_execz .LBB0_372
	v_mov_b32_e32 v2, s3
	v_add_co_u32_e32 v2, vcc, 0x2000, v2
	v_mov_b32_e32 v3, s2
	s_nop 0
	v_addc_co_u32_e32 v3, vcc, 0, v3, vcc
	global_load_dword v2, v[2:3], off offset:1024 sc1
	s_add_u32 s8, s3, 0x2400
	s_addc_u32 s9, s2, 0
	s_waitcnt vmcnt(0) lgkmcnt(0)
	v_cmp_eq_u32_e32 vcc, v2, v1
	s_and_saveexec_b64 s[4:5], vcc
	s_cbranch_execz .LBB0_371
	s_add_u32 s6, s42, 0x100200
	s_addc_u32 s7, s43, 0
	s_mov_b32 s14, 1
	s_mov_b64 s[10:11], 0
	s_branch .LBB0_363

.LBB0_363:
	s_and_b32 s15, s14, 0xff
	s_mov_b64 s[18:19], -1
	s_cmp_lg_u32 s15, 0
	s_mov_b64 s[20:21], -1
	s_sleep 1
	s_cbranch_scc1 .LBB0_367
	v_mov_b64_e32 v[2:3], s[6:7]
	global_load_dword v2, v[2:3], off sc1
	s_mov_b64 s[20:21], 0
	s_mov_b64 s[22:23], -1
	s_waitcnt vmcnt(0) lgkmcnt(0)
	v_cmp_eq_u32_e32 vcc, 0, v2
	s_and_saveexec_b64 s[24:25], vcc
	s_cmp_lt_u32 s14, 0x40001
	s_cselect_b64 s[20:21], -1, 0
	s_xor_b64 s[22:23], exec, -1
	s_and_b64 s[20:21], s[20:21], exec
	s_or_b64 exec, exec, s[24:25]
.LBB0_367:
	s_andn2_b64 s[16:17], s[16:17], exec
	s_and_b64 s[22:23], s[22:23], exec
	s_or_b64 s[16:17], s[16:17], s[22:23]
	s_and_saveexec_b64 s[22:23], s[20:21]
	s_cbranch_execz .LBB0_362
	v_mov_b64_e32 v[2:3], s[8:9]
	global_load_dword v2, v[2:3], off sc1
	s_add_i32 s14, s14, 1
	s_or_b64 s[16:17], s[16:17], exec
	s_waitcnt vmcnt(0) lgkmcnt(0)
	v_cmp_ne_u32_e32 vcc, v2, v1
	s_orn2_b64 s[18:19], vcc, exec
	s_branch .LBB0_362
.LBB0_369:
	s_or_b64 exec, exec, s[10:11]
	s_xor_b64 s[8:9], s[12:13], -1
	s_and_saveexec_b64 s[10:11], s[8:9]
	s_xor_b64 s[10:11], exec, s[10:11]
	s_cbranch_execz .LBB0_371
	v_mov_b32_e32 v1, 1
	v_mov_b64_e32 v[2:3], s[6:7]
	global_atomic_add v[2:3], v1, off

.LBB0_372:
	s_andn2_saveexec_b64 s[0:1], s[0:1]
	s_cbranch_execz .LBB0_388
	v_mov_b32_e32 v1, s42
	v_add_co_u32_e32 v4, vcc, 0x103000, v1
	v_mov_b32_e32 v1, s43
	buffer_wbl2 sc1
	s_waitcnt vmcnt(0)
	v_addc_co_u32_e32 v5, vcc, 0, v1, vcc
	v_mov_b32_e32 v1, 1
	global_atomic_add v1, v[4:5], v1, off offset:1024 sc0
	v_cvt_f32_u32_e32 v3, v2
	v_sub_u32_e32 v4, 0, v2
	s_add_u32 s0, s42, 0x103500
	s_addc_u32 s1, s43, 0
	v_rcp_iflag_f32_e32 v3, v3
	s_mov_b64 s[6:7], -1
	v_mul_f32_e32 v3, 0x4f7ffffe, v3
	v_cvt_u32_f32_e32 v3, v3
	v_mul_lo_u32 v4, v4, v3
	v_mul_hi_u32 v4, v3, v4
	v_add_u32_e32 v3, v3, v4
	s_waitcnt vmcnt(0) lgkmcnt(0)
	v_mul_hi_u32 v3, v1, v3
	v_mul_lo_u32 v5, v3, v2
	v_add_u32_e32 v4, 1, v1
	v_sub_u32_e32 v1, v1, v5
	v_add_u32_e32 v6, 1, v3
	v_cmp_ge_u32_e32 vcc, v1, v2
	v_sub_u32_e32 v5, v1, v2
	s_nop 0
	v_cndmask_b32_e32 v3, v3, v6, vcc
	v_cndmask_b32_e32 v1, v1, v5, vcc
	v_add_u32_e32 v5, 1, v3
	v_cmp_ge_u32_e32 vcc, v1, v2
	s_nop 1
	v_cndmask_b32_e32 v1, v3, v5, vcc
	v_mad_u64_u32 v[2:3], s[4:5], v2, v1, v[2:3]
	v_cmp_ne_u32_e32 vcc, v4, v2
	v_mov_b64_e32 v[2:3], s[0:1]
	s_and_saveexec_b64 s[4:5], vcc
	s_cbranch_execz .LBB0_385
	v_mov_b64_e32 v[2:3], s[0:1]
	global_load_dword v2, v[2:3], off sc1
	s_mov_b64 s[10:11], 0
	s_waitcnt vmcnt(0) lgkmcnt(0)
	v_cmp_eq_u32_e32 vcc, v2, v1
	s_and_saveexec_b64 s[8:9], vcc
	s_cbranch_execz .LBB0_384
	s_add_u32 s6, s42, 0x100200
	s_addc_u32 s7, s43, 0
	s_mov_b32 s14, 1
	s_branch .LBB0_377

.LBB0_379:
	v_mov_b64_e32 v[2:3], s[6:7]
	global_load_dword v2, v[2:3], off sc1
	s_mov_b64 s[18:19], 0
	s_mov_b64 s[16:17], -1
	s_waitcnt vmcnt(0) lgkmcnt(0)
	v_cmp_eq_u32_e32 vcc, 0, v2
	s_and_saveexec_b64 s[20:21], vcc
	s_cmp_lt_u32 s14, 0x40001
	s_cselect_b64 s[18:19], -1, 0
	s_xor_b64 s[16:17], exec, -1
	s_and_b64 s[18:19], s[18:19], exec
	s_or_b64 exec, exec, s[20:21]
	s_mov_b64 s[20:21], -1
	s_and_saveexec_b64 s[22:23], s[18:19]
	s_cbranch_execz .LBB0_376
.LBB0_382:
	v_mov_b64_e32 v[2:3], s[0:1]
	global_load_dword v2, v[2:3], off sc1
	s_add_i32 s14, s14, 1
	s_or_b64 s[16:17], s[16:17], exec
	s_waitcnt vmcnt(0) lgkmcnt(0)
	v_cmp_ne_u32_e32 vcc, v2, v1
	s_orn2_b64 s[20:21], vcc, exec
	s_branch .LBB0_376

.LBB0_385:
	s_or_b64 exec, exec, s[4:5]
	s_and_saveexec_b64 s[0:1], s[6:7]
	s_cbranch_execz .LBB0_387
	v_mov_b32_e32 v1, 1
	global_atomic_add v[2:3], v1, off
.LBB0_387:
	s_or_b64 exec, exec, s[0:1]
	v_mov_b32_e32 v1, s3
	v_add_co_u32_e32 v2, vcc, 0x2000, v1
	v_mov_b32_e32 v1, s2
	s_nop 0
	v_addc_co_u32_e32 v3, vcc, 0, v1, vcc
	v_mov_b32_e32 v1, 1
	s_waitcnt vmcnt(0) lgkmcnt(0)
	buffer_inv sc1
	global_atomic_add v[2:3], v1, off offset:1024
	s_waitcnt vmcnt(0)

.LBB0_413:
	v_pk_mul_f32 v[154:155], v[124:125], s[10:11] op_sel_hi:[1,0]
	v_pk_mul_f32 v[120:121], v[124:125], v[120:121]
	v_pk_mul_f32 v[124:125], v[116:117], s[10:11] op_sel_hi:[1,0]
	v_pk_mul_f32 v[156:157], v[126:127], s[10:11] op_sel_hi:[1,0]
	v_pk_mul_f32 v[122:123], v[126:127], v[122:123]
	v_exp_f32_e32 v124, v124
	v_exp_f32_e32 v125, v125
	v_pk_mul_f32 v[126:127], v[118:119], s[10:11] op_sel_hi:[1,0]
	v_exp_f32_e32 v154, v154
	v_exp_f32_e32 v155, v155
	v_exp_f32_e32 v156, v156
	v_exp_f32_e32 v157, v157
	v_exp_f32_e32 v126, v126
	v_exp_f32_e32 v127, v127
	v_pk_add_f32 v[124:125], v[124:125], 1.0 op_sel_hi:[1,0]
	v_pk_add_f32 v[154:155], v[154:155], 1.0 op_sel_hi:[1,0]
	v_pk_add_f32 v[156:157], v[156:157], 1.0 op_sel_hi:[1,0]
	v_rcp_f32_e32 v124, v124
	v_rcp_f32_e32 v125, v125
	v_pk_add_f32 v[126:127], v[126:127], 1.0 op_sel_hi:[1,0]
	v_rcp_f32_e32 v154, v154
	v_rcp_f32_e32 v155, v155
	v_rcp_f32_e32 v156, v156
	v_rcp_f32_e32 v157, v157
	v_rcp_f32_e32 v126, v126
	v_rcp_f32_e32 v127, v127
	v_pk_mul_f32 v[112:113], v[116:117], v[112:113]
	v_lshl_add_u32 v152, s40, 7, v146
	v_pk_mul_f32 v[114:115], v[118:119], v[114:115]
	v_pk_mul_f32 v[112:113], v[124:125], v[112:113]
	v_lshl_add_u32 v150, s22, 8, v144
	v_ashrrev_i32_e32 v153, 31, v152
	v_pk_mul_f32 v[120:121], v[154:155], v[120:121]
	v_pk_mul_f32 v[122:123], v[156:157], v[122:123]
	v_pk_mul_f32 v[114:115], v[126:127], v[114:115]
	v_cvt_pk_bf16_f32 v116, v120, v121
	v_cvt_pk_bf16_f32 v117, v122, v123
	v_cvt_pk_bf16_f32 v118, v112, v113
	v_mov_b64_e32 v[112:113], s[6:7]
	v_cvt_pk_bf16_f32 v119, v114, v115
	v_mad_i64_i32 v[120:121], s[24:25], v150, s39, v[112:113]
	v_lshlrev_b64 v[114:115], 1, v[152:153]
	v_lshl_add_u64 v[120:121], v[120:121], 0, v[114:115]
	global_store_dwordx4 v[120:121], v[116:119], off
	v_pk_mul_f32 v[104:105], v[108:109], v[104:105]
	v_pk_mul_f32 v[106:107], v[110:111], v[106:107]
	v_pk_mul_f32 v[116:117], v[108:109], s[10:11] op_sel_hi:[1,0]
	v_pk_mul_f32 v[108:109], v[100:101], s[10:11] op_sel_hi:[1,0]
	v_pk_mul_f32 v[118:119], v[110:111], s[10:11] op_sel_hi:[1,0]
	v_exp_f32_e32 v108, v108
	v_exp_f32_e32 v109, v109
	v_pk_mul_f32 v[110:111], v[102:103], s[10:11] op_sel_hi:[1,0]
	v_exp_f32_e32 v116, v116
	v_exp_f32_e32 v117, v117
	v_exp_f32_e32 v118, v118
	v_exp_f32_e32 v119, v119
	v_exp_f32_e32 v110, v110
	v_exp_f32_e32 v111, v111
	v_pk_add_f32 v[108:109], v[108:109], 1.0 op_sel_hi:[1,0]
	v_pk_add_f32 v[116:117], v[116:117], 1.0 op_sel_hi:[1,0]
	v_pk_add_f32 v[118:119], v[118:119], 1.0 op_sel_hi:[1,0]
	v_rcp_f32_e32 v108, v108
	v_rcp_f32_e32 v109, v109
	v_pk_add_f32 v[110:111], v[110:111], 1.0 op_sel_hi:[1,0]
	v_rcp_f32_e32 v116, v116
	v_rcp_f32_e32 v117, v117
	v_rcp_f32_e32 v118, v118
	v_rcp_f32_e32 v119, v119
	v_rcp_f32_e32 v110, v110
	v_rcp_f32_e32 v111, v111
	v_pk_mul_f32 v[96:97], v[100:101], v[96:97]
	v_or_b32_e32 v120, 16, v150
	v_pk_mul_f32 v[98:99], v[102:103], v[98:99]
	v_pk_mul_f32 v[100:101], v[108:109], v[96:97]
	v_pk_mul_f32 v[104:105], v[116:117], v[104:105]
	v_pk_mul_f32 v[106:107], v[118:119], v[106:107]
	v_pk_mul_f32 v[102:103], v[110:111], v[98:99]
	v_cvt_pk_bf16_f32 v96, v104, v105
	v_cvt_pk_bf16_f32 v97, v106, v107
	v_cvt_pk_bf16_f32 v98, v100, v101
	v_mad_i64_i32 v[100:101], s[24:25], v120, s39, v[112:113]
	v_lshl_add_u64 v[100:101], v[100:101], 0, v[114:115]
	v_cvt_pk_bf16_f32 v99, v102, v103
	global_store_dwordx4 v[100:101], v[96:99], off
	v_pk_mul_f32 v[88:89], v[92:93], v[88:89]
	v_pk_mul_f32 v[90:91], v[94:95], v[90:91]
	v_pk_mul_f32 v[96:97], v[92:93], s[10:11] op_sel_hi:[1,0]
	v_pk_mul_f32 v[92:93], v[84:85], s[10:11] op_sel_hi:[1,0]
	v_pk_mul_f32 v[98:99], v[94:95], s[10:11] op_sel_hi:[1,0]
	v_exp_f32_e32 v92, v92
	v_exp_f32_e32 v93, v93
	v_pk_mul_f32 v[94:95], v[86:87], s[10:11] op_sel_hi:[1,0]
	v_exp_f32_e32 v96, v96
	v_exp_f32_e32 v97, v97
	v_exp_f32_e32 v98, v98
	v_exp_f32_e32 v99, v99
	v_exp_f32_e32 v94, v94
	v_exp_f32_e32 v95, v95
	v_pk_add_f32 v[92:93], v[92:93], 1.0 op_sel_hi:[1,0]
	v_pk_add_f32 v[96:97], v[96:97], 1.0 op_sel_hi:[1,0]
	v_pk_add_f32 v[98:99], v[98:99], 1.0 op_sel_hi:[1,0]
	v_rcp_f32_e32 v92, v92
	v_rcp_f32_e32 v93, v93
	v_pk_add_f32 v[94:95], v[94:95], 1.0 op_sel_hi:[1,0]
	v_rcp_f32_e32 v96, v96
	v_rcp_f32_e32 v97, v97
	v_rcp_f32_e32 v98, v98
	v_rcp_f32_e32 v99, v99
	v_rcp_f32_e32 v94, v94
	v_rcp_f32_e32 v95, v95
	v_pk_mul_f32 v[80:81], v[84:85], v[80:81]
	v_or_b32_e32 v100, 32, v150
	v_pk_mul_f32 v[82:83], v[86:87], v[82:83]
	v_pk_mul_f32 v[84:85], v[92:93], v[80:81]
	v_pk_mul_f32 v[88:89], v[96:97], v[88:89]
	v_pk_mul_f32 v[90:91], v[98:99], v[90:91]
	v_pk_mul_f32 v[86:87], v[94:95], v[82:83]
	v_cvt_pk_bf16_f32 v80, v88, v89
	v_cvt_pk_bf16_f32 v81, v90, v91
	v_cvt_pk_bf16_f32 v82, v84, v85
	v_mad_i64_i32 v[84:85], s[24:25], v100, s39, v[112:113]
	v_lshl_add_u64 v[84:85], v[84:85], 0, v[114:115]
	v_cvt_pk_bf16_f32 v83, v86, v87
	global_store_dwordx4 v[84:85], v[80:83], off
	v_pk_mul_f32 v[72:73], v[76:77], v[72:73]
	v_pk_mul_f32 v[74:75], v[78:79], v[74:75]
	v_pk_mul_f32 v[80:81], v[76:77], s[10:11] op_sel_hi:[1,0]
	v_pk_mul_f32 v[76:77], v[68:69], s[10:11] op_sel_hi:[1,0]
	v_pk_mul_f32 v[82:83], v[78:79], s[10:11] op_sel_hi:[1,0]
	v_exp_f32_e32 v76, v76
	v_exp_f32_e32 v77, v77
	v_pk_mul_f32 v[78:79], v[70:71], s[10:11] op_sel_hi:[1,0]
	v_exp_f32_e32 v80, v80
	v_exp_f32_e32 v81, v81
	v_exp_f32_e32 v82, v82
	v_exp_f32_e32 v83, v83
	v_exp_f32_e32 v78, v78
	v_exp_f32_e32 v79, v79
	v_pk_add_f32 v[76:77], v[76:77], 1.0 op_sel_hi:[1,0]
	v_pk_add_f32 v[80:81], v[80:81], 1.0 op_sel_hi:[1,0]
	v_pk_add_f32 v[82:83], v[82:83], 1.0 op_sel_hi:[1,0]
	v_rcp_f32_e32 v76, v76
	v_rcp_f32_e32 v77, v77
	v_pk_add_f32 v[78:79], v[78:79], 1.0 op_sel_hi:[1,0]
	v_rcp_f32_e32 v80, v80
	v_rcp_f32_e32 v81, v81
	v_rcp_f32_e32 v82, v82
	v_rcp_f32_e32 v83, v83
	v_rcp_f32_e32 v78, v78
	v_rcp_f32_e32 v79, v79
	v_pk_mul_f32 v[64:65], v[68:69], v[64:65]
	v_or_b32_e32 v84, 48, v150
	v_pk_mul_f32 v[66:67], v[70:71], v[66:67]
	v_pk_mul_f32 v[68:69], v[76:77], v[64:65]
	v_pk_mul_f32 v[72:73], v[80:81], v[72:73]
	v_pk_mul_f32 v[74:75], v[82:83], v[74:75]
	v_pk_mul_f32 v[70:71], v[78:79], v[66:67]
	v_cvt_pk_bf16_f32 v64, v72, v73
	v_cvt_pk_bf16_f32 v65, v74, v75
	v_cvt_pk_bf16_f32 v66, v68, v69
	v_mad_i64_i32 v[68:69], s[24:25], v84, s39, v[112:113]
	v_lshl_add_u64 v[68:69], v[68:69], 0, v[114:115]
	v_cvt_pk_bf16_f32 v67, v70, v71
	global_store_dwordx4 v[68:69], v[64:67], off
	v_pk_mul_f32 v[56:57], v[60:61], v[56:57]
	v_pk_mul_f32 v[58:59], v[62:63], v[58:59]
	v_pk_mul_f32 v[64:65], v[60:61], s[10:11] op_sel_hi:[1,0]
	v_pk_mul_f32 v[60:61], v[52:53], s[10:11] op_sel_hi:[1,0]
	v_pk_mul_f32 v[66:67], v[62:63], s[10:11] op_sel_hi:[1,0]
	v_exp_f32_e32 v60, v60
	v_exp_f32_e32 v61, v61
	v_pk_mul_f32 v[62:63], v[54:55], s[10:11] op_sel_hi:[1,0]
	v_exp_f32_e32 v64, v64
	v_exp_f32_e32 v65, v65
	v_exp_f32_e32 v66, v66
	v_exp_f32_e32 v67, v67
	v_exp_f32_e32 v62, v62
	v_exp_f32_e32 v63, v63
	v_pk_add_f32 v[60:61], v[60:61], 1.0 op_sel_hi:[1,0]
	v_pk_add_f32 v[64:65], v[64:65], 1.0 op_sel_hi:[1,0]
	v_pk_add_f32 v[66:67], v[66:67], 1.0 op_sel_hi:[1,0]
	v_rcp_f32_e32 v60, v60
	v_rcp_f32_e32 v61, v61
	v_pk_add_f32 v[62:63], v[62:63], 1.0 op_sel_hi:[1,0]
	v_rcp_f32_e32 v64, v64
	v_rcp_f32_e32 v65, v65
	v_rcp_f32_e32 v66, v66
	v_rcp_f32_e32 v67, v67
	v_rcp_f32_e32 v62, v62
	v_rcp_f32_e32 v63, v63
	v_pk_mul_f32 v[48:49], v[52:53], v[48:49]
	v_add_u32_e32 v68, 0x80, v150
	v_pk_mul_f32 v[50:51], v[54:55], v[50:51]
	v_pk_mul_f32 v[52:53], v[60:61], v[48:49]
	v_pk_mul_f32 v[56:57], v[64:65], v[56:57]
	v_pk_mul_f32 v[58:59], v[66:67], v[58:59]
	v_pk_mul_f32 v[54:55], v[62:63], v[50:51]
	v_cvt_pk_bf16_f32 v48, v56, v57
	v_cvt_pk_bf16_f32 v49, v58, v59
	v_cvt_pk_bf16_f32 v50, v52, v53
	v_mad_i64_i32 v[52:53], s[24:25], v68, s39, v[112:113]
	v_lshl_add_u64 v[52:53], v[52:53], 0, v[114:115]
	v_cvt_pk_bf16_f32 v51, v54, v55
	global_store_dwordx4 v[52:53], v[48:51], off
	v_pk_mul_f32 v[40:41], v[44:45], v[40:41]
	v_pk_mul_f32 v[42:43], v[46:47], v[42:43]
	v_pk_mul_f32 v[48:49], v[44:45], s[10:11] op_sel_hi:[1,0]
	v_pk_mul_f32 v[44:45], v[36:37], s[10:11] op_sel_hi:[1,0]
	v_pk_mul_f32 v[50:51], v[46:47], s[10:11] op_sel_hi:[1,0]
	v_exp_f32_e32 v44, v44
	v_exp_f32_e32 v45, v45
	v_pk_mul_f32 v[46:47], v[38:39], s[10:11] op_sel_hi:[1,0]
	v_exp_f32_e32 v48, v48
	v_exp_f32_e32 v49, v49
	v_exp_f32_e32 v50, v50
	v_exp_f32_e32 v51, v51
	v_exp_f32_e32 v46, v46
	v_exp_f32_e32 v47, v47
	v_pk_add_f32 v[44:45], v[44:45], 1.0 op_sel_hi:[1,0]
	v_pk_add_f32 v[48:49], v[48:49], 1.0 op_sel_hi:[1,0]
	v_pk_add_f32 v[50:51], v[50:51], 1.0 op_sel_hi:[1,0]
	v_rcp_f32_e32 v44, v44
	v_rcp_f32_e32 v45, v45
	v_pk_add_f32 v[46:47], v[46:47], 1.0 op_sel_hi:[1,0]
	v_rcp_f32_e32 v48, v48
	v_rcp_f32_e32 v49, v49
	v_rcp_f32_e32 v50, v50
	v_rcp_f32_e32 v51, v51
	v_rcp_f32_e32 v46, v46
	v_rcp_f32_e32 v47, v47
	v_pk_mul_f32 v[32:33], v[36:37], v[32:33]
	v_add_u32_e32 v52, 0x90, v150
	v_pk_mul_f32 v[34:35], v[38:39], v[34:35]
	v_pk_mul_f32 v[36:37], v[44:45], v[32:33]
	v_pk_mul_f32 v[40:41], v[48:49], v[40:41]
	v_pk_mul_f32 v[42:43], v[50:51], v[42:43]
	v_pk_mul_f32 v[38:39], v[46:47], v[34:35]
	v_cvt_pk_bf16_f32 v32, v40, v41
	v_cvt_pk_bf16_f32 v33, v42, v43
	v_cvt_pk_bf16_f32 v34, v36, v37
	v_mad_i64_i32 v[36:37], s[24:25], v52, s39, v[112:113]
	v_lshl_add_u64 v[36:37], v[36:37], 0, v[114:115]
	v_cvt_pk_bf16_f32 v35, v38, v39
	global_store_dwordx4 v[36:37], v[32:35], off
	v_pk_mul_f32 v[24:25], v[28:29], v[24:25]
	v_pk_mul_f32 v[26:27], v[30:31], v[26:27]
	v_pk_mul_f32 v[32:33], v[28:29], s[10:11] op_sel_hi:[1,0]
	v_pk_mul_f32 v[28:29], v[20:21], s[10:11] op_sel_hi:[1,0]
	v_pk_mul_f32 v[34:35], v[30:31], s[10:11] op_sel_hi:[1,0]
	v_exp_f32_e32 v28, v28
	v_exp_f32_e32 v29, v29
	v_pk_mul_f32 v[30:31], v[22:23], s[10:11] op_sel_hi:[1,0]
	v_exp_f32_e32 v32, v32
	v_exp_f32_e32 v33, v33
	v_exp_f32_e32 v34, v34
	v_exp_f32_e32 v35, v35
	v_exp_f32_e32 v30, v30
	v_exp_f32_e32 v31, v31
	v_pk_add_f32 v[28:29], v[28:29], 1.0 op_sel_hi:[1,0]
	v_pk_add_f32 v[32:33], v[32:33], 1.0 op_sel_hi:[1,0]
	v_pk_add_f32 v[34:35], v[34:35], 1.0 op_sel_hi:[1,0]
	v_rcp_f32_e32 v28, v28
	v_rcp_f32_e32 v29, v29
	v_pk_add_f32 v[30:31], v[30:31], 1.0 op_sel_hi:[1,0]
	v_rcp_f32_e32 v32, v32
	v_rcp_f32_e32 v33, v33
	v_rcp_f32_e32 v34, v34
	v_rcp_f32_e32 v35, v35
	v_rcp_f32_e32 v30, v30
	v_rcp_f32_e32 v31, v31
	v_pk_mul_f32 v[16:17], v[20:21], v[16:17]
	v_add_u32_e32 v36, 0xa0, v150
	v_pk_mul_f32 v[18:19], v[22:23], v[18:19]
	v_pk_mul_f32 v[20:21], v[28:29], v[16:17]
	v_pk_mul_f32 v[24:25], v[32:33], v[24:25]
	v_pk_mul_f32 v[26:27], v[34:35], v[26:27]
	v_pk_mul_f32 v[22:23], v[30:31], v[18:19]
	v_cvt_pk_bf16_f32 v16, v24, v25
	v_cvt_pk_bf16_f32 v17, v26, v27
	v_cvt_pk_bf16_f32 v18, v20, v21
	v_mad_i64_i32 v[20:21], s[24:25], v36, s39, v[112:113]
	v_lshl_add_u64 v[20:21], v[20:21], 0, v[114:115]
	v_cvt_pk_bf16_f32 v19, v22, v23
	global_store_dwordx4 v[20:21], v[16:19], off
	v_pk_mul_f32 v[8:9], v[12:13], v[8:9]
	v_pk_mul_f32 v[10:11], v[14:15], v[10:11]
	v_pk_mul_f32 v[16:17], v[12:13], s[10:11] op_sel_hi:[1,0]
	v_pk_mul_f32 v[12:13], v[4:5], s[10:11] op_sel_hi:[1,0]
	v_pk_mul_f32 v[18:19], v[14:15], s[10:11] op_sel_hi:[1,0]
	v_exp_f32_e32 v12, v12
	v_exp_f32_e32 v13, v13
	v_pk_mul_f32 v[14:15], v[6:7], s[10:11] op_sel_hi:[1,0]
	v_exp_f32_e32 v16, v16
	v_exp_f32_e32 v17, v17
	v_exp_f32_e32 v18, v18
	v_exp_f32_e32 v19, v19
	v_exp_f32_e32 v14, v14
	v_exp_f32_e32 v15, v15
	v_pk_add_f32 v[12:13], v[12:13], 1.0 op_sel_hi:[1,0]
	v_pk_add_f32 v[16:17], v[16:17], 1.0 op_sel_hi:[1,0]
	v_pk_add_f32 v[18:19], v[18:19], 1.0 op_sel_hi:[1,0]
	v_rcp_f32_e32 v12, v12
	v_rcp_f32_e32 v13, v13
	v_pk_add_f32 v[14:15], v[14:15], 1.0 op_sel_hi:[1,0]
	v_rcp_f32_e32 v16, v16
	v_rcp_f32_e32 v17, v17
	v_rcp_f32_e32 v18, v18
	v_rcp_f32_e32 v19, v19
	v_rcp_f32_e32 v14, v14
	v_rcp_f32_e32 v15, v15
	v_pk_mul_f32 v[0:1], v[4:5], v[0:1]
	v_add_u32_e32 v20, 0xb0, v150
	v_pk_mul_f32 v[2:3], v[6:7], v[2:3]
	v_pk_mul_f32 v[4:5], v[12:13], v[0:1]
	v_pk_mul_f32 v[8:9], v[16:17], v[8:9]
	v_pk_mul_f32 v[10:11], v[18:19], v[10:11]
	v_pk_mul_f32 v[6:7], v[14:15], v[2:3]
	v_cvt_pk_bf16_f32 v0, v8, v9
	v_cvt_pk_bf16_f32 v1, v10, v11
	v_cvt_pk_bf16_f32 v2, v4, v5
	v_mad_i64_i32 v[4:5], s[24:25], v20, s39, v[112:113]
	v_lshl_add_u64 v[4:5], v[4:5], 0, v[114:115]
	s_andn2_b64 vcc, exec, s[4:5]
	s_mov_b64 s[4:5], -1
	v_cvt_pk_bf16_f32 v3, v6, v7
	global_store_dwordx4 v[4:5], v[0:3], off
	s_cbranch_vccnz .LBB0_406
	v_readlane_b32 s4, v255, 6
	v_readlane_b32 s5, v255, 7
	s_and_b64 vcc, exec, s[4:5]
	s_cbranch_vccnz .LBB0_405
	s_barrier
	s_branch .LBB0_405

.LBB0_423:
	global_load_dword v47, v[0:1], off sc1
	global_load_dword v32, v[2:3], off sc1
	global_load_dword v33, v[4:5], off sc1
	global_load_dword v34, v[6:7], off sc1
	global_load_dword v35, v[8:9], off sc1
	global_load_dword v36, v[10:11], off sc1
	global_load_dword v37, v[12:13], off sc1
	global_load_dword v38, v[14:15], off sc1
	global_load_dword v39, v[16:17], off sc1
	global_load_dword v40, v[18:19], off sc1
	global_load_dword v41, v[20:21], off sc1
	global_load_dword v42, v[22:23], off sc1
	global_load_dword v43, v[24:25], off sc1
	global_load_dword v44, v[26:27], off sc1
	global_load_dword v45, v[28:29], off sc1
	global_load_dword v46, v[30:31], off sc1
	s_or_b64 s[12:13], s[12:13], exec
	s_or_b64 s[10:11], s[10:11], exec
	s_waitcnt vmcnt(0) lgkmcnt(0)
	v_add_u32_e32 v48, v32, v47
	v_add_u32_e32 v48, v48, v33
	v_add_u32_e32 v48, v48, v34
	v_add_u32_e32 v48, v48, v35
	v_add_u32_e32 v48, v48, v36
	v_add_u32_e32 v48, v48, v37
	v_add_u32_e32 v48, v48, v38
	v_add_u32_e32 v48, v48, v39
	v_add_u32_e32 v48, v48, v40
	v_add_u32_e32 v48, v48, v41
	v_add_u32_e32 v48, v48, v42
	v_add_u32_e32 v48, v48, v43
	v_add_u32_e32 v48, v48, v44
	v_add_u32_e32 v48, v48, v45
	v_add_u32_e32 v48, v48, v46
	v_cmp_ne_u32_e32 vcc, s2, v48
	s_and_saveexec_b64 s[16:17], vcc
	s_cbranch_execz .LBB0_422
	s_and_b32 s14, s3, 0xff
	s_mov_b64 s[18:19], -1
	s_cmp_eq_u32 s14, 0
	s_mov_b64 s[22:23], -1
	s_mov_b64 s[20:21], -1
	s_sleep 1
	s_cbranch_scc1 .LBB0_426
	s_and_saveexec_b64 s[24:25], s[22:23]
	s_cbranch_execz .LBB0_421
	s_branch .LBB0_429
.LBB0_426:
	v_mov_b64_e32 v[48:49], s[4:5]
	global_load_dword v48, v[48:49], off sc1
	s_mov_b64 s[22:23], 0
	s_waitcnt vmcnt(0) lgkmcnt(0)
	v_cmp_eq_u32_e32 vcc, 0, v48
	s_and_saveexec_b64 s[24:25], vcc
	s_cmp_lt_u32 s3, 0x40001
	s_cselect_b64 s[14:15], -1, 0
	s_xor_b64 s[20:21], exec, -1
	s_and_b64 s[22:23], s[14:15], exec
	s_or_b64 exec, exec, s[24:25]
	s_and_saveexec_b64 s[24:25], s[22:23]
	s_cbranch_execz .LBB0_421

.LBB0_430:
	s_or_b64 exec, exec, s[6:7]
	s_xor_b64 s[2:3], s[8:9], -1
	s_and_saveexec_b64 s[6:7], s[2:3]
	s_xor_b64 s[6:7], exec, s[6:7]
	s_cbranch_execz .LBB0_432
	v_mov_b32_e32 v2, 1
	v_mov_b64_e32 v[0:1], s[4:5]
	global_atomic_add v[0:1], v2, off

.LBB0_433:
	s_lshl_b32 s1, s1, 8
	s_add_u32 s1, s46, s1
	s_addc_u32 s3, s47, 0
	v_mov_b32_e32 v1, s1
	v_add_co_u32_e32 v4, vcc, 0x101000, v1
	v_mov_b32_e32 v1, s3
	s_nop 0
	v_addc_co_u32_e32 v5, vcc, 0, v1, vcc
	v_mov_b32_e32 v1, 1
	global_atomic_add v1, v[4:5], v1, off offset:1024 sc0
	v_cvt_f32_u32_e32 v3, v2
	v_sub_u32_e32 v4, 0, v2
	s_add_u32 s2, s1, 0x100000
	s_addc_u32 s1, s3, 0
	v_rcp_iflag_f32_e32 v3, v3
	s_nop 0
	v_mul_f32_e32 v3, 0x4f7ffffe, v3
	v_cvt_u32_f32_e32 v3, v3
	v_mul_lo_u32 v4, v4, v3
	v_mul_hi_u32 v4, v3, v4
	v_add_u32_e32 v3, v3, v4
	s_waitcnt vmcnt(0) lgkmcnt(0)
	v_mul_hi_u32 v3, v1, v3
	v_mul_lo_u32 v5, v3, v2
	v_add_u32_e32 v4, 1, v1
	v_sub_u32_e32 v1, v1, v5
	v_add_u32_e32 v6, 1, v3
	v_cmp_ge_u32_e32 vcc, v1, v2
	v_sub_u32_e32 v5, v1, v2
	s_nop 0
	v_cndmask_b32_e32 v3, v3, v6, vcc
	v_cndmask_b32_e32 v1, v1, v5, vcc
	v_add_u32_e32 v5, 1, v3
	v_cmp_ge_u32_e32 vcc, v1, v2
	s_nop 1
	v_cndmask_b32_e32 v1, v3, v5, vcc
	v_mad_u64_u32 v[2:3], s[4:5], v2, v1, v[2:3]
	v_cmp_ne_u32_e32 vcc, v4, v2
	s_and_saveexec_b64 s[4:5], vcc
	s_xor_b64 s[4:5], exec, s[4:5]
	s_cbranch_execz .LBB0_446
	v_mov_b32_e32 v0, s2
	v_add_co_u32_e32 v2, vcc, 0x2000, v0
	v_mov_b32_e32 v0, s1
	s_nop 0
	v_addc_co_u32_e32 v3, vcc, 0, v0, vcc
	global_load_dword v0, v[2:3], off offset:1024 sc1
	s_add_u32 s10, s2, 0x2400
	s_addc_u32 s11, s1, 0
	s_waitcnt vmcnt(0) lgkmcnt(0)
	v_cmp_eq_u32_e32 vcc, v0, v1
	s_and_saveexec_b64 s[6:7], vcc
	s_cbranch_execz .LBB0_445
	s_add_u32 s8, s46, 0x100200
	s_addc_u32 s9, s47, 0
	s_mov_b32 s3, 1
	s_mov_b64 s[12:13], 0
	s_branch .LBB0_437

.LBB0_437:
	s_and_b32 s14, s3, 0xff
	s_mov_b64 s[20:21], -1
	s_cmp_lg_u32 s14, 0
	s_mov_b64 s[22:23], -1
	s_sleep 1
	s_cbranch_scc1 .LBB0_441
	v_mov_b64_e32 v[2:3], s[8:9]
	global_load_dword v0, v[2:3], off sc1
	s_mov_b64 s[22:23], 0
	s_mov_b64 s[24:25], -1
	s_waitcnt vmcnt(0) lgkmcnt(0)
	v_cmp_eq_u32_e32 vcc, 0, v0
	s_and_saveexec_b64 s[26:27], vcc
	s_cmp_lt_u32 s3, 0x40001
	s_cselect_b64 s[14:15], -1, 0
	s_xor_b64 s[24:25], exec, -1
	s_and_b64 s[22:23], s[14:15], exec
	s_or_b64 exec, exec, s[26:27]
.LBB0_441:
	s_andn2_b64 s[14:15], s[18:19], exec
	s_and_b64 s[18:19], s[24:25], exec
	s_or_b64 s[18:19], s[14:15], s[18:19]
	s_and_saveexec_b64 s[24:25], s[22:23]
	s_cbranch_execz .LBB0_436
	v_mov_b64_e32 v[2:3], s[10:11]
	global_load_dword v0, v[2:3], off sc1
	s_add_i32 s3, s3, 1
	s_or_b64 s[18:19], s[18:19], exec
	s_waitcnt vmcnt(0) lgkmcnt(0)
	v_cmp_ne_u32_e32 vcc, v0, v1
	s_orn2_b64 s[20:21], vcc, exec
	s_branch .LBB0_436
.LBB0_443:
	s_or_b64 exec, exec, s[12:13]
	s_xor_b64 s[10:11], s[16:17], -1
	s_and_saveexec_b64 s[12:13], s[10:11]
	s_xor_b64 s[12:13], exec, s[12:13]
	s_cbranch_execz .LBB0_445
	v_mov_b32_e32 v2, 1
	v_mov_b64_e32 v[0:1], s[8:9]
	global_atomic_add v[0:1], v2, off

.LBB0_446:
	s_andn2_saveexec_b64 s[4:5], s[4:5]
	s_cbranch_execz .LBB0_462
	v_mov_b32_e32 v1, s46
	v_add_co_u32_e32 v2, vcc, 0x103000, v1
	v_mov_b32_e32 v1, s47
	buffer_wbl2 sc1
	s_waitcnt vmcnt(0)
	v_addc_co_u32_e32 v3, vcc, 0, v1, vcc
	v_mov_b32_e32 v1, 1
	global_atomic_add v1, v[2:3], v1, off offset:1024 sc0
	v_cvt_f32_u32_e32 v2, v0
	v_sub_u32_e32 v3, 0, v0
	s_add_u32 s4, s46, 0x103500
	s_addc_u32 s5, s47, 0
	v_rcp_iflag_f32_e32 v2, v2
	s_mov_b64 s[8:9], -1
	v_mul_f32_e32 v2, 0x4f7ffffe, v2
	v_cvt_u32_f32_e32 v2, v2
	v_mul_lo_u32 v3, v3, v2
	v_mul_hi_u32 v3, v2, v3
	v_add_u32_e32 v2, v2, v3
	s_waitcnt vmcnt(0) lgkmcnt(0)
	v_mul_hi_u32 v2, v1, v2
	v_mul_lo_u32 v4, v2, v0
	v_add_u32_e32 v3, 1, v1
	v_sub_u32_e32 v1, v1, v4
	v_add_u32_e32 v5, 1, v2
	v_cmp_ge_u32_e32 vcc, v1, v0
	v_sub_u32_e32 v4, v1, v0
	s_nop 0
	v_cndmask_b32_e32 v2, v2, v5, vcc
	v_cndmask_b32_e32 v1, v1, v4, vcc
	v_add_u32_e32 v4, 1, v2
	v_cmp_ge_u32_e32 vcc, v1, v0
	s_nop 1
	v_cndmask_b32_e32 v2, v2, v4, vcc
	v_mad_u64_u32 v[0:1], s[6:7], v0, v2, v[0:1]
	v_cmp_ne_u32_e32 vcc, v3, v0
	v_mov_b64_e32 v[0:1], s[4:5]
	s_and_saveexec_b64 s[6:7], vcc
	s_cbranch_execz .LBB0_459
	v_mov_b64_e32 v[0:1], s[4:5]
	global_load_dword v0, v[0:1], off sc1
	s_mov_b64 s[12:13], 0
	s_waitcnt vmcnt(0) lgkmcnt(0)
	v_cmp_eq_u32_e32 vcc, v0, v2
	s_and_saveexec_b64 s[10:11], vcc
	s_cbranch_execz .LBB0_458
	s_add_u32 s8, s46, 0x100200
	s_addc_u32 s9, s47, 0
	s_mov_b32 s3, 1
	s_branch .LBB0_451

.LBB0_453:
	v_mov_b64_e32 v[0:1], s[8:9]
	global_load_dword v0, v[0:1], off sc1
	s_mov_b64 s[20:21], 0
	s_mov_b64 s[18:19], -1
	s_waitcnt vmcnt(0) lgkmcnt(0)
	v_cmp_eq_u32_e32 vcc, 0, v0
	s_and_saveexec_b64 s[22:23], vcc
	s_cmp_lt_u32 s3, 0x40001
	s_cselect_b64 s[14:15], -1, 0
	s_xor_b64 s[18:19], exec, -1
	s_and_b64 s[20:21], s[14:15], exec
	s_or_b64 exec, exec, s[22:23]
	s_mov_b64 s[22:23], -1
	s_and_saveexec_b64 s[24:25], s[20:21]
	s_cbranch_execz .LBB0_450
.LBB0_456:
	v_mov_b64_e32 v[0:1], s[4:5]
	global_load_dword v0, v[0:1], off sc1
	s_add_i32 s3, s3, 1
	s_or_b64 s[18:19], s[18:19], exec
	s_waitcnt vmcnt(0) lgkmcnt(0)
	v_cmp_ne_u32_e32 vcc, v0, v2
	s_orn2_b64 s[22:23], vcc, exec
	s_branch .LBB0_450

.LBB0_459:
	s_or_b64 exec, exec, s[6:7]
	s_and_saveexec_b64 s[4:5], s[8:9]
	s_cbranch_execz .LBB0_461
	v_mov_b32_e32 v2, 1
	global_atomic_add v[0:1], v2, off
.LBB0_461:
	s_or_b64 exec, exec, s[4:5]
	v_mov_b32_e32 v0, s2
	v_add_co_u32_e32 v0, vcc, 0x2000, v0
	v_mov_b32_e32 v1, s1
	s_nop 0
	v_addc_co_u32_e32 v1, vcc, 0, v1, vcc
	v_mov_b32_e32 v2, 1
	s_waitcnt vmcnt(0) lgkmcnt(0)
	buffer_inv sc1
	global_atomic_add v[0:1], v2, off offset:1024
	s_waitcnt vmcnt(0)

.LBB0_489:
	v_lshl_add_u32 v196, s40, 8, v205
	v_lshl_add_u32 v192, s41, 8, v207
	v_ashrrev_i32_e32 v193, 31, v192
	v_ashrrev_i32_e32 v197, 31, v196
	v_lshl_add_u64 v[194:195], v[192:193], 2, s[52:53]
	v_lshlrev_b64 v[128:129], 13, v[196:197]
	v_lshl_add_u64 v[128:129], v[194:195], 0, v[128:129]
	global_load_dwordx4 v[214:217], v[128:129], off
	global_load_dwordx4 v[218:221], v[128:129], off offset:16
	global_load_dwordx4 v[222:225], v[128:129], off offset:512
	global_load_dwordx4 v[226:229], v[128:129], off offset:528
	v_or_b32_e32 v202, 16, v196
	v_or_b32_e32 v200, 32, v196
	v_or_b32_e32 v198, 48, v196
	v_ashrrev_i32_e32 v203, 31, v202
	v_ashrrev_i32_e32 v201, 31, v200
	v_ashrrev_i32_e32 v199, 31, v198
	v_lshlrev_b64 v[128:129], 13, v[202:203]
	v_lshlrev_b64 v[130:131], 13, v[200:201]
	v_lshlrev_b64 v[132:133], 13, v[198:199]
	v_lshl_add_u64 v[128:129], v[194:195], 0, v[128:129]
	v_lshl_add_u64 v[130:131], v[194:195], 0, v[130:131]
	v_lshl_add_u64 v[132:133], v[194:195], 0, v[132:133]
	global_load_dwordx4 v[168:171], v[128:129], off offset:16
	global_load_dwordx4 v[172:175], v[128:129], off
	global_load_dwordx4 v[160:163], v[128:129], off offset:528
	global_load_dwordx4 v[164:167], v[128:129], off offset:512
	global_load_dwordx4 v[152:155], v[130:131], off offset:16
	global_load_dwordx4 v[156:159], v[130:131], off
	global_load_dwordx4 v[144:147], v[130:131], off offset:528
	global_load_dwordx4 v[148:151], v[130:131], off offset:512
	global_load_dwordx4 v[136:139], v[132:133], off offset:16
	global_load_dwordx4 v[140:143], v[132:133], off
	s_nop 0
	global_load_dwordx4 v[128:131], v[132:133], off offset:528
	s_nop 0
	global_load_dwordx4 v[132:135], v[132:133], off offset:512
	v_and_b32_e32 v212, 64, v211
	v_xor_b32_e32 v204, 16, v211
	v_add_u32_e32 v231, 64, v212
	v_xor_b32_e32 v230, 32, v211
	v_cmp_lt_i32_e32 vcc, v204, v231
	v_lshlrev_b64 v[212:213], 12, v[196:197]
	s_waitcnt vmcnt(0)
	v_pk_fma_f32 v[126:127], v[126:127], 0.5, v[216:217] op_sel_hi:[1,0,1]
	v_cndmask_b32_e32 v204, v211, v204, vcc
	v_cmp_lt_i32_e32 vcc, v230, v231
	v_pk_fma_f32 v[124:125], v[124:125], 0.5, v[214:215] op_sel_hi:[1,0,1]
	v_pk_fma_f32 v[122:123], v[122:123], 0.5, v[220:221] op_sel_hi:[1,0,1]
	v_pk_fma_f32 v[120:121], v[120:121], 0.5, v[218:219] op_sel_hi:[1,0,1]
	v_pk_fma_f32 v[118:119], v[118:119], 0.5, v[224:225] op_sel_hi:[1,0,1]
	v_pk_fma_f32 v[116:117], v[116:117], 0.5, v[222:223] op_sel_hi:[1,0,1]
	v_pk_fma_f32 v[214:215], v[114:115], 0.5, v[228:229] op_sel_hi:[1,0,1]
	v_pk_fma_f32 v[216:217], v[112:113], 0.5, v[226:227] op_sel_hi:[1,0,1]
	v_cndmask_b32_e32 v232, v211, v230, vcc
	v_lshl_add_u64 v[230:231], s[16:17], 0, v[212:213]
	v_lshlrev_b32_e32 v212, 2, v204
	v_cvt_pk_bf16_f32 v112, v124, v125
	v_cvt_pk_bf16_f32 v113, v126, v127
	v_cvt_pk_bf16_f32 v114, v120, v121
	v_mul_f32_e32 v115, v125, v125
	v_mul_f32_e32 v125, v127, v127
	v_mul_f32_e32 v121, v121, v121
	v_mul_f32_e32 v127, v123, v123
	v_mul_f32_e32 v204, v117, v117
	v_mul_f32_e32 v213, v119, v119
	v_mul_f32_e32 v218, v217, v217
	v_mul_f32_e32 v219, v215, v215
	v_fmac_f32_e32 v115, v124, v124
	v_fmac_f32_e32 v125, v126, v126
	v_fmac_f32_e32 v121, v120, v120
	v_fmac_f32_e32 v127, v122, v122
	v_fmac_f32_e32 v204, v116, v116
	v_fmac_f32_e32 v213, v118, v118
	v_fmac_f32_e32 v218, v216, v216
	v_fmac_f32_e32 v219, v214, v214
	v_add_f32_e32 v115, v115, v125
	v_add_f32_e32 v120, v121, v127
	v_add_f32_e32 v121, v204, v213
	v_add_f32_e32 v124, v218, v219
	v_add_f32_e32 v115, v115, v120
	v_add_f32_e32 v120, v121, v124
	v_add_f32_e32 v120, v115, v120
	ds_bpermute_b32 v121, v212, v120
	v_lshl_add_u64 v[230:231], v[192:193], 1, v[230:231]
	v_cvt_pk_bf16_f32 v115, v122, v123
	global_store_dwordx4 v[230:231], v[112:115], off
	v_cvt_pk_bf16_f32 v116, v116, v117
	v_cvt_pk_bf16_f32 v117, v118, v119
	v_cvt_pk_bf16_f32 v118, v216, v217
	v_cvt_pk_bf16_f32 v119, v214, v215
	global_store_dwordx4 v[230:231], v[116:119], off offset:256
	s_waitcnt lgkmcnt(0)
	v_add_f32_e32 v114, v120, v121
	v_lshlrev_b32_e32 v120, 2, v232
	ds_bpermute_b32 v115, v120, v114
	v_lshl_add_u64 v[112:113], v[196:197], 2, s[12:13]
	s_and_saveexec_b64 s[4:5], s[6:7]
	s_cbranch_execz .LBB0_491
	s_waitcnt lgkmcnt(0)
	v_add_f32_e32 v114, v114, v115
	global_atomic_add_f32 v[112:113], v114, off
.LBB0_491:
	s_or_b64 exec, exec, s[4:5]
	v_pk_fma_f32 v[108:109], v[108:109], 0.5, v[172:173] op_sel_hi:[1,0,1]
	v_pk_fma_f32 v[110:111], v[110:111], 0.5, v[174:175] op_sel_hi:[1,0,1]
	v_pk_fma_f32 v[118:119], v[104:105], 0.5, v[168:169] op_sel_hi:[1,0,1]
	v_cvt_pk_bf16_f32 v104, v108, v109
	v_mul_f32_e32 v109, v109, v109
	v_fmac_f32_e32 v109, v108, v108
	v_mul_f32_e32 v108, v111, v111
	v_pk_fma_f32 v[116:117], v[106:107], 0.5, v[170:171] op_sel_hi:[1,0,1]
	v_fmac_f32_e32 v108, v110, v110
	v_cvt_pk_bf16_f32 v105, v110, v111
	v_add_f32_e32 v108, v109, v108
	v_mul_f32_e32 v109, v119, v119
	v_mul_f32_e32 v110, v117, v117
	v_fmac_f32_e32 v109, v118, v118
	v_fmac_f32_e32 v110, v116, v116
	v_pk_fma_f32 v[102:103], v[102:103], 0.5, v[166:167] op_sel_hi:[1,0,1]
	v_pk_fma_f32 v[100:101], v[100:101], 0.5, v[164:165] op_sel_hi:[1,0,1]
	v_add_f32_e32 v109, v109, v110
	v_pk_fma_f32 v[110:111], v[96:97], 0.5, v[160:161] op_sel_hi:[1,0,1]
	v_mul_f32_e32 v96, v101, v101
	v_mul_f32_e32 v97, v103, v103
	v_cvt_pk_bf16_f32 v106, v118, v119
	v_cvt_pk_bf16_f32 v107, v116, v117
	v_add_f32_e32 v116, v108, v109
	v_pk_fma_f32 v[108:109], v[98:99], 0.5, v[162:163] op_sel_hi:[1,0,1]
	v_fmac_f32_e32 v96, v100, v100
	v_fmac_f32_e32 v97, v102, v102
	v_add_f32_e32 v96, v96, v97
	v_mul_f32_e32 v97, v111, v111
	v_mul_f32_e32 v98, v109, v109
	v_fmac_f32_e32 v97, v110, v110
	v_fmac_f32_e32 v98, v108, v108
	v_add_f32_e32 v97, v97, v98
	v_add_f32_e32 v96, v96, v97
	v_add_f32_e32 v99, v116, v96
	ds_bpermute_b32 v116, v212, v99
	s_waitcnt lgkmcnt(0)
	v_lshlrev_b64 v[114:115], 12, v[202:203]
	v_lshl_add_u64 v[96:97], s[16:17], 0, v[114:115]
	v_lshl_add_u64 v[114:115], v[192:193], 1, v[96:97]
	global_store_dwordx4 v[114:115], v[104:107], off
	v_add_f32_e32 v96, v99, v116
	ds_bpermute_b32 v97, v120, v96
	v_cvt_pk_bf16_f32 v98, v100, v101
	v_cvt_pk_bf16_f32 v99, v102, v103
	v_cvt_pk_bf16_f32 v100, v110, v111
	v_cvt_pk_bf16_f32 v101, v108, v109
	global_store_dwordx4 v[114:115], v[98:101], off offset:256
	s_and_saveexec_b64 s[4:5], s[6:7]
	s_cbranch_execz .LBB0_493
	s_waitcnt lgkmcnt(0)
	v_add_f32_e32 v96, v96, v97
	global_atomic_add_f32 v[112:113], v96, off offset:64
.LBB0_493:
	s_or_b64 exec, exec, s[4:5]
	v_pk_fma_f32 v[92:93], v[92:93], 0.5, v[156:157] op_sel_hi:[1,0,1]
	v_pk_fma_f32 v[94:95], v[94:95], 0.5, v[158:159] op_sel_hi:[1,0,1]
	v_pk_fma_f32 v[100:101], v[88:89], 0.5, v[152:153] op_sel_hi:[1,0,1]
	v_cvt_pk_bf16_f32 v88, v92, v93
	v_mul_f32_e32 v93, v93, v93
	v_fmac_f32_e32 v93, v92, v92
	v_mul_f32_e32 v92, v95, v95
	v_pk_fma_f32 v[98:99], v[90:91], 0.5, v[154:155] op_sel_hi:[1,0,1]
	v_fmac_f32_e32 v92, v94, v94
	v_cvt_pk_bf16_f32 v89, v94, v95
	v_add_f32_e32 v92, v93, v92
	v_mul_f32_e32 v93, v101, v101
	v_mul_f32_e32 v94, v99, v99
	v_fmac_f32_e32 v93, v100, v100
	v_fmac_f32_e32 v94, v98, v98
	v_pk_fma_f32 v[86:87], v[86:87], 0.5, v[150:151] op_sel_hi:[1,0,1]
	v_pk_fma_f32 v[84:85], v[84:85], 0.5, v[148:149] op_sel_hi:[1,0,1]
	v_add_f32_e32 v93, v93, v94
	v_pk_fma_f32 v[94:95], v[80:81], 0.5, v[144:145] op_sel_hi:[1,0,1]
	v_mul_f32_e32 v80, v85, v85
	v_mul_f32_e32 v81, v87, v87
	v_cvt_pk_bf16_f32 v90, v100, v101
	v_cvt_pk_bf16_f32 v91, v98, v99
	v_add_f32_e32 v98, v92, v93
	v_pk_fma_f32 v[92:93], v[82:83], 0.5, v[146:147] op_sel_hi:[1,0,1]
	v_fmac_f32_e32 v80, v84, v84
	v_fmac_f32_e32 v81, v86, v86
	v_add_f32_e32 v80, v80, v81
	v_mul_f32_e32 v81, v95, v95
	v_mul_f32_e32 v82, v93, v93
	v_fmac_f32_e32 v81, v94, v94
	v_fmac_f32_e32 v82, v92, v92
	v_add_f32_e32 v81, v81, v82
	v_add_f32_e32 v80, v80, v81
	v_add_f32_e32 v83, v98, v80
	ds_bpermute_b32 v98, v212, v83
	s_waitcnt lgkmcnt(0)
	v_lshlrev_b64 v[96:97], 12, v[200:201]
	v_lshl_add_u64 v[80:81], s[16:17], 0, v[96:97]
	v_lshl_add_u64 v[96:97], v[192:193], 1, v[80:81]
	global_store_dwordx4 v[96:97], v[88:91], off
	v_add_f32_e32 v80, v83, v98
	ds_bpermute_b32 v81, v120, v80
	v_cvt_pk_bf16_f32 v82, v84, v85
	v_cvt_pk_bf16_f32 v83, v86, v87
	v_cvt_pk_bf16_f32 v84, v94, v95
	v_cvt_pk_bf16_f32 v85, v92, v93
	global_store_dwordx4 v[96:97], v[82:85], off offset:256
	s_and_saveexec_b64 s[4:5], s[6:7]
	s_cbranch_execz .LBB0_495
	s_waitcnt lgkmcnt(0)
	v_add_f32_e32 v80, v80, v81
	global_atomic_add_f32 v[112:113], v80, off offset:128
.LBB0_495:
	s_or_b64 exec, exec, s[4:5]
	v_pk_fma_f32 v[76:77], v[76:77], 0.5, v[140:141] op_sel_hi:[1,0,1]
	v_pk_fma_f32 v[78:79], v[78:79], 0.5, v[142:143] op_sel_hi:[1,0,1]
	v_pk_fma_f32 v[84:85], v[72:73], 0.5, v[136:137] op_sel_hi:[1,0,1]
	v_cvt_pk_bf16_f32 v72, v76, v77
	v_mul_f32_e32 v77, v77, v77
	v_fmac_f32_e32 v77, v76, v76
	v_mul_f32_e32 v76, v79, v79
	v_pk_fma_f32 v[82:83], v[74:75], 0.5, v[138:139] op_sel_hi:[1,0,1]
	v_fmac_f32_e32 v76, v78, v78
	v_cvt_pk_bf16_f32 v73, v78, v79
	v_add_f32_e32 v76, v77, v76
	v_mul_f32_e32 v77, v85, v85
	v_mul_f32_e32 v78, v83, v83
	v_fmac_f32_e32 v77, v84, v84
	v_fmac_f32_e32 v78, v82, v82
	v_pk_fma_f32 v[70:71], v[70:71], 0.5, v[134:135] op_sel_hi:[1,0,1]
	v_pk_fma_f32 v[68:69], v[68:69], 0.5, v[132:133] op_sel_hi:[1,0,1]
	v_add_f32_e32 v77, v77, v78
	v_pk_fma_f32 v[78:79], v[64:65], 0.5, v[128:129] op_sel_hi:[1,0,1]
	v_mul_f32_e32 v64, v69, v69
	v_mul_f32_e32 v65, v71, v71
	v_cvt_pk_bf16_f32 v74, v84, v85
	v_cvt_pk_bf16_f32 v75, v82, v83
	v_add_f32_e32 v82, v76, v77
	v_pk_fma_f32 v[76:77], v[66:67], 0.5, v[130:131] op_sel_hi:[1,0,1]
	v_fmac_f32_e32 v64, v68, v68
	v_fmac_f32_e32 v65, v70, v70
	v_add_f32_e32 v64, v64, v65
	v_mul_f32_e32 v65, v79, v79
	v_mul_f32_e32 v66, v77, v77
	v_fmac_f32_e32 v65, v78, v78
	v_fmac_f32_e32 v66, v76, v76
	v_add_f32_e32 v65, v65, v66
	v_add_f32_e32 v64, v64, v65
	v_add_f32_e32 v67, v82, v64
	ds_bpermute_b32 v82, v212, v67
	s_waitcnt lgkmcnt(0)
	v_lshlrev_b64 v[80:81], 12, v[198:199]
	v_lshl_add_u64 v[64:65], s[16:17], 0, v[80:81]
	v_lshl_add_u64 v[80:81], v[192:193], 1, v[64:65]
	global_store_dwordx4 v[80:81], v[72:75], off
	v_add_f32_e32 v64, v67, v82
	ds_bpermute_b32 v65, v120, v64
	v_cvt_pk_bf16_f32 v66, v68, v69
	v_cvt_pk_bf16_f32 v67, v70, v71
	v_cvt_pk_bf16_f32 v68, v78, v79
	v_cvt_pk_bf16_f32 v69, v76, v77
	global_store_dwordx4 v[80:81], v[66:69], off offset:256
	s_and_saveexec_b64 s[4:5], s[6:7]
	s_cbranch_execz .LBB0_497
	s_waitcnt lgkmcnt(0)
	v_add_f32_e32 v64, v64, v65
	global_atomic_add_f32 v[112:113], v64, off offset:192
.LBB0_497:
	s_or_b64 exec, exec, s[4:5]
	v_add_u32_e32 v138, 0x80, v196
	v_ashrrev_i32_e32 v139, 31, v138
	s_waitcnt lgkmcnt(0)
	v_lshlrev_b64 v[64:65], 13, v[138:139]
	v_lshl_add_u64 v[64:65], v[194:195], 0, v[64:65]
	global_load_dwordx4 v[122:125], v[64:65], off
	global_load_dwordx4 v[126:129], v[64:65], off offset:16
	global_load_dwordx4 v[130:133], v[64:65], off offset:512
	global_load_dwordx4 v[134:137], v[64:65], off offset:528
	v_add_u32_e32 v118, 0x90, v196
	v_add_u32_e32 v116, 0xa0, v196
	v_add_u32_e32 v114, 0xb0, v196
	v_ashrrev_i32_e32 v119, 31, v118
	v_ashrrev_i32_e32 v117, 31, v116
	v_ashrrev_i32_e32 v115, 31, v114
	v_lshlrev_b64 v[64:65], 13, v[118:119]
	v_lshlrev_b64 v[66:67], 13, v[116:117]
	v_lshlrev_b64 v[68:69], 13, v[114:115]
	v_lshl_add_u64 v[64:65], v[194:195], 0, v[64:65]
	v_lshl_add_u64 v[66:67], v[194:195], 0, v[66:67]
	v_lshl_add_u64 v[68:69], v[194:195], 0, v[68:69]
	global_load_dwordx4 v[104:107], v[64:65], off offset:16
	global_load_dwordx4 v[108:111], v[64:65], off
	global_load_dwordx4 v[96:99], v[64:65], off offset:528
	global_load_dwordx4 v[100:103], v[64:65], off offset:512
	global_load_dwordx4 v[88:91], v[66:67], off offset:16
	global_load_dwordx4 v[92:95], v[66:67], off
	global_load_dwordx4 v[80:83], v[66:67], off offset:528
	global_load_dwordx4 v[84:87], v[66:67], off offset:512
	global_load_dwordx4 v[72:75], v[68:69], off offset:16
	global_load_dwordx4 v[76:79], v[68:69], off
	s_nop 0
	global_load_dwordx4 v[64:67], v[68:69], off offset:528
	s_nop 0
	global_load_dwordx4 v[68:71], v[68:69], off offset:512
	v_lshlrev_b64 v[138:139], 12, v[138:139]
	s_waitcnt vmcnt(0)
	v_pk_fma_f32 v[62:63], v[62:63], 0.5, v[124:125] op_sel_hi:[1,0,1]
	v_pk_fma_f32 v[60:61], v[60:61], 0.5, v[122:123] op_sel_hi:[1,0,1]
	v_pk_fma_f32 v[58:59], v[58:59], 0.5, v[128:129] op_sel_hi:[1,0,1]
	v_pk_fma_f32 v[56:57], v[56:57], 0.5, v[126:127] op_sel_hi:[1,0,1]
	v_pk_fma_f32 v[54:55], v[54:55], 0.5, v[132:133] op_sel_hi:[1,0,1]
	v_pk_fma_f32 v[52:53], v[52:53], 0.5, v[130:131] op_sel_hi:[1,0,1]
	v_pk_fma_f32 v[122:123], v[50:51], 0.5, v[136:137] op_sel_hi:[1,0,1]
	v_pk_fma_f32 v[124:125], v[48:49], 0.5, v[134:135] op_sel_hi:[1,0,1]
	v_cvt_pk_bf16_f32 v48, v60, v61
	v_cvt_pk_bf16_f32 v49, v62, v63
	v_cvt_pk_bf16_f32 v50, v56, v57
	v_cvt_pk_bf16_f32 v51, v58, v59
	v_mul_f32_e32 v61, v61, v61
	v_mul_f32_e32 v63, v63, v63
	v_mul_f32_e32 v57, v57, v57
	v_mul_f32_e32 v59, v59, v59
	v_mul_f32_e32 v121, v53, v53
	v_mul_f32_e32 v126, v55, v55
	v_mul_f32_e32 v127, v125, v125
	v_mul_f32_e32 v128, v123, v123
	v_fmac_f32_e32 v61, v60, v60
	v_fmac_f32_e32 v63, v62, v62
	v_fmac_f32_e32 v57, v56, v56
	v_fmac_f32_e32 v59, v58, v58
	v_fmac_f32_e32 v121, v52, v52
	v_fmac_f32_e32 v126, v54, v54
	v_fmac_f32_e32 v127, v124, v124
	v_fmac_f32_e32 v128, v122, v122
	v_add_f32_e32 v56, v61, v63
	v_add_f32_e32 v57, v57, v59
	v_add_f32_e32 v58, v121, v126
	v_add_f32_e32 v59, v127, v128
	v_add_f32_e32 v56, v56, v57
	v_add_f32_e32 v57, v58, v59
	v_add_f32_e32 v58, v56, v57
	ds_bpermute_b32 v59, v212, v58
	v_lshl_add_u64 v[56:57], s[16:17], 0, v[138:139]
	v_lshl_add_u64 v[56:57], v[192:193], 1, v[56:57]
	global_store_dwordx4 v[56:57], v[48:51], off
	s_waitcnt lgkmcnt(0)
	s_nop 0
	v_add_f32_e32 v48, v58, v59
	ds_bpermute_b32 v49, v120, v48
	v_cvt_pk_bf16_f32 v50, v52, v53
	v_cvt_pk_bf16_f32 v51, v54, v55
	v_cvt_pk_bf16_f32 v52, v124, v125
	v_cvt_pk_bf16_f32 v53, v122, v123
	global_store_dwordx4 v[56:57], v[50:53], off offset:256
	s_and_saveexec_b64 s[4:5], s[6:7]
	s_cbranch_execz .LBB0_499
	s_waitcnt lgkmcnt(0)
	v_add_f32_e32 v48, v48, v49
	global_atomic_add_f32 v[112:113], v48, off offset:512
.LBB0_499:
	s_or_b64 exec, exec, s[4:5]
	v_pk_fma_f32 v[44:45], v[44:45], 0.5, v[108:109] op_sel_hi:[1,0,1]
	v_pk_fma_f32 v[46:47], v[46:47], 0.5, v[110:111] op_sel_hi:[1,0,1]
	v_pk_fma_f32 v[52:53], v[40:41], 0.5, v[104:105] op_sel_hi:[1,0,1]
	v_cvt_pk_bf16_f32 v40, v44, v45
	v_mul_f32_e32 v45, v45, v45
	v_fmac_f32_e32 v45, v44, v44
	v_mul_f32_e32 v44, v47, v47
	v_pk_fma_f32 v[50:51], v[42:43], 0.5, v[106:107] op_sel_hi:[1,0,1]
	v_fmac_f32_e32 v44, v46, v46
	v_cvt_pk_bf16_f32 v41, v46, v47
	v_add_f32_e32 v44, v45, v44
	v_mul_f32_e32 v45, v53, v53
	v_mul_f32_e32 v46, v51, v51
	v_fmac_f32_e32 v45, v52, v52
	v_fmac_f32_e32 v46, v50, v50
	v_pk_fma_f32 v[38:39], v[38:39], 0.5, v[102:103] op_sel_hi:[1,0,1]
	v_pk_fma_f32 v[36:37], v[36:37], 0.5, v[100:101] op_sel_hi:[1,0,1]
	v_add_f32_e32 v45, v45, v46
	v_pk_fma_f32 v[46:47], v[32:33], 0.5, v[96:97] op_sel_hi:[1,0,1]
	v_mul_f32_e32 v32, v37, v37
	v_mul_f32_e32 v33, v39, v39
	v_cvt_pk_bf16_f32 v42, v52, v53
	v_cvt_pk_bf16_f32 v43, v50, v51
	v_add_f32_e32 v50, v44, v45
	v_pk_fma_f32 v[44:45], v[34:35], 0.5, v[98:99] op_sel_hi:[1,0,1]
	v_fmac_f32_e32 v32, v36, v36
	v_fmac_f32_e32 v33, v38, v38
	v_add_f32_e32 v32, v32, v33
	v_mul_f32_e32 v33, v47, v47
	v_mul_f32_e32 v34, v45, v45
	v_fmac_f32_e32 v33, v46, v46
	v_fmac_f32_e32 v34, v44, v44
	v_add_f32_e32 v33, v33, v34
	v_add_f32_e32 v32, v32, v33
	v_add_f32_e32 v35, v50, v32
	ds_bpermute_b32 v50, v212, v35
	s_waitcnt lgkmcnt(0)
	v_lshlrev_b64 v[48:49], 12, v[118:119]
	v_lshl_add_u64 v[32:33], s[16:17], 0, v[48:49]
	v_lshl_add_u64 v[48:49], v[192:193], 1, v[32:33]
	global_store_dwordx4 v[48:49], v[40:43], off
	v_add_f32_e32 v32, v35, v50
	ds_bpermute_b32 v33, v120, v32
	v_cvt_pk_bf16_f32 v34, v36, v37
	v_cvt_pk_bf16_f32 v35, v38, v39
	v_cvt_pk_bf16_f32 v36, v46, v47
	v_cvt_pk_bf16_f32 v37, v44, v45
	global_store_dwordx4 v[48:49], v[34:37], off offset:256
	s_and_saveexec_b64 s[4:5], s[6:7]
	s_cbranch_execz .LBB0_501
	s_waitcnt lgkmcnt(0)
	v_add_f32_e32 v32, v32, v33
	global_atomic_add_f32 v[112:113], v32, off offset:576
.LBB0_501:
	s_or_b64 exec, exec, s[4:5]
	v_pk_fma_f32 v[28:29], v[28:29], 0.5, v[92:93] op_sel_hi:[1,0,1]
	v_pk_fma_f32 v[30:31], v[30:31], 0.5, v[94:95] op_sel_hi:[1,0,1]
	v_pk_fma_f32 v[36:37], v[24:25], 0.5, v[88:89] op_sel_hi:[1,0,1]
	v_cvt_pk_bf16_f32 v24, v28, v29
	v_mul_f32_e32 v29, v29, v29
	v_fmac_f32_e32 v29, v28, v28
	v_mul_f32_e32 v28, v31, v31
	v_pk_fma_f32 v[34:35], v[26:27], 0.5, v[90:91] op_sel_hi:[1,0,1]
	v_fmac_f32_e32 v28, v30, v30
	v_cvt_pk_bf16_f32 v25, v30, v31
	v_add_f32_e32 v28, v29, v28
	v_mul_f32_e32 v29, v37, v37
	v_mul_f32_e32 v30, v35, v35
	v_fmac_f32_e32 v29, v36, v36
	v_fmac_f32_e32 v30, v34, v34
	v_pk_fma_f32 v[22:23], v[22:23], 0.5, v[86:87] op_sel_hi:[1,0,1]
	v_pk_fma_f32 v[20:21], v[20:21], 0.5, v[84:85] op_sel_hi:[1,0,1]
	v_add_f32_e32 v29, v29, v30
	v_pk_fma_f32 v[30:31], v[16:17], 0.5, v[80:81] op_sel_hi:[1,0,1]
	v_mul_f32_e32 v16, v21, v21
	v_mul_f32_e32 v17, v23, v23
	v_cvt_pk_bf16_f32 v26, v36, v37
	v_cvt_pk_bf16_f32 v27, v34, v35
	v_add_f32_e32 v34, v28, v29
	v_pk_fma_f32 v[28:29], v[18:19], 0.5, v[82:83] op_sel_hi:[1,0,1]
	v_fmac_f32_e32 v16, v20, v20
	v_fmac_f32_e32 v17, v22, v22
	v_add_f32_e32 v16, v16, v17
	v_mul_f32_e32 v17, v31, v31
	v_mul_f32_e32 v18, v29, v29
	v_fmac_f32_e32 v17, v30, v30
	v_fmac_f32_e32 v18, v28, v28
	v_add_f32_e32 v17, v17, v18
	v_add_f32_e32 v16, v16, v17
	v_add_f32_e32 v19, v34, v16
	ds_bpermute_b32 v34, v212, v19
	s_waitcnt lgkmcnt(0)
	v_lshlrev_b64 v[32:33], 12, v[116:117]
	v_lshl_add_u64 v[16:17], s[16:17], 0, v[32:33]
	v_lshl_add_u64 v[32:33], v[192:193], 1, v[16:17]
	global_store_dwordx4 v[32:33], v[24:27], off
	v_add_f32_e32 v16, v19, v34
	ds_bpermute_b32 v17, v120, v16
	v_cvt_pk_bf16_f32 v18, v20, v21
	v_cvt_pk_bf16_f32 v19, v22, v23
	v_cvt_pk_bf16_f32 v20, v30, v31
	v_cvt_pk_bf16_f32 v21, v28, v29
	global_store_dwordx4 v[32:33], v[18:21], off offset:256
	s_and_saveexec_b64 s[4:5], s[6:7]
	s_cbranch_execz .LBB0_503
	s_waitcnt lgkmcnt(0)
	v_add_f32_e32 v16, v16, v17
	global_atomic_add_f32 v[112:113], v16, off offset:640
.LBB0_503:
	s_or_b64 exec, exec, s[4:5]
	v_pk_fma_f32 v[12:13], v[12:13], 0.5, v[76:77] op_sel_hi:[1,0,1]
	v_pk_fma_f32 v[14:15], v[14:15], 0.5, v[78:79] op_sel_hi:[1,0,1]
	v_pk_fma_f32 v[20:21], v[8:9], 0.5, v[72:73] op_sel_hi:[1,0,1]
	v_cvt_pk_bf16_f32 v8, v12, v13
	v_mul_f32_e32 v13, v13, v13
	v_fmac_f32_e32 v13, v12, v12
	v_mul_f32_e32 v12, v15, v15
	v_pk_fma_f32 v[18:19], v[10:11], 0.5, v[74:75] op_sel_hi:[1,0,1]
	v_fmac_f32_e32 v12, v14, v14
	v_cvt_pk_bf16_f32 v9, v14, v15
	v_add_f32_e32 v12, v13, v12
	v_mul_f32_e32 v13, v21, v21
	v_mul_f32_e32 v14, v19, v19
	v_fmac_f32_e32 v13, v20, v20
	v_fmac_f32_e32 v14, v18, v18
	v_pk_fma_f32 v[6:7], v[6:7], 0.5, v[70:71] op_sel_hi:[1,0,1]
	v_pk_fma_f32 v[4:5], v[4:5], 0.5, v[68:69] op_sel_hi:[1,0,1]
	v_add_f32_e32 v13, v13, v14
	v_pk_fma_f32 v[14:15], v[0:1], 0.5, v[64:65] op_sel_hi:[1,0,1]
	v_mul_f32_e32 v0, v5, v5
	v_mul_f32_e32 v1, v7, v7
	v_cvt_pk_bf16_f32 v10, v20, v21
	v_cvt_pk_bf16_f32 v11, v18, v19
	v_add_f32_e32 v18, v12, v13
	v_pk_fma_f32 v[12:13], v[2:3], 0.5, v[66:67] op_sel_hi:[1,0,1]
	v_fmac_f32_e32 v0, v4, v4
	v_fmac_f32_e32 v1, v6, v6
	v_add_f32_e32 v0, v0, v1
	v_mul_f32_e32 v1, v15, v15
	v_mul_f32_e32 v2, v13, v13
	v_fmac_f32_e32 v1, v14, v14
	v_fmac_f32_e32 v2, v12, v12
	v_add_f32_e32 v1, v1, v2
	v_add_f32_e32 v0, v0, v1
	v_add_f32_e32 v3, v18, v0
	ds_bpermute_b32 v18, v212, v3
	s_waitcnt lgkmcnt(0)
	v_lshlrev_b64 v[16:17], 12, v[114:115]
	v_lshl_add_u64 v[0:1], s[16:17], 0, v[16:17]
	v_lshl_add_u64 v[16:17], v[192:193], 1, v[0:1]
	global_store_dwordx4 v[16:17], v[8:11], off
	v_add_f32_e32 v0, v3, v18
	ds_bpermute_b32 v1, v120, v0
	v_cvt_pk_bf16_f32 v2, v4, v5
	v_cvt_pk_bf16_f32 v3, v6, v7
	v_cvt_pk_bf16_f32 v4, v14, v15
	v_cvt_pk_bf16_f32 v5, v12, v13
	global_store_dwordx4 v[16:17], v[2:5], off offset:256
	s_and_saveexec_b64 s[4:5], s[6:7]
	s_cbranch_execz .LBB0_505
	s_waitcnt lgkmcnt(0)
	v_add_f32_e32 v0, v0, v1
	global_atomic_add_f32 v[112:113], v0, off offset:704

.LBB0_515:
	global_load_dword v47, v[0:1], off sc1
	global_load_dword v32, v[2:3], off sc1
	global_load_dword v33, v[4:5], off sc1
	global_load_dword v34, v[6:7], off sc1
	global_load_dword v35, v[8:9], off sc1
	global_load_dword v36, v[10:11], off sc1
	global_load_dword v37, v[12:13], off sc1
	global_load_dword v38, v[14:15], off sc1
	global_load_dword v39, v[16:17], off sc1
	global_load_dword v40, v[18:19], off sc1
	global_load_dword v41, v[20:21], off sc1
	global_load_dword v42, v[22:23], off sc1
	global_load_dword v43, v[24:25], off sc1
	global_load_dword v44, v[26:27], off sc1
	global_load_dword v45, v[28:29], off sc1
	global_load_dword v46, v[30:31], off sc1
	s_or_b64 s[16:17], s[16:17], exec
	s_or_b64 s[12:13], s[12:13], exec
	s_waitcnt vmcnt(0) lgkmcnt(0)
	v_add_u32_e32 v48, v32, v47
	v_add_u32_e32 v48, v48, v33
	v_add_u32_e32 v48, v48, v34
	v_add_u32_e32 v48, v48, v35
	v_add_u32_e32 v48, v48, v36
	v_add_u32_e32 v48, v48, v37
	v_add_u32_e32 v48, v48, v38
	v_add_u32_e32 v48, v48, v39
	v_add_u32_e32 v48, v48, v40
	v_add_u32_e32 v48, v48, v41
	v_add_u32_e32 v48, v48, v42
	v_add_u32_e32 v48, v48, v43
	v_add_u32_e32 v48, v48, v44
	v_add_u32_e32 v48, v48, v45
	v_add_u32_e32 v48, v48, v46
	v_cmp_ne_u32_e32 vcc, s2, v48
	s_and_saveexec_b64 s[18:19], vcc
	s_cbranch_execz .LBB0_514
	s_and_b32 s14, s3, 0xff
	s_mov_b64 s[20:21], -1
	s_cmp_eq_u32 s14, 0
	s_mov_b64 s[24:25], -1
	s_mov_b64 s[22:23], -1
	s_sleep 1
	s_cbranch_scc1 .LBB0_518
	s_and_saveexec_b64 s[26:27], s[24:25]
	s_cbranch_execz .LBB0_513
	s_branch .LBB0_521
.LBB0_518:
	v_mov_b64_e32 v[48:49], s[6:7]
	global_load_dword v48, v[48:49], off sc1
	s_mov_b64 s[24:25], 0
	s_waitcnt vmcnt(0) lgkmcnt(0)
	v_cmp_eq_u32_e32 vcc, 0, v48
	s_and_saveexec_b64 s[26:27], vcc
	s_cmp_lt_u32 s3, 0x40001
	s_cselect_b64 s[14:15], -1, 0
	s_xor_b64 s[22:23], exec, -1
	s_and_b64 s[24:25], s[14:15], exec
	s_or_b64 exec, exec, s[26:27]
	s_and_saveexec_b64 s[26:27], s[24:25]
	s_cbranch_execz .LBB0_513

.LBB0_522:
	s_or_b64 exec, exec, s[8:9]
	s_xor_b64 s[2:3], s[10:11], -1
	s_and_saveexec_b64 s[8:9], s[2:3]
	s_xor_b64 s[8:9], exec, s[8:9]
	s_cbranch_execz .LBB0_524
	v_mov_b32_e32 v2, 1
	v_mov_b64_e32 v[0:1], s[6:7]
	global_atomic_add v[0:1], v2, off

.LBB0_525:
	s_lshl_b32 s1, s1, 8
	s_add_u32 s1, s4, s1
	s_addc_u32 s3, s5, 0
	v_mov_b32_e32 v1, s1
	v_add_co_u32_e32 v4, vcc, 0x101000, v1
	v_mov_b32_e32 v1, s3
	s_nop 0
	v_addc_co_u32_e32 v5, vcc, 0, v1, vcc
	v_mov_b32_e32 v1, 1
	global_atomic_add v1, v[4:5], v1, off offset:1024 sc0
	v_cvt_f32_u32_e32 v3, v2
	v_sub_u32_e32 v4, 0, v2
	s_add_u32 s2, s1, 0x100000
	s_addc_u32 s1, s3, 0
	v_rcp_iflag_f32_e32 v3, v3
	s_nop 0
	v_mul_f32_e32 v3, 0x4f7ffffe, v3
	v_cvt_u32_f32_e32 v3, v3
	v_mul_lo_u32 v4, v4, v3
	v_mul_hi_u32 v4, v3, v4
	v_add_u32_e32 v3, v3, v4
	s_waitcnt vmcnt(0) lgkmcnt(0)
	v_mul_hi_u32 v3, v1, v3
	v_mul_lo_u32 v5, v3, v2
	v_add_u32_e32 v4, 1, v1
	v_sub_u32_e32 v1, v1, v5
	v_add_u32_e32 v6, 1, v3
	v_cmp_ge_u32_e32 vcc, v1, v2
	v_sub_u32_e32 v5, v1, v2
	s_nop 0
	v_cndmask_b32_e32 v3, v3, v6, vcc
	v_cndmask_b32_e32 v1, v1, v5, vcc
	v_add_u32_e32 v5, 1, v3
	v_cmp_ge_u32_e32 vcc, v1, v2
	s_nop 1
	v_cndmask_b32_e32 v1, v3, v5, vcc
	v_mad_u64_u32 v[2:3], s[6:7], v2, v1, v[2:3]
	v_cmp_ne_u32_e32 vcc, v4, v2
	s_and_saveexec_b64 s[6:7], vcc
	s_xor_b64 s[6:7], exec, s[6:7]
	s_cbranch_execz .LBB0_538
	v_mov_b32_e32 v0, s2
	v_add_co_u32_e32 v2, vcc, 0x2000, v0
	v_mov_b32_e32 v0, s1
	s_nop 0
	v_addc_co_u32_e32 v3, vcc, 0, v0, vcc
	global_load_dword v0, v[2:3], off offset:1024 sc1
	s_add_u32 s12, s2, 0x2400
	s_addc_u32 s13, s1, 0
	s_waitcnt vmcnt(0) lgkmcnt(0)
	v_cmp_eq_u32_e32 vcc, v0, v1
	s_and_saveexec_b64 s[8:9], vcc
	s_cbranch_execz .LBB0_537
	s_add_u32 s10, s4, 0x100200
	s_addc_u32 s11, s5, 0
	s_mov_b32 s3, 1
	s_mov_b64 s[16:17], 0
	s_branch .LBB0_529

.LBB0_529:
	s_and_b32 s14, s3, 0xff
	s_mov_b64 s[22:23], -1
	s_cmp_lg_u32 s14, 0
	s_mov_b64 s[24:25], -1
	s_sleep 1
	s_cbranch_scc1 .LBB0_533
	v_mov_b64_e32 v[2:3], s[10:11]
	global_load_dword v0, v[2:3], off sc1
	s_mov_b64 s[24:25], 0
	s_mov_b64 s[26:27], -1
	s_waitcnt vmcnt(0) lgkmcnt(0)
	v_cmp_eq_u32_e32 vcc, 0, v0
	s_and_saveexec_b64 s[28:29], vcc
	s_cmp_lt_u32 s3, 0x40001
	s_cselect_b64 s[14:15], -1, 0
	s_xor_b64 s[26:27], exec, -1
	s_and_b64 s[24:25], s[14:15], exec
	s_or_b64 exec, exec, s[28:29]
.LBB0_533:
	s_andn2_b64 s[14:15], s[20:21], exec
	s_and_b64 s[20:21], s[26:27], exec
	s_or_b64 s[20:21], s[14:15], s[20:21]
	s_and_saveexec_b64 s[26:27], s[24:25]
	s_cbranch_execz .LBB0_528
	v_mov_b64_e32 v[2:3], s[12:13]
	global_load_dword v0, v[2:3], off sc1
	s_add_i32 s3, s3, 1
	s_or_b64 s[20:21], s[20:21], exec
	s_waitcnt vmcnt(0) lgkmcnt(0)
	v_cmp_ne_u32_e32 vcc, v0, v1
	s_orn2_b64 s[22:23], vcc, exec
	s_branch .LBB0_528
.LBB0_535:
	s_or_b64 exec, exec, s[16:17]
	s_xor_b64 s[12:13], s[18:19], -1
	s_and_saveexec_b64 s[14:15], s[12:13]
	s_xor_b64 s[14:15], exec, s[14:15]
	s_cbranch_execz .LBB0_537
	v_mov_b32_e32 v2, 1
	v_mov_b64_e32 v[0:1], s[10:11]
	global_atomic_add v[0:1], v2, off

.LBB0_538:
	s_andn2_saveexec_b64 s[6:7], s[6:7]
	s_cbranch_execz .LBB0_554
	v_mov_b32_e32 v1, s4
	v_add_co_u32_e32 v2, vcc, 0x103000, v1
	v_mov_b32_e32 v1, s5
	buffer_wbl2 sc1
	s_waitcnt vmcnt(0)
	v_addc_co_u32_e32 v3, vcc, 0, v1, vcc
	v_mov_b32_e32 v1, 1
	global_atomic_add v1, v[2:3], v1, off offset:1024 sc0
	v_cvt_f32_u32_e32 v2, v0
	v_sub_u32_e32 v3, 0, v0
	s_add_u32 s6, s4, 0x103500
	s_addc_u32 s7, s5, 0
	v_rcp_iflag_f32_e32 v2, v2
	s_mov_b64 s[10:11], -1
	v_mul_f32_e32 v2, 0x4f7ffffe, v2
	v_cvt_u32_f32_e32 v2, v2
	v_mul_lo_u32 v3, v3, v2
	v_mul_hi_u32 v3, v2, v3
	v_add_u32_e32 v2, v2, v3
	s_waitcnt vmcnt(0) lgkmcnt(0)
	v_mul_hi_u32 v2, v1, v2
	v_mul_lo_u32 v4, v2, v0
	v_add_u32_e32 v3, 1, v1
	v_sub_u32_e32 v1, v1, v4
	v_add_u32_e32 v5, 1, v2
	v_cmp_ge_u32_e32 vcc, v1, v0
	v_sub_u32_e32 v4, v1, v0
	s_nop 0
	v_cndmask_b32_e32 v2, v2, v5, vcc
	v_cndmask_b32_e32 v1, v1, v4, vcc
	v_add_u32_e32 v4, 1, v2
	v_cmp_ge_u32_e32 vcc, v1, v0
	s_nop 1
	v_cndmask_b32_e32 v2, v2, v4, vcc
	v_mad_u64_u32 v[0:1], s[8:9], v0, v2, v[0:1]
	v_cmp_ne_u32_e32 vcc, v3, v0
	v_mov_b64_e32 v[0:1], s[6:7]
	s_and_saveexec_b64 s[8:9], vcc
	s_cbranch_execz .LBB0_551
	v_mov_b64_e32 v[0:1], s[6:7]
	global_load_dword v0, v[0:1], off sc1
	s_mov_b64 s[16:17], 0
	s_waitcnt vmcnt(0) lgkmcnt(0)
	v_cmp_eq_u32_e32 vcc, v0, v2
	s_and_saveexec_b64 s[12:13], vcc
	s_cbranch_execz .LBB0_550
	s_add_u32 s10, s4, 0x100200
	s_addc_u32 s11, s5, 0
	s_mov_b32 s3, 1
	s_mov_b64 s[4:5], 0
	s_branch .LBB0_543

.LBB0_545:
	v_mov_b64_e32 v[0:1], s[10:11]
	global_load_dword v0, v[0:1], off sc1
	s_mov_b64 s[20:21], 0
	s_mov_b64 s[18:19], -1
	s_waitcnt vmcnt(0) lgkmcnt(0)
	v_cmp_eq_u32_e32 vcc, 0, v0
	s_and_saveexec_b64 s[22:23], vcc
	s_cmp_lt_u32 s3, 0x40001
	s_cselect_b64 s[14:15], -1, 0
	s_xor_b64 s[18:19], exec, -1
	s_and_b64 s[20:21], s[14:15], exec
	s_or_b64 exec, exec, s[22:23]
	s_mov_b64 s[22:23], -1
	s_and_saveexec_b64 s[24:25], s[20:21]
	s_cbranch_execz .LBB0_542
.LBB0_548:
	v_mov_b64_e32 v[0:1], s[6:7]
	global_load_dword v0, v[0:1], off sc1
	s_add_i32 s3, s3, 1
	s_or_b64 s[18:19], s[18:19], exec
	s_waitcnt vmcnt(0) lgkmcnt(0)
	v_cmp_ne_u32_e32 vcc, v0, v2
	s_orn2_b64 s[22:23], vcc, exec
	s_branch .LBB0_542

.LBB0_551:
	s_or_b64 exec, exec, s[8:9]
	s_and_saveexec_b64 s[4:5], s[10:11]
	s_cbranch_execz .LBB0_553
	v_mov_b32_e32 v2, 1
	global_atomic_add v[0:1], v2, off

.LBB0_557:
	s_or_b64 exec, exec, s[4:5]
	v_bitop3_b32 v1, v20, s31, 3 bitop3:0xc8
	v_lshlrev_b32_e32 v8, 2, v1
	v_lshl_add_u64 v[2:3], v[24:25], 0, v[8:9]
	global_store_dword v[2:3], v0, off

.LBB0_570:
	s_or_b64 exec, exec, s[4:5]
	v_ashrrev_i32_e32 v0, 12, v20
	v_mad_i32_i24 v24, v0, 6, v26
	v_ashrrev_i32_e32 v25, 31, v24
	v_lshlrev_b64 v[24:25], 14, v[24:25]
	v_and_b32_e32 v0, 0xffc, v20
	v_lshl_add_u64 v[24:25], s[12:13], 0, v[24:25]
	v_lshlrev_b32_e32 v8, 2, v0
	v_lshl_add_u64 v[34:35], v[24:25], 0, v[8:9]
	global_store_dword v[34:35], v4, off
	v_mov_b32_e32 v0, v251
	v_add_f32_e32 v1, v1, v5
	v_fmamk_f32 v0, v0, 0x3a000000, v29
	v_mul_f32_e32 v4, 0x4f800000, v0
	v_cmp_gt_f32_e32 vcc, s14, v0
	s_nop 1
	v_cndmask_b32_e32 v0, v0, v4, vcc
	v_sqrt_f32_e32 v4, v0
	s_nop 0
	v_add_u32_e32 v8, -1, v4
	v_add_u32_e32 v19, 1, v4
	v_fma_f32 v21, -v8, v4, v0
	v_fma_f32 v33, -v19, v4, v0
	v_cmp_ge_f32_e64 s[10:11], 0, v21
	s_nop 1
	v_cndmask_b32_e64 v4, v4, v8, s[10:11]
	v_cmp_lt_f32_e64 s[10:11], 0, v33
	s_nop 1
	v_cndmask_b32_e64 v4, v4, v19, s[10:11]
	v_mul_f32_e32 v8, 0x37800000, v4
	v_cndmask_b32_e32 v4, v4, v8, vcc
	v_cmp_class_f32_e32 vcc, v0, v30
	s_nop 1
	v_cndmask_b32_e32 v0, v4, v0, vcc
	v_div_scale_f32 v4, s[4:5], v0, v0, 1.0
	v_rcp_f32_e32 v8, v4
	v_div_scale_f32 v19, vcc, 1.0, v0, 1.0
	v_fma_f32 v21, -v4, v8, 1.0
	v_fmac_f32_e32 v8, v21, v8
	v_mul_f32_e32 v21, v19, v8
	v_fma_f32 v33, -v4, v21, v19
	v_fmac_f32_e32 v21, v33, v8
	v_fma_f32 v4, -v4, v21, v19
	v_div_fmas_f32 v4, v4, v8, v21
	v_div_fixup_f32 v0, v4, v0, 1.0
	v_fma_f32 v0, v1, v0, v17
	v_cmp_ngt_f32_e32 vcc, 0, v0
	s_and_saveexec_b64 s[4:5], vcc
	s_xor_b64 s[4:5], exec, s[4:5]
	s_cbranch_execz .LBB0_572
	v_mul_f32_e32 v1, 0xbfb8aa3b, v0
	v_rndne_f32_e32 v4, v1
	v_sub_f32_e32 v5, v1, v4
	v_fma_f32 v1, v0, s15, -v1
	v_fmac_f32_e32 v1, 0xb2a5705f, v0
	v_add_f32_e32 v1, v5, v1
	v_cvt_i32_f32_e32 v4, v4
	v_exp_f32_e32 v1, v1
	v_cmp_nlt_f32_e32 vcc, s20, v0
	v_ldexp_f32 v1, v1, v4
	s_nop 0
	v_cndmask_b32_e32 v1, 0, v1, vcc
	v_cmp_ngt_f32_e32 vcc, s21, v0
	s_nop 1
	v_cndmask_b32_e32 v8, v32, v1, vcc
	v_add_f32_e32 v4, 1.0, v8
	v_add_f32_e32 v0, -1.0, v4
	v_sub_f32_e32 v1, v0, v4
	v_add_f32_e32 v1, 1.0, v1
	v_sub_f32_e32 v0, v8, v0
	v_add_f32_e32 v5, v0, v1
	v_frexp_mant_f32_e32 v19, v4
	v_cvt_f64_f32_e32 v[0:1], v4
	v_frexp_exp_i32_f64_e32 v0, v[0:1]
	v_cmp_gt_f32_e32 vcc, s23, v19
	s_nop 1
	v_subbrev_co_u32_e32 v21, vcc, 0, v0, vcc
	v_sub_u32_e32 v0, 0, v21
	v_ldexp_f32 v1, v4, v0
	v_add_f32_e32 v4, -1.0, v1
	v_add_f32_e32 v19, 1.0, v1
	v_ldexp_f32 v0, v5, v0
	v_add_f32_e32 v5, 1.0, v4
	v_add_f32_e32 v33, -1.0, v19
	v_sub_f32_e32 v5, v1, v5
	v_sub_f32_e32 v1, v1, v33
	v_add_f32_e32 v5, v0, v5
	v_add_f32_e32 v0, v0, v1
	v_add_f32_e32 v33, v19, v0
	v_rcp_f32_e32 v38, v33
	v_sub_f32_e32 v1, v19, v33
	v_add_f32_e32 v19, v0, v1
	v_add_f32_e32 v1, v4, v5
	v_mul_f32_e32 v40, v1, v38
	v_sub_f32_e32 v0, v4, v1
	v_mul_f32_e32 v4, v33, v40
	v_fma_f32 v34, v40, v33, -v4
	v_fmac_f32_e32 v34, v40, v19
	v_add_f32_e32 v39, v5, v0
	v_add_f32_e32 v0, v4, v34
	v_sub_f32_e32 v5, v1, v0
	v_pk_add_f32 v[36:37], v[0:1], v[4:5] neg_lo:[0,1] neg_hi:[0,1]
	v_mov_b32_e32 v35, v0
	v_pk_add_f32 v[0:1], v[36:37], v[34:35] neg_lo:[0,1] neg_hi:[0,1]
	v_cmp_neq_f32_e32 vcc, s22, v8
	v_add_f32_e32 v1, v39, v1
	v_add_f32_e32 v0, v0, v1
	v_add_f32_e32 v1, v5, v0
	v_mul_f32_e32 v39, v38, v1
	v_mul_f32_e32 v4, v33, v39
	v_fma_f32 v34, v39, v33, -v4
	v_fmac_f32_e32 v34, v39, v19
	v_sub_f32_e32 v5, v5, v1
	v_add_f32_e32 v19, v0, v5
	v_add_f32_e32 v0, v4, v34
	v_sub_f32_e32 v5, v1, v0
	v_pk_add_f32 v[36:37], v[0:1], v[4:5] neg_lo:[0,1] neg_hi:[0,1]
	v_mov_b32_e32 v35, v0
	v_pk_add_f32 v[0:1], v[36:37], v[34:35] neg_lo:[0,1] neg_hi:[0,1]
	s_nop 0
	v_add_f32_e32 v1, v19, v1
	v_add_f32_e32 v0, v0, v1
	v_add_f32_e32 v1, v40, v39
	v_add_f32_e32 v0, v5, v0
	v_sub_f32_e32 v4, v1, v40
	v_mul_f32_e32 v0, v38, v0
	v_sub_f32_e32 v4, v39, v4
	v_add_f32_e32 v4, v4, v0
	v_add_f32_e32 v33, v1, v4
	v_mul_f32_e32 v34, v33, v33
	v_fmamk_f32 v0, v34, 0x3e9b6dac, v31
	v_fmaak_f32 v19, v34, v0, 0x3f2aaada
	v_cvt_f32_i32_e32 v0, v21
	v_sub_f32_e32 v1, v33, v1
	v_sub_f32_e32 v1, v4, v1
	v_ldexp_f32 v21, v1, 1
	v_mul_f32_e32 v1, v33, v34
	v_pk_mul_f32 v[34:35], v[0:1], v[18:19]
	v_ldexp_f32 v5, v33, 1
	v_fma_f32 v4, v0, s24, -v34
	v_fmac_f32_e32 v4, 0xb102e308, v0
	v_pk_add_f32 v[0:1], v[34:35], v[4:5]
	v_mov_b32_e32 v36, v34
	v_sub_f32_e32 v5, v1, v5
	v_sub_f32_e32 v5, v35, v5
	v_add_f32_e32 v37, v21, v5
	v_pk_add_f32 v[34:35], v[0:1], v[34:35] neg_lo:[0,1] neg_hi:[0,1]
	v_pk_add_f32 v[38:39], v[0:1], v[36:37]
	v_mov_b32_e32 v5, v0
	v_mov_b32_e32 v35, v39
	v_pk_add_f32 v[40:41], v[4:5], v[34:35] neg_lo:[0,1] neg_hi:[0,1]
	v_pk_add_f32 v[4:5], v[4:5], v[34:35]
	v_mov_b32_e32 v36, v37
	v_pk_add_f32 v[34:35], v[4:5], v[0:1] op_sel:[1,0] op_sel_hi:[0,1] neg_lo:[0,1] neg_hi:[0,1]
	v_pk_add_f32 v[42:43], v[38:39], v[34:35] op_sel_hi:[1,0] neg_lo:[0,1] neg_hi:[0,1]
	v_mov_b32_e32 v38, v39
	v_mov_b32_e32 v39, v5
	v_pk_mov_b32 v[34:35], v[0:1], v[34:35] op_sel:[1,0]
	v_mov_b32_e32 v37, v0
	v_pk_add_f32 v[34:35], v[38:39], v[34:35] neg_lo:[0,1] neg_hi:[0,1]
	v_mov_b32_e32 v42, v40
	v_pk_add_f32 v[0:1], v[36:37], v[34:35] neg_lo:[0,1] neg_hi:[0,1]
	v_mov_b32_e32 v41, v5
	v_pk_add_f32 v[34:35], v[42:43], v[0:1]
	s_nop 0
	v_pk_add_f32 v[36:37], v[34:35], v[34:35] op_sel:[0,1] op_sel_hi:[1,0]
	s_nop 0
	v_pk_add_f32 v[4:5], v[4:5], v[36:37] op_sel:[1,0] op_sel_hi:[0,1]
	v_mov_b32_e32 v35, v4
	v_pk_add_f32 v[38:39], v[34:35], v[40:41] neg_lo:[0,1] neg_hi:[0,1]
	v_mov_b32_e32 v1, v36
	v_sub_f32_e32 v5, v34, v38
	v_pk_add_f32 v[0:1], v[0:1], v[38:39] neg_lo:[0,1] neg_hi:[0,1]
	v_sub_f32_e32 v5, v40, v5
	v_add_f32_e32 v0, v0, v5
	v_add_f32_e32 v0, v0, v1
	v_add_f32_e32 v0, v4, v0
	v_cndmask_b32_e32 v0, v32, v0, vcc
	v_cmp_lt_f32_e64 vcc, |v8|, s25
	s_nop 1
	v_cndmask_b32_e32 v0, v0, v8, vcc
	v_xor_b32_e32 v1, 0x80000000, v0

.LBB0_574:
	s_or_b64 exec, exec, s[4:5]
	v_bitop3_b32 v0, v20, s29, 1 bitop3:0xc8
	v_lshlrev_b32_e32 v8, 2, v0
	v_lshl_add_u64 v[4:5], v[24:25], 0, v[8:9]
	global_store_dword v[4:5], v1, off
	v_mov_b32_e32 v0, v252
	v_fmamk_f32 v0, v0, 0x3a000000, v29
	v_mul_f32_e32 v1, 0x4f800000, v0
	v_cmp_gt_f32_e32 vcc, s14, v0
	s_nop 1
	v_cndmask_b32_e32 v0, v0, v1, vcc
	v_sqrt_f32_e32 v1, v0
	s_nop 0
	v_add_u32_e32 v4, -1, v1
	v_add_u32_e32 v5, 1, v1
	v_fma_f32 v8, -v4, v1, v0
	v_fma_f32 v19, -v5, v1, v0
	v_cmp_ge_f32_e64 s[10:11], 0, v8
	s_nop 1
	v_cndmask_b32_e64 v1, v1, v4, s[10:11]
	v_cmp_lt_f32_e64 s[10:11], 0, v19
	s_nop 1
	v_cndmask_b32_e64 v1, v1, v5, s[10:11]
	v_mul_f32_e32 v4, 0x37800000, v1
	v_cndmask_b32_e32 v1, v1, v4, vcc
	v_cmp_class_f32_e32 vcc, v0, v30
	s_nop 1
	v_cndmask_b32_e32 v0, v1, v0, vcc
	v_div_scale_f32 v1, s[4:5], v0, v0, 1.0
	v_rcp_f32_e32 v4, v1
	v_div_scale_f32 v5, vcc, 1.0, v0, 1.0
	v_fma_f32 v8, -v1, v4, 1.0
	v_fmac_f32_e32 v4, v8, v4
	v_mul_f32_e32 v8, v5, v4
	v_fma_f32 v19, -v1, v8, v5
	v_fmac_f32_e32 v8, v19, v4
	v_fma_f32 v1, -v1, v8, v5
	v_div_fmas_f32 v1, v1, v4, v8
	v_div_fixup_f32 v0, v1, v0, 1.0
	v_add_f32_e32 v1, v2, v6
	v_fma_f32 v0, v1, v0, v17
	v_cmp_ngt_f32_e32 vcc, 0, v0
	s_and_saveexec_b64 s[4:5], vcc
	s_xor_b64 s[4:5], exec, s[4:5]
	s_cbranch_execz .LBB0_576
	v_mul_f32_e32 v1, 0xbfb8aa3b, v0
	v_rndne_f32_e32 v2, v1
	v_sub_f32_e32 v4, v1, v2
	v_fma_f32 v1, v0, s15, -v1
	v_fmac_f32_e32 v1, 0xb2a5705f, v0
	v_add_f32_e32 v1, v4, v1
	v_cvt_i32_f32_e32 v2, v2
	v_exp_f32_e32 v1, v1
	v_cmp_nlt_f32_e32 vcc, s20, v0
	v_ldexp_f32 v1, v1, v2
	s_nop 0
	v_cndmask_b32_e32 v1, 0, v1, vcc
	v_cmp_ngt_f32_e32 vcc, s21, v0
	s_nop 1
	v_cndmask_b32_e32 v2, v32, v1, vcc
	v_add_f32_e32 v4, 1.0, v2
	v_add_f32_e32 v0, -1.0, v4
	v_sub_f32_e32 v1, v0, v4
	v_add_f32_e32 v1, 1.0, v1
	v_sub_f32_e32 v0, v2, v0
	v_add_f32_e32 v5, v0, v1
	v_frexp_mant_f32_e32 v6, v4
	v_cvt_f64_f32_e32 v[0:1], v4
	v_frexp_exp_i32_f64_e32 v0, v[0:1]
	v_cmp_gt_f32_e32 vcc, s23, v6
	s_nop 1
	v_subbrev_co_u32_e32 v6, vcc, 0, v0, vcc
	v_sub_u32_e32 v0, 0, v6
	v_ldexp_f32 v1, v4, v0
	v_add_f32_e32 v4, -1.0, v1
	v_add_f32_e32 v8, 1.0, v1
	v_ldexp_f32 v0, v5, v0
	v_add_f32_e32 v5, 1.0, v4
	v_add_f32_e32 v19, -1.0, v8
	v_sub_f32_e32 v5, v1, v5
	v_sub_f32_e32 v1, v1, v19
	v_add_f32_e32 v5, v0, v5
	v_add_f32_e32 v0, v0, v1
	v_add_f32_e32 v19, v8, v0
	v_rcp_f32_e32 v21, v19
	v_sub_f32_e32 v1, v8, v19
	v_add_f32_e32 v8, v0, v1
	v_add_f32_e32 v1, v4, v5
	v_mul_f32_e32 v38, v1, v21
	v_sub_f32_e32 v0, v4, v1
	v_mul_f32_e32 v4, v19, v38
	v_fma_f32 v34, v38, v19, -v4
	v_fmac_f32_e32 v34, v38, v8
	v_add_f32_e32 v33, v5, v0
	v_add_f32_e32 v0, v4, v34
	v_sub_f32_e32 v5, v1, v0
	v_pk_add_f32 v[36:37], v[0:1], v[4:5] neg_lo:[0,1] neg_hi:[0,1]
	v_mov_b32_e32 v35, v0
	v_pk_add_f32 v[0:1], v[36:37], v[34:35] neg_lo:[0,1] neg_hi:[0,1]
	v_cmp_neq_f32_e32 vcc, s22, v2
	v_add_f32_e32 v1, v33, v1
	v_add_f32_e32 v0, v0, v1
	v_add_f32_e32 v1, v5, v0
	v_mul_f32_e32 v33, v21, v1
	v_mul_f32_e32 v4, v19, v33
	v_fma_f32 v34, v33, v19, -v4
	v_fmac_f32_e32 v34, v33, v8
	v_sub_f32_e32 v5, v5, v1
	v_add_f32_e32 v8, v0, v5
	v_add_f32_e32 v0, v4, v34
	v_sub_f32_e32 v5, v1, v0
	v_pk_add_f32 v[36:37], v[0:1], v[4:5] neg_lo:[0,1] neg_hi:[0,1]
	v_mov_b32_e32 v35, v0
	v_pk_add_f32 v[0:1], v[36:37], v[34:35] neg_lo:[0,1] neg_hi:[0,1]
	s_nop 0
	v_add_f32_e32 v1, v8, v1
	v_add_f32_e32 v0, v0, v1
	v_add_f32_e32 v1, v38, v33
	v_add_f32_e32 v0, v5, v0
	v_sub_f32_e32 v4, v1, v38
	v_mul_f32_e32 v0, v21, v0
	v_sub_f32_e32 v4, v33, v4
	v_add_f32_e32 v4, v4, v0
	v_add_f32_e32 v8, v1, v4
	v_mul_f32_e32 v21, v8, v8
	v_fmamk_f32 v0, v21, 0x3e9b6dac, v31
	v_fmaak_f32 v19, v21, v0, 0x3f2aaada
	v_cvt_f32_i32_e32 v0, v6
	v_sub_f32_e32 v1, v8, v1
	v_sub_f32_e32 v1, v4, v1
	v_ldexp_f32 v6, v1, 1
	v_mul_f32_e32 v1, v8, v21
	v_pk_mul_f32 v[34:35], v[0:1], v[18:19]
	v_ldexp_f32 v5, v8, 1
	v_fma_f32 v4, v0, s24, -v34
	v_fmac_f32_e32 v4, 0xb102e308, v0
	v_pk_add_f32 v[0:1], v[34:35], v[4:5]
	v_mov_b32_e32 v36, v34
	v_sub_f32_e32 v5, v1, v5
	v_sub_f32_e32 v5, v35, v5
	v_add_f32_e32 v37, v6, v5
	v_pk_add_f32 v[34:35], v[0:1], v[34:35] neg_lo:[0,1] neg_hi:[0,1]
	v_pk_add_f32 v[38:39], v[0:1], v[36:37]
	v_mov_b32_e32 v5, v0
	v_mov_b32_e32 v35, v39
	v_pk_add_f32 v[40:41], v[4:5], v[34:35] neg_lo:[0,1] neg_hi:[0,1]
	v_pk_add_f32 v[4:5], v[4:5], v[34:35]
	v_mov_b32_e32 v36, v37
	v_pk_add_f32 v[34:35], v[4:5], v[0:1] op_sel:[1,0] op_sel_hi:[0,1] neg_lo:[0,1] neg_hi:[0,1]
	v_pk_add_f32 v[42:43], v[38:39], v[34:35] op_sel_hi:[1,0] neg_lo:[0,1] neg_hi:[0,1]
	v_mov_b32_e32 v38, v39
	v_mov_b32_e32 v39, v5
	v_pk_mov_b32 v[34:35], v[0:1], v[34:35] op_sel:[1,0]
	v_mov_b32_e32 v37, v0
	v_pk_add_f32 v[34:35], v[38:39], v[34:35] neg_lo:[0,1] neg_hi:[0,1]
	v_mov_b32_e32 v42, v40
	v_pk_add_f32 v[0:1], v[36:37], v[34:35] neg_lo:[0,1] neg_hi:[0,1]
	v_mov_b32_e32 v41, v5
	v_pk_add_f32 v[34:35], v[42:43], v[0:1]
	s_nop 0
	v_pk_add_f32 v[36:37], v[34:35], v[34:35] op_sel:[0,1] op_sel_hi:[1,0]
	s_nop 0
	v_pk_add_f32 v[4:5], v[4:5], v[36:37] op_sel:[1,0] op_sel_hi:[0,1]
	v_mov_b32_e32 v35, v4
	v_pk_add_f32 v[38:39], v[34:35], v[40:41] neg_lo:[0,1] neg_hi:[0,1]
	v_mov_b32_e32 v1, v36
	v_sub_f32_e32 v5, v34, v38
	v_pk_add_f32 v[0:1], v[0:1], v[38:39] neg_lo:[0,1] neg_hi:[0,1]
	v_sub_f32_e32 v5, v40, v5
	v_add_f32_e32 v0, v0, v5
	v_add_f32_e32 v0, v0, v1
	v_add_f32_e32 v0, v4, v0
	v_cndmask_b32_e32 v0, v32, v0, vcc
	v_cmp_lt_f32_e64 vcc, |v2|, s25
	s_nop 1
	v_cndmask_b32_e32 v0, v0, v2, vcc
	v_xor_b32_e32 v1, 0x80000000, v0

.LBB0_578:
	s_or_b64 exec, exec, s[4:5]
	v_bitop3_b32 v0, v20, s30, 2 bitop3:0xc8
	v_lshlrev_b32_e32 v8, 2, v0
	v_lshl_add_u64 v[4:5], v[24:25], 0, v[8:9]
	global_store_dword v[4:5], v1, off
	v_mov_b32_e32 v0, v253
	v_fmamk_f32 v0, v0, 0x3a000000, v29
	v_mul_f32_e32 v1, 0x4f800000, v0
	v_cmp_gt_f32_e32 vcc, s14, v0
	s_nop 1
	v_cndmask_b32_e32 v0, v0, v1, vcc
	v_sqrt_f32_e32 v1, v0
	s_nop 0
	v_add_u32_e32 v2, -1, v1
	v_add_u32_e32 v4, 1, v1
	v_fma_f32 v5, -v2, v1, v0
	v_fma_f32 v6, -v4, v1, v0
	v_cmp_ge_f32_e64 s[10:11], 0, v5
	s_nop 1
	v_cndmask_b32_e64 v1, v1, v2, s[10:11]
	v_cmp_lt_f32_e64 s[10:11], 0, v6
	s_nop 1
	v_cndmask_b32_e64 v1, v1, v4, s[10:11]
	v_mul_f32_e32 v2, 0x37800000, v1
	v_cndmask_b32_e32 v1, v1, v2, vcc
	v_cmp_class_f32_e32 vcc, v0, v30
	s_nop 1
	v_cndmask_b32_e32 v0, v1, v0, vcc
	v_div_scale_f32 v1, s[4:5], v0, v0, 1.0
	v_rcp_f32_e32 v2, v1
	v_div_scale_f32 v4, vcc, 1.0, v0, 1.0
	v_fma_f32 v5, -v1, v2, 1.0
	v_fmac_f32_e32 v2, v5, v2
	v_mul_f32_e32 v5, v4, v2
	v_fma_f32 v6, -v1, v5, v4
	v_fmac_f32_e32 v5, v6, v2
	v_fma_f32 v1, -v1, v5, v4
	v_div_fmas_f32 v1, v1, v2, v5
	v_div_fixup_f32 v0, v1, v0, 1.0
	v_add_f32_e32 v1, v3, v7
	v_fmac_f32_e32 v17, v1, v0
	v_cmp_ngt_f32_e32 vcc, 0, v17
	s_and_saveexec_b64 s[4:5], vcc
	s_xor_b64 s[4:5], exec, s[4:5]
	s_cbranch_execz .LBB0_580
	v_mul_f32_e32 v0, 0xbfb8aa3b, v17
	v_rndne_f32_e32 v1, v0
	v_sub_f32_e32 v2, v0, v1
	v_fma_f32 v0, v17, s15, -v0
	v_fmac_f32_e32 v0, 0xb2a5705f, v17
	v_add_f32_e32 v0, v2, v0
	v_cvt_i32_f32_e32 v1, v1
	v_exp_f32_e32 v0, v0
	v_cmp_nlt_f32_e32 vcc, s20, v17
	v_ldexp_f32 v0, v0, v1
	s_nop 0
	v_cndmask_b32_e32 v0, 0, v0, vcc
	v_cmp_ngt_f32_e32 vcc, s21, v17
	s_nop 1
	v_cndmask_b32_e32 v8, v32, v0, vcc
	v_add_f32_e32 v2, 1.0, v8
	v_add_f32_e32 v0, -1.0, v2
	v_sub_f32_e32 v1, v0, v2
	v_add_f32_e32 v1, 1.0, v1
	v_sub_f32_e32 v0, v8, v0
	v_add_f32_e32 v3, v0, v1
	v_frexp_mant_f32_e32 v4, v2
	v_cvt_f64_f32_e32 v[0:1], v2
	v_frexp_exp_i32_f64_e32 v0, v[0:1]
	v_cmp_gt_f32_e32 vcc, s23, v4
	s_nop 1
	v_subbrev_co_u32_e32 v17, vcc, 0, v0, vcc
	v_sub_u32_e32 v0, 0, v17
	v_ldexp_f32 v1, v2, v0
	v_add_f32_e32 v2, -1.0, v1
	v_add_f32_e32 v4, 1.0, v1
	v_ldexp_f32 v0, v3, v0
	v_add_f32_e32 v3, 1.0, v2
	v_add_f32_e32 v5, -1.0, v4
	v_sub_f32_e32 v3, v1, v3
	v_sub_f32_e32 v1, v1, v5
	v_add_f32_e32 v3, v0, v3
	v_add_f32_e32 v0, v0, v1
	v_add_f32_e32 v19, v4, v0
	v_rcp_f32_e32 v22, v19
	v_sub_f32_e32 v1, v4, v19
	v_add_f32_e32 v21, v0, v1
	v_add_f32_e32 v1, v2, v3
	v_mul_f32_e32 v33, v1, v22
	v_sub_f32_e32 v0, v2, v1
	v_mul_f32_e32 v2, v19, v33
	v_fma_f32 v4, v33, v19, -v2
	v_fmac_f32_e32 v4, v33, v21
	v_add_f32_e32 v23, v3, v0
	v_add_f32_e32 v0, v2, v4
	v_sub_f32_e32 v3, v1, v0
	v_pk_add_f32 v[6:7], v[0:1], v[2:3] neg_lo:[0,1] neg_hi:[0,1]
	v_mov_b32_e32 v5, v0
	v_pk_add_f32 v[0:1], v[6:7], v[4:5] neg_lo:[0,1] neg_hi:[0,1]
	v_cmp_neq_f32_e32 vcc, s22, v8
	v_add_f32_e32 v1, v23, v1
	v_add_f32_e32 v0, v0, v1
	v_add_f32_e32 v1, v3, v0
	v_mul_f32_e32 v23, v22, v1
	v_mul_f32_e32 v2, v19, v23
	v_fma_f32 v4, v23, v19, -v2
	v_fmac_f32_e32 v4, v23, v21
	v_sub_f32_e32 v3, v3, v1
	v_add_f32_e32 v19, v0, v3
	v_add_f32_e32 v0, v2, v4
	v_sub_f32_e32 v3, v1, v0
	v_pk_add_f32 v[6:7], v[0:1], v[2:3] neg_lo:[0,1] neg_hi:[0,1]
	v_mov_b32_e32 v5, v0
	v_pk_add_f32 v[0:1], v[6:7], v[4:5] neg_lo:[0,1] neg_hi:[0,1]
	s_nop 0
	v_add_f32_e32 v1, v19, v1
	v_add_f32_e32 v0, v0, v1
	v_add_f32_e32 v1, v33, v23
	v_add_f32_e32 v0, v3, v0
	v_sub_f32_e32 v2, v1, v33
	v_mul_f32_e32 v0, v22, v0
	v_sub_f32_e32 v2, v23, v2
	v_add_f32_e32 v2, v2, v0
	v_add_f32_e32 v4, v1, v2
	v_mul_f32_e32 v5, v4, v4
	v_fmamk_f32 v0, v5, 0x3e9b6dac, v31
	v_fmaak_f32 v19, v5, v0, 0x3f2aaada
	v_cvt_f32_i32_e32 v0, v17
	v_sub_f32_e32 v1, v4, v1
	v_sub_f32_e32 v1, v2, v1
	v_ldexp_f32 v6, v1, 1
	v_mul_f32_e32 v1, v4, v5
	v_ldexp_f32 v3, v4, 1
	v_pk_mul_f32 v[4:5], v[0:1], v[18:19]
	s_nop 0
	v_fma_f32 v2, v0, s24, -v4
	v_fmac_f32_e32 v2, 0xb102e308, v0
	v_pk_add_f32 v[0:1], v[4:5], v[2:3]
	s_nop 0
	v_sub_f32_e32 v3, v1, v3
	v_sub_f32_e32 v3, v5, v3
	v_add_f32_e32 v7, v6, v3
	v_mov_b32_e32 v6, v4
	v_pk_add_f32 v[4:5], v[0:1], v[4:5] neg_lo:[0,1] neg_hi:[0,1]
	v_pk_add_f32 v[22:23], v[0:1], v[6:7]
	v_mov_b32_e32 v3, v0
	v_mov_b32_e32 v5, v23
	v_pk_add_f32 v[34:35], v[2:3], v[4:5] neg_lo:[0,1] neg_hi:[0,1]
	v_pk_add_f32 v[2:3], v[2:3], v[4:5]
	v_mov_b32_e32 v6, v7
	v_pk_add_f32 v[4:5], v[2:3], v[0:1] op_sel:[1,0] op_sel_hi:[0,1] neg_lo:[0,1] neg_hi:[0,1]
	v_pk_add_f32 v[36:37], v[22:23], v[4:5] op_sel_hi:[1,0] neg_lo:[0,1] neg_hi:[0,1]
	v_mov_b32_e32 v22, v23
	v_mov_b32_e32 v23, v3
	v_pk_mov_b32 v[4:5], v[0:1], v[4:5] op_sel:[1,0]
	v_mov_b32_e32 v7, v0
	v_pk_add_f32 v[4:5], v[22:23], v[4:5] neg_lo:[0,1] neg_hi:[0,1]
	v_mov_b32_e32 v36, v34
	v_pk_add_f32 v[0:1], v[6:7], v[4:5] neg_lo:[0,1] neg_hi:[0,1]
	v_mov_b32_e32 v35, v3
	v_pk_add_f32 v[4:5], v[36:37], v[0:1]
	s_nop 0
	v_pk_add_f32 v[6:7], v[4:5], v[4:5] op_sel:[0,1] op_sel_hi:[1,0]
	s_nop 0
	v_pk_add_f32 v[2:3], v[2:3], v[6:7] op_sel:[1,0] op_sel_hi:[0,1]
	v_mov_b32_e32 v5, v2
	v_pk_add_f32 v[22:23], v[4:5], v[34:35] neg_lo:[0,1] neg_hi:[0,1]
	v_mov_b32_e32 v1, v6
	v_sub_f32_e32 v3, v4, v22
	v_pk_add_f32 v[0:1], v[0:1], v[22:23] neg_lo:[0,1] neg_hi:[0,1]
	v_sub_f32_e32 v3, v34, v3
	v_add_f32_e32 v0, v0, v3
	v_add_f32_e32 v0, v0, v1
	v_add_f32_e32 v0, v2, v0
	v_cndmask_b32_e32 v0, v32, v0, vcc
	v_cmp_lt_f32_e64 vcc, |v8|, s25
	s_nop 1
	v_cndmask_b32_e32 v0, v0, v8, vcc
	v_xor_b32_e32 v0, 0x80000000, v0

.LBB0_600:
	s_lshl_b32 s36, s10, 8
	v_cndmask_b32_e64 v128, 0, 1, s[24:25]
	v_add_u32_e32 v186, s36, v172
	v_cmp_ne_u32_e64 s[10:11], 1, v128
	s_andn2_b64 vcc, exec, s[24:25]
	v_ashrrev_i32_e32 v187, 31, v186
	s_cbranch_vccnz .LBB0_602
	v_lshl_add_u64 v[128:129], v[186:187], 2, s[18:19]
	global_load_dword v128, v[128:129], off
	s_waitcnt vmcnt(0) lgkmcnt(0)
	v_fmamk_f32 v128, v128, 0x3a000000, v208
	v_mul_f32_e32 v129, 0x4f800000, v128
	v_cmp_gt_f32_e32 vcc, s54, v128
	s_nop 1
	v_cndmask_b32_e32 v128, v128, v129, vcc
	v_sqrt_f32_e32 v129, v128
	s_nop 0
	v_add_u32_e32 v130, -1, v129
	v_add_u32_e32 v131, 1, v129
	v_fma_f32 v132, -v130, v129, v128
	v_fma_f32 v133, -v131, v129, v128
	v_cmp_ge_f32_e64 s[12:13], 0, v132
	s_nop 1
	v_cndmask_b32_e64 v129, v129, v130, s[12:13]
	v_cmp_lt_f32_e64 s[12:13], 0, v133
	s_nop 1
	v_cndmask_b32_e64 v129, v129, v131, s[12:13]
	v_mul_f32_e32 v130, 0x37800000, v129
	v_cndmask_b32_e32 v129, v129, v130, vcc
	v_cmp_class_f32_e32 vcc, v128, v209
	s_nop 1
	v_cndmask_b32_e32 v128, v129, v128, vcc
	v_div_scale_f32 v129, s[4:5], v128, v128, 1.0
	v_rcp_f32_e32 v130, v129
	v_div_scale_f32 v131, vcc, 1.0, v128, 1.0
	v_fma_f32 v132, -v129, v130, 1.0
	v_fmac_f32_e32 v130, v132, v130
	v_mul_f32_e32 v132, v131, v130
	v_fma_f32 v133, -v129, v132, v131
	v_fmac_f32_e32 v132, v133, v130
	v_fma_f32 v129, -v129, v132, v131
	v_div_fmas_f32 v129, v129, v130, v132
	v_div_fixup_f32 v158, v129, v128, 1.0
	s_branch .LBB0_603

.LBB0_607:
	s_or_b64 exec, exec, s[4:5]
	s_and_b64 vcc, exec, s[10:11]
	s_cbranch_vccnz .LBB0_609
	s_ashr_i32 s37, s36, 31
	v_lshl_add_u64 v[128:129], s[36:37], 0, v[172:173]
	v_lshl_add_u64 v[128:129], v[128:129], 2, s[18:19]
	global_load_dword v128, v[128:129], off offset:64
	s_waitcnt vmcnt(0) lgkmcnt(0)
	v_fmamk_f32 v128, v128, 0x3a000000, v208
	v_mul_f32_e32 v129, 0x4f800000, v128
	v_cmp_gt_f32_e32 vcc, s54, v128
	s_nop 1
	v_cndmask_b32_e32 v128, v128, v129, vcc
	v_sqrt_f32_e32 v129, v128
	s_nop 0
	v_add_u32_e32 v130, -1, v129
	v_add_u32_e32 v131, 1, v129
	v_fma_f32 v134, -v130, v129, v128
	v_fma_f32 v135, -v131, v129, v128
	v_cmp_ge_f32_e64 s[12:13], 0, v134
	s_nop 1
	v_cndmask_b32_e64 v129, v129, v130, s[12:13]
	v_cmp_lt_f32_e64 s[12:13], 0, v135
	s_nop 1
	v_cndmask_b32_e64 v129, v129, v131, s[12:13]
	v_mul_f32_e32 v130, 0x37800000, v129
	v_cndmask_b32_e32 v129, v129, v130, vcc
	v_cmp_class_f32_e32 vcc, v128, v209
	s_nop 1
	v_cndmask_b32_e32 v128, v129, v128, vcc
	v_div_scale_f32 v129, s[4:5], v128, v128, 1.0
	v_rcp_f32_e32 v130, v129
	v_div_scale_f32 v131, vcc, 1.0, v128, 1.0
	v_fma_f32 v134, -v129, v130, 1.0
	v_fmac_f32_e32 v130, v134, v130
	v_mul_f32_e32 v134, v131, v130
	v_fma_f32 v135, -v129, v134, v131
	v_fmac_f32_e32 v134, v135, v130
	v_fma_f32 v129, -v129, v134, v131
	v_div_fmas_f32 v129, v129, v130, v134
	v_div_fixup_f32 v156, v129, v128, 1.0
	s_branch .LBB0_610

.LBB0_614:
	s_or_b64 exec, exec, s[4:5]
	s_and_b64 vcc, exec, s[10:11]
	s_cbranch_vccnz .LBB0_616
	s_ashr_i32 s37, s36, 31
	v_lshl_add_u64 v[128:129], s[36:37], 0, v[172:173]
	v_lshl_add_u64 v[128:129], v[128:129], 2, s[18:19]
	global_load_dword v128, v[128:129], off offset:128
	s_waitcnt vmcnt(0) lgkmcnt(0)
	v_fmamk_f32 v128, v128, 0x3a000000, v208
	v_mul_f32_e32 v129, 0x4f800000, v128
	v_cmp_gt_f32_e32 vcc, s54, v128
	s_nop 1
	v_cndmask_b32_e32 v128, v128, v129, vcc
	v_sqrt_f32_e32 v129, v128
	s_nop 0
	v_add_u32_e32 v130, -1, v129
	v_add_u32_e32 v131, 1, v129
	v_fma_f32 v134, -v130, v129, v128
	v_fma_f32 v135, -v131, v129, v128
	v_cmp_ge_f32_e64 s[12:13], 0, v134
	s_nop 1
	v_cndmask_b32_e64 v129, v129, v130, s[12:13]
	v_cmp_lt_f32_e64 s[12:13], 0, v135
	s_nop 1
	v_cndmask_b32_e64 v129, v129, v131, s[12:13]
	v_mul_f32_e32 v130, 0x37800000, v129
	v_cndmask_b32_e32 v129, v129, v130, vcc
	v_cmp_class_f32_e32 vcc, v128, v209
	s_nop 1
	v_cndmask_b32_e32 v128, v129, v128, vcc
	v_div_scale_f32 v129, s[4:5], v128, v128, 1.0
	v_rcp_f32_e32 v130, v129
	v_div_scale_f32 v131, vcc, 1.0, v128, 1.0
	v_fma_f32 v134, -v129, v130, 1.0
	v_fmac_f32_e32 v130, v134, v130
	v_mul_f32_e32 v134, v131, v130
	v_fma_f32 v135, -v129, v134, v131
	v_fmac_f32_e32 v134, v135, v130
	v_fma_f32 v129, -v129, v134, v131
	v_div_fmas_f32 v129, v129, v130, v134
	v_div_fixup_f32 v154, v129, v128, 1.0
	s_branch .LBB0_617

.LBB0_621:
	s_or_b64 exec, exec, s[4:5]
	s_and_b64 vcc, exec, s[10:11]
	s_cbranch_vccnz .LBB0_623
	s_ashr_i32 s37, s36, 31
	v_lshl_add_u64 v[128:129], s[36:37], 0, v[172:173]
	v_lshl_add_u64 v[128:129], v[128:129], 2, s[18:19]
	global_load_dword v128, v[128:129], off offset:192
	s_waitcnt vmcnt(0) lgkmcnt(0)
	v_fmamk_f32 v128, v128, 0x3a000000, v208
	v_mul_f32_e32 v129, 0x4f800000, v128
	v_cmp_gt_f32_e32 vcc, s54, v128
	s_nop 1
	v_cndmask_b32_e32 v128, v128, v129, vcc
	v_sqrt_f32_e32 v129, v128
	s_nop 0
	v_add_u32_e32 v130, -1, v129
	v_add_u32_e32 v131, 1, v129
	v_fma_f32 v134, -v130, v129, v128
	v_fma_f32 v135, -v131, v129, v128
	v_cmp_ge_f32_e64 s[12:13], 0, v134
	s_nop 1
	v_cndmask_b32_e64 v129, v129, v130, s[12:13]
	v_cmp_lt_f32_e64 s[12:13], 0, v135
	s_nop 1
	v_cndmask_b32_e64 v129, v129, v131, s[12:13]
	v_mul_f32_e32 v130, 0x37800000, v129
	v_cndmask_b32_e32 v129, v129, v130, vcc
	v_cmp_class_f32_e32 vcc, v128, v209
	s_nop 1
	v_cndmask_b32_e32 v128, v129, v128, vcc
	v_div_scale_f32 v129, s[4:5], v128, v128, 1.0
	v_rcp_f32_e32 v130, v129
	v_div_scale_f32 v131, vcc, 1.0, v128, 1.0
	v_fma_f32 v134, -v129, v130, 1.0
	v_fmac_f32_e32 v130, v134, v130
	v_mul_f32_e32 v134, v131, v130
	v_fma_f32 v135, -v129, v134, v131
	v_fmac_f32_e32 v134, v135, v130
	v_fma_f32 v129, -v129, v134, v131
	v_div_fmas_f32 v129, v129, v130, v134
	v_div_fixup_f32 v152, v129, v128, 1.0
	s_branch .LBB0_624

.LBB0_628:
	s_or_b64 exec, exec, s[4:5]
	s_and_b64 vcc, exec, s[10:11]
	s_cbranch_vccnz .LBB0_630
	s_ashr_i32 s37, s36, 31
	v_lshl_add_u64 v[128:129], s[36:37], 0, v[172:173]
	v_lshl_add_u64 v[128:129], v[128:129], 2, s[18:19]
	global_load_dword v128, v[128:129], off offset:512
	s_waitcnt vmcnt(0) lgkmcnt(0)
	v_fmamk_f32 v128, v128, 0x3a000000, v208
	v_mul_f32_e32 v129, 0x4f800000, v128
	v_cmp_gt_f32_e32 vcc, s54, v128
	s_nop 1
	v_cndmask_b32_e32 v128, v128, v129, vcc
	v_sqrt_f32_e32 v129, v128
	s_nop 0
	v_add_u32_e32 v130, -1, v129
	v_add_u32_e32 v131, 1, v129
	v_fma_f32 v134, -v130, v129, v128
	v_fma_f32 v135, -v131, v129, v128
	v_cmp_ge_f32_e64 s[12:13], 0, v134
	s_nop 1
	v_cndmask_b32_e64 v129, v129, v130, s[12:13]
	v_cmp_lt_f32_e64 s[12:13], 0, v135
	s_nop 1
	v_cndmask_b32_e64 v129, v129, v131, s[12:13]
	v_mul_f32_e32 v130, 0x37800000, v129
	v_cndmask_b32_e32 v129, v129, v130, vcc
	v_cmp_class_f32_e32 vcc, v128, v209
	s_nop 1
	v_cndmask_b32_e32 v128, v129, v128, vcc
	v_div_scale_f32 v129, s[4:5], v128, v128, 1.0
	v_rcp_f32_e32 v130, v129
	v_div_scale_f32 v131, vcc, 1.0, v128, 1.0
	v_fma_f32 v134, -v129, v130, 1.0
	v_fmac_f32_e32 v130, v134, v130
	v_mul_f32_e32 v134, v131, v130
	v_fma_f32 v135, -v129, v134, v131
	v_fmac_f32_e32 v134, v135, v130
	v_fma_f32 v129, -v129, v134, v131
	v_div_fmas_f32 v129, v129, v130, v134
	v_div_fixup_f32 v142, v129, v128, 1.0
	s_branch .LBB0_631

.LBB0_635:
	s_or_b64 exec, exec, s[4:5]
	s_and_b64 vcc, exec, s[10:11]
	s_cbranch_vccnz .LBB0_637
	s_ashr_i32 s37, s36, 31
	v_lshl_add_u64 v[128:129], s[36:37], 0, v[172:173]
	v_lshl_add_u64 v[128:129], v[128:129], 2, s[18:19]
	global_load_dword v128, v[128:129], off offset:576
	s_waitcnt vmcnt(0) lgkmcnt(0)
	v_fmamk_f32 v128, v128, 0x3a000000, v208
	v_mul_f32_e32 v129, 0x4f800000, v128
	v_cmp_gt_f32_e32 vcc, s54, v128
	s_nop 1
	v_cndmask_b32_e32 v128, v128, v129, vcc
	v_sqrt_f32_e32 v129, v128
	s_nop 0
	v_add_u32_e32 v130, -1, v129
	v_add_u32_e32 v131, 1, v129
	v_fma_f32 v134, -v130, v129, v128
	v_fma_f32 v135, -v131, v129, v128
	v_cmp_ge_f32_e64 s[12:13], 0, v134
	s_nop 1
	v_cndmask_b32_e64 v129, v129, v130, s[12:13]
	v_cmp_lt_f32_e64 s[12:13], 0, v135
	s_nop 1
	v_cndmask_b32_e64 v129, v129, v131, s[12:13]
	v_mul_f32_e32 v130, 0x37800000, v129
	v_cndmask_b32_e32 v129, v129, v130, vcc
	v_cmp_class_f32_e32 vcc, v128, v209
	s_nop 1
	v_cndmask_b32_e32 v128, v129, v128, vcc
	v_div_scale_f32 v129, s[4:5], v128, v128, 1.0
	v_rcp_f32_e32 v130, v129
	v_div_scale_f32 v131, vcc, 1.0, v128, 1.0
	v_fma_f32 v134, -v129, v130, 1.0
	v_fmac_f32_e32 v130, v134, v130
	v_mul_f32_e32 v134, v131, v130
	v_fma_f32 v135, -v129, v134, v131
	v_fmac_f32_e32 v134, v135, v130
	v_fma_f32 v129, -v129, v134, v131
	v_div_fmas_f32 v129, v129, v130, v134
	v_div_fixup_f32 v136, v129, v128, 1.0
	s_branch .LBB0_638

.LBB0_642:
	s_or_b64 exec, exec, s[4:5]
	s_and_b64 vcc, exec, s[10:11]
	s_cbranch_vccnz .LBB0_644
	s_ashr_i32 s37, s36, 31
	v_lshl_add_u64 v[128:129], s[36:37], 0, v[172:173]
	v_lshl_add_u64 v[128:129], v[128:129], 2, s[18:19]
	global_load_dword v128, v[128:129], off offset:640
	s_waitcnt vmcnt(0) lgkmcnt(0)
	v_fmamk_f32 v128, v128, 0x3a000000, v208
	v_mul_f32_e32 v129, 0x4f800000, v128
	v_cmp_gt_f32_e32 vcc, s54, v128
	s_nop 1
	v_cndmask_b32_e32 v128, v128, v129, vcc
	v_sqrt_f32_e32 v129, v128
	s_nop 0
	v_add_u32_e32 v130, -1, v129
	v_add_u32_e32 v131, 1, v129
	v_fma_f32 v134, -v130, v129, v128
	v_fma_f32 v135, -v131, v129, v128
	v_cmp_ge_f32_e64 s[12:13], 0, v134
	s_nop 1
	v_cndmask_b32_e64 v129, v129, v130, s[12:13]
	v_cmp_lt_f32_e64 s[12:13], 0, v135
	s_nop 1
	v_cndmask_b32_e64 v129, v129, v131, s[12:13]
	v_mul_f32_e32 v130, 0x37800000, v129
	v_cndmask_b32_e32 v129, v129, v130, vcc
	v_cmp_class_f32_e32 vcc, v128, v209
	s_nop 1
	v_cndmask_b32_e32 v128, v129, v128, vcc
	v_div_scale_f32 v129, s[4:5], v128, v128, 1.0
	v_rcp_f32_e32 v130, v129
	v_div_scale_f32 v131, vcc, 1.0, v128, 1.0
	v_fma_f32 v134, -v129, v130, 1.0
	v_fmac_f32_e32 v130, v134, v130
	v_mul_f32_e32 v134, v131, v130
	v_fma_f32 v135, -v129, v134, v131
	v_fmac_f32_e32 v134, v135, v130
	v_fma_f32 v129, -v129, v134, v131
	v_div_fmas_f32 v129, v129, v130, v134
	v_div_fixup_f32 v130, v129, v128, 1.0
	s_branch .LBB0_645

.LBB0_649:
	s_or_b64 exec, exec, s[4:5]
	s_and_b64 vcc, exec, s[10:11]
	s_cbranch_vccnz .LBB0_651
	s_ashr_i32 s37, s36, 31
	v_lshl_add_u64 v[128:129], s[36:37], 0, v[172:173]
	v_lshl_add_u64 v[128:129], v[128:129], 2, s[18:19]
	global_load_dword v128, v[128:129], off offset:704
	s_waitcnt vmcnt(0) lgkmcnt(0)
	v_fmamk_f32 v128, v128, 0x3a000000, v208
	v_mul_f32_e32 v129, 0x4f800000, v128
	v_cmp_gt_f32_e32 vcc, s54, v128
	s_nop 1
	v_cndmask_b32_e32 v128, v128, v129, vcc
	v_sqrt_f32_e32 v129, v128
	s_nop 0
	v_add_u32_e32 v131, -1, v129
	v_add_u32_e32 v134, 1, v129
	v_fma_f32 v135, -v131, v129, v128
	v_fma_f32 v137, -v134, v129, v128
	v_cmp_ge_f32_e64 s[10:11], 0, v135
	s_nop 1
	v_cndmask_b32_e64 v129, v129, v131, s[10:11]
	v_cmp_lt_f32_e64 s[10:11], 0, v137
	s_nop 1
	v_cndmask_b32_e64 v129, v129, v134, s[10:11]
	v_mul_f32_e32 v131, 0x37800000, v129
	v_cndmask_b32_e32 v129, v129, v131, vcc
	v_cmp_class_f32_e32 vcc, v128, v209
	s_nop 1
	v_cndmask_b32_e32 v128, v129, v128, vcc
	v_div_scale_f32 v129, s[4:5], v128, v128, 1.0
	v_rcp_f32_e32 v131, v129
	v_div_scale_f32 v134, vcc, 1.0, v128, 1.0
	v_fma_f32 v135, -v129, v131, 1.0
	v_fmac_f32_e32 v131, v135, v131
	v_mul_f32_e32 v135, v134, v131
	v_fma_f32 v137, -v129, v135, v134
	v_fmac_f32_e32 v135, v137, v131
	v_fma_f32 v129, -v129, v135, v134
	v_div_fmas_f32 v129, v129, v131, v135
	v_div_fixup_f32 v128, v129, v128, 1.0
	s_branch .LBB0_652

.LBB0_656:
	s_or_b64 exec, exec, s[4:5]
	s_lshl_b32 s38, s16, 1
	s_cmp_lt_i32 s16, 6
	s_cselect_b64 s[4:5], -1, 0
	s_sub_i32 s10, s38, 18
	s_cmp_lt_u32 s10, 8
	s_cselect_b64 s[10:11], -1, 0
	s_or_b64 s[4:5], s[4:5], s[10:11]
	s_cmp_gt_u32 s38, 27
	s_cselect_b64 s[10:11], -1, 0
	s_or_b64 s[46:47], s[4:5], s[10:11]
	s_cmp_lt_u32 s38, 26
	s_cselect_b32 s4, s55, 0x200
	s_cmp_gt_u32 s38, 23
	s_cselect_b32 s4, s4, 0x100
	s_cmp_gt_u32 s38, 11
	s_cselect_b32 s5, s4, 0x80
	s_cmp_gt_i32 s16, 2
	s_waitcnt lgkmcnt(0)
	s_barrier
	s_cselect_b32 s4, s5, 0
	s_lshl_b32 s20, s4, 2
	v_cndmask_b32_e64 v129, 0, 1, s[46:47]
	v_lshl_add_u64 v[140:141], v[176:177], 0, s[20:21]
	s_waitcnt lgkmcnt(0)
	v_mov_b32_e32 v132, 1.0
	v_cmp_ne_u32_e64 s[12:13], 1, v129
	s_andn2_b64 vcc, exec, s[46:47]
	v_mov_b32_e32 v144, 1.0
	v_mov_b32_e32 v145, 1.0
	v_mov_b32_e32 v146, 1.0
	v_mov_b32_e32 v147, 1.0
	s_cbranch_vccnz .LBB0_658
	global_load_dwordx4 v[144:147], v[140:141], off
.LBB0_658:
	s_or_b32 s4, s38, 1
	s_cmp_gt_i32 s4, 5
	s_cselect_b32 s5, s5, 0
	s_lshl_b32 s20, s5, 2
	s_cmp_lt_i32 s4, 12
	s_cselect_b64 s[16:17], -1, 0
	s_sub_i32 s5, s38, 17
	s_cmp_lt_u32 s5, 8
	s_cselect_b64 s[46:47], -1, 0
	s_or_b64 s[16:17], s[16:17], s[46:47]
	s_or_b64 s[16:17], s[16:17], s[10:11]
	v_cndmask_b32_e64 v129, 0, 1, s[16:17]
	v_lshl_add_u64 v[160:161], v[176:177], 0, s[20:21]
	v_cmp_ne_u32_e64 s[10:11], 1, v129
	s_andn2_b64 vcc, exec, s[16:17]
	v_mov_b32_e32 v133, 1.0
	v_mov_b32_e32 v134, 1.0
	v_mov_b32_e32 v135, 1.0
	s_cbranch_vccnz .LBB0_660
	global_load_dwordx4 v[132:135], v[160:161], off
.LBB0_660:
	v_mov_b32_e32 v138, 1.0
	s_and_b64 vcc, exec, s[12:13]
	v_mov_b32_e32 v148, 1.0
	v_mov_b32_e32 v149, 1.0
	v_mov_b32_e32 v150, 1.0
	v_mov_b32_e32 v151, 1.0
	s_cbranch_vccnz .LBB0_662
	global_load_dwordx4 v[148:151], v[140:141], off offset:16
.LBB0_662:
	s_and_b64 vcc, exec, s[10:11]
	v_mov_b32_e32 v139, 1.0
	v_mov_b32_e32 v140, 1.0
	v_mov_b32_e32 v141, 1.0
	s_cbranch_vccnz .LBB0_664
	global_load_dwordx4 v[138:141], v[160:161], off offset:16

.LBB0_666:
	s_ashr_i32 s39, s38, 31
	s_lshl_b64 s[16:17], s[38:39], 22
	v_lshlrev_b64 v[162:163], 8, v[186:187]
	s_add_u32 s38, s45, s16
	s_waitcnt vmcnt(0) lgkmcnt(0)
	v_pk_mul_f32 v[186:187], v[144:145], v[160:161]
	v_mov_b32_e32 v204, v161
	s_addc_u32 s39, s49, s17
	v_pk_mul_f32 v[160:161], v[148:149], v[160:161]
	v_pk_mul_f32 v[214:215], v[150:151], v[204:205] op_sel_hi:[1,0]
	v_pk_mul_f32 v[124:125], v[124:125], v[186:187]
	v_pk_mul_f32 v[186:187], v[122:123], v[214:215]
	v_pk_mul_f32 v[122:123], v[120:121], v[160:161]
	v_cvt_pk_bf16_f32 v120, v124, v125
	v_lshl_add_u64 v[124:125], s[38:39], 0, v[162:163]
	v_pk_mul_f32 v[212:213], v[146:147], v[204:205] op_sel_hi:[1,0]
	v_lshl_add_u64 v[124:125], v[174:175], 1, v[124:125]
	s_and_b64 vcc, exec, s[10:11]
	v_pk_mul_f32 v[126:127], v[126:127], v[212:213]
	s_nop 0
	v_cvt_pk_bf16_f32 v121, v126, v127
	v_cvt_pk_bf16_f32 v122, v122, v123
	v_cvt_pk_bf16_f32 v123, v186, v187
	global_store_dwordx4 v[124:125], v[120:123], off
	s_cbranch_vccnz .LBB0_668
	s_add_i32 s5, 0, 0x20000
	v_add_u32_e32 v120, s5, v189
	ds_read_b128 v[120:123], v120 offset:16
	s_waitcnt lgkmcnt(0)
	v_mov_b32_e32 v124, v121
	v_mov_b32_e32 v125, v122
	v_mov_b32_e32 v121, v123
	v_pk_add_f32 v[120:121], v[124:125], v[120:121]
	s_nop 0
	v_add_f32_e32 v120, v120, v121
	v_fmamk_f32 v120, v120, 0x3c000000, v208
	v_mul_f32_e32 v121, 0x4f800000, v120
	v_cmp_gt_f32_e32 vcc, s54, v120
	s_nop 1
	v_cndmask_b32_e32 v120, v120, v121, vcc
	v_sqrt_f32_e32 v121, v120
	s_nop 0
	v_add_u32_e32 v122, -1, v121
	v_add_u32_e32 v123, 1, v121
	v_fma_f32 v124, -v122, v121, v120
	v_fma_f32 v125, -v123, v121, v120
	v_cmp_ge_f32_e64 s[16:17], 0, v124
	s_nop 1
	v_cndmask_b32_e64 v121, v121, v122, s[16:17]
	v_cmp_lt_f32_e64 s[16:17], 0, v125
	s_nop 1
	v_cndmask_b32_e64 v121, v121, v123, s[16:17]
	v_mul_f32_e32 v122, 0x37800000, v121
	v_cndmask_b32_e32 v121, v121, v122, vcc
	v_cmp_class_f32_e32 vcc, v120, v209
	s_nop 1
	v_cndmask_b32_e32 v120, v121, v120, vcc
	v_div_scale_f32 v121, s[16:17], v120, v120, 1.0
	v_rcp_f32_e32 v122, v121
	s_nop 0
	v_fma_f32 v123, -v121, v122, 1.0
	v_fmac_f32_e32 v122, v123, v122
	v_div_scale_f32 v123, vcc, 1.0, v120, 1.0
	v_mul_f32_e32 v124, v123, v122
	v_fma_f32 v125, -v121, v124, v123
	v_fmac_f32_e32 v124, v125, v122
	v_fma_f32 v121, -v121, v124, v123
	v_div_fmas_f32 v121, v121, v122, v124
	v_div_fixup_f32 v120, v121, v120, 1.0
	v_mul_f32_e32 v158, v158, v120
.LBB0_668:
	s_ashr_i32 s5, s4, 31
	v_mov_b32_e32 v159, v158
	s_lshl_b64 s[4:5], s[4:5], 22
	s_add_u32 s46, s45, s4
	v_pk_mul_f32 v[120:121], v[132:133], v[158:159]
	v_mov_b32_e32 v122, v158
	s_addc_u32 s47, s49, s5
	v_pk_mul_f32 v[124:125], v[134:135], v[122:123] op_sel_hi:[1,0]
	v_pk_mul_f32 v[126:127], v[138:139], v[158:159]
	v_pk_mul_f32 v[122:123], v[140:141], v[122:123] op_sel_hi:[1,0]
	v_pk_mul_f32 v[116:117], v[116:117], v[120:121]
	v_pk_mul_f32 v[120:121], v[114:115], v[122:123]
	v_pk_mul_f32 v[114:115], v[112:113], v[126:127]
	v_cvt_pk_bf16_f32 v112, v116, v117
	v_lshl_add_u64 v[116:117], s[46:47], 0, v[162:163]
	v_pk_mul_f32 v[118:119], v[118:119], v[124:125]
	v_lshl_add_u64 v[116:117], v[174:175], 1, v[116:117]
	v_cvt_pk_bf16_f32 v113, v118, v119
	v_cvt_pk_bf16_f32 v114, v114, v115
	v_cvt_pk_bf16_f32 v115, v120, v121
	global_store_dwordx4 v[116:117], v[112:115], off
	s_and_b64 vcc, exec, s[12:13]
	v_mov_b32_e32 v116, v156
	v_mov_b64_e32 v[112:113], v[156:157]
	v_mov_b64_e32 v[114:115], v[158:159]
	s_cbranch_vccnz .LBB0_670
	v_add_u32_e32 v112, 0, v191
	v_add_u32_e32 v112, 0x20000, v112
	ds_read_b128 v[112:115], v112
	s_waitcnt lgkmcnt(0)
	v_mov_b32_e32 v116, v113
	v_mov_b32_e32 v117, v114
	v_mov_b32_e32 v113, v115
	v_pk_add_f32 v[112:113], v[116:117], v[112:113]
	s_nop 0
	v_add_f32_e32 v112, v112, v113
	v_fmamk_f32 v112, v112, 0x3c000000, v208
	v_mul_f32_e32 v113, 0x4f800000, v112
	v_cmp_gt_f32_e32 vcc, s54, v112
	s_nop 1
	v_cndmask_b32_e32 v112, v112, v113, vcc
	v_sqrt_f32_e32 v113, v112
	s_nop 0
	v_add_u32_e32 v114, -1, v113
	v_add_u32_e32 v115, 1, v113
	v_fma_f32 v116, -v114, v113, v112
	v_fma_f32 v117, -v115, v113, v112
	v_cmp_ge_f32_e64 s[16:17], 0, v116
	s_nop 1
	v_cndmask_b32_e64 v113, v113, v114, s[16:17]
	v_cmp_lt_f32_e64 s[16:17], 0, v117
	s_nop 1
	v_cndmask_b32_e64 v113, v113, v115, s[16:17]
	v_mul_f32_e32 v114, 0x37800000, v113
	v_cndmask_b32_e32 v113, v113, v114, vcc
	v_cmp_class_f32_e32 vcc, v112, v209
	s_nop 1
	v_cndmask_b32_e32 v112, v113, v112, vcc
	v_div_scale_f32 v113, s[4:5], v112, v112, 1.0
	v_rcp_f32_e32 v114, v113
	s_nop 0
	v_fma_f32 v115, -v113, v114, 1.0
	v_fmac_f32_e32 v114, v115, v114
	v_div_scale_f32 v115, vcc, 1.0, v112, 1.0
	v_mul_f32_e32 v116, v115, v114
	v_fma_f32 v117, -v113, v116, v115
	v_fmac_f32_e32 v116, v117, v114
	v_fma_f32 v113, -v113, v116, v115
	v_div_fmas_f32 v113, v113, v114, v116
	v_div_fixup_f32 v112, v113, v112, 1.0
	v_mul_f32_e32 v112, v156, v112
	v_mov_b32_e32 v116, v112
.LBB0_670:
	v_add_u32_e32 v114, s36, v190
	v_mov_b32_e32 v113, v116
	v_ashrrev_i32_e32 v115, 31, v114
	v_pk_mul_f32 v[120:121], v[144:145], v[112:113]
	v_lshlrev_b64 v[114:115], 8, v[114:115]
	v_pk_mul_f32 v[118:119], v[146:147], v[116:117] op_sel_hi:[1,0]
	v_pk_mul_f32 v[116:117], v[150:151], v[116:117] op_sel_hi:[1,0]
	v_pk_mul_f32 v[112:113], v[148:149], v[112:113]
	v_pk_mul_f32 v[108:109], v[108:109], v[120:121]
	v_pk_mul_f32 v[116:117], v[106:107], v[116:117]
	v_pk_mul_f32 v[106:107], v[104:105], v[112:113]
	v_cvt_pk_bf16_f32 v104, v108, v109
	v_lshl_add_u64 v[108:109], s[38:39], 0, v[114:115]
	v_lshl_add_u64 v[108:109], v[174:175], 1, v[108:109]
	s_and_b64 vcc, exec, s[10:11]
	v_pk_mul_f32 v[110:111], v[110:111], v[118:119]
	s_nop 0
	v_cvt_pk_bf16_f32 v105, v110, v111
	v_cvt_pk_bf16_f32 v106, v106, v107
	v_cvt_pk_bf16_f32 v107, v116, v117
	global_store_dwordx4 v[108:109], v[104:107], off
	s_cbranch_vccnz .LBB0_672
	s_add_i32 s4, 0, 0x20000
	v_add_u32_e32 v104, s4, v191
	ds_read_b128 v[104:107], v104 offset:16
	s_waitcnt lgkmcnt(0)
	v_mov_b32_e32 v108, v105
	v_mov_b32_e32 v109, v106
	v_mov_b32_e32 v105, v107
	v_pk_add_f32 v[104:105], v[108:109], v[104:105]
	s_nop 0
	v_add_f32_e32 v104, v104, v105
	v_fmamk_f32 v104, v104, 0x3c000000, v208
	v_mul_f32_e32 v105, 0x4f800000, v104
	v_cmp_gt_f32_e32 vcc, s54, v104
	s_nop 1
	v_cndmask_b32_e32 v104, v104, v105, vcc
	v_sqrt_f32_e32 v105, v104
	s_nop 0
	v_add_u32_e32 v106, -1, v105
	v_add_u32_e32 v107, 1, v105
	v_fma_f32 v108, -v106, v105, v104
	v_fma_f32 v109, -v107, v105, v104
	v_cmp_ge_f32_e64 s[16:17], 0, v108
	s_nop 1
	v_cndmask_b32_e64 v105, v105, v106, s[16:17]
	v_cmp_lt_f32_e64 s[16:17], 0, v109
	s_nop 1
	v_cndmask_b32_e64 v105, v105, v107, s[16:17]
	v_mul_f32_e32 v106, 0x37800000, v105
	v_cndmask_b32_e32 v105, v105, v106, vcc
	v_cmp_class_f32_e32 vcc, v104, v209
	s_nop 1
	v_cndmask_b32_e32 v104, v105, v104, vcc
	v_div_scale_f32 v105, s[4:5], v104, v104, 1.0
	v_rcp_f32_e32 v106, v105
	s_nop 0
	v_fma_f32 v107, -v105, v106, 1.0
	v_fmac_f32_e32 v106, v107, v106
	v_div_scale_f32 v107, vcc, 1.0, v104, 1.0
	v_mul_f32_e32 v108, v107, v106
	v_fma_f32 v109, -v105, v108, v107
	v_fmac_f32_e32 v108, v109, v106
	v_fma_f32 v105, -v105, v108, v107
	v_div_fmas_f32 v105, v105, v106, v108
	v_div_fixup_f32 v104, v105, v104, 1.0
	v_mul_f32_e32 v156, v156, v104
.LBB0_672:
	s_nop 0
	v_pk_mul_f32 v[104:105], v[134:135], v[156:157] op_sel_hi:[1,0]
	v_mov_b32_e32 v157, v156
	v_pk_mul_f32 v[106:107], v[132:133], v[156:157]
	v_pk_mul_f32 v[108:109], v[140:141], v[156:157] op_sel_hi:[1,0]
	v_pk_mul_f32 v[110:111], v[138:139], v[156:157]
	v_pk_mul_f32 v[100:101], v[100:101], v[106:107]
	v_pk_mul_f32 v[102:103], v[102:103], v[104:105]
	v_pk_mul_f32 v[104:105], v[98:99], v[108:109]
	v_pk_mul_f32 v[98:99], v[96:97], v[110:111]
	v_cvt_pk_bf16_f32 v96, v100, v101
	v_lshl_add_u64 v[100:101], s[46:47], 0, v[114:115]
	v_cvt_pk_bf16_f32 v97, v102, v103
	v_cvt_pk_bf16_f32 v98, v98, v99
	v_cvt_pk_bf16_f32 v99, v104, v105
	v_lshl_add_u64 v[100:101], v[174:175], 1, v[100:101]
	global_store_dwordx4 v[100:101], v[96:99], off
	s_and_b64 vcc, exec, s[12:13]
	v_mov_b32_e32 v100, v154
	v_mov_b64_e32 v[96:97], v[154:155]
	v_mov_b64_e32 v[98:99], v[156:157]
	s_cbranch_vccnz .LBB0_674
	v_add_u32_e32 v96, 0, v193
	v_add_u32_e32 v96, 0x20000, v96
	ds_read_b128 v[96:99], v96
	s_waitcnt lgkmcnt(0)
	v_mov_b32_e32 v100, v97
	v_mov_b32_e32 v101, v98
	v_mov_b32_e32 v97, v99
	v_pk_add_f32 v[96:97], v[100:101], v[96:97]
	s_nop 0
	v_add_f32_e32 v96, v96, v97
	v_fmamk_f32 v96, v96, 0x3c000000, v208
	v_mul_f32_e32 v97, 0x4f800000, v96
	v_cmp_gt_f32_e32 vcc, s54, v96
	s_nop 1
	v_cndmask_b32_e32 v96, v96, v97, vcc
	v_sqrt_f32_e32 v97, v96
	s_nop 0
	v_add_u32_e32 v98, -1, v97
	v_add_u32_e32 v99, 1, v97
	v_fma_f32 v100, -v98, v97, v96
	v_fma_f32 v101, -v99, v97, v96
	v_cmp_ge_f32_e64 s[16:17], 0, v100
	s_nop 1
	v_cndmask_b32_e64 v97, v97, v98, s[16:17]
	v_cmp_lt_f32_e64 s[16:17], 0, v101
	s_nop 1
	v_cndmask_b32_e64 v97, v97, v99, s[16:17]
	v_mul_f32_e32 v98, 0x37800000, v97
	v_cndmask_b32_e32 v97, v97, v98, vcc
	v_cmp_class_f32_e32 vcc, v96, v209
	s_nop 1
	v_cndmask_b32_e32 v96, v97, v96, vcc
	v_div_scale_f32 v97, s[4:5], v96, v96, 1.0
	v_rcp_f32_e32 v98, v97
	s_nop 0
	v_fma_f32 v99, -v97, v98, 1.0
	v_fmac_f32_e32 v98, v99, v98
	v_div_scale_f32 v99, vcc, 1.0, v96, 1.0
	v_mul_f32_e32 v100, v99, v98
	v_fma_f32 v101, -v97, v100, v99
	v_fmac_f32_e32 v100, v101, v98
	v_fma_f32 v97, -v97, v100, v99
	v_div_fmas_f32 v97, v97, v98, v100
	v_div_fixup_f32 v96, v97, v96, 1.0
	v_mul_f32_e32 v96, v154, v96
	v_mov_b32_e32 v100, v96
.LBB0_674:
	v_add_u32_e32 v98, s36, v192
	v_mov_b32_e32 v97, v100
	v_ashrrev_i32_e32 v99, 31, v98
	v_pk_mul_f32 v[104:105], v[144:145], v[96:97]
	v_lshlrev_b64 v[98:99], 8, v[98:99]
	v_pk_mul_f32 v[102:103], v[146:147], v[100:101] op_sel_hi:[1,0]
	v_pk_mul_f32 v[100:101], v[150:151], v[100:101] op_sel_hi:[1,0]
	v_pk_mul_f32 v[96:97], v[148:149], v[96:97]
	v_pk_mul_f32 v[92:93], v[92:93], v[104:105]
	v_pk_mul_f32 v[100:101], v[90:91], v[100:101]
	v_pk_mul_f32 v[90:91], v[88:89], v[96:97]
	v_cvt_pk_bf16_f32 v88, v92, v93
	v_lshl_add_u64 v[92:93], s[38:39], 0, v[98:99]
	v_lshl_add_u64 v[92:93], v[174:175], 1, v[92:93]
	s_and_b64 vcc, exec, s[10:11]
	v_pk_mul_f32 v[94:95], v[94:95], v[102:103]
	s_nop 0
	v_cvt_pk_bf16_f32 v89, v94, v95
	v_cvt_pk_bf16_f32 v90, v90, v91
	v_cvt_pk_bf16_f32 v91, v100, v101
	global_store_dwordx4 v[92:93], v[88:91], off
	s_cbranch_vccnz .LBB0_676
	s_add_i32 s4, 0, 0x20000
	v_add_u32_e32 v88, s4, v193
	ds_read_b128 v[88:91], v88 offset:16
	s_waitcnt lgkmcnt(0)
	v_mov_b32_e32 v92, v89
	v_mov_b32_e32 v93, v90
	v_mov_b32_e32 v89, v91
	v_pk_add_f32 v[88:89], v[92:93], v[88:89]
	s_nop 0
	v_add_f32_e32 v88, v88, v89
	v_fmamk_f32 v88, v88, 0x3c000000, v208
	v_mul_f32_e32 v89, 0x4f800000, v88
	v_cmp_gt_f32_e32 vcc, s54, v88
	s_nop 1
	v_cndmask_b32_e32 v88, v88, v89, vcc
	v_sqrt_f32_e32 v89, v88
	s_nop 0
	v_add_u32_e32 v90, -1, v89
	v_add_u32_e32 v91, 1, v89
	v_fma_f32 v92, -v90, v89, v88
	v_fma_f32 v93, -v91, v89, v88
	v_cmp_ge_f32_e64 s[16:17], 0, v92
	s_nop 1
	v_cndmask_b32_e64 v89, v89, v90, s[16:17]
	v_cmp_lt_f32_e64 s[16:17], 0, v93
	s_nop 1
	v_cndmask_b32_e64 v89, v89, v91, s[16:17]
	v_mul_f32_e32 v90, 0x37800000, v89
	v_cndmask_b32_e32 v89, v89, v90, vcc
	v_cmp_class_f32_e32 vcc, v88, v209
	s_nop 1
	v_cndmask_b32_e32 v88, v89, v88, vcc
	v_div_scale_f32 v89, s[4:5], v88, v88, 1.0
	v_rcp_f32_e32 v90, v89
	s_nop 0
	v_fma_f32 v91, -v89, v90, 1.0
	v_fmac_f32_e32 v90, v91, v90
	v_div_scale_f32 v91, vcc, 1.0, v88, 1.0
	v_mul_f32_e32 v92, v91, v90
	v_fma_f32 v93, -v89, v92, v91
	v_fmac_f32_e32 v92, v93, v90
	v_fma_f32 v89, -v89, v92, v91
	v_div_fmas_f32 v89, v89, v90, v92
	v_div_fixup_f32 v88, v89, v88, 1.0
	v_mul_f32_e32 v154, v154, v88
.LBB0_676:
	s_nop 0
	v_pk_mul_f32 v[88:89], v[134:135], v[154:155] op_sel_hi:[1,0]
	v_mov_b32_e32 v155, v154
	v_pk_mul_f32 v[90:91], v[132:133], v[154:155]
	v_pk_mul_f32 v[92:93], v[140:141], v[154:155] op_sel_hi:[1,0]
	v_pk_mul_f32 v[94:95], v[138:139], v[154:155]
	v_pk_mul_f32 v[84:85], v[84:85], v[90:91]
	v_pk_mul_f32 v[86:87], v[86:87], v[88:89]
	v_pk_mul_f32 v[88:89], v[82:83], v[92:93]
	v_pk_mul_f32 v[82:83], v[80:81], v[94:95]
	v_cvt_pk_bf16_f32 v80, v84, v85
	v_lshl_add_u64 v[84:85], s[46:47], 0, v[98:99]
	v_cvt_pk_bf16_f32 v81, v86, v87
	v_cvt_pk_bf16_f32 v82, v82, v83
	v_cvt_pk_bf16_f32 v83, v88, v89
	v_lshl_add_u64 v[84:85], v[174:175], 1, v[84:85]
	global_store_dwordx4 v[84:85], v[80:83], off
	s_and_b64 vcc, exec, s[12:13]
	v_mov_b32_e32 v84, v152
	v_mov_b64_e32 v[80:81], v[152:153]
	v_mov_b64_e32 v[82:83], v[154:155]
	s_cbranch_vccnz .LBB0_678
	v_add_u32_e32 v80, 0, v195
	v_add_u32_e32 v80, 0x20000, v80
	ds_read_b128 v[80:83], v80
	s_waitcnt lgkmcnt(0)
	v_mov_b32_e32 v84, v81
	v_mov_b32_e32 v85, v82
	v_mov_b32_e32 v81, v83
	v_pk_add_f32 v[80:81], v[84:85], v[80:81]
	s_nop 0
	v_add_f32_e32 v80, v80, v81
	v_fmamk_f32 v80, v80, 0x3c000000, v208
	v_mul_f32_e32 v81, 0x4f800000, v80
	v_cmp_gt_f32_e32 vcc, s54, v80
	s_nop 1
	v_cndmask_b32_e32 v80, v80, v81, vcc
	v_sqrt_f32_e32 v81, v80
	s_nop 0
	v_add_u32_e32 v82, -1, v81
	v_add_u32_e32 v83, 1, v81
	v_fma_f32 v84, -v82, v81, v80
	v_fma_f32 v85, -v83, v81, v80
	v_cmp_ge_f32_e64 s[16:17], 0, v84
	s_nop 1
	v_cndmask_b32_e64 v81, v81, v82, s[16:17]
	v_cmp_lt_f32_e64 s[16:17], 0, v85
	s_nop 1
	v_cndmask_b32_e64 v81, v81, v83, s[16:17]
	v_mul_f32_e32 v82, 0x37800000, v81
	v_cndmask_b32_e32 v81, v81, v82, vcc
	v_cmp_class_f32_e32 vcc, v80, v209
	s_nop 1
	v_cndmask_b32_e32 v80, v81, v80, vcc
	v_div_scale_f32 v81, s[4:5], v80, v80, 1.0
	v_rcp_f32_e32 v82, v81
	s_nop 0
	v_fma_f32 v83, -v81, v82, 1.0
	v_fmac_f32_e32 v82, v83, v82
	v_div_scale_f32 v83, vcc, 1.0, v80, 1.0
	v_mul_f32_e32 v84, v83, v82
	v_fma_f32 v85, -v81, v84, v83
	v_fmac_f32_e32 v84, v85, v82
	v_fma_f32 v81, -v81, v84, v83
	v_div_fmas_f32 v81, v81, v82, v84
	v_div_fixup_f32 v80, v81, v80, 1.0
	v_mul_f32_e32 v80, v152, v80
	v_mov_b32_e32 v84, v80
.LBB0_678:
	v_add_u32_e32 v82, s36, v194
	v_mov_b32_e32 v81, v84
	v_ashrrev_i32_e32 v83, 31, v82
	v_pk_mul_f32 v[88:89], v[144:145], v[80:81]
	v_lshlrev_b64 v[82:83], 8, v[82:83]
	v_pk_mul_f32 v[86:87], v[146:147], v[84:85] op_sel_hi:[1,0]
	v_pk_mul_f32 v[84:85], v[150:151], v[84:85] op_sel_hi:[1,0]
	v_pk_mul_f32 v[80:81], v[148:149], v[80:81]
	v_pk_mul_f32 v[76:77], v[76:77], v[88:89]
	v_pk_mul_f32 v[84:85], v[74:75], v[84:85]
	v_pk_mul_f32 v[74:75], v[72:73], v[80:81]
	v_cvt_pk_bf16_f32 v72, v76, v77
	v_lshl_add_u64 v[76:77], s[38:39], 0, v[82:83]
	v_lshl_add_u64 v[76:77], v[174:175], 1, v[76:77]
	s_and_b64 vcc, exec, s[10:11]
	v_pk_mul_f32 v[78:79], v[78:79], v[86:87]
	s_nop 0
	v_cvt_pk_bf16_f32 v73, v78, v79
	v_cvt_pk_bf16_f32 v74, v74, v75
	v_cvt_pk_bf16_f32 v75, v84, v85
	global_store_dwordx4 v[76:77], v[72:75], off
	s_cbranch_vccnz .LBB0_680
	s_add_i32 s4, 0, 0x20000
	v_add_u32_e32 v72, s4, v195
	ds_read_b128 v[72:75], v72 offset:16
	s_waitcnt lgkmcnt(0)
	v_mov_b32_e32 v76, v73
	v_mov_b32_e32 v77, v74
	v_mov_b32_e32 v73, v75
	v_pk_add_f32 v[72:73], v[76:77], v[72:73]
	s_nop 0
	v_add_f32_e32 v72, v72, v73
	v_fmamk_f32 v72, v72, 0x3c000000, v208
	v_mul_f32_e32 v73, 0x4f800000, v72
	v_cmp_gt_f32_e32 vcc, s54, v72
	s_nop 1
	v_cndmask_b32_e32 v72, v72, v73, vcc
	v_sqrt_f32_e32 v73, v72
	s_nop 0
	v_add_u32_e32 v74, -1, v73
	v_add_u32_e32 v75, 1, v73
	v_fma_f32 v76, -v74, v73, v72
	v_fma_f32 v77, -v75, v73, v72
	v_cmp_ge_f32_e64 s[16:17], 0, v76
	s_nop 1
	v_cndmask_b32_e64 v73, v73, v74, s[16:17]
	v_cmp_lt_f32_e64 s[16:17], 0, v77
	s_nop 1
	v_cndmask_b32_e64 v73, v73, v75, s[16:17]
	v_mul_f32_e32 v74, 0x37800000, v73
	v_cndmask_b32_e32 v73, v73, v74, vcc
	v_cmp_class_f32_e32 vcc, v72, v209
	s_nop 1
	v_cndmask_b32_e32 v72, v73, v72, vcc
	v_div_scale_f32 v73, s[4:5], v72, v72, 1.0
	v_rcp_f32_e32 v74, v73
	s_nop 0
	v_fma_f32 v75, -v73, v74, 1.0
	v_fmac_f32_e32 v74, v75, v74
	v_div_scale_f32 v75, vcc, 1.0, v72, 1.0
	v_mul_f32_e32 v76, v75, v74
	v_fma_f32 v77, -v73, v76, v75
	v_fmac_f32_e32 v76, v77, v74
	v_fma_f32 v73, -v73, v76, v75
	v_div_fmas_f32 v73, v73, v74, v76
	v_div_fixup_f32 v72, v73, v72, 1.0
	v_mul_f32_e32 v152, v152, v72
.LBB0_680:
	s_nop 0
	v_pk_mul_f32 v[72:73], v[134:135], v[152:153] op_sel_hi:[1,0]
	v_mov_b32_e32 v153, v152
	v_pk_mul_f32 v[74:75], v[132:133], v[152:153]
	v_pk_mul_f32 v[76:77], v[140:141], v[152:153] op_sel_hi:[1,0]
	v_pk_mul_f32 v[78:79], v[138:139], v[152:153]
	v_pk_mul_f32 v[68:69], v[68:69], v[74:75]
	v_pk_mul_f32 v[70:71], v[70:71], v[72:73]
	v_pk_mul_f32 v[72:73], v[66:67], v[76:77]
	v_pk_mul_f32 v[66:67], v[64:65], v[78:79]
	v_cvt_pk_bf16_f32 v64, v68, v69
	v_lshl_add_u64 v[68:69], s[46:47], 0, v[82:83]
	v_cvt_pk_bf16_f32 v65, v70, v71
	v_cvt_pk_bf16_f32 v66, v66, v67
	v_cvt_pk_bf16_f32 v67, v72, v73
	v_lshl_add_u64 v[68:69], v[174:175], 1, v[68:69]
	global_store_dwordx4 v[68:69], v[64:67], off
	s_and_b64 vcc, exec, s[12:13]
	v_mov_b32_e32 v68, v142
	v_mov_b64_e32 v[64:65], v[142:143]
	v_mov_b64_e32 v[66:67], v[144:145]
	s_cbranch_vccnz .LBB0_682
	v_add_u32_e32 v64, 0, v197
	v_add_u32_e32 v64, 0x20000, v64
	ds_read_b128 v[64:67], v64
	s_waitcnt lgkmcnt(0)
	v_mov_b32_e32 v68, v65
	v_mov_b32_e32 v69, v66
	v_mov_b32_e32 v65, v67
	v_pk_add_f32 v[64:65], v[68:69], v[64:65]
	s_nop 0
	v_add_f32_e32 v64, v64, v65
	v_fmamk_f32 v64, v64, 0x3c000000, v208
	v_mul_f32_e32 v65, 0x4f800000, v64
	v_cmp_gt_f32_e32 vcc, s54, v64
	s_nop 1
	v_cndmask_b32_e32 v64, v64, v65, vcc
	v_sqrt_f32_e32 v65, v64
	s_nop 0
	v_add_u32_e32 v66, -1, v65
	v_add_u32_e32 v67, 1, v65
	v_fma_f32 v68, -v66, v65, v64
	v_fma_f32 v69, -v67, v65, v64
	v_cmp_ge_f32_e64 s[16:17], 0, v68
	s_nop 1
	v_cndmask_b32_e64 v65, v65, v66, s[16:17]
	v_cmp_lt_f32_e64 s[16:17], 0, v69
	s_nop 1
	v_cndmask_b32_e64 v65, v65, v67, s[16:17]
	v_mul_f32_e32 v66, 0x37800000, v65
	v_cndmask_b32_e32 v65, v65, v66, vcc
	v_cmp_class_f32_e32 vcc, v64, v209
	s_nop 1
	v_cndmask_b32_e32 v64, v65, v64, vcc
	v_div_scale_f32 v65, s[4:5], v64, v64, 1.0
	v_rcp_f32_e32 v66, v65
	s_nop 0
	v_fma_f32 v67, -v65, v66, 1.0
	v_fmac_f32_e32 v66, v67, v66
	v_div_scale_f32 v67, vcc, 1.0, v64, 1.0
	v_mul_f32_e32 v68, v67, v66
	v_fma_f32 v69, -v65, v68, v67
	v_fmac_f32_e32 v68, v69, v66
	v_fma_f32 v65, -v65, v68, v67
	v_div_fmas_f32 v65, v65, v66, v68
	v_div_fixup_f32 v64, v65, v64, 1.0
	v_mul_f32_e32 v64, v142, v64
	v_mov_b32_e32 v68, v64
.LBB0_682:
	v_add_u32_e32 v66, s36, v196
	v_mov_b32_e32 v65, v68
	v_ashrrev_i32_e32 v67, 31, v66
	v_pk_mul_f32 v[72:73], v[144:145], v[64:65]
	v_lshlrev_b64 v[66:67], 8, v[66:67]
	v_pk_mul_f32 v[70:71], v[146:147], v[68:69] op_sel_hi:[1,0]
	v_pk_mul_f32 v[68:69], v[150:151], v[68:69] op_sel_hi:[1,0]
	v_pk_mul_f32 v[64:65], v[148:149], v[64:65]
	v_pk_mul_f32 v[60:61], v[60:61], v[72:73]
	v_pk_mul_f32 v[68:69], v[58:59], v[68:69]
	v_pk_mul_f32 v[58:59], v[56:57], v[64:65]
	v_cvt_pk_bf16_f32 v56, v60, v61
	v_lshl_add_u64 v[60:61], s[38:39], 0, v[66:67]
	v_lshl_add_u64 v[60:61], v[174:175], 1, v[60:61]
	s_and_b64 vcc, exec, s[10:11]
	v_pk_mul_f32 v[62:63], v[62:63], v[70:71]
	s_nop 0
	v_cvt_pk_bf16_f32 v57, v62, v63
	v_cvt_pk_bf16_f32 v58, v58, v59
	v_cvt_pk_bf16_f32 v59, v68, v69
	global_store_dwordx4 v[60:61], v[56:59], off
	s_cbranch_vccnz .LBB0_684
	s_add_i32 s4, 0, 0x20000
	v_add_u32_e32 v56, s4, v197
	ds_read_b128 v[56:59], v56 offset:16
	s_waitcnt lgkmcnt(0)
	v_mov_b32_e32 v60, v57
	v_mov_b32_e32 v61, v58
	v_mov_b32_e32 v57, v59
	v_pk_add_f32 v[56:57], v[60:61], v[56:57]
	s_nop 0
	v_add_f32_e32 v56, v56, v57
	v_fmamk_f32 v56, v56, 0x3c000000, v208
	v_mul_f32_e32 v57, 0x4f800000, v56
	v_cmp_gt_f32_e32 vcc, s54, v56
	s_nop 1
	v_cndmask_b32_e32 v56, v56, v57, vcc
	v_sqrt_f32_e32 v57, v56
	s_nop 0
	v_add_u32_e32 v58, -1, v57
	v_add_u32_e32 v59, 1, v57
	v_fma_f32 v60, -v58, v57, v56
	v_fma_f32 v61, -v59, v57, v56
	v_cmp_ge_f32_e64 s[16:17], 0, v60
	s_nop 1
	v_cndmask_b32_e64 v57, v57, v58, s[16:17]
	v_cmp_lt_f32_e64 s[16:17], 0, v61
	s_nop 1
	v_cndmask_b32_e64 v57, v57, v59, s[16:17]
	v_mul_f32_e32 v58, 0x37800000, v57
	v_cndmask_b32_e32 v57, v57, v58, vcc
	v_cmp_class_f32_e32 vcc, v56, v209
	s_nop 1
	v_cndmask_b32_e32 v56, v57, v56, vcc
	v_div_scale_f32 v57, s[4:5], v56, v56, 1.0
	v_rcp_f32_e32 v58, v57
	s_nop 0
	v_fma_f32 v59, -v57, v58, 1.0
	v_fmac_f32_e32 v58, v59, v58
	v_div_scale_f32 v59, vcc, 1.0, v56, 1.0
	v_mul_f32_e32 v60, v59, v58
	v_fma_f32 v61, -v57, v60, v59
	v_fmac_f32_e32 v60, v61, v58
	v_fma_f32 v57, -v57, v60, v59
	v_div_fmas_f32 v57, v57, v58, v60
	v_div_fixup_f32 v56, v57, v56, 1.0
	v_mul_f32_e32 v142, v142, v56
.LBB0_684:
	s_nop 0
	v_pk_mul_f32 v[56:57], v[134:135], v[142:143] op_sel_hi:[1,0]
	v_mov_b32_e32 v143, v142
	v_pk_mul_f32 v[58:59], v[132:133], v[142:143]
	v_pk_mul_f32 v[60:61], v[140:141], v[142:143] op_sel_hi:[1,0]
	v_pk_mul_f32 v[62:63], v[138:139], v[142:143]
	v_pk_mul_f32 v[52:53], v[52:53], v[58:59]
	v_pk_mul_f32 v[54:55], v[54:55], v[56:57]
	v_pk_mul_f32 v[56:57], v[50:51], v[60:61]
	v_pk_mul_f32 v[50:51], v[48:49], v[62:63]
	v_cvt_pk_bf16_f32 v48, v52, v53
	v_lshl_add_u64 v[52:53], s[46:47], 0, v[66:67]
	v_cvt_pk_bf16_f32 v49, v54, v55
	v_cvt_pk_bf16_f32 v50, v50, v51
	v_cvt_pk_bf16_f32 v51, v56, v57
	v_lshl_add_u64 v[52:53], v[174:175], 1, v[52:53]
	global_store_dwordx4 v[52:53], v[48:51], off
	s_and_b64 vcc, exec, s[12:13]
	v_mov_b32_e32 v52, v136
	v_mov_b64_e32 v[48:49], v[136:137]
	v_mov_b64_e32 v[50:51], v[138:139]
	s_cbranch_vccnz .LBB0_686
	v_add_u32_e32 v48, 0, v199
	v_add_u32_e32 v48, 0x20000, v48
	ds_read_b128 v[48:51], v48
	s_waitcnt lgkmcnt(0)
	v_mov_b32_e32 v52, v49
	v_mov_b32_e32 v53, v50
	v_mov_b32_e32 v49, v51
	v_pk_add_f32 v[48:49], v[52:53], v[48:49]
	s_nop 0
	v_add_f32_e32 v48, v48, v49
	v_fmamk_f32 v48, v48, 0x3c000000, v208
	v_mul_f32_e32 v49, 0x4f800000, v48
	v_cmp_gt_f32_e32 vcc, s54, v48
	s_nop 1
	v_cndmask_b32_e32 v48, v48, v49, vcc
	v_sqrt_f32_e32 v49, v48
	s_nop 0
	v_add_u32_e32 v50, -1, v49
	v_add_u32_e32 v51, 1, v49
	v_fma_f32 v52, -v50, v49, v48
	v_fma_f32 v53, -v51, v49, v48
	v_cmp_ge_f32_e64 s[16:17], 0, v52
	s_nop 1
	v_cndmask_b32_e64 v49, v49, v50, s[16:17]
	v_cmp_lt_f32_e64 s[16:17], 0, v53
	s_nop 1
	v_cndmask_b32_e64 v49, v49, v51, s[16:17]
	v_mul_f32_e32 v50, 0x37800000, v49
	v_cndmask_b32_e32 v49, v49, v50, vcc
	v_cmp_class_f32_e32 vcc, v48, v209
	s_nop 1
	v_cndmask_b32_e32 v48, v49, v48, vcc
	v_div_scale_f32 v49, s[4:5], v48, v48, 1.0
	v_rcp_f32_e32 v50, v49
	s_nop 0
	v_fma_f32 v51, -v49, v50, 1.0
	v_fmac_f32_e32 v50, v51, v50
	v_div_scale_f32 v51, vcc, 1.0, v48, 1.0
	v_mul_f32_e32 v52, v51, v50
	v_fma_f32 v53, -v49, v52, v51
	v_fmac_f32_e32 v52, v53, v50
	v_fma_f32 v49, -v49, v52, v51
	v_div_fmas_f32 v49, v49, v50, v52
	v_div_fixup_f32 v48, v49, v48, 1.0
	v_mul_f32_e32 v48, v136, v48
	v_mov_b32_e32 v52, v48
.LBB0_686:
	v_add_u32_e32 v50, s36, v198
	v_mov_b32_e32 v49, v52
	v_ashrrev_i32_e32 v51, 31, v50
	v_pk_mul_f32 v[56:57], v[144:145], v[48:49]
	v_lshlrev_b64 v[50:51], 8, v[50:51]
	v_pk_mul_f32 v[54:55], v[146:147], v[52:53] op_sel_hi:[1,0]
	v_pk_mul_f32 v[52:53], v[150:151], v[52:53] op_sel_hi:[1,0]
	v_pk_mul_f32 v[48:49], v[148:149], v[48:49]
	v_pk_mul_f32 v[44:45], v[44:45], v[56:57]
	v_pk_mul_f32 v[52:53], v[42:43], v[52:53]
	v_pk_mul_f32 v[42:43], v[40:41], v[48:49]
	v_cvt_pk_bf16_f32 v40, v44, v45
	v_lshl_add_u64 v[44:45], s[38:39], 0, v[50:51]
	v_lshl_add_u64 v[44:45], v[174:175], 1, v[44:45]
	s_and_b64 vcc, exec, s[10:11]
	v_pk_mul_f32 v[46:47], v[46:47], v[54:55]
	s_nop 0
	v_cvt_pk_bf16_f32 v41, v46, v47
	v_cvt_pk_bf16_f32 v42, v42, v43
	v_cvt_pk_bf16_f32 v43, v52, v53
	global_store_dwordx4 v[44:45], v[40:43], off
	s_cbranch_vccnz .LBB0_688
	s_add_i32 s4, 0, 0x20000
	v_add_u32_e32 v40, s4, v199
	ds_read_b128 v[40:43], v40 offset:16
	s_waitcnt lgkmcnt(0)
	v_mov_b32_e32 v44, v41
	v_mov_b32_e32 v45, v42
	v_mov_b32_e32 v41, v43
	v_pk_add_f32 v[40:41], v[44:45], v[40:41]
	s_nop 0
	v_add_f32_e32 v40, v40, v41
	v_fmamk_f32 v40, v40, 0x3c000000, v208
	v_mul_f32_e32 v41, 0x4f800000, v40
	v_cmp_gt_f32_e32 vcc, s54, v40
	s_nop 1
	v_cndmask_b32_e32 v40, v40, v41, vcc
	v_sqrt_f32_e32 v41, v40
	s_nop 0
	v_add_u32_e32 v42, -1, v41
	v_add_u32_e32 v43, 1, v41
	v_fma_f32 v44, -v42, v41, v40
	v_fma_f32 v45, -v43, v41, v40
	v_cmp_ge_f32_e64 s[16:17], 0, v44
	s_nop 1
	v_cndmask_b32_e64 v41, v41, v42, s[16:17]
	v_cmp_lt_f32_e64 s[16:17], 0, v45
	s_nop 1
	v_cndmask_b32_e64 v41, v41, v43, s[16:17]
	v_mul_f32_e32 v42, 0x37800000, v41
	v_cndmask_b32_e32 v41, v41, v42, vcc
	v_cmp_class_f32_e32 vcc, v40, v209
	s_nop 1
	v_cndmask_b32_e32 v40, v41, v40, vcc
	v_div_scale_f32 v41, s[4:5], v40, v40, 1.0
	v_rcp_f32_e32 v42, v41
	s_nop 0
	v_fma_f32 v43, -v41, v42, 1.0
	v_fmac_f32_e32 v42, v43, v42
	v_div_scale_f32 v43, vcc, 1.0, v40, 1.0
	v_mul_f32_e32 v44, v43, v42
	v_fma_f32 v45, -v41, v44, v43
	v_fmac_f32_e32 v44, v45, v42
	v_fma_f32 v41, -v41, v44, v43
	v_div_fmas_f32 v41, v41, v42, v44
	v_div_fixup_f32 v40, v41, v40, 1.0
	v_mul_f32_e32 v136, v136, v40
.LBB0_688:
	s_nop 0
	v_pk_mul_f32 v[40:41], v[134:135], v[136:137] op_sel_hi:[1,0]
	v_mov_b32_e32 v137, v136
	v_pk_mul_f32 v[42:43], v[132:133], v[136:137]
	v_pk_mul_f32 v[44:45], v[140:141], v[136:137] op_sel_hi:[1,0]
	v_pk_mul_f32 v[46:47], v[138:139], v[136:137]
	v_pk_mul_f32 v[36:37], v[36:37], v[42:43]
	v_pk_mul_f32 v[38:39], v[38:39], v[40:41]
	v_pk_mul_f32 v[40:41], v[34:35], v[44:45]
	v_pk_mul_f32 v[34:35], v[32:33], v[46:47]
	v_cvt_pk_bf16_f32 v32, v36, v37
	v_lshl_add_u64 v[36:37], s[46:47], 0, v[50:51]
	v_cvt_pk_bf16_f32 v33, v38, v39
	v_cvt_pk_bf16_f32 v34, v34, v35
	v_cvt_pk_bf16_f32 v35, v40, v41
	v_lshl_add_u64 v[36:37], v[174:175], 1, v[36:37]
	global_store_dwordx4 v[36:37], v[32:35], off
	s_and_b64 vcc, exec, s[12:13]
	v_mov_b32_e32 v36, v130
	v_mov_b64_e32 v[32:33], v[130:131]
	v_mov_b64_e32 v[34:35], v[132:133]
	s_cbranch_vccnz .LBB0_690
	v_add_u32_e32 v32, 0, v201
	v_add_u32_e32 v32, 0x20000, v32
	ds_read_b128 v[32:35], v32
	s_waitcnt lgkmcnt(0)
	v_mov_b32_e32 v36, v33
	v_mov_b32_e32 v37, v34
	v_mov_b32_e32 v33, v35
	v_pk_add_f32 v[32:33], v[36:37], v[32:33]
	s_nop 0
	v_add_f32_e32 v32, v32, v33
	v_fmamk_f32 v32, v32, 0x3c000000, v208
	v_mul_f32_e32 v33, 0x4f800000, v32
	v_cmp_gt_f32_e32 vcc, s54, v32
	s_nop 1
	v_cndmask_b32_e32 v32, v32, v33, vcc
	v_sqrt_f32_e32 v33, v32
	s_nop 0
	v_add_u32_e32 v34, -1, v33
	v_add_u32_e32 v35, 1, v33
	v_fma_f32 v36, -v34, v33, v32
	v_fma_f32 v37, -v35, v33, v32
	v_cmp_ge_f32_e64 s[16:17], 0, v36
	s_nop 1
	v_cndmask_b32_e64 v33, v33, v34, s[16:17]
	v_cmp_lt_f32_e64 s[16:17], 0, v37
	s_nop 1
	v_cndmask_b32_e64 v33, v33, v35, s[16:17]
	v_mul_f32_e32 v34, 0x37800000, v33
	v_cndmask_b32_e32 v33, v33, v34, vcc
	v_cmp_class_f32_e32 vcc, v32, v209
	s_nop 1
	v_cndmask_b32_e32 v32, v33, v32, vcc
	v_div_scale_f32 v33, s[4:5], v32, v32, 1.0
	v_rcp_f32_e32 v34, v33
	s_nop 0
	v_fma_f32 v35, -v33, v34, 1.0
	v_fmac_f32_e32 v34, v35, v34
	v_div_scale_f32 v35, vcc, 1.0, v32, 1.0
	v_mul_f32_e32 v36, v35, v34
	v_fma_f32 v37, -v33, v36, v35
	v_fmac_f32_e32 v36, v37, v34
	v_fma_f32 v33, -v33, v36, v35
	v_div_fmas_f32 v33, v33, v34, v36
	v_div_fixup_f32 v32, v33, v32, 1.0
	v_mul_f32_e32 v32, v130, v32
	v_mov_b32_e32 v36, v32
.LBB0_690:
	v_add_u32_e32 v34, s36, v200
	v_mov_b32_e32 v33, v36
	v_ashrrev_i32_e32 v35, 31, v34
	v_pk_mul_f32 v[40:41], v[144:145], v[32:33]
	v_lshlrev_b64 v[34:35], 8, v[34:35]
	v_pk_mul_f32 v[38:39], v[146:147], v[36:37] op_sel_hi:[1,0]
	v_pk_mul_f32 v[36:37], v[150:151], v[36:37] op_sel_hi:[1,0]
	v_pk_mul_f32 v[32:33], v[148:149], v[32:33]
	v_pk_mul_f32 v[28:29], v[28:29], v[40:41]
	v_pk_mul_f32 v[36:37], v[26:27], v[36:37]
	v_pk_mul_f32 v[26:27], v[24:25], v[32:33]
	v_cvt_pk_bf16_f32 v24, v28, v29
	v_lshl_add_u64 v[28:29], s[38:39], 0, v[34:35]
	v_lshl_add_u64 v[28:29], v[174:175], 1, v[28:29]
	s_and_b64 vcc, exec, s[10:11]
	v_pk_mul_f32 v[30:31], v[30:31], v[38:39]
	s_nop 0
	v_cvt_pk_bf16_f32 v25, v30, v31
	v_cvt_pk_bf16_f32 v26, v26, v27
	v_cvt_pk_bf16_f32 v27, v36, v37
	global_store_dwordx4 v[28:29], v[24:27], off
	s_cbranch_vccnz .LBB0_692
	s_add_i32 s4, 0, 0x20000
	v_add_u32_e32 v24, s4, v201
	ds_read_b128 v[24:27], v24 offset:16
	s_waitcnt lgkmcnt(0)
	v_mov_b32_e32 v28, v25
	v_mov_b32_e32 v29, v26
	v_mov_b32_e32 v25, v27
	v_pk_add_f32 v[24:25], v[28:29], v[24:25]
	s_nop 0
	v_add_f32_e32 v24, v24, v25
	v_fmamk_f32 v24, v24, 0x3c000000, v208
	v_mul_f32_e32 v25, 0x4f800000, v24
	v_cmp_gt_f32_e32 vcc, s54, v24
	s_nop 1
	v_cndmask_b32_e32 v24, v24, v25, vcc
	v_sqrt_f32_e32 v25, v24
	s_nop 0
	v_add_u32_e32 v26, -1, v25
	v_add_u32_e32 v27, 1, v25
	v_fma_f32 v28, -v26, v25, v24
	v_fma_f32 v29, -v27, v25, v24
	v_cmp_ge_f32_e64 s[16:17], 0, v28
	s_nop 1
	v_cndmask_b32_e64 v25, v25, v26, s[16:17]
	v_cmp_lt_f32_e64 s[16:17], 0, v29
	s_nop 1
	v_cndmask_b32_e64 v25, v25, v27, s[16:17]
	v_mul_f32_e32 v26, 0x37800000, v25
	v_cndmask_b32_e32 v25, v25, v26, vcc
	v_cmp_class_f32_e32 vcc, v24, v209
	s_nop 1
	v_cndmask_b32_e32 v24, v25, v24, vcc
	v_div_scale_f32 v25, s[4:5], v24, v24, 1.0
	v_rcp_f32_e32 v26, v25
	s_nop 0
	v_fma_f32 v27, -v25, v26, 1.0
	v_fmac_f32_e32 v26, v27, v26
	v_div_scale_f32 v27, vcc, 1.0, v24, 1.0
	v_mul_f32_e32 v28, v27, v26
	v_fma_f32 v29, -v25, v28, v27
	v_fmac_f32_e32 v28, v29, v26
	v_fma_f32 v25, -v25, v28, v27
	v_div_fmas_f32 v25, v25, v26, v28
	v_div_fixup_f32 v24, v25, v24, 1.0
	v_mul_f32_e32 v130, v130, v24
.LBB0_692:
	s_nop 0
	v_pk_mul_f32 v[24:25], v[134:135], v[130:131] op_sel_hi:[1,0]
	v_mov_b32_e32 v131, v130
	v_pk_mul_f32 v[26:27], v[132:133], v[130:131]
	v_pk_mul_f32 v[28:29], v[140:141], v[130:131] op_sel_hi:[1,0]
	v_pk_mul_f32 v[30:31], v[138:139], v[130:131]
	v_pk_mul_f32 v[20:21], v[20:21], v[26:27]
	v_pk_mul_f32 v[22:23], v[22:23], v[24:25]
	v_pk_mul_f32 v[24:25], v[18:19], v[28:29]
	v_pk_mul_f32 v[18:19], v[16:17], v[30:31]
	v_cvt_pk_bf16_f32 v16, v20, v21
	v_lshl_add_u64 v[20:21], s[46:47], 0, v[34:35]
	v_cvt_pk_bf16_f32 v17, v22, v23
	v_cvt_pk_bf16_f32 v18, v18, v19
	v_cvt_pk_bf16_f32 v19, v24, v25
	v_lshl_add_u64 v[20:21], v[174:175], 1, v[20:21]
	global_store_dwordx4 v[20:21], v[16:19], off
	s_and_b64 vcc, exec, s[12:13]
	v_mov_b32_e32 v20, v128
	v_mov_b64_e32 v[16:17], v[128:129]
	v_mov_b64_e32 v[18:19], v[130:131]
	s_cbranch_vccnz .LBB0_694
	v_add_u32_e32 v16, 0, v203
	v_add_u32_e32 v16, 0x20000, v16
	ds_read_b128 v[16:19], v16
	s_waitcnt lgkmcnt(0)
	v_mov_b32_e32 v20, v17
	v_mov_b32_e32 v21, v18
	v_mov_b32_e32 v17, v19
	v_pk_add_f32 v[16:17], v[20:21], v[16:17]
	s_nop 0
	v_add_f32_e32 v16, v16, v17
	v_fmamk_f32 v16, v16, 0x3c000000, v208
	v_mul_f32_e32 v17, 0x4f800000, v16
	v_cmp_gt_f32_e32 vcc, s54, v16
	s_nop 1
	v_cndmask_b32_e32 v16, v16, v17, vcc
	v_sqrt_f32_e32 v17, v16
	s_nop 0
	v_add_u32_e32 v18, -1, v17
	v_add_u32_e32 v19, 1, v17
	v_fma_f32 v20, -v18, v17, v16
	v_fma_f32 v21, -v19, v17, v16
	v_cmp_ge_f32_e64 s[12:13], 0, v20
	s_nop 1
	v_cndmask_b32_e64 v17, v17, v18, s[12:13]
	v_cmp_lt_f32_e64 s[12:13], 0, v21
	s_nop 1
	v_cndmask_b32_e64 v17, v17, v19, s[12:13]
	v_mul_f32_e32 v18, 0x37800000, v17
	v_cndmask_b32_e32 v17, v17, v18, vcc
	v_cmp_class_f32_e32 vcc, v16, v209
	s_nop 1
	v_cndmask_b32_e32 v16, v17, v16, vcc
	v_div_scale_f32 v17, s[4:5], v16, v16, 1.0
	v_rcp_f32_e32 v18, v17
	s_nop 0
	v_fma_f32 v19, -v17, v18, 1.0
	v_fmac_f32_e32 v18, v19, v18
	v_div_scale_f32 v19, vcc, 1.0, v16, 1.0
	v_mul_f32_e32 v20, v19, v18
	v_fma_f32 v21, -v17, v20, v19
	v_fmac_f32_e32 v20, v21, v18
	v_fma_f32 v17, -v17, v20, v19
	v_div_fmas_f32 v17, v17, v18, v20
	v_div_fixup_f32 v16, v17, v16, 1.0
	v_mul_f32_e32 v16, v128, v16
	v_mov_b32_e32 v20, v16
.LBB0_694:
	v_add_u32_e32 v18, s36, v202
	v_mov_b32_e32 v17, v20
	v_ashrrev_i32_e32 v19, 31, v18
	v_pk_mul_f32 v[24:25], v[144:145], v[16:17]
	v_lshlrev_b64 v[18:19], 8, v[18:19]
	v_pk_mul_f32 v[22:23], v[146:147], v[20:21] op_sel_hi:[1,0]
	v_pk_mul_f32 v[20:21], v[150:151], v[20:21] op_sel_hi:[1,0]
	v_pk_mul_f32 v[16:17], v[148:149], v[16:17]
	v_pk_mul_f32 v[12:13], v[12:13], v[24:25]
	v_pk_mul_f32 v[20:21], v[10:11], v[20:21]
	v_pk_mul_f32 v[10:11], v[8:9], v[16:17]
	v_cvt_pk_bf16_f32 v8, v12, v13
	v_lshl_add_u64 v[12:13], s[38:39], 0, v[18:19]
	v_lshl_add_u64 v[12:13], v[174:175], 1, v[12:13]
	s_and_b64 vcc, exec, s[10:11]
	v_pk_mul_f32 v[14:15], v[14:15], v[22:23]
	s_nop 0
	v_cvt_pk_bf16_f32 v9, v14, v15
	v_cvt_pk_bf16_f32 v10, v10, v11
	v_cvt_pk_bf16_f32 v11, v20, v21
	global_store_dwordx4 v[12:13], v[8:11], off
	s_cbranch_vccnz .LBB0_696
	s_add_i32 s4, 0, 0x20000
	v_add_u32_e32 v8, s4, v203
	ds_read_b128 v[8:11], v8 offset:16
	s_waitcnt lgkmcnt(0)
	v_mov_b32_e32 v12, v9
	v_mov_b32_e32 v13, v10
	v_mov_b32_e32 v9, v11
	v_pk_add_f32 v[8:9], v[12:13], v[8:9]
	s_nop 0
	v_add_f32_e32 v8, v8, v9
	v_fmamk_f32 v8, v8, 0x3c000000, v208
	v_mul_f32_e32 v9, 0x4f800000, v8
	v_cmp_gt_f32_e32 vcc, s54, v8
	s_nop 1
	v_cndmask_b32_e32 v8, v8, v9, vcc
	v_sqrt_f32_e32 v9, v8
	s_nop 0
	v_add_u32_e32 v10, -1, v9
	v_add_u32_e32 v11, 1, v9
	v_fma_f32 v12, -v10, v9, v8
	v_fma_f32 v13, -v11, v9, v8
	v_cmp_ge_f32_e64 s[10:11], 0, v12
	s_nop 1
	v_cndmask_b32_e64 v9, v9, v10, s[10:11]
	v_cmp_lt_f32_e64 s[10:11], 0, v13
	s_nop 1
	v_cndmask_b32_e64 v9, v9, v11, s[10:11]
	v_mul_f32_e32 v10, 0x37800000, v9
	v_cndmask_b32_e32 v9, v9, v10, vcc
	v_cmp_class_f32_e32 vcc, v8, v209
	s_nop 1
	v_cndmask_b32_e32 v8, v9, v8, vcc
	v_div_scale_f32 v9, s[4:5], v8, v8, 1.0
	v_rcp_f32_e32 v10, v9
	s_nop 0
	v_fma_f32 v11, -v9, v10, 1.0
	v_fmac_f32_e32 v10, v11, v10
	v_div_scale_f32 v11, vcc, 1.0, v8, 1.0
	v_mul_f32_e32 v12, v11, v10
	v_fma_f32 v13, -v9, v12, v11
	v_fmac_f32_e32 v12, v13, v10
	v_fma_f32 v9, -v9, v12, v11
	v_div_fmas_f32 v9, v9, v10, v12
	v_div_fixup_f32 v8, v9, v8, 1.0
	v_mul_f32_e32 v128, v128, v8
.LBB0_696:
	s_nop 0
	v_pk_mul_f32 v[8:9], v[134:135], v[128:129] op_sel_hi:[1,0]
	v_mov_b32_e32 v129, v128
	v_pk_mul_f32 v[10:11], v[132:133], v[128:129]
	v_pk_mul_f32 v[12:13], v[140:141], v[128:129] op_sel_hi:[1,0]
	v_pk_mul_f32 v[14:15], v[138:139], v[128:129]
	v_pk_mul_f32 v[4:5], v[4:5], v[10:11]
	v_pk_mul_f32 v[6:7], v[6:7], v[8:9]
	v_pk_mul_f32 v[8:9], v[2:3], v[12:13]
	v_pk_mul_f32 v[2:3], v[0:1], v[14:15]
	v_cvt_pk_bf16_f32 v0, v4, v5
	v_lshl_add_u64 v[4:5], s[46:47], 0, v[18:19]
	v_lshl_add_u64 v[4:5], v[174:175], 1, v[4:5]
	s_andn2_b64 vcc, exec, s[8:9]
	s_mov_b64 s[4:5], -1
	v_cvt_pk_bf16_f32 v1, v6, v7
	v_cvt_pk_bf16_f32 v2, v2, v3
	v_cvt_pk_bf16_f32 v3, v8, v9
	global_store_dwordx4 v[4:5], v[0:3], off
	s_cbranch_vccnz .LBB0_589
	v_readlane_b32 s4, v255, 6
	v_readlane_b32 s5, v255, 7
	s_and_b64 vcc, exec, s[4:5]
	s_cbranch_vccnz .LBB0_588
	s_barrier
	s_branch .LBB0_588

.LBB0_706:
	global_load_dword v47, v[0:1], off sc1
	global_load_dword v32, v[2:3], off sc1
	global_load_dword v33, v[4:5], off sc1
	global_load_dword v34, v[6:7], off sc1
	global_load_dword v35, v[8:9], off sc1
	global_load_dword v36, v[10:11], off sc1
	global_load_dword v37, v[12:13], off sc1
	global_load_dword v38, v[14:15], off sc1
	global_load_dword v39, v[16:17], off sc1
	global_load_dword v40, v[18:19], off sc1
	global_load_dword v41, v[20:21], off sc1
	global_load_dword v42, v[22:23], off sc1
	global_load_dword v43, v[24:25], off sc1
	global_load_dword v44, v[26:27], off sc1
	global_load_dword v45, v[28:29], off sc1
	global_load_dword v46, v[30:31], off sc1
	s_or_b64 s[16:17], s[16:17], exec
	s_or_b64 s[12:13], s[12:13], exec
	s_waitcnt vmcnt(0) lgkmcnt(0)
	v_add_u32_e32 v48, v32, v47
	v_add_u32_e32 v48, v48, v33
	v_add_u32_e32 v48, v48, v34
	v_add_u32_e32 v48, v48, v35
	v_add_u32_e32 v48, v48, v36
	v_add_u32_e32 v48, v48, v37
	v_add_u32_e32 v48, v48, v38
	v_add_u32_e32 v48, v48, v39
	v_add_u32_e32 v48, v48, v40
	v_add_u32_e32 v48, v48, v41
	v_add_u32_e32 v48, v48, v42
	v_add_u32_e32 v48, v48, v43
	v_add_u32_e32 v48, v48, v44
	v_add_u32_e32 v48, v48, v45
	v_add_u32_e32 v48, v48, v46
	v_cmp_ne_u32_e32 vcc, s14, v48
	s_and_saveexec_b64 s[18:19], vcc
	s_cbranch_execz .LBB0_705
	s_and_b32 s22, s15, 0xff
	s_mov_b64 s[20:21], -1
	s_cmp_eq_u32 s22, 0
	s_mov_b64 s[24:25], -1
	s_mov_b64 s[22:23], -1
	s_sleep 1
	s_cbranch_scc1 .LBB0_709
	s_and_saveexec_b64 s[26:27], s[24:25]
	s_cbranch_execz .LBB0_704
	s_branch .LBB0_712
.LBB0_709:
	v_mov_b64_e32 v[48:49], s[6:7]
	global_load_dword v48, v[48:49], off sc1
	s_mov_b64 s[24:25], 0
	s_waitcnt vmcnt(0) lgkmcnt(0)
	v_cmp_eq_u32_e32 vcc, 0, v48
	s_and_saveexec_b64 s[26:27], vcc
	s_cmp_lt_u32 s15, 0x40001
	s_cselect_b64 s[24:25], -1, 0
	s_xor_b64 s[22:23], exec, -1
	s_and_b64 s[24:25], s[24:25], exec
	s_or_b64 exec, exec, s[26:27]
	s_and_saveexec_b64 s[26:27], s[24:25]
	s_cbranch_execz .LBB0_704

.LBB0_713:
	s_or_b64 exec, exec, s[8:9]
	s_xor_b64 s[8:9], s[10:11], -1
	s_and_saveexec_b64 s[10:11], s[8:9]
	s_xor_b64 s[8:9], exec, s[10:11]
	s_cbranch_execz .LBB0_715
	v_mov_b32_e32 v2, 1
	v_mov_b64_e32 v[0:1], s[6:7]
	global_atomic_add v[0:1], v2, off

.LBB0_716:
	s_lshl_b32 s3, s3, 8
	s_add_u32 s3, s4, s3
	s_addc_u32 s6, s5, 0
	v_mov_b32_e32 v1, s3
	v_add_co_u32_e32 v4, vcc, 0x101000, v1
	v_mov_b32_e32 v1, s6
	s_nop 0
	v_addc_co_u32_e32 v5, vcc, 0, v1, vcc
	v_mov_b32_e32 v1, 1
	global_atomic_add v1, v[4:5], v1, off offset:1024 sc0
	v_cvt_f32_u32_e32 v3, v2
	v_sub_u32_e32 v4, 0, v2
	s_add_u32 s14, s3, 0x100000
	s_addc_u32 s3, s6, 0
	v_rcp_iflag_f32_e32 v3, v3
	s_nop 0
	v_mul_f32_e32 v3, 0x4f7ffffe, v3
	v_cvt_u32_f32_e32 v3, v3
	v_mul_lo_u32 v4, v4, v3
	v_mul_hi_u32 v4, v3, v4
	v_add_u32_e32 v3, v3, v4
	s_waitcnt vmcnt(0) lgkmcnt(0)
	v_mul_hi_u32 v3, v1, v3
	v_mul_lo_u32 v5, v3, v2
	v_add_u32_e32 v4, 1, v1
	v_sub_u32_e32 v1, v1, v5
	v_add_u32_e32 v6, 1, v3
	v_cmp_ge_u32_e32 vcc, v1, v2
	v_sub_u32_e32 v5, v1, v2
	s_nop 0
	v_cndmask_b32_e32 v3, v3, v6, vcc
	v_cndmask_b32_e32 v1, v1, v5, vcc
	v_add_u32_e32 v5, 1, v3
	v_cmp_ge_u32_e32 vcc, v1, v2
	s_nop 1
	v_cndmask_b32_e32 v1, v3, v5, vcc
	v_mad_u64_u32 v[2:3], s[6:7], v2, v1, v[2:3]
	v_cmp_ne_u32_e32 vcc, v4, v2
	s_and_saveexec_b64 s[6:7], vcc
	s_xor_b64 s[6:7], exec, s[6:7]
	s_cbranch_execz .LBB0_729
	v_mov_b32_e32 v0, s14
	v_add_co_u32_e32 v2, vcc, 0x2000, v0
	v_mov_b32_e32 v0, s3
	s_nop 0
	v_addc_co_u32_e32 v3, vcc, 0, v0, vcc
	global_load_dword v0, v[2:3], off offset:1024 sc1
	s_add_u32 s12, s14, 0x2400
	s_addc_u32 s13, s3, 0
	s_waitcnt vmcnt(0) lgkmcnt(0)
	v_cmp_eq_u32_e32 vcc, v0, v1
	s_and_saveexec_b64 s[8:9], vcc
	s_cbranch_execz .LBB0_728
	s_add_u32 s10, s4, 0x100200
	s_addc_u32 s11, s5, 0
	s_mov_b32 s15, 1
	s_mov_b64 s[16:17], 0
	s_branch .LBB0_720

.LBB0_720:
	s_and_b32 s24, s15, 0xff
	s_mov_b64 s[22:23], -1
	s_cmp_lg_u32 s24, 0
	s_mov_b64 s[24:25], -1
	s_sleep 1
	s_cbranch_scc1 .LBB0_724
	v_mov_b64_e32 v[2:3], s[10:11]
	global_load_dword v0, v[2:3], off sc1
	s_mov_b64 s[24:25], 0
	s_mov_b64 s[26:27], -1
	s_waitcnt vmcnt(0) lgkmcnt(0)
	v_cmp_eq_u32_e32 vcc, 0, v0
	s_and_saveexec_b64 s[28:29], vcc
	s_cmp_lt_u32 s15, 0x40001
	s_cselect_b64 s[24:25], -1, 0
	s_xor_b64 s[26:27], exec, -1
	s_and_b64 s[24:25], s[24:25], exec
	s_or_b64 exec, exec, s[28:29]
.LBB0_724:
	s_andn2_b64 s[20:21], s[20:21], exec
	s_and_b64 s[26:27], s[26:27], exec
	s_or_b64 s[20:21], s[20:21], s[26:27]
	s_and_saveexec_b64 s[26:27], s[24:25]
	s_cbranch_execz .LBB0_719
	v_mov_b64_e32 v[2:3], s[12:13]
	global_load_dword v0, v[2:3], off sc1
	s_add_i32 s15, s15, 1
	s_or_b64 s[20:21], s[20:21], exec
	s_waitcnt vmcnt(0) lgkmcnt(0)
	v_cmp_ne_u32_e32 vcc, v0, v1
	s_orn2_b64 s[22:23], vcc, exec
	s_branch .LBB0_719
.LBB0_726:
	s_or_b64 exec, exec, s[16:17]
	s_xor_b64 s[12:13], s[18:19], -1
	s_and_saveexec_b64 s[16:17], s[12:13]
	s_xor_b64 s[16:17], exec, s[16:17]
	s_cbranch_execz .LBB0_728
	v_mov_b32_e32 v2, 1
	v_mov_b64_e32 v[0:1], s[10:11]
	global_atomic_add v[0:1], v2, off

.LBB0_729:
	s_andn2_saveexec_b64 s[6:7], s[6:7]
	s_cbranch_execz .LBB0_745
	v_mov_b32_e32 v1, s4
	v_add_co_u32_e32 v2, vcc, 0x103000, v1
	v_mov_b32_e32 v1, s5
	buffer_wbl2 sc1
	s_waitcnt vmcnt(0)
	v_addc_co_u32_e32 v3, vcc, 0, v1, vcc
	v_mov_b32_e32 v1, 1
	global_atomic_add v1, v[2:3], v1, off offset:1024 sc0
	v_cvt_f32_u32_e32 v2, v0
	v_sub_u32_e32 v3, 0, v0
	s_add_u32 s6, s4, 0x103500
	s_addc_u32 s7, s5, 0
	v_rcp_iflag_f32_e32 v2, v2
	s_mov_b64 s[10:11], -1
	v_mul_f32_e32 v2, 0x4f7ffffe, v2
	v_cvt_u32_f32_e32 v2, v2
	v_mul_lo_u32 v3, v3, v2
	v_mul_hi_u32 v3, v2, v3
	v_add_u32_e32 v2, v2, v3
	s_waitcnt vmcnt(0) lgkmcnt(0)
	v_mul_hi_u32 v2, v1, v2
	v_mul_lo_u32 v4, v2, v0
	v_add_u32_e32 v3, 1, v1
	v_sub_u32_e32 v1, v1, v4
	v_add_u32_e32 v5, 1, v2
	v_cmp_ge_u32_e32 vcc, v1, v0
	v_sub_u32_e32 v4, v1, v0
	s_nop 0
	v_cndmask_b32_e32 v2, v2, v5, vcc
	v_cndmask_b32_e32 v1, v1, v4, vcc
	v_add_u32_e32 v4, 1, v2
	v_cmp_ge_u32_e32 vcc, v1, v0
	s_nop 1
	v_cndmask_b32_e32 v2, v2, v4, vcc
	v_mad_u64_u32 v[0:1], s[8:9], v0, v2, v[0:1]
	v_cmp_ne_u32_e32 vcc, v3, v0
	v_mov_b64_e32 v[0:1], s[6:7]
	s_and_saveexec_b64 s[8:9], vcc
	s_cbranch_execz .LBB0_742
	v_mov_b64_e32 v[0:1], s[6:7]
	global_load_dword v0, v[0:1], off sc1
	s_mov_b64 s[16:17], 0
	s_waitcnt vmcnt(0) lgkmcnt(0)
	v_cmp_eq_u32_e32 vcc, v0, v2
	s_and_saveexec_b64 s[12:13], vcc
	s_cbranch_execz .LBB0_741
	s_add_u32 s10, s4, 0x100200
	s_addc_u32 s11, s5, 0
	s_mov_b32 s15, 1
	s_mov_b64 s[4:5], 0
	s_branch .LBB0_734

.LBB0_736:
	v_mov_b64_e32 v[0:1], s[10:11]
	global_load_dword v0, v[0:1], off sc1
	s_mov_b64 s[20:21], 0
	s_mov_b64 s[18:19], -1
	s_waitcnt vmcnt(0) lgkmcnt(0)
	v_cmp_eq_u32_e32 vcc, 0, v0
	s_and_saveexec_b64 s[22:23], vcc
	s_cmp_lt_u32 s15, 0x40001
	s_cselect_b64 s[20:21], -1, 0
	s_xor_b64 s[18:19], exec, -1
	s_and_b64 s[20:21], s[20:21], exec
	s_or_b64 exec, exec, s[22:23]
	s_mov_b64 s[22:23], -1
	s_and_saveexec_b64 s[24:25], s[20:21]
	s_cbranch_execz .LBB0_733
.LBB0_739:
	v_mov_b64_e32 v[0:1], s[6:7]
	global_load_dword v0, v[0:1], off sc1
	s_add_i32 s15, s15, 1
	s_or_b64 s[18:19], s[18:19], exec
	s_waitcnt vmcnt(0) lgkmcnt(0)
	v_cmp_ne_u32_e32 vcc, v0, v2
	s_orn2_b64 s[22:23], vcc, exec
	s_branch .LBB0_733

.LBB0_744:
	s_or_b64 exec, exec, s[4:5]
	v_mov_b32_e32 v0, s14
	v_add_co_u32_e32 v0, vcc, 0x2000, v0
	v_mov_b32_e32 v1, s3
	s_nop 0
	v_addc_co_u32_e32 v1, vcc, 0, v1, vcc
	v_mov_b32_e32 v2, 1
	s_waitcnt vmcnt(0) lgkmcnt(0)
	buffer_inv sc1
	global_atomic_add v[0:1], v2, off offset:1024
	s_waitcnt vmcnt(0)

.LBB0_803:
	s_sext_i32_i8 s4, s18
	s_lshl_b32 s20, s4, 8
	s_sext_i32_i8 s4, s16
	s_lshl_b32 s4, s4, 1
	s_ashr_i32 s5, s4, 31
	v_add_u32_e32 v148, s20, v154
	s_lshl_b64 s[8:9], s[4:5], 18
	v_ashrrev_i32_e32 v149, 31, v148
	s_add_u32 s16, s82, s8
	s_waitcnt vmcnt(0)
	v_pk_mul_f32 v[170:171], v[128:129], v[150:151] op_sel_hi:[1,0]
	v_lshlrev_b64 v[148:149], 8, v[148:149]
	s_addc_u32 s17, s26, s9
	v_pk_mul_f32 v[174:175], v[132:133], v[150:151] op_sel_hi:[1,0]
	v_pk_mul_f32 v[176:177], v[134:135], v[150:151] op_sel_hi:[1,0]
	v_pk_mul_f32 v[140:141], v[140:141], v[170:171]
	v_pk_mul_f32 v[170:171], v[138:139], v[176:177]
	v_pk_mul_f32 v[138:139], v[136:137], v[174:175]
	v_cvt_pk_bf16_f32 v136, v140, v141
	v_lshl_add_u64 v[140:141], s[16:17], 0, v[148:149]
	v_pk_mul_f32 v[172:173], v[130:131], v[150:151] op_sel_hi:[1,0]
	v_lshl_add_u64 v[140:141], v[146:147], 1, v[140:141]
	s_and_b64 vcc, exec, s[6:7]
	v_pk_mul_f32 v[142:143], v[142:143], v[172:173]
	s_nop 0
	v_cvt_pk_bf16_f32 v137, v142, v143
	v_cvt_pk_bf16_f32 v138, v138, v139
	v_cvt_pk_bf16_f32 v139, v170, v171
	global_store_dwordx4 v[140:141], v[136:139], off
	s_cbranch_vccnz .LBB0_805
	s_add_i32 s5, 0, 0x20000
	v_add_u32_e32 v136, s5, v169
	ds_read_b128 v[136:139], v136 offset:16
	s_waitcnt lgkmcnt(0)
	v_mov_b32_e32 v140, v137
	v_mov_b32_e32 v141, v138
	v_mov_b32_e32 v137, v139
	v_pk_add_f32 v[136:137], v[140:141], v[136:137]
	s_nop 0
	v_add_f32_e32 v136, v136, v137
	v_fmamk_f32 v136, v136, 0x3c000000, v151
	v_mul_f32_e32 v137, 0x4f800000, v136
	v_cmp_gt_f32_e32 vcc, s37, v136
	s_nop 1
	v_cndmask_b32_e32 v136, v136, v137, vcc
	v_sqrt_f32_e32 v137, v136
	s_nop 0
	v_add_u32_e32 v138, -1, v137
	v_add_u32_e32 v139, 1, v137
	v_fma_f32 v140, -v138, v137, v136
	v_fma_f32 v141, -v139, v137, v136
	v_cmp_ge_f32_e64 s[8:9], 0, v140
	s_nop 1
	v_cndmask_b32_e64 v137, v137, v138, s[8:9]
	v_cmp_lt_f32_e64 s[8:9], 0, v141
	s_nop 1
	v_cndmask_b32_e64 v137, v137, v139, s[8:9]
	v_mul_f32_e32 v138, 0x37800000, v137
	v_cndmask_b32_e32 v137, v137, v138, vcc
	v_cmp_class_f32_e32 vcc, v136, v152
	s_nop 1
	v_cndmask_b32_e32 v136, v137, v136, vcc
	v_div_scale_f32 v137, s[8:9], v136, v136, 1.0
	v_rcp_f32_e32 v138, v137
	s_nop 0
	v_fma_f32 v139, -v137, v138, 1.0
	v_fmac_f32_e32 v138, v139, v138
	v_div_scale_f32 v139, vcc, 1.0, v136, 1.0
	v_mul_f32_e32 v140, v139, v138
	v_fma_f32 v141, -v137, v140, v139
	v_fmac_f32_e32 v140, v141, v138
	v_fma_f32 v137, -v137, v140, v139
	v_div_fmas_f32 v137, v137, v138, v140
	v_div_fixup_f32 v144, v137, v136, 1.0
.LBB0_805:
	s_or_b32 s4, s4, 1
	s_ashr_i32 s5, s4, 31
	s_lshl_b64 s[4:5], s[4:5], 18
	s_add_u32 s18, s82, s4
	v_pk_mul_f32 v[136:137], v[112:113], v[144:145] op_sel_hi:[1,0]
	s_addc_u32 s19, s26, s5
	v_pk_mul_f32 v[140:141], v[120:121], v[144:145] op_sel_hi:[1,0]
	v_pk_mul_f32 v[142:143], v[122:123], v[144:145] op_sel_hi:[1,0]
	v_pk_mul_f32 v[124:125], v[124:125], v[136:137]
	v_pk_mul_f32 v[138:139], v[114:115], v[144:145] op_sel_hi:[1,0]
	v_pk_mul_f32 v[136:137], v[118:119], v[142:143]
	v_pk_mul_f32 v[118:119], v[116:117], v[140:141]
	v_cvt_pk_bf16_f32 v116, v124, v125
	v_lshl_add_u64 v[124:125], s[18:19], 0, v[148:149]
	v_pk_mul_f32 v[126:127], v[126:127], v[138:139]
	v_lshl_add_u64 v[124:125], v[146:147], 1, v[124:125]
	v_cvt_pk_bf16_f32 v117, v126, v127
	v_cvt_pk_bf16_f32 v118, v118, v119
	v_cvt_pk_bf16_f32 v119, v136, v137
	global_store_dwordx4 v[124:125], v[116:119], off
	s_and_b64 vcc, exec, s[6:7]
	v_mov_b32_e32 v124, 1.0
	v_mov_b32_e32 v118, 1.0
	s_cbranch_vccnz .LBB0_807
	v_add_u32_e32 v116, 0, v167
	v_add_u32_e32 v116, 0x20000, v116
	ds_read_b128 v[124:127], v116
	s_waitcnt lgkmcnt(0)
	v_mov_b32_e32 v116, v125
	v_mov_b32_e32 v117, v126
	v_mov_b32_e32 v125, v127
	v_pk_add_f32 v[116:117], v[116:117], v[124:125]
	s_nop 0
	v_add_f32_e32 v116, v116, v117
	v_fmamk_f32 v116, v116, 0x3c000000, v151
	v_mul_f32_e32 v117, 0x4f800000, v116
	v_cmp_gt_f32_e32 vcc, s37, v116
	s_nop 1
	v_cndmask_b32_e32 v116, v116, v117, vcc
	v_sqrt_f32_e32 v117, v116
	s_nop 0
	v_add_u32_e32 v119, -1, v117
	v_add_u32_e32 v124, 1, v117
	v_fma_f32 v125, -v119, v117, v116
	v_fma_f32 v126, -v124, v117, v116
	v_cmp_ge_f32_e64 s[8:9], 0, v125
	s_nop 1
	v_cndmask_b32_e64 v117, v117, v119, s[8:9]
	v_cmp_lt_f32_e64 s[8:9], 0, v126
	s_nop 1
	v_cndmask_b32_e64 v117, v117, v124, s[8:9]
	v_mul_f32_e32 v119, 0x37800000, v117
	v_cndmask_b32_e32 v117, v117, v119, vcc
	v_cmp_class_f32_e32 vcc, v116, v152
	s_nop 1
	v_cndmask_b32_e32 v116, v117, v116, vcc
	v_div_scale_f32 v117, s[4:5], v116, v116, 1.0
	v_rcp_f32_e32 v119, v117
	s_nop 0
	v_fma_f32 v124, -v117, v119, 1.0
	v_fmac_f32_e32 v119, v124, v119
	v_div_scale_f32 v124, vcc, 1.0, v116, 1.0
	v_mul_f32_e32 v125, v124, v119
	v_fma_f32 v126, -v117, v125, v124
	v_fmac_f32_e32 v125, v126, v119
	v_fma_f32 v117, -v117, v125, v124
	v_div_fmas_f32 v117, v117, v119, v125
	v_div_fixup_f32 v124, v117, v116, 1.0
.LBB0_807:
	v_add_u32_e32 v116, s20, v168
	v_ashrrev_i32_e32 v117, 31, v116
	v_pk_mul_f32 v[136:137], v[128:129], v[124:125] op_sel_hi:[1,0]
	v_lshlrev_b64 v[116:117], 8, v[116:117]
	v_pk_mul_f32 v[126:127], v[130:131], v[124:125] op_sel_hi:[1,0]
	v_pk_mul_f32 v[138:139], v[134:135], v[124:125] op_sel_hi:[1,0]
	v_pk_mul_f32 v[124:125], v[132:133], v[124:125] op_sel_hi:[1,0]
	v_pk_mul_f32 v[108:109], v[108:109], v[136:137]
	v_pk_mul_f32 v[110:111], v[110:111], v[126:127]
	v_pk_mul_f32 v[126:127], v[106:107], v[138:139]
	v_pk_mul_f32 v[106:107], v[104:105], v[124:125]
	v_cvt_pk_bf16_f32 v104, v108, v109
	v_lshl_add_u64 v[108:109], s[16:17], 0, v[116:117]
	v_lshl_add_u64 v[108:109], v[146:147], 1, v[108:109]
	s_and_b64 vcc, exec, s[6:7]
	v_cvt_pk_bf16_f32 v105, v110, v111
	v_cvt_pk_bf16_f32 v106, v106, v107
	v_cvt_pk_bf16_f32 v107, v126, v127
	global_store_dwordx4 v[108:109], v[104:107], off
	s_cbranch_vccnz .LBB0_809
	s_add_i32 s4, 0, 0x20000
	v_add_u32_e32 v104, s4, v167
	ds_read_b128 v[104:107], v104 offset:16
	s_waitcnt lgkmcnt(0)
	v_mov_b32_e32 v108, v105
	v_mov_b32_e32 v109, v106
	v_mov_b32_e32 v105, v107
	v_pk_add_f32 v[104:105], v[108:109], v[104:105]
	s_nop 0
	v_add_f32_e32 v104, v104, v105
	v_fmamk_f32 v104, v104, 0x3c000000, v151
	v_mul_f32_e32 v105, 0x4f800000, v104
	v_cmp_gt_f32_e32 vcc, s37, v104
	s_nop 1
	v_cndmask_b32_e32 v104, v104, v105, vcc
	v_sqrt_f32_e32 v105, v104
	s_nop 0
	v_add_u32_e32 v106, -1, v105
	v_add_u32_e32 v107, 1, v105
	v_fma_f32 v108, -v106, v105, v104
	v_fma_f32 v109, -v107, v105, v104
	v_cmp_ge_f32_e64 s[8:9], 0, v108
	s_nop 1
	v_cndmask_b32_e64 v105, v105, v106, s[8:9]
	v_cmp_lt_f32_e64 s[8:9], 0, v109
	s_nop 1
	v_cndmask_b32_e64 v105, v105, v107, s[8:9]
	v_mul_f32_e32 v106, 0x37800000, v105
	v_cndmask_b32_e32 v105, v105, v106, vcc
	v_cmp_class_f32_e32 vcc, v104, v152
	s_nop 1
	v_cndmask_b32_e32 v104, v105, v104, vcc
	v_div_scale_f32 v105, s[4:5], v104, v104, 1.0
	v_rcp_f32_e32 v106, v105
	s_nop 0
	v_fma_f32 v107, -v105, v106, 1.0
	v_fmac_f32_e32 v106, v107, v106
	v_div_scale_f32 v107, vcc, 1.0, v104, 1.0
	v_mul_f32_e32 v108, v107, v106
	v_fma_f32 v109, -v105, v108, v107
	v_fmac_f32_e32 v108, v109, v106
	v_fma_f32 v105, -v105, v108, v107
	v_div_fmas_f32 v105, v105, v106, v108
	v_div_fixup_f32 v118, v105, v104, 1.0
.LBB0_809:
	s_nop 0
	v_pk_mul_f32 v[106:107], v[112:113], v[118:119] op_sel_hi:[1,0]
	v_pk_mul_f32 v[104:105], v[114:115], v[118:119] op_sel_hi:[1,0]
	v_pk_mul_f32 v[108:109], v[122:123], v[118:119] op_sel_hi:[1,0]
	v_pk_mul_f32 v[110:111], v[120:121], v[118:119] op_sel_hi:[1,0]
	v_pk_mul_f32 v[100:101], v[100:101], v[106:107]
	v_pk_mul_f32 v[102:103], v[102:103], v[104:105]
	v_pk_mul_f32 v[104:105], v[98:99], v[108:109]
	v_pk_mul_f32 v[98:99], v[96:97], v[110:111]
	v_cvt_pk_bf16_f32 v96, v100, v101
	v_lshl_add_u64 v[100:101], s[18:19], 0, v[116:117]
	v_cvt_pk_bf16_f32 v97, v102, v103
	v_cvt_pk_bf16_f32 v98, v98, v99
	v_lshl_add_u64 v[100:101], v[146:147], 1, v[100:101]
	v_cvt_pk_bf16_f32 v99, v104, v105
	global_store_dwordx4 v[100:101], v[96:99], off
	s_and_b64 vcc, exec, s[6:7]
	v_mov_b32_e32 v100, 1.0
	v_mov_b32_e32 v98, 1.0
	s_cbranch_vccnz .LBB0_811
	v_add_u32_e32 v96, 0, v165
	v_add_u32_e32 v96, 0x20000, v96
	ds_read_b128 v[100:103], v96
	s_waitcnt lgkmcnt(0)
	v_mov_b32_e32 v96, v101
	v_mov_b32_e32 v97, v102
	v_mov_b32_e32 v101, v103
	v_pk_add_f32 v[96:97], v[96:97], v[100:101]
	s_nop 0
	v_add_f32_e32 v96, v96, v97
	v_fmamk_f32 v96, v96, 0x3c000000, v151
	v_mul_f32_e32 v97, 0x4f800000, v96
	v_cmp_gt_f32_e32 vcc, s37, v96
	s_nop 1
	v_cndmask_b32_e32 v96, v96, v97, vcc
	v_sqrt_f32_e32 v97, v96
	s_nop 0
	v_add_u32_e32 v99, -1, v97
	v_add_u32_e32 v100, 1, v97
	v_fma_f32 v101, -v99, v97, v96
	v_fma_f32 v102, -v100, v97, v96
	v_cmp_ge_f32_e64 s[8:9], 0, v101
	s_nop 1
	v_cndmask_b32_e64 v97, v97, v99, s[8:9]
	v_cmp_lt_f32_e64 s[8:9], 0, v102
	s_nop 1
	v_cndmask_b32_e64 v97, v97, v100, s[8:9]
	v_mul_f32_e32 v99, 0x37800000, v97
	v_cndmask_b32_e32 v97, v97, v99, vcc
	v_cmp_class_f32_e32 vcc, v96, v152
	s_nop 1
	v_cndmask_b32_e32 v96, v97, v96, vcc
	v_div_scale_f32 v97, s[4:5], v96, v96, 1.0
	v_rcp_f32_e32 v99, v97
	s_nop 0
	v_fma_f32 v100, -v97, v99, 1.0
	v_fmac_f32_e32 v99, v100, v99
	v_div_scale_f32 v100, vcc, 1.0, v96, 1.0
	v_mul_f32_e32 v101, v100, v99
	v_fma_f32 v102, -v97, v101, v100
	v_fmac_f32_e32 v101, v102, v99
	v_fma_f32 v97, -v97, v101, v100
	v_div_fmas_f32 v97, v97, v99, v101
	v_div_fixup_f32 v100, v97, v96, 1.0
.LBB0_811:
	v_add_u32_e32 v96, s20, v166
	v_ashrrev_i32_e32 v97, 31, v96
	v_pk_mul_f32 v[104:105], v[128:129], v[100:101] op_sel_hi:[1,0]
	v_lshlrev_b64 v[96:97], 8, v[96:97]
	v_pk_mul_f32 v[102:103], v[130:131], v[100:101] op_sel_hi:[1,0]
	v_pk_mul_f32 v[106:107], v[134:135], v[100:101] op_sel_hi:[1,0]
	v_pk_mul_f32 v[100:101], v[132:133], v[100:101] op_sel_hi:[1,0]
	v_pk_mul_f32 v[92:93], v[92:93], v[104:105]
	v_pk_mul_f32 v[94:95], v[94:95], v[102:103]
	v_pk_mul_f32 v[102:103], v[90:91], v[106:107]
	v_pk_mul_f32 v[90:91], v[88:89], v[100:101]
	v_cvt_pk_bf16_f32 v88, v92, v93
	v_lshl_add_u64 v[92:93], s[16:17], 0, v[96:97]
	v_lshl_add_u64 v[92:93], v[146:147], 1, v[92:93]
	s_and_b64 vcc, exec, s[6:7]
	v_cvt_pk_bf16_f32 v89, v94, v95
	v_cvt_pk_bf16_f32 v90, v90, v91
	v_cvt_pk_bf16_f32 v91, v102, v103
	global_store_dwordx4 v[92:93], v[88:91], off
	s_cbranch_vccnz .LBB0_813
	s_add_i32 s4, 0, 0x20000
	v_add_u32_e32 v88, s4, v165
	ds_read_b128 v[88:91], v88 offset:16
	s_waitcnt lgkmcnt(0)
	v_mov_b32_e32 v92, v89
	v_mov_b32_e32 v93, v90
	v_mov_b32_e32 v89, v91
	v_pk_add_f32 v[88:89], v[92:93], v[88:89]
	s_nop 0
	v_add_f32_e32 v88, v88, v89
	v_fmamk_f32 v88, v88, 0x3c000000, v151
	v_mul_f32_e32 v89, 0x4f800000, v88
	v_cmp_gt_f32_e32 vcc, s37, v88
	s_nop 1
	v_cndmask_b32_e32 v88, v88, v89, vcc
	v_sqrt_f32_e32 v89, v88
	s_nop 0
	v_add_u32_e32 v90, -1, v89
	v_add_u32_e32 v91, 1, v89
	v_fma_f32 v92, -v90, v89, v88
	v_fma_f32 v93, -v91, v89, v88
	v_cmp_ge_f32_e64 s[8:9], 0, v92
	s_nop 1
	v_cndmask_b32_e64 v89, v89, v90, s[8:9]
	v_cmp_lt_f32_e64 s[8:9], 0, v93
	s_nop 1
	v_cndmask_b32_e64 v89, v89, v91, s[8:9]
	v_mul_f32_e32 v90, 0x37800000, v89
	v_cndmask_b32_e32 v89, v89, v90, vcc
	v_cmp_class_f32_e32 vcc, v88, v152
	s_nop 1
	v_cndmask_b32_e32 v88, v89, v88, vcc
	v_div_scale_f32 v89, s[4:5], v88, v88, 1.0
	v_rcp_f32_e32 v90, v89
	s_nop 0
	v_fma_f32 v91, -v89, v90, 1.0
	v_fmac_f32_e32 v90, v91, v90
	v_div_scale_f32 v91, vcc, 1.0, v88, 1.0
	v_mul_f32_e32 v92, v91, v90
	v_fma_f32 v93, -v89, v92, v91
	v_fmac_f32_e32 v92, v93, v90
	v_fma_f32 v89, -v89, v92, v91
	v_div_fmas_f32 v89, v89, v90, v92
	v_div_fixup_f32 v98, v89, v88, 1.0
.LBB0_813:
	s_nop 0
	v_pk_mul_f32 v[90:91], v[112:113], v[98:99] op_sel_hi:[1,0]
	v_pk_mul_f32 v[88:89], v[114:115], v[98:99] op_sel_hi:[1,0]
	v_pk_mul_f32 v[92:93], v[122:123], v[98:99] op_sel_hi:[1,0]
	v_pk_mul_f32 v[94:95], v[120:121], v[98:99] op_sel_hi:[1,0]
	v_pk_mul_f32 v[84:85], v[84:85], v[90:91]
	v_pk_mul_f32 v[86:87], v[86:87], v[88:89]
	v_pk_mul_f32 v[88:89], v[82:83], v[92:93]
	v_pk_mul_f32 v[82:83], v[80:81], v[94:95]
	v_cvt_pk_bf16_f32 v80, v84, v85
	v_lshl_add_u64 v[84:85], s[18:19], 0, v[96:97]
	v_cvt_pk_bf16_f32 v81, v86, v87
	v_cvt_pk_bf16_f32 v82, v82, v83
	v_lshl_add_u64 v[84:85], v[146:147], 1, v[84:85]
	v_cvt_pk_bf16_f32 v83, v88, v89
	global_store_dwordx4 v[84:85], v[80:83], off
	s_and_b64 vcc, exec, s[6:7]
	v_mov_b32_e32 v84, 1.0
	v_mov_b32_e32 v82, 1.0
	s_cbranch_vccnz .LBB0_815
	v_add_u32_e32 v80, 0, v163
	v_add_u32_e32 v80, 0x20000, v80
	ds_read_b128 v[84:87], v80
	s_waitcnt lgkmcnt(0)
	v_mov_b32_e32 v80, v85
	v_mov_b32_e32 v81, v86
	v_mov_b32_e32 v85, v87
	v_pk_add_f32 v[80:81], v[80:81], v[84:85]
	s_nop 0
	v_add_f32_e32 v80, v80, v81
	v_fmamk_f32 v80, v80, 0x3c000000, v151
	v_mul_f32_e32 v81, 0x4f800000, v80
	v_cmp_gt_f32_e32 vcc, s37, v80
	s_nop 1
	v_cndmask_b32_e32 v80, v80, v81, vcc
	v_sqrt_f32_e32 v81, v80
	s_nop 0
	v_add_u32_e32 v83, -1, v81
	v_add_u32_e32 v84, 1, v81
	v_fma_f32 v85, -v83, v81, v80
	v_fma_f32 v86, -v84, v81, v80
	v_cmp_ge_f32_e64 s[8:9], 0, v85
	s_nop 1
	v_cndmask_b32_e64 v81, v81, v83, s[8:9]
	v_cmp_lt_f32_e64 s[8:9], 0, v86
	s_nop 1
	v_cndmask_b32_e64 v81, v81, v84, s[8:9]
	v_mul_f32_e32 v83, 0x37800000, v81
	v_cndmask_b32_e32 v81, v81, v83, vcc
	v_cmp_class_f32_e32 vcc, v80, v152
	s_nop 1
	v_cndmask_b32_e32 v80, v81, v80, vcc
	v_div_scale_f32 v81, s[4:5], v80, v80, 1.0
	v_rcp_f32_e32 v83, v81
	s_nop 0
	v_fma_f32 v84, -v81, v83, 1.0
	v_fmac_f32_e32 v83, v84, v83
	v_div_scale_f32 v84, vcc, 1.0, v80, 1.0
	v_mul_f32_e32 v85, v84, v83
	v_fma_f32 v86, -v81, v85, v84
	v_fmac_f32_e32 v85, v86, v83
	v_fma_f32 v81, -v81, v85, v84
	v_div_fmas_f32 v81, v81, v83, v85
	v_div_fixup_f32 v84, v81, v80, 1.0
.LBB0_815:
	v_add_u32_e32 v80, s20, v164
	v_ashrrev_i32_e32 v81, 31, v80
	v_pk_mul_f32 v[88:89], v[128:129], v[84:85] op_sel_hi:[1,0]
	v_lshlrev_b64 v[80:81], 8, v[80:81]
	v_pk_mul_f32 v[86:87], v[130:131], v[84:85] op_sel_hi:[1,0]
	v_pk_mul_f32 v[90:91], v[134:135], v[84:85] op_sel_hi:[1,0]
	v_pk_mul_f32 v[84:85], v[132:133], v[84:85] op_sel_hi:[1,0]
	v_pk_mul_f32 v[76:77], v[76:77], v[88:89]
	v_pk_mul_f32 v[78:79], v[78:79], v[86:87]
	v_pk_mul_f32 v[86:87], v[74:75], v[90:91]
	v_pk_mul_f32 v[74:75], v[72:73], v[84:85]
	v_cvt_pk_bf16_f32 v72, v76, v77
	v_lshl_add_u64 v[76:77], s[16:17], 0, v[80:81]
	v_lshl_add_u64 v[76:77], v[146:147], 1, v[76:77]
	s_and_b64 vcc, exec, s[6:7]
	v_cvt_pk_bf16_f32 v73, v78, v79
	v_cvt_pk_bf16_f32 v74, v74, v75
	v_cvt_pk_bf16_f32 v75, v86, v87
	global_store_dwordx4 v[76:77], v[72:75], off
	s_cbranch_vccnz .LBB0_817
	s_add_i32 s4, 0, 0x20000
	v_add_u32_e32 v72, s4, v163
	ds_read_b128 v[72:75], v72 offset:16
	s_waitcnt lgkmcnt(0)
	v_mov_b32_e32 v76, v73
	v_mov_b32_e32 v77, v74
	v_mov_b32_e32 v73, v75
	v_pk_add_f32 v[72:73], v[76:77], v[72:73]
	s_nop 0
	v_add_f32_e32 v72, v72, v73
	v_fmamk_f32 v72, v72, 0x3c000000, v151
	v_mul_f32_e32 v73, 0x4f800000, v72
	v_cmp_gt_f32_e32 vcc, s37, v72
	s_nop 1
	v_cndmask_b32_e32 v72, v72, v73, vcc
	v_sqrt_f32_e32 v73, v72
	s_nop 0
	v_add_u32_e32 v74, -1, v73
	v_add_u32_e32 v75, 1, v73
	v_fma_f32 v76, -v74, v73, v72
	v_fma_f32 v77, -v75, v73, v72
	v_cmp_ge_f32_e64 s[8:9], 0, v76
	s_nop 1
	v_cndmask_b32_e64 v73, v73, v74, s[8:9]
	v_cmp_lt_f32_e64 s[8:9], 0, v77
	s_nop 1
	v_cndmask_b32_e64 v73, v73, v75, s[8:9]
	v_mul_f32_e32 v74, 0x37800000, v73
	v_cndmask_b32_e32 v73, v73, v74, vcc
	v_cmp_class_f32_e32 vcc, v72, v152
	s_nop 1
	v_cndmask_b32_e32 v72, v73, v72, vcc
	v_div_scale_f32 v73, s[4:5], v72, v72, 1.0
	v_rcp_f32_e32 v74, v73
	s_nop 0
	v_fma_f32 v75, -v73, v74, 1.0
	v_fmac_f32_e32 v74, v75, v74
	v_div_scale_f32 v75, vcc, 1.0, v72, 1.0
	v_mul_f32_e32 v76, v75, v74
	v_fma_f32 v77, -v73, v76, v75
	v_fmac_f32_e32 v76, v77, v74
	v_fma_f32 v73, -v73, v76, v75
	v_div_fmas_f32 v73, v73, v74, v76
	v_div_fixup_f32 v82, v73, v72, 1.0
.LBB0_817:
	s_nop 0
	v_pk_mul_f32 v[74:75], v[112:113], v[82:83] op_sel_hi:[1,0]
	v_pk_mul_f32 v[72:73], v[114:115], v[82:83] op_sel_hi:[1,0]
	v_pk_mul_f32 v[76:77], v[122:123], v[82:83] op_sel_hi:[1,0]
	v_pk_mul_f32 v[78:79], v[120:121], v[82:83] op_sel_hi:[1,0]
	v_pk_mul_f32 v[68:69], v[68:69], v[74:75]
	v_pk_mul_f32 v[70:71], v[70:71], v[72:73]
	v_pk_mul_f32 v[72:73], v[66:67], v[76:77]
	v_pk_mul_f32 v[66:67], v[64:65], v[78:79]
	v_cvt_pk_bf16_f32 v64, v68, v69
	v_lshl_add_u64 v[68:69], s[18:19], 0, v[80:81]
	v_cvt_pk_bf16_f32 v65, v70, v71
	v_cvt_pk_bf16_f32 v66, v66, v67
	v_lshl_add_u64 v[68:69], v[146:147], 1, v[68:69]
	v_cvt_pk_bf16_f32 v67, v72, v73
	global_store_dwordx4 v[68:69], v[64:67], off
	s_and_b64 vcc, exec, s[6:7]
	v_mov_b32_e32 v68, 1.0
	v_mov_b32_e32 v66, 1.0
	s_cbranch_vccnz .LBB0_819
	v_add_u32_e32 v64, 0, v161
	v_add_u32_e32 v64, 0x20000, v64
	ds_read_b128 v[68:71], v64
	s_waitcnt lgkmcnt(0)
	v_mov_b32_e32 v64, v69
	v_mov_b32_e32 v65, v70
	v_mov_b32_e32 v69, v71
	v_pk_add_f32 v[64:65], v[64:65], v[68:69]
	s_nop 0
	v_add_f32_e32 v64, v64, v65
	v_fmamk_f32 v64, v64, 0x3c000000, v151
	v_mul_f32_e32 v65, 0x4f800000, v64
	v_cmp_gt_f32_e32 vcc, s37, v64
	s_nop 1
	v_cndmask_b32_e32 v64, v64, v65, vcc
	v_sqrt_f32_e32 v65, v64
	s_nop 0
	v_add_u32_e32 v67, -1, v65
	v_add_u32_e32 v68, 1, v65
	v_fma_f32 v69, -v67, v65, v64
	v_fma_f32 v70, -v68, v65, v64
	v_cmp_ge_f32_e64 s[8:9], 0, v69
	s_nop 1
	v_cndmask_b32_e64 v65, v65, v67, s[8:9]
	v_cmp_lt_f32_e64 s[8:9], 0, v70
	s_nop 1
	v_cndmask_b32_e64 v65, v65, v68, s[8:9]
	v_mul_f32_e32 v67, 0x37800000, v65
	v_cndmask_b32_e32 v65, v65, v67, vcc
	v_cmp_class_f32_e32 vcc, v64, v152
	s_nop 1
	v_cndmask_b32_e32 v64, v65, v64, vcc
	v_div_scale_f32 v65, s[4:5], v64, v64, 1.0
	v_rcp_f32_e32 v67, v65
	s_nop 0
	v_fma_f32 v68, -v65, v67, 1.0
	v_fmac_f32_e32 v67, v68, v67
	v_div_scale_f32 v68, vcc, 1.0, v64, 1.0
	v_mul_f32_e32 v69, v68, v67
	v_fma_f32 v70, -v65, v69, v68
	v_fmac_f32_e32 v69, v70, v67
	v_fma_f32 v65, -v65, v69, v68
	v_div_fmas_f32 v65, v65, v67, v69
	v_div_fixup_f32 v68, v65, v64, 1.0
.LBB0_819:
	v_add_u32_e32 v64, s20, v162
	v_ashrrev_i32_e32 v65, 31, v64
	v_pk_mul_f32 v[72:73], v[128:129], v[68:69] op_sel_hi:[1,0]
	v_lshlrev_b64 v[64:65], 8, v[64:65]
	v_pk_mul_f32 v[70:71], v[130:131], v[68:69] op_sel_hi:[1,0]
	v_pk_mul_f32 v[74:75], v[134:135], v[68:69] op_sel_hi:[1,0]
	v_pk_mul_f32 v[68:69], v[132:133], v[68:69] op_sel_hi:[1,0]
	v_pk_mul_f32 v[60:61], v[60:61], v[72:73]
	v_pk_mul_f32 v[62:63], v[62:63], v[70:71]
	v_pk_mul_f32 v[70:71], v[58:59], v[74:75]
	v_pk_mul_f32 v[58:59], v[56:57], v[68:69]
	v_cvt_pk_bf16_f32 v56, v60, v61
	v_lshl_add_u64 v[60:61], s[16:17], 0, v[64:65]
	v_lshl_add_u64 v[60:61], v[146:147], 1, v[60:61]
	s_and_b64 vcc, exec, s[6:7]
	v_cvt_pk_bf16_f32 v57, v62, v63
	v_cvt_pk_bf16_f32 v58, v58, v59
	v_cvt_pk_bf16_f32 v59, v70, v71
	global_store_dwordx4 v[60:61], v[56:59], off
	s_cbranch_vccnz .LBB0_821
	s_add_i32 s4, 0, 0x20000
	v_add_u32_e32 v56, s4, v161
	ds_read_b128 v[56:59], v56 offset:16
	s_waitcnt lgkmcnt(0)
	v_mov_b32_e32 v60, v57
	v_mov_b32_e32 v61, v58
	v_mov_b32_e32 v57, v59
	v_pk_add_f32 v[56:57], v[60:61], v[56:57]
	s_nop 0
	v_add_f32_e32 v56, v56, v57
	v_fmamk_f32 v56, v56, 0x3c000000, v151
	v_mul_f32_e32 v57, 0x4f800000, v56
	v_cmp_gt_f32_e32 vcc, s37, v56
	s_nop 1
	v_cndmask_b32_e32 v56, v56, v57, vcc
	v_sqrt_f32_e32 v57, v56
	s_nop 0
	v_add_u32_e32 v58, -1, v57
	v_add_u32_e32 v59, 1, v57
	v_fma_f32 v60, -v58, v57, v56
	v_fma_f32 v61, -v59, v57, v56
	v_cmp_ge_f32_e64 s[8:9], 0, v60
	s_nop 1
	v_cndmask_b32_e64 v57, v57, v58, s[8:9]
	v_cmp_lt_f32_e64 s[8:9], 0, v61
	s_nop 1
	v_cndmask_b32_e64 v57, v57, v59, s[8:9]
	v_mul_f32_e32 v58, 0x37800000, v57
	v_cndmask_b32_e32 v57, v57, v58, vcc
	v_cmp_class_f32_e32 vcc, v56, v152
	s_nop 1
	v_cndmask_b32_e32 v56, v57, v56, vcc
	v_div_scale_f32 v57, s[4:5], v56, v56, 1.0
	v_rcp_f32_e32 v58, v57
	s_nop 0
	v_fma_f32 v59, -v57, v58, 1.0
	v_fmac_f32_e32 v58, v59, v58
	v_div_scale_f32 v59, vcc, 1.0, v56, 1.0
	v_mul_f32_e32 v60, v59, v58
	v_fma_f32 v61, -v57, v60, v59
	v_fmac_f32_e32 v60, v61, v58
	v_fma_f32 v57, -v57, v60, v59
	v_div_fmas_f32 v57, v57, v58, v60
	v_div_fixup_f32 v66, v57, v56, 1.0
.LBB0_821:
	s_nop 0
	v_pk_mul_f32 v[58:59], v[112:113], v[66:67] op_sel_hi:[1,0]
	v_pk_mul_f32 v[56:57], v[114:115], v[66:67] op_sel_hi:[1,0]
	v_pk_mul_f32 v[60:61], v[122:123], v[66:67] op_sel_hi:[1,0]
	v_pk_mul_f32 v[62:63], v[120:121], v[66:67] op_sel_hi:[1,0]
	v_pk_mul_f32 v[52:53], v[52:53], v[58:59]
	v_pk_mul_f32 v[54:55], v[54:55], v[56:57]
	v_pk_mul_f32 v[56:57], v[50:51], v[60:61]
	v_pk_mul_f32 v[50:51], v[48:49], v[62:63]
	v_cvt_pk_bf16_f32 v48, v52, v53
	v_lshl_add_u64 v[52:53], s[18:19], 0, v[64:65]
	v_cvt_pk_bf16_f32 v49, v54, v55
	v_cvt_pk_bf16_f32 v50, v50, v51
	v_lshl_add_u64 v[52:53], v[146:147], 1, v[52:53]
	v_cvt_pk_bf16_f32 v51, v56, v57
	global_store_dwordx4 v[52:53], v[48:51], off
	s_and_b64 vcc, exec, s[6:7]
	v_mov_b32_e32 v52, 1.0
	v_mov_b32_e32 v50, 1.0
	s_cbranch_vccnz .LBB0_823
	v_add_u32_e32 v48, 0, v159
	v_add_u32_e32 v48, 0x20000, v48
	ds_read_b128 v[52:55], v48
	s_waitcnt lgkmcnt(0)
	v_mov_b32_e32 v48, v53
	v_mov_b32_e32 v49, v54
	v_mov_b32_e32 v53, v55
	v_pk_add_f32 v[48:49], v[48:49], v[52:53]
	s_nop 0
	v_add_f32_e32 v48, v48, v49
	v_fmamk_f32 v48, v48, 0x3c000000, v151
	v_mul_f32_e32 v49, 0x4f800000, v48
	v_cmp_gt_f32_e32 vcc, s37, v48
	s_nop 1
	v_cndmask_b32_e32 v48, v48, v49, vcc
	v_sqrt_f32_e32 v49, v48
	s_nop 0
	v_add_u32_e32 v51, -1, v49
	v_add_u32_e32 v52, 1, v49
	v_fma_f32 v53, -v51, v49, v48
	v_fma_f32 v54, -v52, v49, v48
	v_cmp_ge_f32_e64 s[8:9], 0, v53
	s_nop 1
	v_cndmask_b32_e64 v49, v49, v51, s[8:9]
	v_cmp_lt_f32_e64 s[8:9], 0, v54
	s_nop 1
	v_cndmask_b32_e64 v49, v49, v52, s[8:9]
	v_mul_f32_e32 v51, 0x37800000, v49
	v_cndmask_b32_e32 v49, v49, v51, vcc
	v_cmp_class_f32_e32 vcc, v48, v152
	s_nop 1
	v_cndmask_b32_e32 v48, v49, v48, vcc
	v_div_scale_f32 v49, s[4:5], v48, v48, 1.0
	v_rcp_f32_e32 v51, v49
	s_nop 0
	v_fma_f32 v52, -v49, v51, 1.0
	v_fmac_f32_e32 v51, v52, v51
	v_div_scale_f32 v52, vcc, 1.0, v48, 1.0
	v_mul_f32_e32 v53, v52, v51
	v_fma_f32 v54, -v49, v53, v52
	v_fmac_f32_e32 v53, v54, v51
	v_fma_f32 v49, -v49, v53, v52
	v_div_fmas_f32 v49, v49, v51, v53
	v_div_fixup_f32 v52, v49, v48, 1.0
.LBB0_823:
	v_add_u32_e32 v48, s20, v160
	v_ashrrev_i32_e32 v49, 31, v48
	v_pk_mul_f32 v[56:57], v[128:129], v[52:53] op_sel_hi:[1,0]
	v_lshlrev_b64 v[48:49], 8, v[48:49]
	v_pk_mul_f32 v[54:55], v[130:131], v[52:53] op_sel_hi:[1,0]
	v_pk_mul_f32 v[58:59], v[134:135], v[52:53] op_sel_hi:[1,0]
	v_pk_mul_f32 v[52:53], v[132:133], v[52:53] op_sel_hi:[1,0]
	v_pk_mul_f32 v[44:45], v[44:45], v[56:57]
	v_pk_mul_f32 v[46:47], v[46:47], v[54:55]
	v_pk_mul_f32 v[54:55], v[42:43], v[58:59]
	v_pk_mul_f32 v[42:43], v[40:41], v[52:53]
	v_cvt_pk_bf16_f32 v40, v44, v45
	v_lshl_add_u64 v[44:45], s[16:17], 0, v[48:49]
	v_lshl_add_u64 v[44:45], v[146:147], 1, v[44:45]
	s_and_b64 vcc, exec, s[6:7]
	v_cvt_pk_bf16_f32 v41, v46, v47
	v_cvt_pk_bf16_f32 v42, v42, v43
	v_cvt_pk_bf16_f32 v43, v54, v55
	global_store_dwordx4 v[44:45], v[40:43], off
	s_cbranch_vccnz .LBB0_825
	s_add_i32 s4, 0, 0x20000
	v_add_u32_e32 v40, s4, v159
	ds_read_b128 v[40:43], v40 offset:16
	s_waitcnt lgkmcnt(0)
	v_mov_b32_e32 v44, v41
	v_mov_b32_e32 v45, v42
	v_mov_b32_e32 v41, v43
	v_pk_add_f32 v[40:41], v[44:45], v[40:41]
	s_nop 0
	v_add_f32_e32 v40, v40, v41
	v_fmamk_f32 v40, v40, 0x3c000000, v151
	v_mul_f32_e32 v41, 0x4f800000, v40
	v_cmp_gt_f32_e32 vcc, s37, v40
	s_nop 1
	v_cndmask_b32_e32 v40, v40, v41, vcc
	v_sqrt_f32_e32 v41, v40
	s_nop 0
	v_add_u32_e32 v42, -1, v41
	v_add_u32_e32 v43, 1, v41
	v_fma_f32 v44, -v42, v41, v40
	v_fma_f32 v45, -v43, v41, v40
	v_cmp_ge_f32_e64 s[8:9], 0, v44
	s_nop 1
	v_cndmask_b32_e64 v41, v41, v42, s[8:9]
	v_cmp_lt_f32_e64 s[8:9], 0, v45
	s_nop 1
	v_cndmask_b32_e64 v41, v41, v43, s[8:9]
	v_mul_f32_e32 v42, 0x37800000, v41
	v_cndmask_b32_e32 v41, v41, v42, vcc
	v_cmp_class_f32_e32 vcc, v40, v152
	s_nop 1
	v_cndmask_b32_e32 v40, v41, v40, vcc
	v_div_scale_f32 v41, s[4:5], v40, v40, 1.0
	v_rcp_f32_e32 v42, v41
	s_nop 0
	v_fma_f32 v43, -v41, v42, 1.0
	v_fmac_f32_e32 v42, v43, v42
	v_div_scale_f32 v43, vcc, 1.0, v40, 1.0
	v_mul_f32_e32 v44, v43, v42
	v_fma_f32 v45, -v41, v44, v43
	v_fmac_f32_e32 v44, v45, v42
	v_fma_f32 v41, -v41, v44, v43
	v_div_fmas_f32 v41, v41, v42, v44
	v_div_fixup_f32 v50, v41, v40, 1.0
.LBB0_825:
	s_nop 0
	v_pk_mul_f32 v[42:43], v[112:113], v[50:51] op_sel_hi:[1,0]
	v_pk_mul_f32 v[40:41], v[114:115], v[50:51] op_sel_hi:[1,0]
	v_pk_mul_f32 v[44:45], v[122:123], v[50:51] op_sel_hi:[1,0]
	v_pk_mul_f32 v[46:47], v[120:121], v[50:51] op_sel_hi:[1,0]
	v_pk_mul_f32 v[36:37], v[36:37], v[42:43]
	v_pk_mul_f32 v[38:39], v[38:39], v[40:41]
	v_pk_mul_f32 v[40:41], v[34:35], v[44:45]
	v_pk_mul_f32 v[34:35], v[32:33], v[46:47]
	v_cvt_pk_bf16_f32 v32, v36, v37
	v_lshl_add_u64 v[36:37], s[18:19], 0, v[48:49]
	v_cvt_pk_bf16_f32 v33, v38, v39
	v_cvt_pk_bf16_f32 v34, v34, v35
	v_lshl_add_u64 v[36:37], v[146:147], 1, v[36:37]
	v_cvt_pk_bf16_f32 v35, v40, v41
	global_store_dwordx4 v[36:37], v[32:35], off
	s_and_b64 vcc, exec, s[6:7]
	v_mov_b32_e32 v36, 1.0
	v_mov_b32_e32 v34, 1.0
	s_cbranch_vccnz .LBB0_827
	v_add_u32_e32 v32, 0, v157
	v_add_u32_e32 v32, 0x20000, v32
	ds_read_b128 v[36:39], v32
	s_waitcnt lgkmcnt(0)
	v_mov_b32_e32 v32, v37
	v_mov_b32_e32 v33, v38
	v_mov_b32_e32 v37, v39
	v_pk_add_f32 v[32:33], v[32:33], v[36:37]
	s_nop 0
	v_add_f32_e32 v32, v32, v33
	v_fmamk_f32 v32, v32, 0x3c000000, v151
	v_mul_f32_e32 v33, 0x4f800000, v32
	v_cmp_gt_f32_e32 vcc, s37, v32
	s_nop 1
	v_cndmask_b32_e32 v32, v32, v33, vcc
	v_sqrt_f32_e32 v33, v32
	s_nop 0
	v_add_u32_e32 v35, -1, v33
	v_add_u32_e32 v36, 1, v33
	v_fma_f32 v37, -v35, v33, v32
	v_fma_f32 v38, -v36, v33, v32
	v_cmp_ge_f32_e64 s[8:9], 0, v37
	s_nop 1
	v_cndmask_b32_e64 v33, v33, v35, s[8:9]
	v_cmp_lt_f32_e64 s[8:9], 0, v38
	s_nop 1
	v_cndmask_b32_e64 v33, v33, v36, s[8:9]
	v_mul_f32_e32 v35, 0x37800000, v33
	v_cndmask_b32_e32 v33, v33, v35, vcc
	v_cmp_class_f32_e32 vcc, v32, v152
	s_nop 1
	v_cndmask_b32_e32 v32, v33, v32, vcc
	v_div_scale_f32 v33, s[4:5], v32, v32, 1.0
	v_rcp_f32_e32 v35, v33
	s_nop 0
	v_fma_f32 v36, -v33, v35, 1.0
	v_fmac_f32_e32 v35, v36, v35
	v_div_scale_f32 v36, vcc, 1.0, v32, 1.0
	v_mul_f32_e32 v37, v36, v35
	v_fma_f32 v38, -v33, v37, v36
	v_fmac_f32_e32 v37, v38, v35
	v_fma_f32 v33, -v33, v37, v36
	v_div_fmas_f32 v33, v33, v35, v37
	v_div_fixup_f32 v36, v33, v32, 1.0
.LBB0_827:
	v_add_u32_e32 v32, s20, v158
	v_ashrrev_i32_e32 v33, 31, v32
	v_pk_mul_f32 v[40:41], v[128:129], v[36:37] op_sel_hi:[1,0]
	v_lshlrev_b64 v[32:33], 8, v[32:33]
	v_pk_mul_f32 v[38:39], v[130:131], v[36:37] op_sel_hi:[1,0]
	v_pk_mul_f32 v[42:43], v[134:135], v[36:37] op_sel_hi:[1,0]
	v_pk_mul_f32 v[36:37], v[132:133], v[36:37] op_sel_hi:[1,0]
	v_pk_mul_f32 v[28:29], v[28:29], v[40:41]
	v_pk_mul_f32 v[30:31], v[30:31], v[38:39]
	v_pk_mul_f32 v[38:39], v[26:27], v[42:43]
	v_pk_mul_f32 v[26:27], v[24:25], v[36:37]
	v_cvt_pk_bf16_f32 v24, v28, v29
	v_lshl_add_u64 v[28:29], s[16:17], 0, v[32:33]
	v_lshl_add_u64 v[28:29], v[146:147], 1, v[28:29]
	s_and_b64 vcc, exec, s[6:7]
	v_cvt_pk_bf16_f32 v25, v30, v31
	v_cvt_pk_bf16_f32 v26, v26, v27
	v_cvt_pk_bf16_f32 v27, v38, v39
	global_store_dwordx4 v[28:29], v[24:27], off
	s_cbranch_vccnz .LBB0_829
	s_add_i32 s4, 0, 0x20000
	v_add_u32_e32 v24, s4, v157
	ds_read_b128 v[24:27], v24 offset:16
	s_waitcnt lgkmcnt(0)
	v_mov_b32_e32 v28, v25
	v_mov_b32_e32 v29, v26
	v_mov_b32_e32 v25, v27
	v_pk_add_f32 v[24:25], v[28:29], v[24:25]
	s_nop 0
	v_add_f32_e32 v24, v24, v25
	v_fmamk_f32 v24, v24, 0x3c000000, v151
	v_mul_f32_e32 v25, 0x4f800000, v24
	v_cmp_gt_f32_e32 vcc, s37, v24
	s_nop 1
	v_cndmask_b32_e32 v24, v24, v25, vcc
	v_sqrt_f32_e32 v25, v24
	s_nop 0
	v_add_u32_e32 v26, -1, v25
	v_add_u32_e32 v27, 1, v25
	v_fma_f32 v28, -v26, v25, v24
	v_fma_f32 v29, -v27, v25, v24
	v_cmp_ge_f32_e64 s[8:9], 0, v28
	s_nop 1
	v_cndmask_b32_e64 v25, v25, v26, s[8:9]
	v_cmp_lt_f32_e64 s[8:9], 0, v29
	s_nop 1
	v_cndmask_b32_e64 v25, v25, v27, s[8:9]
	v_mul_f32_e32 v26, 0x37800000, v25
	v_cndmask_b32_e32 v25, v25, v26, vcc
	v_cmp_class_f32_e32 vcc, v24, v152
	s_nop 1
	v_cndmask_b32_e32 v24, v25, v24, vcc
	v_div_scale_f32 v25, s[4:5], v24, v24, 1.0
	v_rcp_f32_e32 v26, v25
	s_nop 0
	v_fma_f32 v27, -v25, v26, 1.0
	v_fmac_f32_e32 v26, v27, v26
	v_div_scale_f32 v27, vcc, 1.0, v24, 1.0
	v_mul_f32_e32 v28, v27, v26
	v_fma_f32 v29, -v25, v28, v27
	v_fmac_f32_e32 v28, v29, v26
	v_fma_f32 v25, -v25, v28, v27
	v_div_fmas_f32 v25, v25, v26, v28
	v_div_fixup_f32 v34, v25, v24, 1.0
.LBB0_829:
	s_nop 0
	v_pk_mul_f32 v[26:27], v[112:113], v[34:35] op_sel_hi:[1,0]
	v_pk_mul_f32 v[24:25], v[114:115], v[34:35] op_sel_hi:[1,0]
	v_pk_mul_f32 v[28:29], v[122:123], v[34:35] op_sel_hi:[1,0]
	v_pk_mul_f32 v[30:31], v[120:121], v[34:35] op_sel_hi:[1,0]
	v_pk_mul_f32 v[20:21], v[20:21], v[26:27]
	v_pk_mul_f32 v[22:23], v[22:23], v[24:25]
	v_pk_mul_f32 v[24:25], v[18:19], v[28:29]
	v_pk_mul_f32 v[18:19], v[16:17], v[30:31]
	v_cvt_pk_bf16_f32 v16, v20, v21
	v_lshl_add_u64 v[20:21], s[18:19], 0, v[32:33]
	v_cvt_pk_bf16_f32 v17, v22, v23
	v_cvt_pk_bf16_f32 v18, v18, v19
	v_lshl_add_u64 v[20:21], v[146:147], 1, v[20:21]
	v_cvt_pk_bf16_f32 v19, v24, v25
	global_store_dwordx4 v[20:21], v[16:19], off
	s_and_b64 vcc, exec, s[6:7]
	v_mov_b32_e32 v20, 1.0
	v_mov_b32_e32 v18, 1.0
	s_cbranch_vccnz .LBB0_831
	v_add_u32_e32 v16, 0, v155
	v_add_u32_e32 v16, 0x20000, v16
	ds_read_b128 v[20:23], v16
	s_waitcnt lgkmcnt(0)
	v_mov_b32_e32 v16, v21
	v_mov_b32_e32 v17, v22
	v_mov_b32_e32 v21, v23
	v_pk_add_f32 v[16:17], v[16:17], v[20:21]
	s_nop 0
	v_add_f32_e32 v16, v16, v17
	v_fmamk_f32 v16, v16, 0x3c000000, v151
	v_mul_f32_e32 v17, 0x4f800000, v16
	v_cmp_gt_f32_e32 vcc, s37, v16
	s_nop 1
	v_cndmask_b32_e32 v16, v16, v17, vcc
	v_sqrt_f32_e32 v17, v16
	s_nop 0
	v_add_u32_e32 v19, -1, v17
	v_add_u32_e32 v20, 1, v17
	v_fma_f32 v21, -v19, v17, v16
	v_fma_f32 v22, -v20, v17, v16
	v_cmp_ge_f32_e64 s[8:9], 0, v21
	s_nop 1
	v_cndmask_b32_e64 v17, v17, v19, s[8:9]
	v_cmp_lt_f32_e64 s[8:9], 0, v22
	s_nop 1
	v_cndmask_b32_e64 v17, v17, v20, s[8:9]
	v_mul_f32_e32 v19, 0x37800000, v17
	v_cndmask_b32_e32 v17, v17, v19, vcc
	v_cmp_class_f32_e32 vcc, v16, v152
	s_nop 1
	v_cndmask_b32_e32 v16, v17, v16, vcc
	v_div_scale_f32 v17, s[4:5], v16, v16, 1.0
	v_rcp_f32_e32 v19, v17
	s_nop 0
	v_fma_f32 v20, -v17, v19, 1.0
	v_fmac_f32_e32 v19, v20, v19
	v_div_scale_f32 v20, vcc, 1.0, v16, 1.0
	v_mul_f32_e32 v21, v20, v19
	v_fma_f32 v22, -v17, v21, v20
	v_fmac_f32_e32 v21, v22, v19
	v_fma_f32 v17, -v17, v21, v20
	v_div_fmas_f32 v17, v17, v19, v21
	v_div_fixup_f32 v20, v17, v16, 1.0
.LBB0_831:
	v_add_u32_e32 v16, s20, v156
	v_ashrrev_i32_e32 v17, 31, v16
	v_pk_mul_f32 v[24:25], v[128:129], v[20:21] op_sel_hi:[1,0]
	v_lshlrev_b64 v[16:17], 8, v[16:17]
	v_pk_mul_f32 v[22:23], v[130:131], v[20:21] op_sel_hi:[1,0]
	v_pk_mul_f32 v[26:27], v[134:135], v[20:21] op_sel_hi:[1,0]
	v_pk_mul_f32 v[20:21], v[132:133], v[20:21] op_sel_hi:[1,0]
	v_pk_mul_f32 v[12:13], v[12:13], v[24:25]
	v_pk_mul_f32 v[14:15], v[14:15], v[22:23]
	v_pk_mul_f32 v[22:23], v[10:11], v[26:27]
	v_pk_mul_f32 v[10:11], v[8:9], v[20:21]
	v_cvt_pk_bf16_f32 v8, v12, v13
	v_lshl_add_u64 v[12:13], s[16:17], 0, v[16:17]
	v_lshl_add_u64 v[12:13], v[146:147], 1, v[12:13]
	s_and_b64 vcc, exec, s[6:7]
	v_cvt_pk_bf16_f32 v9, v14, v15
	v_cvt_pk_bf16_f32 v10, v10, v11
	v_cvt_pk_bf16_f32 v11, v22, v23
	global_store_dwordx4 v[12:13], v[8:11], off
	s_cbranch_vccnz .LBB0_833
	s_add_i32 s4, 0, 0x20000
	v_add_u32_e32 v8, s4, v155
	ds_read_b128 v[8:11], v8 offset:16
	s_waitcnt lgkmcnt(0)
	v_mov_b32_e32 v12, v9
	v_mov_b32_e32 v13, v10
	v_mov_b32_e32 v9, v11
	v_pk_add_f32 v[8:9], v[12:13], v[8:9]
	s_nop 0
	v_add_f32_e32 v8, v8, v9
	v_fmamk_f32 v8, v8, 0x3c000000, v151
	v_mul_f32_e32 v9, 0x4f800000, v8
	v_cmp_gt_f32_e32 vcc, s37, v8
	s_nop 1
	v_cndmask_b32_e32 v8, v8, v9, vcc
	v_sqrt_f32_e32 v9, v8
	s_nop 0
	v_add_u32_e32 v10, -1, v9
	v_add_u32_e32 v11, 1, v9
	v_fma_f32 v12, -v10, v9, v8
	v_fma_f32 v13, -v11, v9, v8
	v_cmp_ge_f32_e64 s[6:7], 0, v12
	s_nop 1
	v_cndmask_b32_e64 v9, v9, v10, s[6:7]
	v_cmp_lt_f32_e64 s[6:7], 0, v13
	s_nop 1
	v_cndmask_b32_e64 v9, v9, v11, s[6:7]
	v_mul_f32_e32 v10, 0x37800000, v9
	v_cndmask_b32_e32 v9, v9, v10, vcc
	v_cmp_class_f32_e32 vcc, v8, v152
	s_nop 1
	v_cndmask_b32_e32 v8, v9, v8, vcc
	v_div_scale_f32 v9, s[4:5], v8, v8, 1.0
	v_rcp_f32_e32 v10, v9
	s_nop 0
	v_fma_f32 v11, -v9, v10, 1.0
	v_fmac_f32_e32 v10, v11, v10
	v_div_scale_f32 v11, vcc, 1.0, v8, 1.0
	v_mul_f32_e32 v12, v11, v10
	v_fma_f32 v13, -v9, v12, v11
	v_fmac_f32_e32 v12, v13, v10
	v_fma_f32 v9, -v9, v12, v11
	v_div_fmas_f32 v9, v9, v10, v12
	v_div_fixup_f32 v18, v9, v8, 1.0
.LBB0_833:
	s_nop 0
	v_pk_mul_f32 v[10:11], v[112:113], v[18:19] op_sel_hi:[1,0]
	v_pk_mul_f32 v[8:9], v[114:115], v[18:19] op_sel_hi:[1,0]
	v_pk_mul_f32 v[12:13], v[122:123], v[18:19] op_sel_hi:[1,0]
	v_pk_mul_f32 v[14:15], v[120:121], v[18:19] op_sel_hi:[1,0]
	v_pk_mul_f32 v[4:5], v[4:5], v[10:11]
	v_pk_mul_f32 v[6:7], v[6:7], v[8:9]
	v_pk_mul_f32 v[8:9], v[2:3], v[12:13]
	v_pk_mul_f32 v[2:3], v[0:1], v[14:15]
	v_cvt_pk_bf16_f32 v0, v4, v5
	v_lshl_add_u64 v[4:5], s[18:19], 0, v[16:17]
	v_lshl_add_u64 v[4:5], v[146:147], 1, v[4:5]
	v_cvt_pk_bf16_f32 v1, v6, v7
	v_cvt_pk_bf16_f32 v2, v2, v3
	v_cvt_pk_bf16_f32 v3, v8, v9
	global_store_dwordx4 v[4:5], v[0:3], off
	s_waitcnt vmcnt(0)
	s_barrier
	s_waitcnt vmcnt(0)
	v_readlane_b32 s4, v254, 8
	v_readlane_b32 s5, v254, 9
	s_and_b64 vcc, exec, s[4:5]
	s_waitcnt lgkmcnt(0)
	s_barrier
	s_cbranch_vccnz .LBB0_749
	v_mbcnt_lo_u32_b32 v0, -1, 0
	v_mbcnt_hi_u32_b32 v0, -1, v0
	s_nop 0
	v_cmp_eq_u32_e32 vcc, 0, v0
	s_and_saveexec_b64 s[4:5], vcc
	s_cbranch_execz .LBB0_748
	buffer_wbl2 sc1
	s_waitcnt vmcnt(0)
	s_waitcnt vmcnt(0)
	v_mov_b64_e32 v[0:1], s[12:13]
	global_atomic_add v[0:1], v153, off
	s_branch .LBB0_748

.LBB0_852:
	s_and_b64 s[14:15], s[70:71], exec
	s_cselect_b32 s24, 2, 4
	s_cmpk_lt_i32 s31, 0xf0
	s_cselect_b32 s25, 6, 5
	s_cselect_b32 s29, 8, 10
	s_lshl_b64 s[14:15], s[88:89], 8
	s_add_u32 s14, s59, s14
	s_addc_u32 s15, s18, s15
	s_add_i32 s0, s0, s5
	v_mbcnt_lo_u32_b32 v4, -1, 0
	v_mbcnt_hi_u32_b32 v4, -1, v4
	v_readlane_b32 s5, v254, 7
	v_and_or_b32 v130, v4, 31, s58
	v_ashrrev_i32_e32 v2, 2, v4
	v_lshlrev_b64 v[0:1], 8, v[130:131]
	v_and_b32_e32 v2, -8, v2
	v_add_u32_e32 v10, s5, v4
	s_max_i32 s0, s0, 0
	v_ashrrev_i32_e32 v3, 31, v2
	v_lshl_add_u64 v[0:1], s[14:15], 0, v[0:1]
	v_ashrrev_i32_e32 v11, 4, v10
	v_lshl_add_u64 v[0:1], v[2:3], 1, v[0:1]
	v_add_u32_e32 v2, s0, v11
	v_ashrrev_i32_e32 v3, 31, v2
	v_lshlrev_b32_e32 v12, 4, v4
	v_lshlrev_b64 v[2:3], 8, v[2:3]
	s_mov_b64 s[14:15], 0x2000
	global_load_dwordx4 v[160:163], v[0:1], off
	global_load_dwordx4 v[156:159], v[0:1], off offset:32
	global_load_dwordx4 v[152:155], v[0:1], off offset:64
	global_load_dwordx4 v[148:151], v[0:1], off offset:96
	global_load_dwordx4 v[144:147], v[0:1], off offset:128
	global_load_dwordx4 v[136:139], v[0:1], off offset:160
	v_and_b32_e32 v130, 0xf0, v12
	v_lshl_add_u64 v[4:5], v[2:3], 0, s[14:15]
	v_lshl_add_u64 v[6:7], s[46:47], 0, v[2:3]
	v_lshl_add_u64 v[6:7], v[6:7], 0, v[130:131]
	v_lshl_add_u64 v[8:9], s[46:47], 0, v[4:5]
	v_lshl_add_u64 v[8:9], v[8:9], 0, v[130:131]
	global_load_dwordx4 v[120:123], v[6:7], off
	global_load_dwordx4 v[124:127], v[8:9], off
	global_load_dwordx4 v[140:143], v[0:1], off offset:192
	global_load_dwordx4 v[132:135], v[0:1], off offset:224
	v_lshl_add_u64 v[0:1], s[76:77], 0, v[2:3]
	v_lshl_add_u64 v[0:1], v[0:1], 0, v[130:131]
	v_lshl_add_u64 v[2:3], s[76:77], 0, v[4:5]
	v_lshl_add_u64 v[2:3], v[2:3], 0, v[130:131]
	global_load_dwordx4 v[112:115], v[0:1], off
	global_load_dwordx4 v[116:119], v[2:3], off
	v_mov_b32_e32 v0, 0xf0
	v_sub_co_u32_e32 v0, vcc, s31, v0
	s_cmpk_gt_i32 s31, 0xbf
	v_readfirstlane_b32 s5, v0
	s_cselect_b64 s[16:17], -1, 0
	s_mul_i32 s14, s5, 6
	s_lshl_b32 s5, s5, 2
	s_add_i32 s15, s5, 0x60
	s_lshl_b32 s5, s31, 2
	s_addk_i32 s14, 0x120
	s_addk_i32 s1, 0xfa90
	s_add_i32 s36, s31, 0xffffff70
	s_add_i32 s37, s5, 0xfffffd00
	s_add_i32 s40, s31, 0x9e
	s_xor_b32 s84, s83, 0xf00
	s_add_u32 s5, s59, s52
	s_addc_u32 s41, s18, s53
	s_add_u32 s52, s5, s74
	s_addc_u32 s53, s41, s75
	s_add_u32 s5, s59, s78
	s_addc_u32 s41, s18, s79
	s_add_u32 s60, s5, s74
	s_addc_u32 s61, s41, s75
	s_lshl_b64 s[6:7], s[6:7], 24
	s_add_u32 s5, s19, s6
	s_addc_u32 s41, s28, s7
	s_lshl_b32 s6, s50, 7
	s_ashr_i32 s7, s6, 31
	s_lshl_b64 s[6:7], s[6:7], 1
	s_add_u32 s85, s5, s6
	s_addc_u32 s86, s41, s7
	s_ashr_i32 s5, s4, 31
	s_lshl_b64 s[4:5], s[4:5], 14
	s_add_u32 s78, s20, s4
	s_addc_u32 s79, s21, s5
	s_and_b64 s[4:5], vcc, exec
	s_cselect_b32 s6, 7, 6
	s_and_b64 s[4:5], s[70:71], exec
	s_cselect_b32 s7, s40, s37
	s_and_b64 s[4:5], vcc, exec
	s_cselect_b32 s15, s36, s15
	s_and_b64 s[4:5], s[70:71], exec
	s_cselect_b32 s36, 0, s37
	s_and_b64 s[4:5], vcc, exec
	v_and_b32_e32 v1, 0x70, v10
	s_movk_i32 s4, 0xf0
	s_waitcnt vmcnt(0)
	s_cselect_b32 s1, s1, s14
	s_cmpk_lt_i32 s31, 0xd0
	v_lshlrev_b32_e32 v0, 8, v11
	v_bitop3_b32 v1, v12, v1, s4 bitop3:0x6c
	s_mov_b32 s0, 0
	s_cselect_b32 s87, 3, s25
	s_cselect_b32 s64, s24, s29
	v_add3_u32 v0, 0, v0, v1
	s_cselect_b32 s65, s3, s6
	s_cselect_b32 s14, s7, s15
	s_cselect_b32 s15, s36, s1
	s_xor_b64 s[88:89], s[16:17], -1
	s_mov_b64 s[40:41], 0xb000
	s_waitcnt vmcnt(0) lgkmcnt(0)
	ds_write_b128 v0, v[120:123] offset:32768
	ds_write_b128 v0, v[124:127] offset:40960
	s_waitcnt lgkmcnt(0)
	s_barrier
	s_branch .LBB0_854

.LBB0_854:
	s_cmp_lg_u32 s0, s87
	s_cselect_b64 s[4:5], -1, 0
	s_or_b64 s[4:5], s[88:89], s[4:5]
	s_and_b64 vcc, exec, s[4:5]
	s_cbranch_vccnz .LBB0_871
	v_readlane_b32 s4, v254, 8
	v_readlane_b32 s5, v254, 9
	s_and_b64 vcc, exec, s[4:5]
	s_cbranch_vccnz .LBB0_870
	v_mbcnt_lo_u32_b32 v0, -1, 0
	v_mbcnt_hi_u32_b32 v0, -1, v0
	s_nop 0
	v_cmp_eq_u32_e32 vcc, 0, v0
	s_and_saveexec_b64 s[4:5], vcc
	s_cbranch_execz .LBB0_869
	v_mov_b64_e32 v[0:1], s[12:13]
	global_load_dword v0, v[0:1], off sc1
	s_waitcnt vmcnt(0) lgkmcnt(0)
	v_cmp_gt_u32_e32 vcc, 16, v0
	s_and_saveexec_b64 s[6:7], vcc
	s_cbranch_execz .LBB0_868
	s_mov_b32 s1, 1
	s_mov_b64 s[50:51], 0
	s_branch .LBB0_860

.LBB0_860:
	s_and_b32 s3, s1, 0xff
	s_mov_b64 s[90:91], -1
	s_cmp_lg_u32 s3, 0
	s_mov_b64 s[16:17], -1
	s_sleep 1
	s_cbranch_scc1 .LBB0_864
	v_mov_b64_e32 v[0:1], s[22:23]
	global_load_dword v0, v[0:1], off sc1
	s_mov_b64 s[16:17], 0
	s_mov_b64 s[92:93], -1
	s_waitcnt vmcnt(0) lgkmcnt(0)
	v_cmp_eq_u32_e32 vcc, 0, v0
	s_and_saveexec_b64 s[94:95], vcc
	s_cmp_lt_u32 s1, 0x40001
	s_cselect_b64 s[16:17], -1, 0
	s_xor_b64 s[92:93], exec, -1
	s_and_b64 s[16:17], s[16:17], exec
	s_or_b64 exec, exec, s[94:95]
.LBB0_864:
	s_andn2_b64 s[24:25], s[76:77], exec
	s_and_b64 s[36:37], s[92:93], exec
	s_or_b64 s[76:77], s[24:25], s[36:37]
	s_and_saveexec_b64 s[92:93], s[16:17]
	s_cbranch_execz .LBB0_859
	v_mov_b64_e32 v[0:1], s[12:13]
	global_load_dword v0, v[0:1], off sc1
	s_add_i32 s1, s1, 1
	s_or_b64 s[76:77], s[76:77], exec
	s_waitcnt vmcnt(0) lgkmcnt(0)
	v_cmp_lt_u32_e32 vcc, 15, v0
	s_orn2_b64 s[90:91], vcc, exec
	s_branch .LBB0_859
.LBB0_866:
	s_or_b64 exec, exec, s[50:51]
	s_xor_b64 s[16:17], s[74:75], -1
	s_and_saveexec_b64 s[24:25], s[16:17]
	s_xor_b64 s[24:25], exec, s[24:25]
	s_cbranch_execz .LBB0_868
	v_mov_b64_e32 v[0:1], s[22:23]
	global_atomic_add v[0:1], v252, off

.LBB0_892:
	s_and_b64 vcc, exec, s[6:7]
	s_cbranch_vccz .LBB0_905
	v_lshlrev_b32_e32 v8, 3, v16
	v_cmp_gt_i32_e64 s[6:7], s36, v8
	v_mov_b32_e32 v4, 0
	v_mov_b32_e32 v5, 0
	v_mov_b32_e32 v6, 0
	v_mov_b32_e32 v7, 0
	v_mov_b32_e32 v0, 0
	v_mov_b32_e32 v1, 0
	v_mov_b32_e32 v2, 0
	v_mov_b32_e32 v3, 0
	s_and_saveexec_b64 s[16:17], s[6:7]
	s_cbranch_execz .LBB0_895
	v_ashrrev_i32_e32 v9, 31, v8
	v_lshl_add_u64 v[4:5], v[8:9], 2, s[4:5]
	global_load_dwordx4 v[0:3], v[4:5], off
	s_nop 0
	global_load_dwordx4 v[4:7], v[4:5], off offset:16

.LBB0_905:
	v_ashrrev_i32_e32 v205, 4, v16
	v_and_b32_e32 v1, 0xfffff0, v205
	v_lshlrev_b32_e32 v2, 1, v205
	v_and_or_b32 v1, v2, 8, v1
	v_lshrrev_b32_e32 v2, 1, v205
	v_and_b32_e32 v4, 3, v205
	v_add_u32_e32 v206, 32, v205
	v_and_or_b32 v2, v2, 4, v4
	v_and_b32_e32 v4, 0xfffff0, v206
	v_lshlrev_b32_e32 v5, 1, v206
	v_lshlrev_b32_e32 v17, 3, v181
	v_and_or_b32 v4, v5, 8, v4
	v_and_b32_e32 v0, 0x78, v17
	v_lshrrev_b32_e32 v1, 1, v1
	v_bfe_u32 v3, v17, 5, 2
	v_lshrrev_b32_e32 v4, 1, v4
	v_or_b32_e32 v1, v1, v3
	v_lshlrev_b32_e32 v184, 1, v0
	v_or_b32_e32 v3, v4, v3
	v_lshlrev_b32_e32 v1, 9, v1
	v_lshlrev_b32_e32 v2, 6, v2
	v_and_b32_e32 v0, 48, v184
	v_lshlrev_b32_e32 v3, 9, v3
	v_or3_b32 v1, v1, v2, v0
	v_or3_b32 v0, v3, v2, v0
	v_add_u32_e32 v214, 0, v1
	v_add_u32_e32 v215, 0, v0
	s_waitcnt lgkmcnt(0)
	s_barrier
	ds_write_b128 v214, v[112:115]
	ds_write_b128 v215, v[116:119]
	s_cmp_gt_i32 s43, 1
	s_cselect_b64 s[4:5], -1, 0
	s_lshl_b32 s3, s3, 6
	s_cmp_lt_i32 s43, 2
	s_cbranch_scc1 .LBB0_907
	s_add_i32 s6, s3, 64
	v_add_u32_e32 v0, s6, v205
	v_ashrrev_i32_e32 v1, 31, v0
	v_add_u32_e32 v4, s6, v206
	v_lshlrev_b64 v[0:1], 8, v[0:1]
	v_ashrrev_i32_e32 v5, 31, v4
	v_lshl_add_u64 v[2:3], s[62:63], 0, v[0:1]
	v_mov_b32_e32 v185, v131
	v_lshlrev_b64 v[4:5], 8, v[4:5]
	v_lshl_add_u64 v[2:3], v[2:3], 0, v[184:185]
	v_lshl_add_u64 v[6:7], s[62:63], 0, v[4:5]
	v_lshl_add_u64 v[0:1], s[74:75], 0, v[0:1]
	v_lshl_add_u64 v[6:7], v[6:7], 0, v[184:185]
	global_load_dwordx4 v[112:115], v[2:3], off
	global_load_dwordx4 v[116:119], v[6:7], off
	v_lshl_add_u64 v[0:1], v[0:1], 0, v[184:185]
	v_lshl_add_u64 v[2:3], s[74:75], 0, v[4:5]
	v_lshl_add_u64 v[2:3], v[2:3], 0, v[184:185]
	global_load_dwordx4 v[120:123], v[0:1], off
	global_load_dwordx4 v[124:127], v[2:3], off

.LBB0_919:
	s_waitcnt vmcnt(0)
	v_add_u32_e32 v112, s74, v205
	v_add_u32_e32 v80, 1, v112
	v_ashrrev_i32_e32 v81, 31, v80
	v_add_u32_e32 v84, 33, v112
	v_lshlrev_b64 v[80:81], 8, v[80:81]
	v_ashrrev_i32_e32 v85, 31, v84
	v_lshl_add_u64 v[82:83], v[186:187], 0, v[80:81]
	v_lshlrev_b64 v[84:85], 8, v[84:85]
	v_lshl_add_u64 v[80:81], v[188:189], 0, v[80:81]
	v_lshl_add_u64 v[86:87], v[186:187], 0, v[84:85]
	global_load_dwordx4 v[164:167], v[82:83], off
	global_load_dwordx4 v[168:171], v[86:87], off
	v_lshl_add_u64 v[82:83], v[188:189], 0, v[84:85]
	global_load_dwordx4 v[172:175], v[80:81], off
	global_load_dwordx4 v[176:179], v[82:83], off
	ds_read2_b64 v[94:97], v185 offset1:32
	v_mov_b64_e32 v[82:83], s[10:11]
	v_mov_b64_e32 v[100:101], s[10:11]
	v_mov_b64_e32 v[80:81], s[8:9]
	v_mov_b64_e32 v[98:99], s[8:9]
	s_waitcnt lgkmcnt(0)
	v_or_b32_e32 v81, 1.0, v95
	v_mov_b32_e32 v80, v94
	v_or_b32_e32 v99, 1.0, v97
	v_mov_b32_e32 v98, v96
	v_cndmask_b32_e64 v129, 0, v218, s[6:7]
	v_cndmask_b32_e64 v130, 0, v219, s[6:7]
	s_nop 1
	v_mfma_f32_32x32x16_bf16 v[80:95], v[80:83], v[128:131], 0
	v_mfma_f32_32x32x16_bf16 v[96:111], v[98:101], v[128:131], 0
	s_setprio 1
	ds_read_b128 v[114:117], v212 offset:49152
	s_waitcnt lgkmcnt(0)
	v_mfma_f32_32x32x16_bf16 v[80:95], v[114:117], v[160:163], v[80:95]
	ds_read_b128 v[114:117], v212 offset:57344
	s_waitcnt lgkmcnt(0)
	v_mfma_f32_32x32x16_bf16 v[96:111], v[114:117], v[160:163], v[96:111]
	ds_read_b128 v[114:117], v211 offset:49152
	s_waitcnt lgkmcnt(0)
	v_mfma_f32_32x32x16_bf16 v[80:95], v[114:117], v[156:159], v[80:95]
	ds_read_b128 v[114:117], v211 offset:57344
	s_waitcnt lgkmcnt(0)
	v_mfma_f32_32x32x16_bf16 v[96:111], v[114:117], v[156:159], v[96:111]
	ds_read_b128 v[114:117], v210 offset:49152
	s_waitcnt lgkmcnt(0)
	v_mfma_f32_32x32x16_bf16 v[80:95], v[114:117], v[152:155], v[80:95]
	ds_read_b128 v[114:117], v210 offset:57344
	s_waitcnt lgkmcnt(0)
	v_mfma_f32_32x32x16_bf16 v[96:111], v[114:117], v[152:155], v[96:111]
	ds_read_b128 v[114:117], v209 offset:49152
	s_waitcnt lgkmcnt(0)
	v_mfma_f32_32x32x16_bf16 v[80:95], v[114:117], v[148:151], v[80:95]
	ds_read_b128 v[114:117], v209 offset:57344
	s_waitcnt lgkmcnt(0)
	v_mfma_f32_32x32x16_bf16 v[96:111], v[114:117], v[148:151], v[96:111]
	ds_read_b128 v[114:117], v212 offset:49280
	s_waitcnt lgkmcnt(0)
	v_mfma_f32_32x32x16_bf16 v[80:95], v[114:117], v[144:147], v[80:95]
	ds_read_b128 v[114:117], v212 offset:57472
	s_waitcnt lgkmcnt(0)
	v_mfma_f32_32x32x16_bf16 v[96:111], v[114:117], v[144:147], v[96:111]
	ds_read_b128 v[114:117], v211 offset:49280
	s_waitcnt lgkmcnt(0)
	v_mfma_f32_32x32x16_bf16 v[80:95], v[114:117], v[136:139], v[80:95]
	ds_read_b128 v[114:117], v211 offset:57472
	s_waitcnt lgkmcnt(0)
	v_mfma_f32_32x32x16_bf16 v[96:111], v[114:117], v[136:139], v[96:111]
	ds_read_b128 v[114:117], v210 offset:49280
	s_waitcnt lgkmcnt(0)
	v_mfma_f32_32x32x16_bf16 v[80:95], v[114:117], v[140:143], v[80:95]
	ds_read_b128 v[114:117], v210 offset:57472
	s_waitcnt lgkmcnt(0)
	v_mfma_f32_32x32x16_bf16 v[96:111], v[114:117], v[140:143], v[96:111]
	ds_read_b128 v[114:117], v209 offset:49280
	s_waitcnt lgkmcnt(0)
	v_mfma_f32_32x32x16_bf16 v[80:95], v[114:117], v[132:135], v[80:95]
	ds_read_b128 v[114:117], v209 offset:57472
	s_waitcnt lgkmcnt(0)
	v_mfma_f32_32x32x16_bf16 v[96:111], v[114:117], v[132:135], v[96:111]
	s_setprio 0
	v_exp_f32_e32 v113, v64
	v_add_f32_e32 v64, 0, v237
	v_add_f32_e32 v64, v239, v64
	v_add_f32_e32 v64, v235, v64
	v_add_f32_e32 v64, v238, v64
	v_add_f32_e32 v64, v233, v64
	v_add_f32_e32 v64, v236, v64
	v_add_f32_e32 v64, v232, v64
	v_add_f32_e32 v64, v234, v64
	v_add_f32_e32 v64, v229, v64
	v_add_f32_e32 v64, v231, v64
	v_add_f32_e32 v64, v227, v64
	v_add_f32_e32 v64, v230, v64
	v_add_f32_e32 v64, v225, v64
	v_exp_f32_e32 v114, v65
	v_add_f32_e32 v64, v228, v64
	v_exp_f32_e32 v115, v66
	v_add_f32_e32 v64, v224, v64
	v_exp_f32_e32 v116, v67
	v_add_f32_e32 v64, v226, v64
	v_exp_f32_e32 v117, v68
	v_add_f32_e32 v64, v113, v64
	v_exp_f32_e32 v118, v69
	v_add_f32_e32 v64, v114, v64
	v_exp_f32_e32 v119, v70
	v_add_f32_e32 v64, v115, v64
	v_exp_f32_e32 v120, v71
	v_add_f32_e32 v64, v116, v64
	v_exp_f32_e32 v121, v72
	v_add_f32_e32 v64, v117, v64
	v_exp_f32_e32 v122, v73
	v_add_f32_e32 v64, v118, v64
	v_exp_f32_e32 v123, v74
	v_add_f32_e32 v64, v119, v64
	v_exp_f32_e32 v124, v75
	v_add_f32_e32 v64, v120, v64
	v_exp_f32_e32 v125, v76
	v_add_f32_e32 v64, v121, v64
	v_exp_f32_e32 v126, v77
	v_add_f32_e32 v64, v122, v64
	v_exp_f32_e32 v127, v78
	v_add_f32_e32 v64, v123, v64
	v_exp_f32_e32 v79, v79
	v_add_f32_e32 v64, v124, v64
	v_add_f32_e32 v64, v125, v64
	v_add_f32_e32 v64, v126, v64
	v_add_f32_e32 v64, v127, v64
	v_add_f32_e32 v221, v79, v64
	v_mov_b32_e32 v222, v221
	s_nop 1
	v_permlane32_swap_b32_e32 v221, v222
	v_cvt_pk_bf16_f32 v64, v237, v239
	v_cvt_pk_bf16_f32 v65, v235, v238
	v_cvt_pk_bf16_f32 v66, v233, v236
	v_cvt_pk_bf16_f32 v67, v232, v234
	v_cvt_pk_bf16_f32 v68, v229, v231
	v_cvt_pk_bf16_f32 v69, v227, v230
	v_cvt_pk_bf16_f32 v70, v225, v228
	v_cvt_pk_bf16_f32 v71, v224, v226
	v_cvt_pk_bf16_f32 v72, v113, v114
	v_cvt_pk_bf16_f32 v73, v115, v116
	v_cvt_pk_bf16_f32 v74, v117, v118
	v_cvt_pk_bf16_f32 v75, v119, v120
	v_cvt_pk_bf16_f32 v76, v121, v122
	v_cvt_pk_bf16_f32 v77, v123, v124
	v_cvt_pk_bf16_f32 v78, v125, v126
	v_cvt_pk_bf16_f32 v79, v127, v79
	s_nop 0
	v_permlane32_swap_b32_e32 v64, v66
	v_permlane32_swap_b32_e32 v65, v67
	v_permlane32_swap_b32_e32 v68, v70
	v_permlane32_swap_b32_e32 v69, v71
	v_permlane32_swap_b32_e32 v72, v74
	v_permlane32_swap_b32_e32 v73, v75
	v_permlane32_swap_b32_e32 v76, v78
	v_permlane32_swap_b32_e32 v77, v79
	s_setprio 1
	ds_read_b64_tr_b16 v[114:115], v203 offset:0
	ds_read_b64_tr_b16 v[116:117], v203 offset:0x800
	ds_read_b64_tr_b16 v[118:119], v203 offset:0x1000
	ds_read_b64_tr_b16 v[120:121], v203 offset:0x1800
	ds_read_b64_tr_b16 v[122:123], v203 offset:0x2000
	ds_read_b64_tr_b16 v[124:125], v203 offset:0x2800
	ds_read_b64_tr_b16 v[224:225], v203 offset:0x3000
	ds_read_b64_tr_b16 v[226:227], v203 offset:0x3800
	s_waitcnt lgkmcnt(0)
	s_nop 0
	v_mfma_f32_32x32x16_bf16 v[48:63], v[64:67], v[114:117], v[48:63]
	ds_read_b64_tr_b16 v[114:115], v203 offset:0x200
	ds_read_b64_tr_b16 v[116:117], v203 offset:0xa00
	v_mfma_f32_32x32x16_bf16 v[48:63], v[68:71], v[118:121], v[48:63]
	ds_read_b64_tr_b16 v[118:119], v203 offset:0x1200
	ds_read_b64_tr_b16 v[120:121], v203 offset:0x1a00
	v_mfma_f32_32x32x16_bf16 v[48:63], v[72:75], v[122:125], v[48:63]
	ds_read_b64_tr_b16 v[122:123], v203 offset:0x2200
	ds_read_b64_tr_b16 v[124:125], v203 offset:0x2a00
	v_mfma_f32_32x32x16_bf16 v[48:63], v[76:79], v[224:227], v[48:63]
	ds_read_b64_tr_b16 v[224:225], v203 offset:0x3200
	ds_read_b64_tr_b16 v[226:227], v203 offset:0x3a00
	s_waitcnt lgkmcnt(0)
	v_mfma_f32_32x32x16_bf16 v[32:47], v[64:67], v[114:117], v[32:47]
	ds_read_b64_tr_b16 v[114:115], v203 offset:0x400
	ds_read_b64_tr_b16 v[116:117], v203 offset:0xc00
	v_mfma_f32_32x32x16_bf16 v[32:47], v[68:71], v[118:121], v[32:47]
	ds_read_b64_tr_b16 v[118:119], v203 offset:0x1400
	ds_read_b64_tr_b16 v[120:121], v203 offset:0x1c00
	v_mfma_f32_32x32x16_bf16 v[32:47], v[72:75], v[122:125], v[32:47]
	ds_read_b64_tr_b16 v[122:123], v203 offset:0x2400
	ds_read_b64_tr_b16 v[124:125], v203 offset:0x2c00
	v_mfma_f32_32x32x16_bf16 v[32:47], v[76:79], v[224:227], v[32:47]
	ds_read_b64_tr_b16 v[224:225], v203 offset:0x3400
	ds_read_b64_tr_b16 v[226:227], v203 offset:0x3c00
	s_waitcnt lgkmcnt(0)
	v_mfma_f32_32x32x16_bf16 v[16:31], v[64:67], v[114:117], v[16:31]
	ds_read_b64_tr_b16 v[114:115], v203 offset:0x600
	ds_read_b64_tr_b16 v[116:117], v203 offset:0xe00
	v_mfma_f32_32x32x16_bf16 v[16:31], v[68:71], v[118:121], v[16:31]
	ds_read_b64_tr_b16 v[118:119], v203 offset:0x1600
	ds_read_b64_tr_b16 v[120:121], v203 offset:0x1e00
	v_mfma_f32_32x32x16_bf16 v[16:31], v[72:75], v[122:125], v[16:31]
	ds_read_b64_tr_b16 v[122:123], v203 offset:0x2600
	ds_read_b64_tr_b16 v[124:125], v203 offset:0x2e00
	v_mfma_f32_32x32x16_bf16 v[16:31], v[76:79], v[224:227], v[16:31]
	ds_read_b64_tr_b16 v[224:225], v203 offset:0x3600
	ds_read_b64_tr_b16 v[226:227], v203 offset:0x3e00
	s_waitcnt lgkmcnt(0)
	v_mfma_f32_32x32x16_bf16 v[0:15], v[64:67], v[114:117], v[0:15]
	v_mfma_f32_32x32x16_bf16 v[0:15], v[68:71], v[118:121], v[0:15]
	v_mfma_f32_32x32x16_bf16 v[0:15], v[72:75], v[122:125], v[0:15]
	v_mfma_f32_32x32x16_bf16 v[0:15], v[76:79], v[224:227], v[0:15]
	s_setprio 0
	s_sub_i32 s3, s74, 63
	s_cmp_le_i32 s74, s42
	s_cselect_b64 s[4:5], -1, 0
	s_cmp_gt_i32 s3, s16
	s_cselect_b64 s[36:37], -1, 0
	s_and_b64 s[4:5], s[4:5], s[36:37]
	s_and_b64 vcc, exec, s[4:5]
	s_cbranch_vccnz .LBB0_921
	v_add_u32_e32 v64, 0x7b, v220
	v_cmp_gt_u32_e32 vcc, s29, v64
	v_add_u32_e32 v64, 0x5b, v220
	s_nop 0
	v_cndmask_b32_e32 v80, v196, v80, vcc
	v_cmp_gt_u32_e32 vcc, s29, v64
	v_add_u32_e32 v64, 0x7a, v220
	s_nop 0
	v_cndmask_b32_e32 v96, v196, v96, vcc
	v_cmp_gt_u32_e32 vcc, s29, v64
	v_add_u32_e32 v64, 0x5a, v220
	s_nop 0
	v_cndmask_b32_e32 v81, v196, v81, vcc
	v_cmp_gt_u32_e32 vcc, s29, v64
	v_add_u32_e32 v64, 0x79, v220
	s_nop 0
	v_cndmask_b32_e32 v97, v196, v97, vcc
	v_cmp_gt_u32_e32 vcc, s29, v64
	v_add_u32_e32 v64, 0x59, v220
	s_nop 0
	v_cndmask_b32_e32 v82, v196, v82, vcc
	v_cmp_gt_u32_e32 vcc, s29, v64
	v_add_u32_e32 v64, 0x78, v220
	s_nop 0
	v_cndmask_b32_e32 v98, v196, v98, vcc
	v_cmp_gt_u32_e32 vcc, s29, v64
	v_add_u32_e32 v64, 0x58, v220
	s_nop 0
	v_cndmask_b32_e32 v83, v196, v83, vcc
	v_cmp_gt_u32_e32 vcc, s29, v64
	v_add_u32_e32 v64, 0x73, v220
	s_nop 0
	v_cndmask_b32_e32 v99, v196, v99, vcc
	v_cmp_gt_u32_e32 vcc, s29, v64
	v_add_u32_e32 v64, 0x53, v220
	s_nop 0
	v_cndmask_b32_e32 v84, v196, v84, vcc
	v_cmp_gt_u32_e32 vcc, s29, v64
	v_add_u32_e32 v64, 0x72, v220
	s_nop 0
	v_cndmask_b32_e32 v100, v196, v100, vcc
	v_cmp_gt_u32_e32 vcc, s29, v64
	v_add_u32_e32 v64, 0x52, v220
	s_nop 0
	v_cndmask_b32_e32 v85, v196, v85, vcc
	v_cmp_gt_u32_e32 vcc, s29, v64
	v_add_u32_e32 v64, 0x71, v220
	s_nop 0
	v_cndmask_b32_e32 v101, v196, v101, vcc
	v_cmp_gt_u32_e32 vcc, s29, v64
	v_add_u32_e32 v64, 0x51, v220
	s_nop 0
	v_cndmask_b32_e32 v86, v196, v86, vcc
	v_cmp_gt_u32_e32 vcc, s29, v64
	v_add_u32_e32 v64, 0x70, v220
	s_nop 0
	v_cndmask_b32_e32 v102, v196, v102, vcc
	v_cmp_gt_u32_e32 vcc, s29, v64
	v_add_u32_e32 v64, 0x50, v220
	s_nop 0
	v_cndmask_b32_e32 v87, v196, v87, vcc
	v_cmp_gt_u32_e32 vcc, s29, v64
	v_add_u32_e32 v64, 0x6b, v220
	s_nop 0
	v_cndmask_b32_e32 v103, v196, v103, vcc
	v_cmp_gt_u32_e32 vcc, s29, v64
	v_add_u32_e32 v64, 0x4b, v220
	s_nop 0
	v_cndmask_b32_e32 v88, v196, v88, vcc
	v_cmp_gt_u32_e32 vcc, s29, v64
	v_add_u32_e32 v64, 0x6a, v220
	s_nop 0
	v_cndmask_b32_e32 v104, v196, v104, vcc
	v_cmp_gt_u32_e32 vcc, s29, v64
	v_add_u32_e32 v64, 0x4a, v220
	s_nop 0
	v_cndmask_b32_e32 v89, v196, v89, vcc
	v_cmp_gt_u32_e32 vcc, s29, v64
	v_add_u32_e32 v64, 0x69, v220
	s_nop 0
	v_cndmask_b32_e32 v105, v196, v105, vcc
	v_cmp_gt_u32_e32 vcc, s29, v64
	v_add_u32_e32 v64, 0x49, v220
	s_nop 0
	v_cndmask_b32_e32 v90, v196, v90, vcc
	v_cmp_gt_u32_e32 vcc, s29, v64
	v_add_u32_e32 v64, 0x68, v220
	s_nop 0
	v_cndmask_b32_e32 v106, v196, v106, vcc
	v_cmp_gt_u32_e32 vcc, s29, v64
	v_add_u32_e32 v64, 0x48, v220
	s_nop 0
	v_cndmask_b32_e32 v91, v196, v91, vcc
	v_cmp_gt_u32_e32 vcc, s29, v64
	v_add_u32_e32 v64, 0x63, v220
	s_nop 0
	v_cndmask_b32_e32 v107, v196, v107, vcc
	v_cmp_gt_u32_e32 vcc, s29, v64
	v_add_u32_e32 v64, 0x43, v220
	s_nop 0
	v_cndmask_b32_e32 v92, v196, v92, vcc
	v_cmp_gt_u32_e32 vcc, s29, v64
	v_add_u32_e32 v64, 0x62, v220
	s_nop 0
	v_cndmask_b32_e32 v108, v196, v108, vcc
	v_cmp_gt_u32_e32 vcc, s29, v64
	v_add_u32_e32 v64, 0x42, v220
	s_nop 0
	v_cndmask_b32_e32 v93, v196, v93, vcc
	v_cmp_gt_u32_e32 vcc, s29, v64
	v_add_u32_e32 v64, 0x61, v220
	s_nop 0
	v_cndmask_b32_e32 v109, v196, v109, vcc
	v_cmp_gt_u32_e32 vcc, s29, v64
	v_add_u32_e32 v64, 0x41, v220
	s_nop 0
	v_cndmask_b32_e32 v94, v196, v94, vcc
	v_cmp_gt_u32_e32 vcc, s29, v64
	v_add_u32_e32 v64, 0x60, v220
	s_nop 0
	v_cndmask_b32_e32 v110, v196, v110, vcc
	v_cmp_gt_u32_e32 vcc, s29, v64
	v_add_u32_e32 v64, 64, v220
	s_nop 0
	v_cndmask_b32_e32 v95, v196, v95, vcc
	v_cmp_gt_u32_e32 vcc, s29, v64
	s_nop 1
	v_cndmask_b32_e32 v111, v196, v111, vcc

.LBB0_926:
	v_exp_f32_e32 v80, v80
	v_exp_f32_e32 v81, v81
	v_exp_f32_e32 v82, v82
	v_exp_f32_e32 v83, v83
	v_exp_f32_e32 v84, v84
	v_exp_f32_e32 v85, v85
	v_exp_f32_e32 v86, v86
	v_exp_f32_e32 v87, v87
	v_exp_f32_e32 v88, v88
	v_exp_f32_e32 v89, v89
	v_exp_f32_e32 v90, v90
	v_exp_f32_e32 v91, v91
	v_exp_f32_e32 v92, v92
	v_exp_f32_e32 v93, v93
	v_exp_f32_e32 v94, v94
	v_exp_f32_e32 v95, v95
	s_waitcnt lgkmcnt(0)
	s_barrier
	s_add_i32 s3, s17, 1
	s_cmp_lt_i32 s3, s43
	s_cselect_b64 s[50:51], -1, 0
	s_cmp_ge_i32 s3, s43
	s_cbranch_scc1 .LBB0_928
	v_add_u32_e32 v64, 0x41, v112
	v_ashrrev_i32_e32 v65, 31, v64
	v_add_u32_e32 v68, 0x61, v112
	v_lshlrev_b64 v[64:65], 8, v[64:65]
	v_ashrrev_i32_e32 v69, 31, v68
	v_lshl_add_u64 v[66:67], v[186:187], 0, v[64:65]
	v_lshlrev_b64 v[68:69], 8, v[68:69]
	v_lshl_add_u64 v[64:65], v[188:189], 0, v[64:65]
	v_lshl_add_u64 v[70:71], v[186:187], 0, v[68:69]
	global_load_dwordx4 v[164:167], v[66:67], off
	global_load_dwordx4 v[168:171], v[70:71], off
	v_lshl_add_u64 v[66:67], v[188:189], 0, v[68:69]
	global_load_dwordx4 v[172:175], v[64:65], off
	global_load_dwordx4 v[176:179], v[66:67], off

.LBB0_941:
	s_add_i32 s0, s81, s0
	s_add_i32 s3, s0, 1
	s_andn2_b32 s3, s3, 63
	s_cmp_gt_i32 s0, -1
	s_cselect_b32 s0, s3, 0
	s_waitcnt vmcnt(0)
	v_add_u32_e32 v112, s0, v205
	v_add_u32_e32 v114, s0, v206
	v_ashrrev_i32_e32 v113, 31, v112
	v_ashrrev_i32_e32 v115, 31, v114
	v_lshlrev_b64 v[120:121], 8, v[112:113]
	v_lshlrev_b64 v[122:123], 8, v[114:115]
	v_lshl_add_u64 v[112:113], s[76:77], 0, v[120:121]
	v_mov_b32_e32 v185, v131
	v_lshl_add_u64 v[114:115], s[76:77], 0, v[122:123]
	v_lshl_add_u64 v[120:121], s[96:97], 0, v[120:121]
	v_lshl_add_u64 v[122:123], s[96:97], 0, v[122:123]
	v_lshl_add_u64 v[112:113], v[112:113], 0, v[184:185]
	v_lshl_add_u64 v[116:117], v[114:115], 0, v[184:185]
	v_lshl_add_u64 v[120:121], v[120:121], 0, v[184:185]
	v_lshl_add_u64 v[124:125], v[122:123], 0, v[184:185]
	global_load_dwordx4 v[112:115], v[112:113], off
	s_nop 0
	global_load_dwordx4 v[116:119], v[116:117], off
	s_nop 0
	global_load_dwordx4 v[120:123], v[120:121], off
	s_nop 0
	global_load_dwordx4 v[124:127], v[124:125], off
	v_or_b32_e32 v130, s58, v197
	v_lshlrev_b64 v[128:129], 8, v[130:131]
	v_lshlrev_b32_e32 v132, 3, v208
	v_ashrrev_i32_e32 v133, 31, v132
	v_lshl_add_u64 v[128:129], s[94:95], 0, v[128:129]
	v_lshl_add_u64 v[128:129], v[132:133], 1, v[128:129]
	global_load_dwordx4 v[160:163], v[128:129], off
	global_load_dwordx4 v[156:159], v[128:129], off offset:32
	global_load_dwordx4 v[152:155], v[128:129], off offset:64
	global_load_dwordx4 v[148:151], v[128:129], off offset:96
	global_load_dwordx4 v[144:147], v[128:129], off offset:128
	global_load_dwordx4 v[136:139], v[128:129], off offset:160
	global_load_dwordx4 v[140:143], v[128:129], off offset:192
	global_load_dwordx4 v[132:135], v[128:129], off offset:224
	v_exp_f32_e32 v128, v64
	v_add_f32_e32 v64, 0, v237
	v_add_f32_e32 v64, v239, v64
	v_add_f32_e32 v64, v235, v64
	v_add_f32_e32 v64, v238, v64
	v_add_f32_e32 v64, v233, v64
	v_add_f32_e32 v64, v236, v64
	v_add_f32_e32 v64, v232, v64
	v_add_f32_e32 v64, v234, v64
	v_add_f32_e32 v64, v229, v64
	v_add_f32_e32 v64, v231, v64
	v_add_f32_e32 v64, v227, v64
	v_add_f32_e32 v64, v230, v64
	v_add_f32_e32 v64, v225, v64
	v_exp_f32_e32 v65, v65
	v_add_f32_e32 v64, v228, v64
	v_exp_f32_e32 v129, v66
	v_add_f32_e32 v64, v224, v64
	v_exp_f32_e32 v130, v67
	v_add_f32_e32 v64, v226, v64
	v_exp_f32_e32 v164, v68
	v_add_f32_e32 v64, v128, v64
	v_exp_f32_e32 v165, v69
	v_add_f32_e32 v64, v65, v64
	v_exp_f32_e32 v166, v70
	v_add_f32_e32 v64, v129, v64
	v_exp_f32_e32 v167, v71
	v_add_f32_e32 v64, v130, v64
	v_exp_f32_e32 v168, v72
	v_add_f32_e32 v64, v164, v64
	v_exp_f32_e32 v169, v73
	v_add_f32_e32 v64, v165, v64
	v_exp_f32_e32 v170, v74
	v_add_f32_e32 v64, v166, v64
	v_exp_f32_e32 v171, v75
	v_add_f32_e32 v64, v167, v64
	v_exp_f32_e32 v172, v76
	v_add_f32_e32 v64, v168, v64
	v_exp_f32_e32 v173, v77
	v_add_f32_e32 v64, v169, v64
	v_exp_f32_e32 v78, v78
	v_add_f32_e32 v64, v170, v64
	v_exp_f32_e32 v79, v79
	v_add_f32_e32 v64, v171, v64
	v_add_f32_e32 v64, v172, v64
	v_add_f32_e32 v64, v173, v64
	v_add_f32_e32 v64, v78, v64
	v_add_f32_e32 v64, v79, v64
	v_mov_b32_e32 v66, v64
	s_nop 1
	v_permlane32_swap_b32_e32 v64, v66
	v_add_f32_e32 v64, v64, v66
	v_fmac_f32_e32 v64, v217, v216
	v_cvt_pk_bf16_f32 v66, v237, v239
	v_cvt_pk_bf16_f32 v67, v235, v238
	v_cvt_pk_bf16_f32 v68, v233, v236
	v_cvt_pk_bf16_f32 v69, v232, v234
	v_cvt_pk_bf16_f32 v70, v229, v231
	v_cvt_pk_bf16_f32 v71, v227, v230
	v_cvt_pk_bf16_f32 v72, v225, v228
	v_cvt_pk_bf16_f32 v73, v224, v226
	v_cvt_pk_bf16_f32 v74, v128, v65
	v_cvt_pk_bf16_f32 v75, v129, v130
	v_cvt_pk_bf16_f32 v76, v164, v165
	v_cvt_pk_bf16_f32 v77, v166, v167
	v_cvt_pk_bf16_f32 v164, v168, v169
	v_cvt_pk_bf16_f32 v165, v170, v171
	v_cvt_pk_bf16_f32 v166, v172, v173
	v_cvt_pk_bf16_f32 v167, v78, v79
	s_nop 0
	v_permlane32_swap_b32_e32 v66, v68
	v_permlane32_swap_b32_e32 v67, v69
	v_permlane32_swap_b32_e32 v70, v72
	v_permlane32_swap_b32_e32 v71, v73
	v_permlane32_swap_b32_e32 v74, v76
	v_permlane32_swap_b32_e32 v75, v77
	v_permlane32_swap_b32_e32 v164, v166
	v_permlane32_swap_b32_e32 v165, v167
	s_setprio 1
	ds_read_b64_tr_b16 v[168:169], v203 offset:0
	ds_read_b64_tr_b16 v[170:171], v203 offset:0x800
	ds_read_b64_tr_b16 v[172:173], v203 offset:0x1000
	ds_read_b64_tr_b16 v[174:175], v203 offset:0x1800
	ds_read_b64_tr_b16 v[176:177], v203 offset:0x2000
	ds_read_b64_tr_b16 v[178:179], v203 offset:0x2800
	ds_read_b64_tr_b16 v[184:185], v203 offset:0x3000
	ds_read_b64_tr_b16 v[186:187], v203 offset:0x3800
	s_waitcnt lgkmcnt(0)
	s_nop 0
	v_mfma_f32_32x32x16_bf16 v[48:63], v[66:69], v[168:171], v[48:63]
	ds_read_b64_tr_b16 v[168:169], v203 offset:0x200
	ds_read_b64_tr_b16 v[170:171], v203 offset:0xa00
	v_mfma_f32_32x32x16_bf16 v[48:63], v[70:73], v[172:175], v[48:63]
	ds_read_b64_tr_b16 v[172:173], v203 offset:0x1200
	ds_read_b64_tr_b16 v[174:175], v203 offset:0x1a00
	v_mfma_f32_32x32x16_bf16 v[48:63], v[74:77], v[176:179], v[48:63]
	ds_read_b64_tr_b16 v[176:177], v203 offset:0x2200
	ds_read_b64_tr_b16 v[178:179], v203 offset:0x2a00
	v_mfma_f32_32x32x16_bf16 v[48:63], v[164:167], v[184:187], v[48:63]
	ds_read_b64_tr_b16 v[184:185], v203 offset:0x3200
	ds_read_b64_tr_b16 v[186:187], v203 offset:0x3a00
	s_waitcnt lgkmcnt(0)
	v_mfma_f32_32x32x16_bf16 v[32:47], v[66:69], v[168:171], v[32:47]
	ds_read_b64_tr_b16 v[168:169], v203 offset:0x400
	ds_read_b64_tr_b16 v[170:171], v203 offset:0xc00
	v_mfma_f32_32x32x16_bf16 v[32:47], v[70:73], v[172:175], v[32:47]
	ds_read_b64_tr_b16 v[172:173], v203 offset:0x1400
	ds_read_b64_tr_b16 v[174:175], v203 offset:0x1c00
	v_mfma_f32_32x32x16_bf16 v[32:47], v[74:77], v[176:179], v[32:47]
	ds_read_b64_tr_b16 v[176:177], v203 offset:0x2400
	ds_read_b64_tr_b16 v[178:179], v203 offset:0x2c00
	v_mfma_f32_32x32x16_bf16 v[32:47], v[164:167], v[184:187], v[32:47]
	ds_read_b64_tr_b16 v[184:185], v203 offset:0x3400
	ds_read_b64_tr_b16 v[186:187], v203 offset:0x3c00
	s_waitcnt lgkmcnt(0)
	v_mfma_f32_32x32x16_bf16 v[16:31], v[66:69], v[168:171], v[16:31]
	ds_read_b64_tr_b16 v[168:169], v203 offset:0x600
	ds_read_b64_tr_b16 v[170:171], v203 offset:0xe00
	v_mfma_f32_32x32x16_bf16 v[16:31], v[70:73], v[172:175], v[16:31]
	ds_read_b64_tr_b16 v[172:173], v203 offset:0x1600
	ds_read_b64_tr_b16 v[174:175], v203 offset:0x1e00
	v_mfma_f32_32x32x16_bf16 v[16:31], v[74:77], v[176:179], v[16:31]
	ds_read_b64_tr_b16 v[176:177], v203 offset:0x2600
	ds_read_b64_tr_b16 v[178:179], v203 offset:0x2e00
	v_mfma_f32_32x32x16_bf16 v[16:31], v[164:167], v[184:187], v[16:31]
	ds_read_b64_tr_b16 v[184:185], v203 offset:0x3600
	ds_read_b64_tr_b16 v[186:187], v203 offset:0x3e00
	s_waitcnt lgkmcnt(0)
	v_mfma_f32_32x32x16_bf16 v[0:15], v[66:69], v[168:171], v[0:15]
	v_mfma_f32_32x32x16_bf16 v[0:15], v[70:73], v[172:175], v[0:15]
	v_mfma_f32_32x32x16_bf16 v[0:15], v[74:77], v[176:179], v[0:15]
	v_mfma_f32_32x32x16_bf16 v[0:15], v[164:167], v[184:187], v[0:15]
	s_setprio 0
	s_andn2_b64 vcc, exec, s[4:5]
	s_cbranch_vccnz .LBB0_952
	s_lshl_b32 s1, s1, 6
	s_sub_i32 s0, s1, 64
	s_add_i32 s1, s1, -1
	s_cmp_gt_i32 s1, s42
	s_cselect_b64 s[4:5], -1, 0
	s_and_b64 vcc, exec, s[4:5]
	s_cbranch_vccnz .LBB0_944
	s_sub_i32 s1, s42, s29
	s_add_i32 s1, s1, 31
	s_cmp_le_i32 s0, s1
	s_cselect_b64 s[4:5], -1, 0

.LBB0_954:
	s_or_b64 exec, exec, s[4:5]
	s_waitcnt lgkmcnt(0)
	ds_read_b128 v[76:79], v201
	ds_read_b128 v[72:75], v201 offset:32
	v_and_b32_e32 v81, 64, v190
	v_xor_b32_e32 v80, 1, v190
	v_add_u32_e32 v81, 64, v81
	s_waitcnt lgkmcnt(1)
	v_rcp_f32_e32 v76, v76
	v_cmp_lt_i32_e32 vcc, v80, v81
	ds_read_b128 v[68:71], v201 offset:64
	ds_read_b128 v[64:67], v201 offset:96
	v_cndmask_b32_e32 v80, v190, v80, vcc
	v_lshlrev_b32_e32 v170, 2, v80
	v_mul_f32_e32 v48, v48, v76
	ds_bpermute_b32 v84, v170, v48
	s_add_u32 s0, s90, s8
	s_addc_u32 s1, s91, s9
	v_and_b32_e32 v80, 1, v181
	v_lshlrev_b32_e32 v130, 1, v197
	v_ashrrev_i32_e32 v181, 31, v180
	v_cmp_eq_u32_e32 vcc, 0, v80
	v_lshl_add_u64 v[80:81], s[0:1], 0, v[130:131]
	v_lshlrev_b64 v[82:83], 12, v[180:181]
	v_lshl_add_u64 v[82:83], v[80:81], 0, v[82:83]
	s_and_saveexec_b64 s[4:5], vcc
	s_cbranch_execz .LBB0_956
	s_waitcnt lgkmcnt(0)
	v_cvt_pk_bf16_f32 v48, v48, v84
	global_store_dword v[82:83], v48, off
.LBB0_956:
	s_or_b64 exec, exec, s[4:5]
	v_mul_f32_e32 v32, v32, v76
	ds_bpermute_b32 v48, v170, v32
	s_and_saveexec_b64 s[4:5], vcc
	s_cbranch_execz .LBB0_958
	s_waitcnt lgkmcnt(0)
	v_cvt_pk_bf16_f32 v32, v32, v48
	global_store_dword v[82:83], v32, off offset:64
.LBB0_958:
	s_or_b64 exec, exec, s[4:5]
	v_mul_f32_e32 v16, v16, v76
	ds_bpermute_b32 v32, v170, v16
	s_and_saveexec_b64 s[4:5], vcc
	s_cbranch_execz .LBB0_960
	s_waitcnt lgkmcnt(0)
	v_cvt_pk_bf16_f32 v16, v16, v32
	global_store_dword v[82:83], v16, off offset:128
.LBB0_960:
	s_or_b64 exec, exec, s[4:5]
	v_mul_f32_e32 v0, v0, v76
	ds_bpermute_b32 v16, v170, v0
	s_and_saveexec_b64 s[4:5], vcc
	s_cbranch_execz .LBB0_962
	s_waitcnt lgkmcnt(0)
	v_cvt_pk_bf16_f32 v0, v0, v16
	global_store_dword v[82:83], v0, off offset:192
.LBB0_962:
	s_or_b64 exec, exec, s[4:5]
	v_rcp_f32_e32 v0, v77
	v_or_b32_e32 v76, 1, v180
	v_ashrrev_i32_e32 v77, 31, v76
	v_lshlrev_b64 v[76:77], 12, v[76:77]
	s_waitcnt lgkmcnt(0)
	v_mul_f32_e32 v16, v49, v0
	ds_bpermute_b32 v32, v170, v16
	v_lshl_add_u64 v[76:77], v[80:81], 0, v[76:77]
	s_and_saveexec_b64 s[4:5], vcc
	s_cbranch_execz .LBB0_964
	s_waitcnt lgkmcnt(0)
	v_cvt_pk_bf16_f32 v16, v16, v32
	global_store_dword v[76:77], v16, off
.LBB0_964:
	s_or_b64 exec, exec, s[4:5]
	v_mul_f32_e32 v16, v33, v0
	s_waitcnt lgkmcnt(0)
	ds_bpermute_b32 v32, v170, v16
	s_and_saveexec_b64 s[4:5], vcc
	s_cbranch_execz .LBB0_966
	s_waitcnt lgkmcnt(0)
	v_cvt_pk_bf16_f32 v16, v16, v32
	global_store_dword v[76:77], v16, off offset:64
.LBB0_966:
	s_or_b64 exec, exec, s[4:5]
	v_mul_f32_e32 v16, v17, v0
	ds_bpermute_b32 v17, v170, v16
	s_and_saveexec_b64 s[4:5], vcc
	s_cbranch_execz .LBB0_968
	s_waitcnt lgkmcnt(0)
	v_cvt_pk_bf16_f32 v16, v16, v17
	global_store_dword v[76:77], v16, off offset:128
.LBB0_968:
	s_or_b64 exec, exec, s[4:5]
	v_mul_f32_e32 v0, v1, v0
	ds_bpermute_b32 v1, v170, v0
	s_and_saveexec_b64 s[4:5], vcc
	s_cbranch_execz .LBB0_970
	s_waitcnt lgkmcnt(0)
	v_cvt_pk_bf16_f32 v0, v0, v1
	global_store_dword v[76:77], v0, off offset:192
.LBB0_970:
	s_or_b64 exec, exec, s[4:5]
	v_rcp_f32_e32 v16, v78
	v_or_b32_e32 v0, 2, v180
	s_waitcnt lgkmcnt(0)
	v_ashrrev_i32_e32 v1, 31, v0
	v_lshlrev_b64 v[0:1], 12, v[0:1]
	v_mul_f32_e32 v17, v50, v16
	ds_bpermute_b32 v32, v170, v17
	v_lshl_add_u64 v[0:1], v[80:81], 0, v[0:1]
	s_and_saveexec_b64 s[4:5], vcc
	s_cbranch_execz .LBB0_972
	s_waitcnt lgkmcnt(0)
	v_cvt_pk_bf16_f32 v17, v17, v32
	global_store_dword v[0:1], v17, off
.LBB0_972:
	s_or_b64 exec, exec, s[4:5]
	v_mul_f32_e32 v17, v34, v16
	s_waitcnt lgkmcnt(0)
	ds_bpermute_b32 v32, v170, v17
	s_and_saveexec_b64 s[4:5], vcc
	s_cbranch_execz .LBB0_974
	s_waitcnt lgkmcnt(0)
	v_cvt_pk_bf16_f32 v17, v17, v32
	global_store_dword v[0:1], v17, off offset:64
.LBB0_974:
	s_or_b64 exec, exec, s[4:5]
	v_mul_f32_e32 v17, v18, v16
	ds_bpermute_b32 v18, v170, v17
	s_and_saveexec_b64 s[4:5], vcc
	s_cbranch_execz .LBB0_976
	s_waitcnt lgkmcnt(0)
	v_cvt_pk_bf16_f32 v17, v17, v18
	global_store_dword v[0:1], v17, off offset:128
.LBB0_976:
	s_or_b64 exec, exec, s[4:5]
	v_mul_f32_e32 v2, v2, v16
	ds_bpermute_b32 v16, v170, v2
	s_and_saveexec_b64 s[4:5], vcc
	s_cbranch_execz .LBB0_978
	s_waitcnt lgkmcnt(0)
	v_cvt_pk_bf16_f32 v2, v2, v16
	global_store_dword v[0:1], v2, off offset:192
.LBB0_978:
	s_or_b64 exec, exec, s[4:5]
	v_rcp_f32_e32 v2, v79
	v_or_b32_e32 v0, 3, v180
	v_ashrrev_i32_e32 v1, 31, v0
	v_lshlrev_b64 v[0:1], 12, v[0:1]
	s_waitcnt lgkmcnt(0)
	v_mul_f32_e32 v16, v51, v2
	ds_bpermute_b32 v17, v170, v16
	v_lshl_add_u64 v[0:1], v[80:81], 0, v[0:1]
	s_and_saveexec_b64 s[4:5], vcc
	s_cbranch_execz .LBB0_980
	s_waitcnt lgkmcnt(0)
	v_cvt_pk_bf16_f32 v16, v16, v17
	global_store_dword v[0:1], v16, off
.LBB0_980:
	s_or_b64 exec, exec, s[4:5]
	v_mul_f32_e32 v16, v35, v2
	s_waitcnt lgkmcnt(0)
	ds_bpermute_b32 v17, v170, v16
	s_and_saveexec_b64 s[4:5], vcc
	s_cbranch_execz .LBB0_982
	s_waitcnt lgkmcnt(0)
	v_cvt_pk_bf16_f32 v16, v16, v17
	global_store_dword v[0:1], v16, off offset:64
.LBB0_982:
	s_or_b64 exec, exec, s[4:5]
	v_mul_f32_e32 v16, v19, v2
	s_waitcnt lgkmcnt(0)
	ds_bpermute_b32 v17, v170, v16
	s_and_saveexec_b64 s[4:5], vcc
	s_cbranch_execz .LBB0_984
	s_waitcnt lgkmcnt(0)
	v_cvt_pk_bf16_f32 v16, v16, v17
	global_store_dword v[0:1], v16, off offset:128
.LBB0_984:
	s_or_b64 exec, exec, s[4:5]
	v_mul_f32_e32 v2, v3, v2
	ds_bpermute_b32 v3, v170, v2
	s_and_saveexec_b64 s[4:5], vcc
	s_cbranch_execz .LBB0_986
	s_waitcnt lgkmcnt(0)
	v_cvt_pk_bf16_f32 v2, v2, v3
	global_store_dword v[0:1], v2, off offset:192
.LBB0_986:
	s_or_b64 exec, exec, s[4:5]
	v_rcp_f32_e32 v2, v72
	v_lshlrev_b64 v[0:1], 12, v[180:181]
	v_lshl_add_u64 v[0:1], v[80:81], 0, v[0:1]
	v_lshl_add_u64 v[0:1], v[0:1], 0, s[34:35]
	s_waitcnt lgkmcnt(0)
	v_mul_f32_e32 v3, v52, v2
	ds_bpermute_b32 v16, v170, v3
	s_and_saveexec_b64 s[4:5], vcc
	s_cbranch_execz .LBB0_988
	s_waitcnt lgkmcnt(0)
	v_cvt_pk_bf16_f32 v3, v3, v16
	global_store_dword v[0:1], v3, off
.LBB0_988:
	s_or_b64 exec, exec, s[4:5]
	v_mul_f32_e32 v3, v36, v2
	s_waitcnt lgkmcnt(0)
	ds_bpermute_b32 v16, v170, v3
	s_and_saveexec_b64 s[4:5], vcc
	s_cbranch_execz .LBB0_990
	s_waitcnt lgkmcnt(0)
	v_cvt_pk_bf16_f32 v3, v3, v16
	global_store_dword v[0:1], v3, off offset:64
.LBB0_990:
	s_or_b64 exec, exec, s[4:5]
	v_mul_f32_e32 v3, v20, v2
	s_waitcnt lgkmcnt(0)
	ds_bpermute_b32 v16, v170, v3
	s_and_saveexec_b64 s[4:5], vcc
	s_cbranch_execz .LBB0_992
	s_waitcnt lgkmcnt(0)
	v_cvt_pk_bf16_f32 v3, v3, v16
	global_store_dword v[0:1], v3, off offset:128
.LBB0_992:
	s_or_b64 exec, exec, s[4:5]
	v_mul_f32_e32 v2, v4, v2
	ds_bpermute_b32 v3, v170, v2
	s_and_saveexec_b64 s[4:5], vcc
	s_cbranch_execz .LBB0_994
	s_waitcnt lgkmcnt(0)
	v_cvt_pk_bf16_f32 v2, v2, v3
	global_store_dword v[0:1], v2, off offset:192
.LBB0_994:
	s_or_b64 exec, exec, s[4:5]
	v_rcp_f32_e32 v2, v73
	v_lshlrev_b64 v[0:1], 12, v[180:181]
	v_lshl_add_u64 v[0:1], v[80:81], 0, v[0:1]
	v_lshl_add_u64 v[0:1], v[0:1], 0, s[48:49]
	s_waitcnt lgkmcnt(0)
	v_mul_f32_e32 v3, v53, v2
	ds_bpermute_b32 v4, v170, v3
	s_and_saveexec_b64 s[4:5], vcc
	s_cbranch_execz .LBB0_996
	s_waitcnt lgkmcnt(0)
	v_cvt_pk_bf16_f32 v3, v3, v4
	global_store_dword v[0:1], v3, off
.LBB0_996:
	s_or_b64 exec, exec, s[4:5]
	v_mul_f32_e32 v3, v37, v2
	s_waitcnt lgkmcnt(0)
	ds_bpermute_b32 v4, v170, v3
	s_and_saveexec_b64 s[4:5], vcc
	s_cbranch_execz .LBB0_998
	s_waitcnt lgkmcnt(0)
	v_cvt_pk_bf16_f32 v3, v3, v4
	global_store_dword v[0:1], v3, off offset:64
.LBB0_998:
	s_or_b64 exec, exec, s[4:5]
	v_mul_f32_e32 v3, v21, v2
	s_waitcnt lgkmcnt(0)
	ds_bpermute_b32 v4, v170, v3
	s_and_saveexec_b64 s[4:5], vcc
	s_cbranch_execz .LBB0_1000
	s_waitcnt lgkmcnt(0)
	v_cvt_pk_bf16_f32 v3, v3, v4
	global_store_dword v[0:1], v3, off offset:128
.LBB0_1000:
	s_or_b64 exec, exec, s[4:5]
	v_mul_f32_e32 v2, v5, v2
	ds_bpermute_b32 v3, v170, v2
	s_and_saveexec_b64 s[4:5], vcc
	s_cbranch_execz .LBB0_1002
	s_waitcnt lgkmcnt(0)
	v_cvt_pk_bf16_f32 v2, v2, v3
	global_store_dword v[0:1], v2, off offset:192
.LBB0_1002:
	s_or_b64 exec, exec, s[4:5]
	v_rcp_f32_e32 v2, v74
	v_lshlrev_b64 v[0:1], 12, v[180:181]
	v_lshl_add_u64 v[0:1], v[80:81], 0, v[0:1]
	v_lshl_add_u64 v[0:1], v[0:1], 0, s[54:55]
	s_waitcnt lgkmcnt(0)
	v_mul_f32_e32 v3, v54, v2
	ds_bpermute_b32 v4, v170, v3
	s_and_saveexec_b64 s[4:5], vcc
	s_cbranch_execz .LBB0_1004
	s_waitcnt lgkmcnt(0)
	v_cvt_pk_bf16_f32 v3, v3, v4
	global_store_dword v[0:1], v3, off
.LBB0_1004:
	s_or_b64 exec, exec, s[4:5]
	v_mul_f32_e32 v3, v38, v2
	s_waitcnt lgkmcnt(0)
	ds_bpermute_b32 v4, v170, v3
	s_and_saveexec_b64 s[4:5], vcc
	s_cbranch_execz .LBB0_1006
	s_waitcnt lgkmcnt(0)
	v_cvt_pk_bf16_f32 v3, v3, v4
	global_store_dword v[0:1], v3, off offset:64
.LBB0_1006:
	s_or_b64 exec, exec, s[4:5]
	v_mul_f32_e32 v3, v22, v2
	s_waitcnt lgkmcnt(0)
	ds_bpermute_b32 v4, v170, v3
	s_and_saveexec_b64 s[4:5], vcc
	s_cbranch_execz .LBB0_1008
	s_waitcnt lgkmcnt(0)
	v_cvt_pk_bf16_f32 v3, v3, v4
	global_store_dword v[0:1], v3, off offset:128
.LBB0_1008:
	s_or_b64 exec, exec, s[4:5]
	v_mul_f32_e32 v2, v6, v2
	ds_bpermute_b32 v3, v170, v2
	s_and_saveexec_b64 s[4:5], vcc
	s_cbranch_execz .LBB0_1010
	s_waitcnt lgkmcnt(0)
	v_cvt_pk_bf16_f32 v2, v2, v3
	global_store_dword v[0:1], v2, off offset:192
.LBB0_1010:
	s_or_b64 exec, exec, s[4:5]
	v_rcp_f32_e32 v2, v75
	v_lshlrev_b64 v[0:1], 12, v[180:181]
	v_lshl_add_u64 v[0:1], v[80:81], 0, v[0:1]
	v_lshl_add_u64 v[0:1], v[0:1], 0, s[40:41]
	s_waitcnt lgkmcnt(0)
	v_mul_f32_e32 v3, v55, v2
	ds_bpermute_b32 v4, v170, v3
	s_and_saveexec_b64 s[4:5], vcc
	s_cbranch_execz .LBB0_1012
	s_waitcnt lgkmcnt(0)
	v_cvt_pk_bf16_f32 v3, v3, v4
	global_store_dword v[0:1], v3, off
.LBB0_1012:
	s_or_b64 exec, exec, s[4:5]
	v_mul_f32_e32 v3, v39, v2
	s_waitcnt lgkmcnt(0)
	ds_bpermute_b32 v4, v170, v3
	s_and_saveexec_b64 s[4:5], vcc
	s_cbranch_execz .LBB0_1014
	s_waitcnt lgkmcnt(0)
	v_cvt_pk_bf16_f32 v3, v3, v4
	global_store_dword v[0:1], v3, off offset:64
.LBB0_1014:
	s_or_b64 exec, exec, s[4:5]
	v_mul_f32_e32 v3, v23, v2
	s_waitcnt lgkmcnt(0)
	ds_bpermute_b32 v4, v170, v3
	s_and_saveexec_b64 s[4:5], vcc
	s_cbranch_execz .LBB0_1016
	s_waitcnt lgkmcnt(0)
	v_cvt_pk_bf16_f32 v3, v3, v4
	global_store_dword v[0:1], v3, off offset:128
.LBB0_1016:
	s_or_b64 exec, exec, s[4:5]
	v_mul_f32_e32 v2, v7, v2
	ds_bpermute_b32 v3, v170, v2
	s_and_saveexec_b64 s[4:5], vcc
	s_cbranch_execz .LBB0_1018
	s_waitcnt lgkmcnt(0)
	v_cvt_pk_bf16_f32 v2, v2, v3
	global_store_dword v[0:1], v2, off offset:192
.LBB0_1018:
	s_or_b64 exec, exec, s[4:5]
	v_rcp_f32_e32 v2, v68
	v_lshlrev_b64 v[0:1], 12, v[180:181]
	v_lshl_add_u64 v[0:1], v[80:81], 0, v[0:1]
	s_mov_b64 s[0:1], 0x10000
	s_waitcnt lgkmcnt(0)
	v_mul_f32_e32 v3, v56, v2
	ds_bpermute_b32 v4, v170, v3
	v_lshl_add_u64 v[0:1], v[0:1], 0, s[0:1]
	s_and_saveexec_b64 s[4:5], vcc
	s_cbranch_execz .LBB0_1020
	s_waitcnt lgkmcnt(0)
	v_cvt_pk_bf16_f32 v3, v3, v4
	global_store_dword v[0:1], v3, off
.LBB0_1020:
	s_or_b64 exec, exec, s[4:5]
	v_mul_f32_e32 v3, v40, v2
	s_waitcnt lgkmcnt(0)
	ds_bpermute_b32 v4, v170, v3
	s_and_saveexec_b64 s[4:5], vcc
	s_cbranch_execz .LBB0_1022
	s_waitcnt lgkmcnt(0)
	v_cvt_pk_bf16_f32 v3, v3, v4
	global_store_dword v[0:1], v3, off offset:64
.LBB0_1022:
	s_or_b64 exec, exec, s[4:5]
	v_mul_f32_e32 v3, v24, v2
	s_waitcnt lgkmcnt(0)
	ds_bpermute_b32 v4, v170, v3
	s_and_saveexec_b64 s[4:5], vcc
	s_cbranch_execz .LBB0_1024
	s_waitcnt lgkmcnt(0)
	v_cvt_pk_bf16_f32 v3, v3, v4
	global_store_dword v[0:1], v3, off offset:128
.LBB0_1024:
	s_or_b64 exec, exec, s[4:5]
	v_mul_f32_e32 v2, v8, v2
	ds_bpermute_b32 v3, v170, v2
	s_and_saveexec_b64 s[4:5], vcc
	s_cbranch_execz .LBB0_1026
	s_waitcnt lgkmcnt(0)
	v_cvt_pk_bf16_f32 v2, v2, v3
	global_store_dword v[0:1], v2, off offset:192
.LBB0_1026:
	s_or_b64 exec, exec, s[4:5]
	v_rcp_f32_e32 v2, v69
	v_lshlrev_b64 v[0:1], 12, v[180:181]
	v_lshl_add_u64 v[0:1], v[80:81], 0, v[0:1]
	s_mov_b64 s[0:1], 0x11000
	s_waitcnt lgkmcnt(0)
	v_mul_f32_e32 v3, v57, v2
	ds_bpermute_b32 v4, v170, v3
	v_lshl_add_u64 v[0:1], v[0:1], 0, s[0:1]
	s_and_saveexec_b64 s[4:5], vcc
	s_cbranch_execz .LBB0_1028
	s_waitcnt lgkmcnt(0)
	v_cvt_pk_bf16_f32 v3, v3, v4
	global_store_dword v[0:1], v3, off
.LBB0_1028:
	s_or_b64 exec, exec, s[4:5]
	v_mul_f32_e32 v3, v41, v2
	s_waitcnt lgkmcnt(0)
	ds_bpermute_b32 v4, v170, v3
	s_and_saveexec_b64 s[4:5], vcc
	s_cbranch_execz .LBB0_1030
	s_waitcnt lgkmcnt(0)
	v_cvt_pk_bf16_f32 v3, v3, v4
	global_store_dword v[0:1], v3, off offset:64
.LBB0_1030:
	s_or_b64 exec, exec, s[4:5]
	v_mul_f32_e32 v3, v25, v2
	s_waitcnt lgkmcnt(0)
	ds_bpermute_b32 v4, v170, v3
	s_and_saveexec_b64 s[4:5], vcc
	s_cbranch_execz .LBB0_1032
	s_waitcnt lgkmcnt(0)
	v_cvt_pk_bf16_f32 v3, v3, v4
	global_store_dword v[0:1], v3, off offset:128
.LBB0_1032:
	s_or_b64 exec, exec, s[4:5]
	v_mul_f32_e32 v2, v9, v2
	ds_bpermute_b32 v3, v170, v2
	s_and_saveexec_b64 s[4:5], vcc
	s_cbranch_execz .LBB0_1034
	s_waitcnt lgkmcnt(0)
	v_cvt_pk_bf16_f32 v2, v2, v3
	global_store_dword v[0:1], v2, off offset:192
.LBB0_1034:
	s_or_b64 exec, exec, s[4:5]
	v_rcp_f32_e32 v2, v70
	v_lshlrev_b64 v[0:1], 12, v[180:181]
	v_lshl_add_u64 v[0:1], v[80:81], 0, v[0:1]
	v_lshl_add_u64 v[0:1], v[0:1], 0, s[56:57]
	s_waitcnt lgkmcnt(0)
	v_mul_f32_e32 v3, v58, v2
	ds_bpermute_b32 v4, v170, v3
	s_and_saveexec_b64 s[4:5], vcc
	s_cbranch_execz .LBB0_1036
	s_waitcnt lgkmcnt(0)
	v_cvt_pk_bf16_f32 v3, v3, v4
	global_store_dword v[0:1], v3, off
.LBB0_1036:
	s_or_b64 exec, exec, s[4:5]
	v_mul_f32_e32 v3, v42, v2
	s_waitcnt lgkmcnt(0)
	ds_bpermute_b32 v4, v170, v3
	s_and_saveexec_b64 s[4:5], vcc
	s_cbranch_execz .LBB0_1038
	s_waitcnt lgkmcnt(0)
	v_cvt_pk_bf16_f32 v3, v3, v4
	global_store_dword v[0:1], v3, off offset:64
.LBB0_1038:
	s_or_b64 exec, exec, s[4:5]
	v_mul_f32_e32 v3, v26, v2
	s_waitcnt lgkmcnt(0)
	ds_bpermute_b32 v4, v170, v3
	s_and_saveexec_b64 s[4:5], vcc
	s_cbranch_execz .LBB0_1040
	s_waitcnt lgkmcnt(0)
	v_cvt_pk_bf16_f32 v3, v3, v4
	global_store_dword v[0:1], v3, off offset:128
.LBB0_1040:
	s_or_b64 exec, exec, s[4:5]
	v_mul_f32_e32 v2, v10, v2
	ds_bpermute_b32 v3, v170, v2
	s_and_saveexec_b64 s[4:5], vcc
	s_cbranch_execz .LBB0_1042
	s_waitcnt lgkmcnt(0)
	v_cvt_pk_bf16_f32 v2, v2, v3
	global_store_dword v[0:1], v2, off offset:192
.LBB0_1042:
	s_or_b64 exec, exec, s[4:5]
	v_rcp_f32_e32 v2, v71
	v_lshlrev_b64 v[0:1], 12, v[180:181]
	v_lshl_add_u64 v[0:1], v[80:81], 0, v[0:1]
	s_mov_b64 s[0:1], 0x13000
	s_waitcnt lgkmcnt(0)
	v_mul_f32_e32 v3, v59, v2
	ds_bpermute_b32 v4, v170, v3
	v_lshl_add_u64 v[0:1], v[0:1], 0, s[0:1]
	s_and_saveexec_b64 s[4:5], vcc
	s_cbranch_execz .LBB0_1044
	s_waitcnt lgkmcnt(0)
	v_cvt_pk_bf16_f32 v3, v3, v4
	global_store_dword v[0:1], v3, off
.LBB0_1044:
	s_or_b64 exec, exec, s[4:5]
	v_mul_f32_e32 v3, v43, v2
	s_waitcnt lgkmcnt(0)
	ds_bpermute_b32 v4, v170, v3
	s_and_saveexec_b64 s[4:5], vcc
	s_cbranch_execz .LBB0_1046
	s_waitcnt lgkmcnt(0)
	v_cvt_pk_bf16_f32 v3, v3, v4
	global_store_dword v[0:1], v3, off offset:64
.LBB0_1046:
	s_or_b64 exec, exec, s[4:5]
	v_mul_f32_e32 v3, v27, v2
	s_waitcnt lgkmcnt(0)
	ds_bpermute_b32 v4, v170, v3
	s_and_saveexec_b64 s[4:5], vcc
	s_cbranch_execz .LBB0_1048
	s_waitcnt lgkmcnt(0)
	v_cvt_pk_bf16_f32 v3, v3, v4
	global_store_dword v[0:1], v3, off offset:128
.LBB0_1048:
	s_or_b64 exec, exec, s[4:5]
	v_mul_f32_e32 v2, v11, v2
	ds_bpermute_b32 v3, v170, v2
	s_and_saveexec_b64 s[4:5], vcc
	s_cbranch_execz .LBB0_1050
	s_waitcnt lgkmcnt(0)
	v_cvt_pk_bf16_f32 v2, v2, v3
	global_store_dword v[0:1], v2, off offset:192
.LBB0_1050:
	s_or_b64 exec, exec, s[4:5]
	v_rcp_f32_e32 v2, v64
	v_lshlrev_b64 v[0:1], 12, v[180:181]
	v_lshl_add_u64 v[0:1], v[80:81], 0, v[0:1]
	s_mov_b64 s[0:1], 0x18000
	s_waitcnt lgkmcnt(0)
	v_mul_f32_e32 v3, v60, v2
	ds_bpermute_b32 v4, v170, v3
	v_lshl_add_u64 v[0:1], v[0:1], 0, s[0:1]
	s_and_saveexec_b64 s[4:5], vcc
	s_cbranch_execz .LBB0_1052
	s_waitcnt lgkmcnt(0)
	v_cvt_pk_bf16_f32 v3, v3, v4
	global_store_dword v[0:1], v3, off
.LBB0_1052:
	s_or_b64 exec, exec, s[4:5]
	v_mul_f32_e32 v3, v44, v2
	s_waitcnt lgkmcnt(0)
	ds_bpermute_b32 v4, v170, v3
	s_and_saveexec_b64 s[4:5], vcc
	s_cbranch_execz .LBB0_1054
	s_waitcnt lgkmcnt(0)
	v_cvt_pk_bf16_f32 v3, v3, v4
	global_store_dword v[0:1], v3, off offset:64
.LBB0_1054:
	s_or_b64 exec, exec, s[4:5]
	v_mul_f32_e32 v3, v28, v2
	s_waitcnt lgkmcnt(0)
	ds_bpermute_b32 v4, v170, v3
	s_and_saveexec_b64 s[4:5], vcc
	s_cbranch_execz .LBB0_1056
	s_waitcnt lgkmcnt(0)
	v_cvt_pk_bf16_f32 v3, v3, v4
	global_store_dword v[0:1], v3, off offset:128
.LBB0_1056:
	s_or_b64 exec, exec, s[4:5]
	v_mul_f32_e32 v2, v12, v2
	ds_bpermute_b32 v3, v170, v2
	s_and_saveexec_b64 s[4:5], vcc
	s_cbranch_execz .LBB0_1058
	s_waitcnt lgkmcnt(0)
	v_cvt_pk_bf16_f32 v2, v2, v3
	global_store_dword v[0:1], v2, off offset:192
.LBB0_1058:
	s_or_b64 exec, exec, s[4:5]
	v_rcp_f32_e32 v2, v65
	v_lshlrev_b64 v[0:1], 12, v[180:181]
	v_lshl_add_u64 v[0:1], v[80:81], 0, v[0:1]
	s_mov_b64 s[0:1], 0x19000
	s_waitcnt lgkmcnt(0)
	v_mul_f32_e32 v3, v61, v2
	ds_bpermute_b32 v4, v170, v3
	v_lshl_add_u64 v[0:1], v[0:1], 0, s[0:1]
	s_and_saveexec_b64 s[4:5], vcc
	s_cbranch_execz .LBB0_1060
	s_waitcnt lgkmcnt(0)
	v_cvt_pk_bf16_f32 v3, v3, v4
	global_store_dword v[0:1], v3, off
.LBB0_1060:
	s_or_b64 exec, exec, s[4:5]
	v_mul_f32_e32 v3, v45, v2
	s_waitcnt lgkmcnt(0)
	ds_bpermute_b32 v4, v170, v3
	s_and_saveexec_b64 s[4:5], vcc
	s_cbranch_execz .LBB0_1062
	s_waitcnt lgkmcnt(0)
	v_cvt_pk_bf16_f32 v3, v3, v4
	global_store_dword v[0:1], v3, off offset:64
.LBB0_1062:
	s_or_b64 exec, exec, s[4:5]
	v_mul_f32_e32 v3, v29, v2
	s_waitcnt lgkmcnt(0)
	ds_bpermute_b32 v4, v170, v3
	s_and_saveexec_b64 s[4:5], vcc
	s_cbranch_execz .LBB0_1064
	s_waitcnt lgkmcnt(0)
	v_cvt_pk_bf16_f32 v3, v3, v4
	global_store_dword v[0:1], v3, off offset:128
.LBB0_1064:
	s_or_b64 exec, exec, s[4:5]
	v_mul_f32_e32 v2, v13, v2
	ds_bpermute_b32 v3, v170, v2
	s_and_saveexec_b64 s[4:5], vcc
	s_cbranch_execz .LBB0_1066
	s_waitcnt lgkmcnt(0)
	v_cvt_pk_bf16_f32 v2, v2, v3
	global_store_dword v[0:1], v2, off offset:192
.LBB0_1066:
	s_or_b64 exec, exec, s[4:5]
	v_rcp_f32_e32 v2, v66
	v_lshlrev_b64 v[0:1], 12, v[180:181]
	v_lshl_add_u64 v[0:1], v[80:81], 0, v[0:1]
	v_lshl_add_u64 v[0:1], v[0:1], 0, s[66:67]
	s_waitcnt lgkmcnt(0)
	v_mul_f32_e32 v3, v62, v2
	ds_bpermute_b32 v4, v170, v3
	s_and_saveexec_b64 s[4:5], vcc
	s_cbranch_execz .LBB0_1068
	s_waitcnt lgkmcnt(0)
	v_cvt_pk_bf16_f32 v3, v3, v4
	global_store_dword v[0:1], v3, off
.LBB0_1068:
	s_or_b64 exec, exec, s[4:5]
	v_mul_f32_e32 v3, v46, v2
	s_waitcnt lgkmcnt(0)
	ds_bpermute_b32 v4, v170, v3
	s_and_saveexec_b64 s[4:5], vcc
	s_cbranch_execz .LBB0_1070
	s_waitcnt lgkmcnt(0)
	v_cvt_pk_bf16_f32 v3, v3, v4
	global_store_dword v[0:1], v3, off offset:64
.LBB0_1070:
	s_or_b64 exec, exec, s[4:5]
	v_mul_f32_e32 v3, v30, v2
	s_waitcnt lgkmcnt(0)
	ds_bpermute_b32 v4, v170, v3
	s_and_saveexec_b64 s[4:5], vcc
	s_cbranch_execz .LBB0_1072
	s_waitcnt lgkmcnt(0)
	v_cvt_pk_bf16_f32 v3, v3, v4
	global_store_dword v[0:1], v3, off offset:128
.LBB0_1072:
	s_or_b64 exec, exec, s[4:5]
	v_mul_f32_e32 v2, v14, v2
	ds_bpermute_b32 v3, v170, v2
	s_and_saveexec_b64 s[4:5], vcc
	s_cbranch_execz .LBB0_1074
	s_waitcnt lgkmcnt(0)
	v_cvt_pk_bf16_f32 v2, v2, v3
	global_store_dword v[0:1], v2, off offset:192
.LBB0_1074:
	s_or_b64 exec, exec, s[4:5]
	v_rcp_f32_e32 v2, v67
	v_lshlrev_b64 v[0:1], 12, v[180:181]
	v_lshl_add_u64 v[0:1], v[80:81], 0, v[0:1]
	v_lshl_add_u64 v[0:1], v[0:1], 0, s[68:69]
	s_waitcnt lgkmcnt(0)
	v_mul_f32_e32 v3, v63, v2
	ds_bpermute_b32 v4, v170, v3
	s_and_saveexec_b64 s[4:5], vcc
	s_cbranch_execz .LBB0_1076
	s_waitcnt lgkmcnt(0)
	v_cvt_pk_bf16_f32 v3, v3, v4
	global_store_dword v[0:1], v3, off
.LBB0_1076:
	s_or_b64 exec, exec, s[4:5]
	v_mul_f32_e32 v3, v47, v2
	s_waitcnt lgkmcnt(0)
	ds_bpermute_b32 v4, v170, v3
	s_and_saveexec_b64 s[4:5], vcc
	s_cbranch_execz .LBB0_1078
	s_waitcnt lgkmcnt(0)
	v_cvt_pk_bf16_f32 v3, v3, v4
	global_store_dword v[0:1], v3, off offset:64
.LBB0_1078:
	s_or_b64 exec, exec, s[4:5]
	v_mul_f32_e32 v3, v31, v2
	s_waitcnt lgkmcnt(0)
	ds_bpermute_b32 v4, v170, v3
	s_and_saveexec_b64 s[4:5], vcc
	s_cbranch_execz .LBB0_1080
	s_waitcnt lgkmcnt(0)
	v_cvt_pk_bf16_f32 v3, v3, v4
	global_store_dword v[0:1], v3, off offset:128
.LBB0_1080:
	s_or_b64 exec, exec, s[4:5]
	v_mul_f32_e32 v2, v15, v2
	ds_bpermute_b32 v3, v170, v2
	s_and_saveexec_b64 s[4:5], vcc
	s_cbranch_execz .LBB0_853
	s_waitcnt lgkmcnt(0)
	v_cvt_pk_bf16_f32 v2, v2, v3
	global_store_dword v[0:1], v2, off offset:192
	s_branch .LBB0_853

.LBB0_1086:
	s_cmpk_lt_i32 s31, 0xa0
	s_cbranch_scc0 .LBB0_838
	v_readlane_b32 s0, v254, 8
	v_readlane_b32 s1, v254, 9
	s_and_b64 vcc, exec, s[0:1]
	s_cbranch_vccnz .LBB0_1102
	v_mbcnt_lo_u32_b32 v0, -1, 0
	v_mbcnt_hi_u32_b32 v0, -1, v0
	s_nop 0
	v_cmp_eq_u32_e32 vcc, 0, v0
	s_and_saveexec_b64 s[4:5], vcc
	s_cbranch_execz .LBB0_1101
	v_mov_b64_e32 v[0:1], s[12:13]
	global_load_dword v0, v[0:1], off sc1
	s_waitcnt vmcnt(0) lgkmcnt(0)
	v_cmp_gt_u32_e32 vcc, 16, v0
	s_and_saveexec_b64 s[6:7], vcc
	s_cbranch_execz .LBB0_1100
	s_mov_b32 s0, 1
	s_mov_b64 s[46:47], 0
	s_branch .LBB0_1092

.LBB0_1092:
	s_and_b32 s1, s0, 0xff
	s_mov_b64 s[70:71], -1
	s_cmp_lg_u32 s1, 0
	s_mov_b64 s[16:17], -1
	s_sleep 1
	s_cbranch_scc1 .LBB0_1096
	v_mov_b64_e32 v[0:1], s[22:23]
	global_load_dword v0, v[0:1], off sc1
	s_mov_b64 s[16:17], 0
	s_mov_b64 s[72:73], -1
	s_waitcnt vmcnt(0) lgkmcnt(0)
	v_cmp_eq_u32_e32 vcc, 0, v0
	s_and_saveexec_b64 s[74:75], vcc
	s_cmp_lt_u32 s0, 0x40001
	s_cselect_b64 s[14:15], -1, 0
	s_xor_b64 s[72:73], exec, -1
	s_and_b64 s[16:17], s[14:15], exec
	s_or_b64 exec, exec, s[74:75]
.LBB0_1096:
	s_andn2_b64 s[14:15], s[52:53], exec
	s_and_b64 s[24:25], s[72:73], exec
	s_or_b64 s[52:53], s[14:15], s[24:25]
	s_and_saveexec_b64 s[72:73], s[16:17]
	s_cbranch_execz .LBB0_1091
	v_mov_b64_e32 v[0:1], s[12:13]
	global_load_dword v0, v[0:1], off sc1
	s_add_i32 s0, s0, 1
	s_or_b64 s[52:53], s[52:53], exec
	s_waitcnt vmcnt(0) lgkmcnt(0)
	v_cmp_lt_u32_e32 vcc, 15, v0
	s_orn2_b64 s[70:71], vcc, exec
	s_branch .LBB0_1091
.LBB0_1098:
	s_or_b64 exec, exec, s[46:47]
	s_xor_b64 s[0:1], s[50:51], -1
	s_and_saveexec_b64 s[14:15], s[0:1]
	s_xor_b64 s[14:15], exec, s[14:15]
	s_cbranch_execz .LBB0_1100
	v_mov_b64_e32 v[0:1], s[22:23]
	global_atomic_add v[0:1], v252, off

.LBB0_1102:
	s_add_i32 s0, s31, 0xa0
	s_and_b32 s0, s0, 0xff
	s_ashr_i32 s4, s0, 6
	s_bfe_u32 s1, s0, 0x20004
	s_ashr_i32 s5, s4, 31
	s_lshl_b32 s0, s1, 14
	s_lshl_b64 s[50:51], s[4:5], 12
	s_or_b32 s0, s0, 0x70000
	s_add_u32 s0, s50, s0
	v_readlane_b32 s3, v255, 28
	s_addc_u32 s7, s51, 0
	s_and_b32 s70, s3, 0xf00
	s_lshl_b32 s3, s4, 8
	s_or_b32 s6, s0, s70
	s_lshl_b32 s0, s1, 10
	s_ashr_i32 s14, s3, 31
	s_add_u32 s4, s0, s3
	s_addc_u32 s5, 0, s14
	s_lshl_b64 s[4:5], s[4:5], 8
	s_add_u32 s72, s82, s4
	s_addc_u32 s73, s26, s5
	s_bitset1_b32 s0, 12
	s_add_u32 s4, s0, s3
	s_addc_u32 s5, 0, s14
	s_lshl_b64 s[4:5], s[4:5], 8
	s_add_u32 s46, s82, s4
	s_addc_u32 s47, s26, s5
	s_lshl_b64 s[4:5], s[6:7], 8
	s_barrier
	s_add_u32 s4, s59, s4
	v_mbcnt_lo_u32_b32 v4, -1, 0
	v_mbcnt_hi_u32_b32 v4, -1, v4
	s_addc_u32 s5, s18, s5
	v_and_or_b32 v130, v4, 31, s58
	v_ashrrev_i32_e32 v2, 2, v4
	v_lshlrev_b64 v[0:1], 8, v[130:131]
	v_and_b32_e32 v2, -8, v2
	v_ashrrev_i32_e32 v3, 31, v2
	v_lshl_add_u64 v[0:1], s[4:5], 0, v[0:1]
	v_lshl_add_u64 v[0:1], v[2:3], 1, v[0:1]
	v_readlane_b32 s0, v254, 7
	global_load_dwordx4 v[144:147], v[0:1], off
	global_load_dwordx4 v[140:143], v[0:1], off offset:32
	global_load_dwordx4 v[136:139], v[0:1], off offset:64
	global_load_dwordx4 v[132:135], v[0:1], off offset:96
	global_load_dwordx4 v[124:127], v[0:1], off offset:128
	global_load_dwordx4 v[120:123], v[0:1], off offset:160
	global_load_dwordx4 v[116:119], v[0:1], off offset:192
	global_load_dwordx4 v[112:115], v[0:1], off offset:224
	v_add_u32_e32 v1, s0, v4
	v_ashrrev_i32_e32 v0, 4, v1
	v_lshlrev_b32_e32 v2, 4, v4
	v_and_b32_e32 v1, 0x70, v1
	s_movk_i32 s3, 0xf0
	v_bitop3_b32 v17, v2, v1, s3 bitop3:0x6c
	v_ashrrev_i32_e32 v1, 31, v0
	v_lshlrev_b64 v[8:9], 8, v[0:1]
	s_mov_b64 s[4:5], 0x2000
	v_lshlrev_b32_e32 v16, 8, v0
	v_and_b32_e32 v130, 0xf0, v2
	v_lshl_add_u64 v[0:1], s[46:47], 0, v[8:9]
	v_lshl_add_u64 v[12:13], v[8:9], 0, s[4:5]
	v_lshl_add_u64 v[8:9], s[72:73], 0, v[8:9]
	v_lshl_add_u64 v[4:5], s[46:47], 0, v[12:13]
	v_lshl_add_u64 v[8:9], v[8:9], 0, v[130:131]
	v_lshl_add_u64 v[12:13], s[72:73], 0, v[12:13]
	global_load_dwordx4 v[8:11], v[8:9], off
	v_lshl_add_u64 v[12:13], v[12:13], 0, v[130:131]
	v_lshl_add_u64 v[0:1], v[0:1], 0, v[130:131]
	v_lshl_add_u64 v[4:5], v[4:5], 0, v[130:131]
	global_load_dwordx4 v[12:15], v[12:13], off
	v_add3_u32 v16, 0, v16, v17
	global_load_dwordx4 v[0:3], v[0:1], off
	s_nop 0
	global_load_dwordx4 v[4:7], v[4:5], off
	s_waitcnt vmcnt(0)
	s_waitcnt vmcnt(0) lgkmcnt(0)
	ds_write_b128 v16, v[8:11] offset:32768
	ds_write_b128 v16, v[12:15] offset:40960
	s_waitcnt lgkmcnt(0)
	s_barrier
	v_mbcnt_lo_u32_b32 v165, -1, 0
	v_mbcnt_hi_u32_b32 v165, -1, v165
	s_nop 0
	v_add_u32_e32 v49, s0, v165
	s_movk_i32 s0, 0xff
	v_cmp_lt_i32_e32 vcc, s0, v49
	v_lshlrev_b32_e32 v48, 3, v165
	s_and_saveexec_b64 s[4:5], vcc
	s_xor_b64 s[4:5], exec, s[4:5]
	v_lshlrev_b32_e32 v48, 3, v165
	s_andn2_saveexec_b64 s[4:5], s[4:5]
	s_cbranch_execz .LBB0_1108
	v_readlane_b32 s0, v255, 27
	s_mov_b64 s[6:7], 0
	s_nop 0
	v_add_u32_e32 v8, s0, v165
	v_readlane_b32 s0, v254, 24
	s_nop 1
	v_add_u32_e32 v9, s0, v48

.LBB0_1108:
	s_or_b64 exec, exec, s[4:5]
	v_ashrrev_i32_e32 v166, 4, v49
	v_and_b32_e32 v10, 0xfffff0, v166
	v_lshlrev_b32_e32 v11, 1, v166
	v_and_or_b32 v10, v11, 8, v10
	v_lshrrev_b32_e32 v11, 1, v166
	v_and_b32_e32 v13, 3, v166
	v_add_u32_e32 v168, 32, v166
	v_and_or_b32 v11, v11, 4, v13
	v_and_b32_e32 v13, 0xfffff0, v168
	v_lshlrev_b32_e32 v14, 1, v168
	v_and_or_b32 v13, v14, 8, v13
	v_and_b32_e32 v9, 0x78, v48
	v_lshrrev_b32_e32 v10, 1, v10
	v_bfe_u32 v12, v48, 5, 2
	v_lshrrev_b32_e32 v13, 1, v13
	v_and_b32_e32 v171, 31, v165
	v_ashrrev_i32_e32 v51, 5, v165
	v_readlane_b32 s0, v255, 18
	v_or_b32_e32 v10, v10, v12
	v_lshlrev_b32_e32 v130, 1, v9
	v_or_b32_e32 v12, v13, v12
	v_or_b32_e32 v8, s0, v171
	v_lshlrev_b32_e32 v164, 2, v51
	v_lshlrev_b32_e32 v50, 3, v171
	v_lshlrev_b32_e32 v10, 9, v10
	v_lshlrev_b32_e32 v11, 6, v11
	v_and_b32_e32 v9, 48, v130
	v_lshlrev_b32_e32 v12, 9, v12
	v_sub_u32_e32 v173, v8, v164
	v_add_u32_e32 v8, 0, v50
	v_or3_b32 v10, v10, v11, v9
	v_or3_b32 v9, v12, v11, v9
	s_mov_b32 s71, s11
	v_add_u32_e32 v8, 0x10800, v8
	v_add_u32_e32 v185, 0, v10
	v_add_u32_e32 v186, 0, v9
	s_waitcnt lgkmcnt(0)
	s_barrier
	ds_write_b128 v185, v[0:3]
	ds_write_b128 v186, v[4:7]
	v_ashrrev_i32_e32 v167, 31, v166
	v_lshlrev_b64 v[0:1], 8, v[166:167]
	s_mov_b64 s[4:5], 0x4000
	v_lshl_add_u64 v[2:3], v[0:1], 0, s[4:5]
	s_mov_b64 s[4:5], 0x6000
	v_lshl_add_u64 v[4:5], s[46:47], 0, v[2:3]
	v_lshl_add_u64 v[0:1], v[0:1], 0, s[4:5]
	v_lshl_add_u64 v[2:3], s[72:73], 0, v[2:3]
	v_lshl_add_u64 v[4:5], v[4:5], 0, v[130:131]
	v_lshl_add_u64 v[6:7], s[46:47], 0, v[0:1]
	v_lshl_add_u64 v[2:3], v[2:3], 0, v[130:131]
	v_lshl_add_u64 v[0:1], s[72:73], 0, v[0:1]
	v_lshl_add_u64 v[6:7], v[6:7], 0, v[130:131]
	global_load_dwordx4 v[32:35], v[4:5], off
	global_load_dwordx4 v[36:39], v[6:7], off
	v_lshl_add_u64 v[0:1], v[0:1], 0, v[130:131]
	global_load_dwordx4 v[40:43], v[2:3], off
	global_load_dwordx4 v[44:47], v[0:1], off
	ds_read2_b64 v[0:3], v8 offset1:32
	v_mov_b64_e32 v[4:5], s[8:9]
	v_mov_b64_e32 v[6:7], s[10:11]
	v_cmp_gt_u32_e64 s[6:7], 32, v165
	s_waitcnt lgkmcnt(0)
	v_or_b32_e32 v5, 1.0, v1
	v_mov_b32_e32 v4, v0
	v_cndmask_b32_e64 v128, 0, v204, s[6:7]
	v_cndmask_b32_e64 v129, 0, v191, s[6:7]
	v_mov_b64_e32 v[8:9], v[128:129]
	v_mov_b64_e32 v[10:11], v[130:131]
	v_mov_b32_e32 v10, s11
	v_or_b32_e32 v0, 1.0, v3
	s_nop 0
	v_mfma_f32_32x32x16_bf16 v[16:31], v[4:7], v[8:11], 0
	v_mov_b64_e32 v[4:5], s[8:9]
	v_mov_b64_e32 v[6:7], s[10:11]
	v_mov_b32_e32 v4, v2
	v_mov_b32_e32 v5, v0
	s_nop 1
	v_mfma_f32_32x32x16_bf16 v[0:15], v[4:7], v[8:11], 0
	s_setprio 1
	v_lshlrev_b32_e32 v57, 4, v51
	v_lshlrev_b32_e32 v51, 4, v165
	v_and_b32_e32 v58, 0x70, v51
	v_lshlrev_b32_e32 v56, 8, v171
	v_xad_u32 v52, v58, v57, 0
	v_add_u32_e32 v181, v52, v56
	ds_read_b128 v[52:55], v181 offset:32768
	v_add_u32_e32 v59, 32, v57
	v_xad_u32 v59, v59, v58, 0
	v_add_u32_e32 v180, v59, v56
	v_add_u32_e32 v59, 64, v57
	v_xad_u32 v59, v59, v58, 0
	v_add_u32_e32 v179, v59, v56
	s_waitcnt lgkmcnt(0)
	v_mfma_f32_32x32x16_bf16 v[16:31], v[52:55], v[144:147], v[16:31]
	ds_read_b128 v[52:55], v181 offset:40960
	v_add_u32_e32 v57, 0x60, v57
	v_xad_u32 v57, v57, v58, 0
	v_add_u32_e32 v169, v57, v56
	s_waitcnt lgkmcnt(0)
	v_mfma_f32_32x32x16_bf16 v[0:15], v[52:55], v[144:147], v[0:15]
	ds_read_b128 v[52:55], v180 offset:32768
	s_waitcnt lgkmcnt(0)
	v_mfma_f32_32x32x16_bf16 v[16:31], v[52:55], v[140:143], v[16:31]
	ds_read_b128 v[52:55], v180 offset:40960
	s_waitcnt lgkmcnt(0)
	v_mfma_f32_32x32x16_bf16 v[0:15], v[52:55], v[140:143], v[0:15]
	ds_read_b128 v[52:55], v179 offset:32768
	s_waitcnt lgkmcnt(0)
	v_mfma_f32_32x32x16_bf16 v[16:31], v[52:55], v[136:139], v[16:31]
	ds_read_b128 v[52:55], v179 offset:40960
	s_waitcnt lgkmcnt(0)
	v_mfma_f32_32x32x16_bf16 v[0:15], v[52:55], v[136:139], v[0:15]
	ds_read_b128 v[52:55], v169 offset:32768
	s_waitcnt lgkmcnt(0)
	v_mfma_f32_32x32x16_bf16 v[16:31], v[52:55], v[132:135], v[16:31]
	ds_read_b128 v[52:55], v169 offset:40960
	s_waitcnt lgkmcnt(0)
	v_mfma_f32_32x32x16_bf16 v[0:15], v[52:55], v[132:135], v[0:15]
	ds_read_b128 v[52:55], v181 offset:32896
	s_waitcnt lgkmcnt(0)
	v_mfma_f32_32x32x16_bf16 v[16:31], v[52:55], v[124:127], v[16:31]
	ds_read_b128 v[52:55], v181 offset:41088
	s_waitcnt lgkmcnt(0)
	v_mfma_f32_32x32x16_bf16 v[0:15], v[52:55], v[124:127], v[0:15]
	ds_read_b128 v[52:55], v180 offset:32896
	s_waitcnt lgkmcnt(0)
	v_mfma_f32_32x32x16_bf16 v[16:31], v[52:55], v[120:123], v[16:31]
	ds_read_b128 v[52:55], v180 offset:41088
	s_waitcnt lgkmcnt(0)
	v_mfma_f32_32x32x16_bf16 v[0:15], v[52:55], v[120:123], v[0:15]
	ds_read_b128 v[52:55], v179 offset:32896
	s_waitcnt lgkmcnt(0)
	v_mfma_f32_32x32x16_bf16 v[16:31], v[52:55], v[116:119], v[16:31]
	ds_read_b128 v[52:55], v179 offset:41088
	s_waitcnt lgkmcnt(0)
	v_mfma_f32_32x32x16_bf16 v[0:15], v[52:55], v[116:119], v[0:15]
	ds_read_b128 v[52:55], v169 offset:32896
	s_waitcnt lgkmcnt(0)
	v_mfma_f32_32x32x16_bf16 v[16:31], v[52:55], v[112:115], v[16:31]
	ds_read_b128 v[52:55], v169 offset:41088
	s_waitcnt lgkmcnt(0)
	v_mfma_f32_32x32x16_bf16 v[0:15], v[52:55], v[112:115], v[0:15]
	s_setprio 0
	v_readlane_b32 s4, v255, 19
	v_readlane_b32 s5, v255, 20
	s_andn2_b64 vcc, exec, s[4:5]
	s_cbranch_vccnz .LBB0_1110
	s_mov_b32 s0, 0x100000
	v_cmp_gt_u32_e32 vcc, s0, v173
	v_subrev_u32_e32 v52, 32, v173
	s_nop 0
	v_cndmask_b32_e32 v16, v196, v16, vcc
	v_cmp_gt_u32_e32 vcc, s0, v52
	v_add_u32_e32 v52, -1, v173
	s_nop 0
	v_cndmask_b32_e32 v0, v196, v0, vcc
	v_cmp_gt_u32_e32 vcc, s0, v52
	v_subrev_u32_e32 v52, 33, v173
	s_nop 0
	v_cndmask_b32_e32 v17, v196, v17, vcc
	v_cmp_gt_u32_e32 vcc, s0, v52
	v_add_u32_e32 v52, -2, v173
	s_nop 0
	v_cndmask_b32_e32 v1, v196, v1, vcc
	v_cmp_gt_u32_e32 vcc, s0, v52
	v_subrev_u32_e32 v52, 34, v173
	s_nop 0
	v_cndmask_b32_e32 v18, v196, v18, vcc
	v_cmp_gt_u32_e32 vcc, s0, v52
	v_add_u32_e32 v52, -3, v173
	s_nop 0
	v_cndmask_b32_e32 v2, v196, v2, vcc
	v_cmp_gt_u32_e32 vcc, s0, v52
	v_subrev_u32_e32 v52, 35, v173
	s_nop 0
	v_cndmask_b32_e32 v19, v196, v19, vcc
	v_cmp_gt_u32_e32 vcc, s0, v52
	v_add_u32_e32 v52, -8, v173
	s_nop 0
	v_cndmask_b32_e32 v3, v196, v3, vcc
	v_cmp_gt_u32_e32 vcc, s0, v52
	v_subrev_u32_e32 v52, 40, v173
	s_nop 0
	v_cndmask_b32_e32 v20, v196, v20, vcc
	v_cmp_gt_u32_e32 vcc, s0, v52
	v_add_u32_e32 v52, -9, v173
	s_nop 0
	v_cndmask_b32_e32 v4, v196, v4, vcc
	v_cmp_gt_u32_e32 vcc, s0, v52
	v_subrev_u32_e32 v52, 41, v173
	s_nop 0
	v_cndmask_b32_e32 v21, v196, v21, vcc
	v_cmp_gt_u32_e32 vcc, s0, v52
	v_add_u32_e32 v52, -10, v173
	s_nop 0
	v_cndmask_b32_e32 v5, v196, v5, vcc
	v_cmp_gt_u32_e32 vcc, s0, v52
	v_subrev_u32_e32 v52, 42, v173
	s_nop 0
	v_cndmask_b32_e32 v22, v196, v22, vcc
	v_cmp_gt_u32_e32 vcc, s0, v52
	v_add_u32_e32 v52, -11, v173
	s_nop 0
	v_cndmask_b32_e32 v6, v196, v6, vcc
	v_cmp_gt_u32_e32 vcc, s0, v52
	v_subrev_u32_e32 v52, 43, v173
	s_nop 0
	v_cndmask_b32_e32 v23, v196, v23, vcc
	v_cmp_gt_u32_e32 vcc, s0, v52
	v_add_u32_e32 v52, -16, v173
	s_nop 0
	v_cndmask_b32_e32 v7, v196, v7, vcc
	v_cmp_gt_u32_e32 vcc, s0, v52
	v_subrev_u32_e32 v52, 48, v173
	s_nop 0
	v_cndmask_b32_e32 v24, v196, v24, vcc
	v_cmp_gt_u32_e32 vcc, s0, v52
	v_subrev_u32_e32 v52, 17, v173
	s_nop 0
	v_cndmask_b32_e32 v8, v196, v8, vcc
	v_cmp_gt_u32_e32 vcc, s0, v52
	v_subrev_u32_e32 v52, 49, v173
	s_nop 0
	v_cndmask_b32_e32 v25, v196, v25, vcc
	v_cmp_gt_u32_e32 vcc, s0, v52
	v_subrev_u32_e32 v52, 18, v173
	s_nop 0
	v_cndmask_b32_e32 v9, v196, v9, vcc
	v_cmp_gt_u32_e32 vcc, s0, v52
	v_subrev_u32_e32 v52, 50, v173
	s_nop 0
	v_cndmask_b32_e32 v26, v196, v26, vcc
	v_cmp_gt_u32_e32 vcc, s0, v52
	v_subrev_u32_e32 v52, 19, v173
	s_nop 0
	v_cndmask_b32_e32 v10, v196, v10, vcc
	v_cmp_gt_u32_e32 vcc, s0, v52
	v_subrev_u32_e32 v52, 51, v173
	s_nop 0
	v_cndmask_b32_e32 v27, v196, v27, vcc
	v_cmp_gt_u32_e32 vcc, s0, v52
	v_subrev_u32_e32 v52, 24, v173
	s_nop 0
	v_cndmask_b32_e32 v11, v196, v11, vcc
	v_cmp_gt_u32_e32 vcc, s0, v52
	v_subrev_u32_e32 v52, 56, v173
	s_nop 0
	v_cndmask_b32_e32 v28, v196, v28, vcc
	v_cmp_gt_u32_e32 vcc, s0, v52
	v_subrev_u32_e32 v52, 25, v173
	s_nop 0
	v_cndmask_b32_e32 v12, v196, v12, vcc
	v_cmp_gt_u32_e32 vcc, s0, v52
	v_subrev_u32_e32 v52, 57, v173
	s_nop 0
	v_cndmask_b32_e32 v29, v196, v29, vcc
	v_cmp_gt_u32_e32 vcc, s0, v52
	v_subrev_u32_e32 v52, 26, v173
	s_nop 0
	v_cndmask_b32_e32 v13, v196, v13, vcc
	v_cmp_gt_u32_e32 vcc, s0, v52
	v_subrev_u32_e32 v52, 58, v173
	s_nop 0
	v_cndmask_b32_e32 v30, v196, v30, vcc
	v_cmp_gt_u32_e32 vcc, s0, v52
	v_subrev_u32_e32 v52, 27, v173
	s_nop 0
	v_cndmask_b32_e32 v14, v196, v14, vcc
	v_cmp_gt_u32_e32 vcc, s0, v52
	v_subrev_u32_e32 v52, 59, v173
	s_nop 0
	v_cndmask_b32_e32 v31, v196, v31, vcc
	v_cmp_gt_u32_e32 vcc, s0, v52
	s_nop 1
	v_cndmask_b32_e32 v15, v196, v15, vcc

.LBB0_1112:
	v_lshlrev_b32_e32 v52, 8, v166
	v_and_b32_e32 v49, 0x70, v49
	v_bitop3_b32 v49, v130, v52, v49 bitop3:0xde
	v_and_b32_e32 v51, 0xc0, v51
	v_lshlrev_b32_e32 v52, 1, v165
	v_and_or_b32 v51, v48, 24, v51
	v_and_b32_e32 v52, 32, v52
	v_and_b32_e32 v48, 0x100, v48
	s_cmp_lg_u32 0, -1
	v_or3_b32 v48, v51, v52, v48
	s_cselect_b32 s0, 0, 0
	v_add_u32_e32 v175, s0, v48
	v_exp_f32_e32 v48, v16
	v_exp_f32_e32 v51, v17
	v_exp_f32_e32 v52, v18
	v_exp_f32_e32 v53, v19
	v_exp_f32_e32 v54, v20
	v_exp_f32_e32 v55, v21
	v_exp_f32_e32 v56, v22
	v_exp_f32_e32 v57, v23
	v_exp_f32_e32 v58, v24
	v_exp_f32_e32 v59, v25
	v_exp_f32_e32 v60, v26
	v_exp_f32_e32 v61, v27
	v_exp_f32_e32 v62, v28
	v_exp_f32_e32 v63, v29
	s_waitcnt vmcnt(0)
	v_add_u32_e32 v174, 0, v49
	v_lshl_add_u64 v[148:149], s[46:47], 0, v[130:131]
	v_lshl_add_u64 v[156:157], s[72:73], 0, v[130:131]
	v_exp_f32_e32 v153, v30
	v_exp_f32_e32 v154, v31
	s_waitcnt vmcnt(0)
	ds_write_b128 v185, v[32:35] offset:16384
	ds_write_b128 v186, v[36:39] offset:16384
	ds_write_b128 v174, v[40:43] offset:49152
	ds_write_b128 v174, v[44:47] offset:57344
	s_waitcnt lgkmcnt(0)
	s_barrier
	v_lshlrev_b64 v[16:17], 8, v[166:167]
	v_lshl_add_u64 v[18:19], v[16:17], 0, s[34:35]
	v_lshl_add_u64 v[20:21], v[148:149], 0, v[18:19]
	v_lshl_add_u64 v[16:17], v[16:17], 0, s[54:55]
	v_lshl_add_u64 v[18:19], v[156:157], 0, v[18:19]
	v_lshl_add_u64 v[22:23], v[148:149], 0, v[16:17]
	global_load_dwordx4 v[96:99], v[20:21], off
	global_load_dwordx4 v[100:103], v[22:23], off
	v_lshl_add_u64 v[16:17], v[156:157], 0, v[16:17]
	global_load_dwordx4 v[104:107], v[18:19], off
	global_load_dwordx4 v[108:111], v[16:17], off
	s_add_i32 s0, 0, 0x10800
	v_add_u32_e32 v198, s0, v50
	ds_read2_b64 v[16:19], v198 offset0:64 offset1:96
	v_mov_b64_e32 v[22:23], s[10:11]
	v_mov_b64_e32 v[26:27], s[10:11]
	v_mov_b64_e32 v[20:21], s[8:9]
	v_mov_b64_e32 v[24:25], s[8:9]
	s_waitcnt lgkmcnt(0)
	v_or_b32_e32 v21, 1.0, v17
	v_mov_b32_e32 v20, v16
	v_or_b32_e32 v25, 1.0, v19
	v_mov_b32_e32 v24, v18
	v_mov_b64_e32 v[28:29], v[128:129]
	v_cndmask_b32_e64 v16, 0, v197, s[6:7]
	v_mov_b64_e32 v[30:31], v[130:131]
	v_mov_b32_e32 v30, v16
	s_nop 1
	v_mfma_f32_32x32x16_bf16 v[64:79], v[20:23], v[28:31], 0
	v_mfma_f32_32x32x16_bf16 v[80:95], v[24:27], v[28:31], 0
	s_setprio 1
	ds_read_b128 v[16:19], v181 offset:49152
	s_waitcnt lgkmcnt(0)
	v_mfma_f32_32x32x16_bf16 v[64:79], v[16:19], v[144:147], v[64:79]
	ds_read_b128 v[16:19], v181 offset:57344
	s_waitcnt lgkmcnt(0)
	v_mfma_f32_32x32x16_bf16 v[80:95], v[16:19], v[144:147], v[80:95]
	ds_read_b128 v[16:19], v180 offset:49152
	s_waitcnt lgkmcnt(0)
	v_mfma_f32_32x32x16_bf16 v[64:79], v[16:19], v[140:143], v[64:79]
	ds_read_b128 v[16:19], v180 offset:57344
	s_waitcnt lgkmcnt(0)
	v_mfma_f32_32x32x16_bf16 v[80:95], v[16:19], v[140:143], v[80:95]
	ds_read_b128 v[16:19], v179 offset:49152
	s_waitcnt lgkmcnt(0)
	v_mfma_f32_32x32x16_bf16 v[64:79], v[16:19], v[136:139], v[64:79]
	ds_read_b128 v[16:19], v179 offset:57344
	s_waitcnt lgkmcnt(0)
	v_mfma_f32_32x32x16_bf16 v[80:95], v[16:19], v[136:139], v[80:95]
	ds_read_b128 v[16:19], v169 offset:49152
	s_waitcnt lgkmcnt(0)
	v_mfma_f32_32x32x16_bf16 v[64:79], v[16:19], v[132:135], v[64:79]
	ds_read_b128 v[16:19], v169 offset:57344
	s_waitcnt lgkmcnt(0)
	v_mfma_f32_32x32x16_bf16 v[80:95], v[16:19], v[132:135], v[80:95]
	ds_read_b128 v[16:19], v181 offset:49280
	s_waitcnt lgkmcnt(0)
	v_mfma_f32_32x32x16_bf16 v[64:79], v[16:19], v[124:127], v[64:79]
	ds_read_b128 v[16:19], v181 offset:57472
	s_waitcnt lgkmcnt(0)
	v_mfma_f32_32x32x16_bf16 v[80:95], v[16:19], v[124:127], v[80:95]
	ds_read_b128 v[16:19], v180 offset:49280
	s_waitcnt lgkmcnt(0)
	v_mfma_f32_32x32x16_bf16 v[64:79], v[16:19], v[120:123], v[64:79]
	ds_read_b128 v[16:19], v180 offset:57472
	s_waitcnt lgkmcnt(0)
	v_mfma_f32_32x32x16_bf16 v[80:95], v[16:19], v[120:123], v[80:95]
	ds_read_b128 v[16:19], v179 offset:49280
	s_waitcnt lgkmcnt(0)
	v_mfma_f32_32x32x16_bf16 v[64:79], v[16:19], v[116:119], v[64:79]
	ds_read_b128 v[16:19], v179 offset:57472
	s_waitcnt lgkmcnt(0)
	v_mfma_f32_32x32x16_bf16 v[80:95], v[16:19], v[116:119], v[80:95]
	ds_read_b128 v[16:19], v169 offset:49280
	s_waitcnt lgkmcnt(0)
	v_mfma_f32_32x32x16_bf16 v[64:79], v[16:19], v[112:115], v[64:79]
	ds_read_b128 v[16:19], v169 offset:57472
	s_waitcnt lgkmcnt(0)
	v_mfma_f32_32x32x16_bf16 v[80:95], v[16:19], v[112:115], v[80:95]
	s_setprio 0
	v_add_f32_e32 v16, 0, v48
	v_add_f32_e32 v16, v51, v16
	v_add_f32_e32 v16, v52, v16
	v_add_f32_e32 v16, v53, v16
	v_add_f32_e32 v16, v54, v16
	v_add_f32_e32 v16, v55, v16
	v_add_f32_e32 v16, v56, v16
	v_add_f32_e32 v16, v57, v16
	v_add_f32_e32 v16, v58, v16
	v_add_f32_e32 v16, v59, v16
	v_add_f32_e32 v16, v60, v16
	v_add_f32_e32 v16, v61, v16
	v_exp_f32_e32 v0, v0
	v_add_f32_e32 v16, v62, v16
	v_exp_f32_e32 v1, v1
	v_add_f32_e32 v16, v63, v16
	v_exp_f32_e32 v2, v2
	v_add_f32_e32 v16, v153, v16
	v_exp_f32_e32 v3, v3
	v_add_f32_e32 v16, v154, v16
	v_exp_f32_e32 v4, v4
	v_add_f32_e32 v16, v0, v16
	v_exp_f32_e32 v5, v5
	v_add_f32_e32 v16, v1, v16
	v_exp_f32_e32 v6, v6
	v_add_f32_e32 v16, v2, v16
	v_exp_f32_e32 v7, v7
	v_add_f32_e32 v16, v3, v16
	v_exp_f32_e32 v8, v8
	v_add_f32_e32 v16, v4, v16
	v_exp_f32_e32 v9, v9
	v_add_f32_e32 v16, v5, v16
	v_exp_f32_e32 v10, v10
	v_add_f32_e32 v16, v6, v16
	v_exp_f32_e32 v11, v11
	v_add_f32_e32 v16, v7, v16
	v_exp_f32_e32 v12, v12
	v_add_f32_e32 v16, v8, v16
	v_exp_f32_e32 v13, v13
	v_add_f32_e32 v16, v9, v16
	v_exp_f32_e32 v14, v14
	v_add_f32_e32 v16, v10, v16
	v_exp_f32_e32 v15, v15
	v_add_f32_e32 v16, v11, v16
	v_add_f32_e32 v16, v12, v16
	v_add_f32_e32 v16, v13, v16
	v_add_f32_e32 v16, v14, v16
	v_add_f32_e32 v176, v15, v16
	v_mov_b32_e32 v177, v176
	v_cvt_pk_bf16_f32 v48, v48, v51
	v_cvt_pk_bf16_f32 v49, v52, v53
	v_cvt_pk_bf16_f32 v50, v54, v55
	v_cvt_pk_bf16_f32 v51, v56, v57
	s_nop 1
	v_permlane32_swap_b32_e32 v176, v177
	v_permlane32_swap_b32_e32 v48, v50
	v_permlane32_swap_b32_e32 v49, v51
	v_cvt_pk_bf16_f32 v150, v58, v59
	v_cvt_pk_bf16_f32 v151, v60, v61
	v_cvt_pk_bf16_f32 v152, v62, v63
	v_cvt_pk_bf16_f32 v153, v153, v154
	v_cvt_pk_bf16_f32 v158, v0, v1
	v_cvt_pk_bf16_f32 v159, v2, v3
	v_cvt_pk_bf16_f32 v160, v4, v5
	v_cvt_pk_bf16_f32 v161, v6, v7
	v_cvt_pk_bf16_f32 v192, v8, v9
	v_cvt_pk_bf16_f32 v193, v10, v11
	v_cvt_pk_bf16_f32 v194, v12, v13
	v_cvt_pk_bf16_f32 v195, v14, v15
	s_nop 0
	v_permlane32_swap_b32_e32 v150, v152
	v_permlane32_swap_b32_e32 v151, v153
	v_permlane32_swap_b32_e32 v158, v160
	v_permlane32_swap_b32_e32 v159, v161
	v_permlane32_swap_b32_e32 v192, v194
	v_permlane32_swap_b32_e32 v193, v195
	s_setprio 1
	ds_read_b64_tr_b16 v[0:1], v175 offset:0
	ds_read_b64_tr_b16 v[2:3], v175 offset:0x800
	ds_read_b64_tr_b16 v[16:17], v175 offset:0x1000
	ds_read_b64_tr_b16 v[18:19], v175 offset:0x1800
	ds_read_b64_tr_b16 v[20:21], v175 offset:0x2000
	ds_read_b64_tr_b16 v[22:23], v175 offset:0x2800
	ds_read_b64_tr_b16 v[24:25], v175 offset:0x3000
	ds_read_b64_tr_b16 v[26:27], v175 offset:0x3800
	s_waitcnt lgkmcnt(0)
	s_nop 0
	v_mfma_f32_32x32x16_bf16 v[0:15], v[48:51], v[0:3], 0
	v_mfma_f32_32x32x16_bf16 v[0:15], v[150:153], v[16:19], v[0:15]
	ds_read_b64_tr_b16 v[16:17], v175 offset:0x200
	ds_read_b64_tr_b16 v[18:19], v175 offset:0xa00
	ds_read_b64_tr_b16 v[32:33], v175 offset:0x1200
	ds_read_b64_tr_b16 v[34:35], v175 offset:0x1a00
	ds_read_b64_tr_b16 v[36:37], v175 offset:0x2200
	ds_read_b64_tr_b16 v[38:39], v175 offset:0x2a00
	ds_read_b64_tr_b16 v[40:41], v175 offset:0x3200
	v_mfma_f32_32x32x16_bf16 v[0:15], v[158:161], v[20:23], v[0:15]
	ds_read_b64_tr_b16 v[42:43], v175 offset:0x3a00
	s_waitcnt lgkmcnt(0)
	v_mfma_f32_32x32x16_bf16 v[0:15], v[192:195], v[24:27], v[0:15]
	v_mfma_f32_32x32x16_bf16 v[16:31], v[48:51], v[16:19], 0
	v_mfma_f32_32x32x16_bf16 v[16:31], v[150:153], v[32:35], v[16:31]
	ds_read_b64_tr_b16 v[32:33], v175 offset:0x400
	ds_read_b64_tr_b16 v[34:35], v175 offset:0xc00
	ds_read_b64_tr_b16 v[52:53], v175 offset:0x1400
	ds_read_b64_tr_b16 v[54:55], v175 offset:0x1c00
	ds_read_b64_tr_b16 v[56:57], v175 offset:0x2400
	ds_read_b64_tr_b16 v[58:59], v175 offset:0x2c00
	ds_read_b64_tr_b16 v[60:61], v175 offset:0x3400
	v_mfma_f32_32x32x16_bf16 v[16:31], v[158:161], v[36:39], v[16:31]
	ds_read_b64_tr_b16 v[62:63], v175 offset:0x3c00
	s_waitcnt lgkmcnt(0)
	v_mfma_f32_32x32x16_bf16 v[16:31], v[192:195], v[40:43], v[16:31]
	v_mfma_f32_32x32x16_bf16 v[32:47], v[48:51], v[32:35], 0
	v_mfma_f32_32x32x16_bf16 v[32:47], v[150:153], v[52:55], v[32:47]
	ds_read_b64_tr_b16 v[52:53], v175 offset:0x600
	ds_read_b64_tr_b16 v[54:55], v175 offset:0xe00
	ds_read_b64_tr_b16 v[200:201], v175 offset:0x1600
	ds_read_b64_tr_b16 v[202:203], v175 offset:0x1e00
	ds_read_b64_tr_b16 v[206:207], v175 offset:0x2600
	ds_read_b64_tr_b16 v[208:209], v175 offset:0x2e00
	ds_read_b64_tr_b16 v[210:211], v175 offset:0x3600
	v_mfma_f32_32x32x16_bf16 v[32:47], v[158:161], v[56:59], v[32:47]
	ds_read_b64_tr_b16 v[212:213], v175 offset:0x3e00
	s_waitcnt lgkmcnt(0)
	v_mfma_f32_32x32x16_bf16 v[32:47], v[192:195], v[60:63], v[32:47]
	v_mfma_f32_32x32x16_bf16 v[48:63], v[48:51], v[52:55], 0
	v_mfma_f32_32x32x16_bf16 v[48:63], v[150:153], v[200:203], v[48:63]
	v_mfma_f32_32x32x16_bf16 v[48:63], v[158:161], v[206:209], v[48:63]
	v_mfma_f32_32x32x16_bf16 v[48:63], v[192:195], v[210:213], v[48:63]
	s_setprio 0
	v_readlane_b32 s4, v255, 23
	v_readlane_b32 s5, v255, 24
	s_andn2_b64 vcc, exec, s[4:5]
	s_cbranch_vccnz .LBB0_1114
	v_subrev_u32_e32 v129, 64, v173
	s_mov_b32 s0, 0x100000
	v_cmp_gt_u32_e32 vcc, s0, v129
	v_add_u32_e32 v129, 0xffffffa0, v173
	s_nop 0
	v_cndmask_b32_e32 v64, v196, v64, vcc
	v_cmp_gt_u32_e32 vcc, s0, v129
	v_add_u32_e32 v129, 0xffffffbf, v173
	s_nop 0
	v_cndmask_b32_e32 v80, v196, v80, vcc
	v_cmp_gt_u32_e32 vcc, s0, v129
	v_add_u32_e32 v129, 0xffffff9f, v173
	s_nop 0
	v_cndmask_b32_e32 v65, v196, v65, vcc
	v_cmp_gt_u32_e32 vcc, s0, v129
	v_add_u32_e32 v129, 0xffffffbe, v173
	s_nop 0
	v_cndmask_b32_e32 v81, v196, v81, vcc
	v_cmp_gt_u32_e32 vcc, s0, v129
	v_add_u32_e32 v129, 0xffffff9e, v173
	s_nop 0
	v_cndmask_b32_e32 v66, v196, v66, vcc
	v_cmp_gt_u32_e32 vcc, s0, v129
	v_add_u32_e32 v129, 0xffffffbd, v173
	s_nop 0
	v_cndmask_b32_e32 v82, v196, v82, vcc
	v_cmp_gt_u32_e32 vcc, s0, v129
	v_add_u32_e32 v129, 0xffffff9d, v173
	s_nop 0
	v_cndmask_b32_e32 v67, v196, v67, vcc
	v_cmp_gt_u32_e32 vcc, s0, v129
	v_add_u32_e32 v129, 0xffffffb8, v173
	s_nop 0
	v_cndmask_b32_e32 v83, v196, v83, vcc
	v_cmp_gt_u32_e32 vcc, s0, v129
	v_add_u32_e32 v129, 0xffffff98, v173
	s_nop 0
	v_cndmask_b32_e32 v68, v196, v68, vcc
	v_cmp_gt_u32_e32 vcc, s0, v129
	v_add_u32_e32 v129, 0xffffffb7, v173
	s_nop 0
	v_cndmask_b32_e32 v84, v196, v84, vcc
	v_cmp_gt_u32_e32 vcc, s0, v129
	v_add_u32_e32 v129, 0xffffff97, v173
	s_nop 0
	v_cndmask_b32_e32 v69, v196, v69, vcc
	v_cmp_gt_u32_e32 vcc, s0, v129
	v_add_u32_e32 v129, 0xffffffb6, v173
	s_nop 0
	v_cndmask_b32_e32 v85, v196, v85, vcc
	v_cmp_gt_u32_e32 vcc, s0, v129
	v_add_u32_e32 v129, 0xffffff96, v173
	s_nop 0
	v_cndmask_b32_e32 v70, v196, v70, vcc
	v_cmp_gt_u32_e32 vcc, s0, v129
	v_add_u32_e32 v129, 0xffffffb5, v173
	s_nop 0
	v_cndmask_b32_e32 v86, v196, v86, vcc
	v_cmp_gt_u32_e32 vcc, s0, v129
	v_add_u32_e32 v129, 0xffffff95, v173
	s_nop 0
	v_cndmask_b32_e32 v71, v196, v71, vcc
	v_cmp_gt_u32_e32 vcc, s0, v129
	v_add_u32_e32 v129, 0xffffffb0, v173
	s_nop 0
	v_cndmask_b32_e32 v87, v196, v87, vcc
	v_cmp_gt_u32_e32 vcc, s0, v129
	v_add_u32_e32 v129, 0xffffff90, v173
	s_nop 0
	v_cndmask_b32_e32 v72, v196, v72, vcc
	v_cmp_gt_u32_e32 vcc, s0, v129
	v_add_u32_e32 v129, 0xffffffaf, v173
	s_nop 0
	v_cndmask_b32_e32 v88, v196, v88, vcc
	v_cmp_gt_u32_e32 vcc, s0, v129
	v_add_u32_e32 v129, 0xffffff8f, v173
	s_nop 0
	v_cndmask_b32_e32 v73, v196, v73, vcc
	v_cmp_gt_u32_e32 vcc, s0, v129
	v_add_u32_e32 v129, 0xffffffae, v173
	s_nop 0
	v_cndmask_b32_e32 v89, v196, v89, vcc
	v_cmp_gt_u32_e32 vcc, s0, v129
	v_add_u32_e32 v129, 0xffffff8e, v173
	s_nop 0
	v_cndmask_b32_e32 v74, v196, v74, vcc
	v_cmp_gt_u32_e32 vcc, s0, v129
	v_add_u32_e32 v129, 0xffffffad, v173
	s_nop 0
	v_cndmask_b32_e32 v90, v196, v90, vcc
	v_cmp_gt_u32_e32 vcc, s0, v129
	v_add_u32_e32 v129, 0xffffff8d, v173
	s_nop 0
	v_cndmask_b32_e32 v75, v196, v75, vcc
	v_cmp_gt_u32_e32 vcc, s0, v129
	v_add_u32_e32 v129, 0xffffffa8, v173
	s_nop 0
	v_cndmask_b32_e32 v91, v196, v91, vcc
	v_cmp_gt_u32_e32 vcc, s0, v129
	v_add_u32_e32 v129, 0xffffff88, v173
	s_nop 0
	v_cndmask_b32_e32 v76, v196, v76, vcc
	v_cmp_gt_u32_e32 vcc, s0, v129
	v_add_u32_e32 v129, 0xffffffa7, v173
	s_nop 0
	v_cndmask_b32_e32 v92, v196, v92, vcc
	v_cmp_gt_u32_e32 vcc, s0, v129
	v_add_u32_e32 v129, 0xffffff87, v173
	s_nop 0
	v_cndmask_b32_e32 v77, v196, v77, vcc
	v_cmp_gt_u32_e32 vcc, s0, v129
	v_add_u32_e32 v129, 0xffffffa6, v173
	s_nop 0
	v_cndmask_b32_e32 v93, v196, v93, vcc
	v_cmp_gt_u32_e32 vcc, s0, v129
	v_add_u32_e32 v129, 0xffffff86, v173
	s_nop 0
	v_cndmask_b32_e32 v78, v196, v78, vcc
	v_cmp_gt_u32_e32 vcc, s0, v129
	v_add_u32_e32 v129, 0xffffffa5, v173
	s_nop 0
	v_cndmask_b32_e32 v94, v196, v94, vcc
	v_cmp_gt_u32_e32 vcc, s0, v129
	v_add_u32_e32 v129, 0xffffff85, v173
	s_nop 0
	v_cndmask_b32_e32 v79, v196, v79, vcc
	v_cmp_gt_u32_e32 vcc, s0, v129
	s_nop 1
	v_cndmask_b32_e32 v95, v196, v95, vcc

.LBB0_1119:
	v_exp_f32_e32 v213, v64
	v_exp_f32_e32 v215, v65
	v_exp_f32_e32 v211, v66
	v_exp_f32_e32 v214, v67
	v_exp_f32_e32 v209, v68
	v_exp_f32_e32 v212, v69
	v_exp_f32_e32 v208, v70
	v_exp_f32_e32 v210, v71
	v_exp_f32_e32 v205, v72
	v_exp_f32_e32 v207, v73
	v_exp_f32_e32 v202, v74
	v_exp_f32_e32 v206, v75
	v_exp_f32_e32 v200, v76
	v_exp_f32_e32 v203, v77
	v_exp_f32_e32 v199, v78
	v_exp_f32_e32 v201, v79
	s_waitcnt lgkmcnt(0)
	s_barrier
	v_lshlrev_b64 v[64:65], 8, v[166:167]
	s_mov_b64 s[4:5], 0xc000
	v_lshl_add_u64 v[66:67], v[64:65], 0, s[4:5]
	s_mov_b64 s[4:5], 0xe000
	v_lshl_add_u64 v[68:69], v[148:149], 0, v[66:67]
	v_lshl_add_u64 v[64:65], v[64:65], 0, s[4:5]
	v_lshl_add_u64 v[66:67], v[156:157], 0, v[66:67]
	v_lshl_add_u64 v[70:71], v[148:149], 0, v[64:65]
	global_load_dwordx4 v[148:151], v[68:69], off
	global_load_dwordx4 v[152:155], v[70:71], off
	v_lshl_add_u64 v[64:65], v[156:157], 0, v[64:65]
	global_load_dwordx4 v[156:159], v[66:67], off
	global_load_dwordx4 v[160:163], v[64:65], off
	ds_read2_b64 v[64:67], v198 offset0:128 offset1:160
	v_mov_b64_e32 v[70:71], s[10:11]
	v_mov_b64_e32 v[74:75], s[10:11]
	v_mov_b64_e32 v[68:69], s[8:9]
	v_mov_b64_e32 v[72:73], s[8:9]
	s_waitcnt lgkmcnt(0)
	v_or_b32_e32 v69, 1.0, v65
	v_mov_b32_e32 v68, v64
	v_or_b32_e32 v73, 1.0, v67
	v_mov_b32_e32 v72, v66
	v_cndmask_b32_e64 v129, 0, v189, s[6:7]
	v_mov_b64_e32 v[76:77], v[128:129]
	v_cndmask_b32_e64 v64, 0, v197, s[6:7]
	v_mov_b64_e32 v[78:79], v[130:131]
	v_mov_b32_e32 v78, v64
	s_nop 1
	v_mfma_f32_32x32x16_bf16 v[96:111], v[68:71], v[76:79], 0
	v_mfma_f32_32x32x16_bf16 v[64:79], v[72:75], v[76:79], 0
	s_setprio 1
	ds_read_b128 v[192:195], v181 offset:32768
	s_waitcnt lgkmcnt(0)
	v_mfma_f32_32x32x16_bf16 v[96:111], v[192:195], v[144:147], v[96:111]
	ds_read_b128 v[192:195], v181 offset:40960
	s_waitcnt lgkmcnt(0)
	v_mfma_f32_32x32x16_bf16 v[64:79], v[192:195], v[144:147], v[64:79]
	ds_read_b128 v[192:195], v180 offset:32768
	s_waitcnt lgkmcnt(0)
	v_mfma_f32_32x32x16_bf16 v[96:111], v[192:195], v[140:143], v[96:111]
	ds_read_b128 v[192:195], v180 offset:40960
	s_waitcnt lgkmcnt(0)
	v_mfma_f32_32x32x16_bf16 v[64:79], v[192:195], v[140:143], v[64:79]
	ds_read_b128 v[192:195], v179 offset:32768
	s_waitcnt lgkmcnt(0)
	v_mfma_f32_32x32x16_bf16 v[96:111], v[192:195], v[136:139], v[96:111]
	ds_read_b128 v[192:195], v179 offset:40960
	s_waitcnt lgkmcnt(0)
	v_mfma_f32_32x32x16_bf16 v[64:79], v[192:195], v[136:139], v[64:79]
	ds_read_b128 v[192:195], v169 offset:32768
	s_waitcnt lgkmcnt(0)
	v_mfma_f32_32x32x16_bf16 v[96:111], v[192:195], v[132:135], v[96:111]
	ds_read_b128 v[192:195], v169 offset:40960
	s_waitcnt lgkmcnt(0)
	v_mfma_f32_32x32x16_bf16 v[64:79], v[192:195], v[132:135], v[64:79]
	ds_read_b128 v[192:195], v181 offset:32896
	s_waitcnt lgkmcnt(0)
	v_mfma_f32_32x32x16_bf16 v[96:111], v[192:195], v[124:127], v[96:111]
	ds_read_b128 v[192:195], v181 offset:41088
	s_waitcnt lgkmcnt(0)
	v_mfma_f32_32x32x16_bf16 v[64:79], v[192:195], v[124:127], v[64:79]
	ds_read_b128 v[192:195], v180 offset:32896
	s_waitcnt lgkmcnt(0)
	v_mfma_f32_32x32x16_bf16 v[96:111], v[192:195], v[120:123], v[96:111]
	ds_read_b128 v[192:195], v180 offset:41088
	s_waitcnt lgkmcnt(0)
	v_mfma_f32_32x32x16_bf16 v[64:79], v[192:195], v[120:123], v[64:79]
	ds_read_b128 v[192:195], v179 offset:32896
	s_waitcnt lgkmcnt(0)
	v_mfma_f32_32x32x16_bf16 v[96:111], v[192:195], v[116:119], v[96:111]
	ds_read_b128 v[192:195], v179 offset:41088
	s_waitcnt lgkmcnt(0)
	v_mfma_f32_32x32x16_bf16 v[64:79], v[192:195], v[116:119], v[64:79]
	ds_read_b128 v[192:195], v169 offset:32896
	s_waitcnt lgkmcnt(0)
	v_mfma_f32_32x32x16_bf16 v[96:111], v[192:195], v[112:115], v[96:111]
	ds_read_b128 v[192:195], v169 offset:41088
	s_waitcnt lgkmcnt(0)
	v_mfma_f32_32x32x16_bf16 v[64:79], v[192:195], v[112:115], v[64:79]
	s_setprio 0
	v_exp_f32_e32 v129, v80
	v_add_f32_e32 v80, 0, v213
	v_add_f32_e32 v80, v215, v80
	v_add_f32_e32 v80, v211, v80
	v_add_f32_e32 v80, v214, v80
	v_add_f32_e32 v80, v209, v80
	v_add_f32_e32 v80, v212, v80
	v_add_f32_e32 v80, v208, v80
	v_add_f32_e32 v80, v210, v80
	v_add_f32_e32 v80, v205, v80
	v_add_f32_e32 v80, v207, v80
	v_add_f32_e32 v80, v202, v80
	v_add_f32_e32 v80, v206, v80
	v_add_f32_e32 v80, v200, v80
	v_exp_f32_e32 v192, v81
	v_add_f32_e32 v80, v203, v80
	v_exp_f32_e32 v193, v82
	v_add_f32_e32 v80, v199, v80
	v_exp_f32_e32 v194, v83
	v_add_f32_e32 v80, v201, v80
	v_exp_f32_e32 v195, v84
	v_add_f32_e32 v80, v129, v80
	v_exp_f32_e32 v216, v85
	v_add_f32_e32 v80, v192, v80
	v_exp_f32_e32 v217, v86
	v_add_f32_e32 v80, v193, v80
	v_exp_f32_e32 v218, v87
	v_add_f32_e32 v80, v194, v80
	v_exp_f32_e32 v219, v88
	v_add_f32_e32 v80, v195, v80
	v_exp_f32_e32 v220, v89
	v_add_f32_e32 v80, v216, v80
	v_exp_f32_e32 v221, v90
	v_add_f32_e32 v80, v217, v80
	v_exp_f32_e32 v222, v91
	v_add_f32_e32 v80, v218, v80
	v_exp_f32_e32 v223, v92
	v_add_f32_e32 v80, v219, v80
	v_exp_f32_e32 v224, v93
	v_add_f32_e32 v80, v220, v80
	v_exp_f32_e32 v225, v94
	v_add_f32_e32 v80, v221, v80
	v_exp_f32_e32 v95, v95
	v_add_f32_e32 v80, v222, v80
	v_add_f32_e32 v80, v223, v80
	v_add_f32_e32 v80, v224, v80
	v_add_f32_e32 v80, v225, v80
	v_add_f32_e32 v187, v95, v80
	v_mov_b32_e32 v188, v187
	s_nop 1
	v_permlane32_swap_b32_e32 v187, v188
	v_cvt_pk_bf16_f32 v80, v213, v215
	v_cvt_pk_bf16_f32 v81, v211, v214
	v_cvt_pk_bf16_f32 v82, v209, v212
	v_cvt_pk_bf16_f32 v83, v208, v210
	v_cvt_pk_bf16_f32 v84, v205, v207
	v_cvt_pk_bf16_f32 v85, v202, v206
	v_cvt_pk_bf16_f32 v86, v200, v203
	v_cvt_pk_bf16_f32 v87, v199, v201
	v_cvt_pk_bf16_f32 v88, v129, v192
	v_cvt_pk_bf16_f32 v89, v193, v194
	v_cvt_pk_bf16_f32 v90, v195, v216
	v_cvt_pk_bf16_f32 v91, v217, v218
	v_cvt_pk_bf16_f32 v92, v219, v220
	v_cvt_pk_bf16_f32 v93, v221, v222
	v_cvt_pk_bf16_f32 v94, v223, v224
	v_cvt_pk_bf16_f32 v95, v225, v95
	s_nop 0
	v_permlane32_swap_b32_e32 v80, v82
	v_permlane32_swap_b32_e32 v81, v83
	v_permlane32_swap_b32_e32 v84, v86
	v_permlane32_swap_b32_e32 v85, v87
	v_permlane32_swap_b32_e32 v88, v90
	v_permlane32_swap_b32_e32 v89, v91
	v_permlane32_swap_b32_e32 v92, v94
	v_permlane32_swap_b32_e32 v93, v95
	s_setprio 1
	ds_read_b64_tr_b16 v[192:193], v175 offset:0x4000
	ds_read_b64_tr_b16 v[194:195], v175 offset:0x4800
	ds_read_b64_tr_b16 v[200:201], v175 offset:0x5000
	ds_read_b64_tr_b16 v[202:203], v175 offset:0x5800
	ds_read_b64_tr_b16 v[206:207], v175 offset:0x6000
	ds_read_b64_tr_b16 v[208:209], v175 offset:0x6800
	ds_read_b64_tr_b16 v[210:211], v175 offset:0x7000
	ds_read_b64_tr_b16 v[212:213], v175 offset:0x7800
	s_waitcnt lgkmcnt(0)
	s_nop 0
	v_mfma_f32_32x32x16_bf16 v[0:15], v[80:83], v[192:195], v[0:15]
	ds_read_b64_tr_b16 v[192:193], v175 offset:0x4200
	ds_read_b64_tr_b16 v[194:195], v175 offset:0x4a00
	v_mfma_f32_32x32x16_bf16 v[0:15], v[84:87], v[200:203], v[0:15]
	ds_read_b64_tr_b16 v[200:201], v175 offset:0x5200
	ds_read_b64_tr_b16 v[202:203], v175 offset:0x5a00
	v_mfma_f32_32x32x16_bf16 v[0:15], v[88:91], v[206:209], v[0:15]
	ds_read_b64_tr_b16 v[206:207], v175 offset:0x6200
	ds_read_b64_tr_b16 v[208:209], v175 offset:0x6a00
	v_mfma_f32_32x32x16_bf16 v[0:15], v[92:95], v[210:213], v[0:15]
	ds_read_b64_tr_b16 v[210:211], v175 offset:0x7200
	ds_read_b64_tr_b16 v[212:213], v175 offset:0x7a00
	s_waitcnt lgkmcnt(0)
	v_mfma_f32_32x32x16_bf16 v[16:31], v[80:83], v[192:195], v[16:31]
	ds_read_b64_tr_b16 v[192:193], v175 offset:0x4400
	ds_read_b64_tr_b16 v[194:195], v175 offset:0x4c00
	v_mfma_f32_32x32x16_bf16 v[16:31], v[84:87], v[200:203], v[16:31]
	ds_read_b64_tr_b16 v[200:201], v175 offset:0x5400
	ds_read_b64_tr_b16 v[202:203], v175 offset:0x5c00
	v_mfma_f32_32x32x16_bf16 v[16:31], v[88:91], v[206:209], v[16:31]
	ds_read_b64_tr_b16 v[206:207], v175 offset:0x6400
	ds_read_b64_tr_b16 v[208:209], v175 offset:0x6c00
	v_mfma_f32_32x32x16_bf16 v[16:31], v[92:95], v[210:213], v[16:31]
	ds_read_b64_tr_b16 v[210:211], v175 offset:0x7400
	ds_read_b64_tr_b16 v[212:213], v175 offset:0x7c00
	s_waitcnt lgkmcnt(0)
	v_mfma_f32_32x32x16_bf16 v[32:47], v[80:83], v[192:195], v[32:47]
	ds_read_b64_tr_b16 v[192:193], v175 offset:0x4600
	ds_read_b64_tr_b16 v[194:195], v175 offset:0x4e00
	v_mfma_f32_32x32x16_bf16 v[32:47], v[84:87], v[200:203], v[32:47]
	ds_read_b64_tr_b16 v[200:201], v175 offset:0x5600
	ds_read_b64_tr_b16 v[202:203], v175 offset:0x5e00
	v_mfma_f32_32x32x16_bf16 v[32:47], v[88:91], v[206:209], v[32:47]
	ds_read_b64_tr_b16 v[206:207], v175 offset:0x6600
	ds_read_b64_tr_b16 v[208:209], v175 offset:0x6e00
	v_mfma_f32_32x32x16_bf16 v[32:47], v[92:95], v[210:213], v[32:47]
	ds_read_b64_tr_b16 v[210:211], v175 offset:0x7600
	ds_read_b64_tr_b16 v[212:213], v175 offset:0x7e00
	s_waitcnt lgkmcnt(0)
	v_mfma_f32_32x32x16_bf16 v[48:63], v[80:83], v[192:195], v[48:63]
	v_mfma_f32_32x32x16_bf16 v[48:63], v[84:87], v[200:203], v[48:63]
	v_mfma_f32_32x32x16_bf16 v[48:63], v[88:91], v[206:209], v[48:63]
	v_mfma_f32_32x32x16_bf16 v[48:63], v[92:95], v[210:213], v[48:63]
	s_setprio 0
	v_readlane_b32 s4, v255, 25
	v_readlane_b32 s5, v255, 26
	s_andn2_b64 vcc, exec, s[4:5]
	s_cbranch_vccnz .LBB0_1121
	v_add_u32_e32 v80, 0xffffff80, v173
	s_mov_b32 s0, 0x100000
	v_cmp_gt_u32_e32 vcc, s0, v80
	v_add_u32_e32 v80, 0xffffff60, v173
	s_nop 0
	v_cndmask_b32_e32 v96, v196, v96, vcc
	v_cmp_gt_u32_e32 vcc, s0, v80
	v_add_u32_e32 v80, 0xffffff7f, v173
	s_nop 0
	v_cndmask_b32_e32 v64, v196, v64, vcc
	v_cmp_gt_u32_e32 vcc, s0, v80
	v_add_u32_e32 v80, 0xffffff5f, v173
	s_nop 0
	v_cndmask_b32_e32 v97, v196, v97, vcc
	v_cmp_gt_u32_e32 vcc, s0, v80
	v_add_u32_e32 v80, 0xffffff7e, v173
	s_nop 0
	v_cndmask_b32_e32 v65, v196, v65, vcc
	v_cmp_gt_u32_e32 vcc, s0, v80
	v_add_u32_e32 v80, 0xffffff5e, v173
	s_nop 0
	v_cndmask_b32_e32 v98, v196, v98, vcc
	v_cmp_gt_u32_e32 vcc, s0, v80
	v_add_u32_e32 v80, 0xffffff7d, v173
	s_nop 0
	v_cndmask_b32_e32 v66, v196, v66, vcc
	v_cmp_gt_u32_e32 vcc, s0, v80
	v_add_u32_e32 v80, 0xffffff5d, v173
	s_nop 0
	v_cndmask_b32_e32 v99, v196, v99, vcc
	v_cmp_gt_u32_e32 vcc, s0, v80
	v_add_u32_e32 v80, 0xffffff78, v173
	s_nop 0
	v_cndmask_b32_e32 v67, v196, v67, vcc
	v_cmp_gt_u32_e32 vcc, s0, v80
	v_add_u32_e32 v80, 0xffffff58, v173
	s_nop 0
	v_cndmask_b32_e32 v100, v196, v100, vcc
	v_cmp_gt_u32_e32 vcc, s0, v80
	v_add_u32_e32 v80, 0xffffff77, v173
	s_nop 0
	v_cndmask_b32_e32 v68, v196, v68, vcc
	v_cmp_gt_u32_e32 vcc, s0, v80
	v_add_u32_e32 v80, 0xffffff57, v173
	s_nop 0
	v_cndmask_b32_e32 v101, v196, v101, vcc
	v_cmp_gt_u32_e32 vcc, s0, v80
	v_add_u32_e32 v80, 0xffffff76, v173
	s_nop 0
	v_cndmask_b32_e32 v69, v196, v69, vcc
	v_cmp_gt_u32_e32 vcc, s0, v80
	v_add_u32_e32 v80, 0xffffff56, v173
	s_nop 0
	v_cndmask_b32_e32 v102, v196, v102, vcc
	v_cmp_gt_u32_e32 vcc, s0, v80
	v_add_u32_e32 v80, 0xffffff75, v173
	s_nop 0
	v_cndmask_b32_e32 v70, v196, v70, vcc
	v_cmp_gt_u32_e32 vcc, s0, v80
	v_add_u32_e32 v80, 0xffffff55, v173
	s_nop 0
	v_cndmask_b32_e32 v103, v196, v103, vcc
	v_cmp_gt_u32_e32 vcc, s0, v80
	v_add_u32_e32 v80, 0xffffff70, v173
	s_nop 0
	v_cndmask_b32_e32 v71, v196, v71, vcc
	v_cmp_gt_u32_e32 vcc, s0, v80
	v_add_u32_e32 v80, 0xffffff50, v173
	s_nop 0
	v_cndmask_b32_e32 v104, v196, v104, vcc
	v_cmp_gt_u32_e32 vcc, s0, v80
	v_add_u32_e32 v80, 0xffffff6f, v173
	s_nop 0
	v_cndmask_b32_e32 v72, v196, v72, vcc
	v_cmp_gt_u32_e32 vcc, s0, v80
	v_add_u32_e32 v80, 0xffffff4f, v173
	s_nop 0
	v_cndmask_b32_e32 v105, v196, v105, vcc
	v_cmp_gt_u32_e32 vcc, s0, v80
	v_add_u32_e32 v80, 0xffffff6e, v173
	s_nop 0
	v_cndmask_b32_e32 v73, v196, v73, vcc
	v_cmp_gt_u32_e32 vcc, s0, v80
	v_add_u32_e32 v80, 0xffffff4e, v173
	s_nop 0
	v_cndmask_b32_e32 v106, v196, v106, vcc
	v_cmp_gt_u32_e32 vcc, s0, v80
	v_add_u32_e32 v80, 0xffffff6d, v173
	s_nop 0
	v_cndmask_b32_e32 v74, v196, v74, vcc
	v_cmp_gt_u32_e32 vcc, s0, v80
	v_add_u32_e32 v80, 0xffffff4d, v173
	s_nop 0
	v_cndmask_b32_e32 v107, v196, v107, vcc
	v_cmp_gt_u32_e32 vcc, s0, v80
	v_add_u32_e32 v80, 0xffffff68, v173
	s_nop 0
	v_cndmask_b32_e32 v75, v196, v75, vcc
	v_cmp_gt_u32_e32 vcc, s0, v80
	v_add_u32_e32 v80, 0xffffff48, v173
	s_nop 0
	v_cndmask_b32_e32 v108, v196, v108, vcc
	v_cmp_gt_u32_e32 vcc, s0, v80
	v_add_u32_e32 v80, 0xffffff67, v173
	s_nop 0
	v_cndmask_b32_e32 v76, v196, v76, vcc
	v_cmp_gt_u32_e32 vcc, s0, v80
	v_add_u32_e32 v80, 0xffffff47, v173
	s_nop 0
	v_cndmask_b32_e32 v109, v196, v109, vcc
	v_cmp_gt_u32_e32 vcc, s0, v80
	v_add_u32_e32 v80, 0xffffff66, v173
	s_nop 0
	v_cndmask_b32_e32 v77, v196, v77, vcc
	v_cmp_gt_u32_e32 vcc, s0, v80
	v_add_u32_e32 v80, 0xffffff46, v173
	s_nop 0
	v_cndmask_b32_e32 v110, v196, v110, vcc
	v_cmp_gt_u32_e32 vcc, s0, v80
	v_add_u32_e32 v80, 0xffffff65, v173
	s_nop 0
	v_cndmask_b32_e32 v78, v196, v78, vcc
	v_cmp_gt_u32_e32 vcc, s0, v80
	v_add_u32_e32 v80, 0xffffff45, v173
	s_nop 0
	v_cndmask_b32_e32 v111, v196, v111, vcc
	v_cmp_gt_u32_e32 vcc, s0, v80
	s_nop 1
	v_cndmask_b32_e32 v79, v196, v79, vcc

.LBB0_1126:
	v_exp_f32_e32 v161, v96
	v_exp_f32_e32 v163, v97
	v_exp_f32_e32 v159, v98
	v_exp_f32_e32 v162, v99
	v_exp_f32_e32 v157, v100
	v_exp_f32_e32 v160, v101
	v_exp_f32_e32 v156, v102
	v_exp_f32_e32 v158, v103
	v_exp_f32_e32 v153, v104
	v_exp_f32_e32 v155, v105
	v_exp_f32_e32 v151, v106
	v_exp_f32_e32 v154, v107
	v_exp_f32_e32 v149, v108
	v_exp_f32_e32 v152, v109
	v_exp_f32_e32 v148, v110
	v_exp_f32_e32 v150, v111
	s_waitcnt lgkmcnt(0)
	s_barrier
	ds_read2_b64 v[80:83], v198 offset0:192 offset1:224
	v_mov_b64_e32 v[86:87], s[10:11]
	v_mov_b64_e32 v[90:91], s[10:11]
	v_mov_b64_e32 v[84:85], s[8:9]
	v_mov_b64_e32 v[88:89], s[8:9]
	s_waitcnt lgkmcnt(0)
	v_or_b32_e32 v85, 1.0, v81
	v_mov_b32_e32 v84, v80
	v_or_b32_e32 v89, 1.0, v83
	v_mov_b32_e32 v88, v82
	v_cndmask_b32_e64 v129, 0, v189, s[6:7]
	v_mov_b64_e32 v[92:93], v[128:129]
	v_cndmask_b32_e64 v80, 0, v197, s[6:7]
	v_mov_b64_e32 v[94:95], v[130:131]
	v_mov_b32_e32 v94, v80
	s_nop 1
	v_mfma_f32_32x32x16_bf16 v[96:111], v[84:87], v[92:95], 0
	v_mfma_f32_32x32x16_bf16 v[80:95], v[88:91], v[92:95], 0
	s_setprio 1
	ds_read_b128 v[192:195], v181 offset:49152
	s_waitcnt lgkmcnt(0)
	v_mfma_f32_32x32x16_bf16 v[96:111], v[192:195], v[144:147], v[96:111]
	ds_read_b128 v[192:195], v181 offset:57344
	s_waitcnt lgkmcnt(0)
	v_mfma_f32_32x32x16_bf16 v[80:95], v[192:195], v[144:147], v[80:95]
	ds_read_b128 v[144:147], v180 offset:49152
	s_waitcnt lgkmcnt(0)
	v_mfma_f32_32x32x16_bf16 v[96:111], v[144:147], v[140:143], v[96:111]
	ds_read_b128 v[144:147], v180 offset:57344
	s_waitcnt lgkmcnt(0)
	v_mfma_f32_32x32x16_bf16 v[80:95], v[144:147], v[140:143], v[80:95]
	ds_read_b128 v[140:143], v179 offset:49152
	s_waitcnt lgkmcnt(0)
	v_mfma_f32_32x32x16_bf16 v[96:111], v[140:143], v[136:139], v[96:111]
	ds_read_b128 v[140:143], v179 offset:57344
	s_waitcnt lgkmcnt(0)
	v_mfma_f32_32x32x16_bf16 v[80:95], v[140:143], v[136:139], v[80:95]
	ds_read_b128 v[136:139], v169 offset:49152
	s_waitcnt lgkmcnt(0)
	v_mfma_f32_32x32x16_bf16 v[96:111], v[136:139], v[132:135], v[96:111]
	ds_read_b128 v[136:139], v169 offset:57344
	s_waitcnt lgkmcnt(0)
	v_mfma_f32_32x32x16_bf16 v[80:95], v[136:139], v[132:135], v[80:95]
	ds_read_b128 v[132:135], v181 offset:49280
	s_waitcnt lgkmcnt(0)
	v_mfma_f32_32x32x16_bf16 v[96:111], v[132:135], v[124:127], v[96:111]
	ds_read_b128 v[132:135], v181 offset:57472
	s_waitcnt lgkmcnt(0)
	v_mfma_f32_32x32x16_bf16 v[80:95], v[132:135], v[124:127], v[80:95]
	ds_read_b128 v[124:127], v180 offset:49280
	s_waitcnt lgkmcnt(0)
	v_mfma_f32_32x32x16_bf16 v[96:111], v[124:127], v[120:123], v[96:111]
	ds_read_b128 v[124:127], v180 offset:57472
	s_waitcnt lgkmcnt(0)
	v_mfma_f32_32x32x16_bf16 v[80:95], v[124:127], v[120:123], v[80:95]
	ds_read_b128 v[120:123], v179 offset:49280
	s_waitcnt lgkmcnt(0)
	v_mfma_f32_32x32x16_bf16 v[96:111], v[120:123], v[116:119], v[96:111]
	ds_read_b128 v[120:123], v179 offset:57472
	s_waitcnt lgkmcnt(0)
	v_mfma_f32_32x32x16_bf16 v[80:95], v[120:123], v[116:119], v[80:95]
	ds_read_b128 v[116:119], v169 offset:49280
	s_waitcnt lgkmcnt(0)
	v_mfma_f32_32x32x16_bf16 v[96:111], v[116:119], v[112:115], v[96:111]
	ds_read_b128 v[116:119], v169 offset:57472
	s_waitcnt lgkmcnt(0)
	v_mfma_f32_32x32x16_bf16 v[80:95], v[116:119], v[112:115], v[80:95]
	s_setprio 0
	v_ashrrev_i32_e32 v169, 31, v168
	v_lshlrev_b64 v[112:113], 8, v[166:167]
	v_lshlrev_b64 v[114:115], 8, v[168:169]
	v_lshl_add_u64 v[112:113], s[72:73], 0, v[112:113]
	v_lshl_add_u64 v[114:115], s[72:73], 0, v[114:115]
	v_lshl_add_u64 v[112:113], v[112:113], 0, v[130:131]
	v_lshl_add_u64 v[116:117], v[114:115], 0, v[130:131]
	global_load_dwordx4 v[112:115], v[112:113], off
	s_nop 0
	global_load_dwordx4 v[116:119], v[116:117], off
	v_exp_f32_e32 v120, v64
	v_add_f32_e32 v64, 0, v161
	v_add_f32_e32 v64, v163, v64
	v_add_f32_e32 v64, v159, v64
	v_add_f32_e32 v64, v162, v64
	v_add_f32_e32 v64, v157, v64
	v_add_f32_e32 v64, v160, v64
	v_add_f32_e32 v64, v156, v64
	v_add_f32_e32 v64, v158, v64
	v_add_f32_e32 v64, v153, v64
	v_add_f32_e32 v64, v155, v64
	v_add_f32_e32 v64, v151, v64
	v_add_f32_e32 v64, v154, v64
	v_add_f32_e32 v64, v149, v64
	v_exp_f32_e32 v121, v65
	v_add_f32_e32 v64, v152, v64
	v_exp_f32_e32 v122, v66
	v_add_f32_e32 v64, v148, v64
	v_exp_f32_e32 v123, v67
	v_add_f32_e32 v64, v150, v64
	v_exp_f32_e32 v124, v68
	v_add_f32_e32 v64, v120, v64
	v_exp_f32_e32 v125, v69
	v_add_f32_e32 v64, v121, v64
	v_exp_f32_e32 v126, v70
	v_add_f32_e32 v64, v122, v64
	v_exp_f32_e32 v127, v71
	v_add_f32_e32 v64, v123, v64
	v_exp_f32_e32 v128, v72
	v_add_f32_e32 v64, v124, v64
	v_exp_f32_e32 v129, v73
	v_add_f32_e32 v64, v125, v64
	v_exp_f32_e32 v130, v74
	v_add_f32_e32 v64, v126, v64
	v_exp_f32_e32 v132, v75
	v_add_f32_e32 v64, v127, v64
	v_exp_f32_e32 v133, v76
	v_add_f32_e32 v64, v128, v64
	v_exp_f32_e32 v134, v77
	v_add_f32_e32 v64, v129, v64
	v_exp_f32_e32 v78, v78
	v_add_f32_e32 v64, v130, v64
	v_exp_f32_e32 v79, v79
	v_add_f32_e32 v64, v132, v64
	v_add_f32_e32 v64, v133, v64
	v_add_f32_e32 v64, v134, v64
	v_add_f32_e32 v64, v78, v64
	v_add_f32_e32 v72, v79, v64
	v_mov_b32_e32 v73, v72
	s_nop 1
	v_permlane32_swap_b32_e32 v72, v73
	v_cvt_pk_bf16_f32 v64, v161, v163
	v_cvt_pk_bf16_f32 v65, v159, v162
	v_cvt_pk_bf16_f32 v66, v157, v160
	v_cvt_pk_bf16_f32 v67, v156, v158
	v_cvt_pk_bf16_f32 v68, v153, v155
	v_cvt_pk_bf16_f32 v69, v151, v154
	v_cvt_pk_bf16_f32 v70, v149, v152
	v_cvt_pk_bf16_f32 v71, v148, v150
	v_cvt_pk_bf16_f32 v74, v120, v121
	v_cvt_pk_bf16_f32 v75, v122, v123
	v_cvt_pk_bf16_f32 v76, v124, v125
	v_cvt_pk_bf16_f32 v77, v126, v127
	v_cvt_pk_bf16_f32 v120, v128, v129
	v_cvt_pk_bf16_f32 v121, v130, v132
	v_cvt_pk_bf16_f32 v122, v133, v134
	v_cvt_pk_bf16_f32 v123, v78, v79
	s_nop 0
	v_permlane32_swap_b32_e32 v64, v66
	v_permlane32_swap_b32_e32 v65, v67
	v_permlane32_swap_b32_e32 v68, v70
	v_permlane32_swap_b32_e32 v69, v71
	v_permlane32_swap_b32_e32 v74, v76
	v_permlane32_swap_b32_e32 v75, v77
	v_permlane32_swap_b32_e32 v120, v122
	v_permlane32_swap_b32_e32 v121, v123
	s_setprio 1
	ds_read_b64_tr_b16 v[124:125], v175 offset:0
	ds_read_b64_tr_b16 v[126:127], v175 offset:0x800
	ds_read_b64_tr_b16 v[132:133], v175 offset:0x1000
	ds_read_b64_tr_b16 v[134:135], v175 offset:0x1800
	ds_read_b64_tr_b16 v[136:137], v175 offset:0x2000
	ds_read_b64_tr_b16 v[138:139], v175 offset:0x2800
	ds_read_b64_tr_b16 v[140:141], v175 offset:0x3000
	ds_read_b64_tr_b16 v[142:143], v175 offset:0x3800
	s_waitcnt lgkmcnt(0)
	s_nop 0
	v_mfma_f32_32x32x16_bf16 v[0:15], v[64:67], v[124:127], v[0:15]
	ds_read_b64_tr_b16 v[124:125], v175 offset:0x200
	ds_read_b64_tr_b16 v[126:127], v175 offset:0xa00
	v_mfma_f32_32x32x16_bf16 v[0:15], v[68:71], v[132:135], v[0:15]
	ds_read_b64_tr_b16 v[132:133], v175 offset:0x1200
	ds_read_b64_tr_b16 v[134:135], v175 offset:0x1a00
	v_mfma_f32_32x32x16_bf16 v[0:15], v[74:77], v[136:139], v[0:15]
	ds_read_b64_tr_b16 v[136:137], v175 offset:0x2200
	ds_read_b64_tr_b16 v[138:139], v175 offset:0x2a00
	v_mfma_f32_32x32x16_bf16 v[0:15], v[120:123], v[140:143], v[0:15]
	ds_read_b64_tr_b16 v[140:141], v175 offset:0x3200
	ds_read_b64_tr_b16 v[142:143], v175 offset:0x3a00
	s_waitcnt lgkmcnt(0)
	v_mfma_f32_32x32x16_bf16 v[16:31], v[64:67], v[124:127], v[16:31]
	ds_read_b64_tr_b16 v[124:125], v175 offset:0x400
	ds_read_b64_tr_b16 v[126:127], v175 offset:0xc00
	v_mfma_f32_32x32x16_bf16 v[16:31], v[68:71], v[132:135], v[16:31]
	ds_read_b64_tr_b16 v[132:133], v175 offset:0x1400
	ds_read_b64_tr_b16 v[134:135], v175 offset:0x1c00
	v_mfma_f32_32x32x16_bf16 v[16:31], v[74:77], v[136:139], v[16:31]
	ds_read_b64_tr_b16 v[136:137], v175 offset:0x2400
	ds_read_b64_tr_b16 v[138:139], v175 offset:0x2c00
	v_mfma_f32_32x32x16_bf16 v[16:31], v[120:123], v[140:143], v[16:31]
	ds_read_b64_tr_b16 v[140:141], v175 offset:0x3400
	ds_read_b64_tr_b16 v[142:143], v175 offset:0x3c00
	s_waitcnt lgkmcnt(0)
	v_mfma_f32_32x32x16_bf16 v[32:47], v[64:67], v[124:127], v[32:47]
	ds_read_b64_tr_b16 v[124:125], v175 offset:0x600
	ds_read_b64_tr_b16 v[126:127], v175 offset:0xe00
	v_mfma_f32_32x32x16_bf16 v[32:47], v[68:71], v[132:135], v[32:47]
	ds_read_b64_tr_b16 v[132:133], v175 offset:0x1600
	ds_read_b64_tr_b16 v[134:135], v175 offset:0x1e00
	v_mfma_f32_32x32x16_bf16 v[32:47], v[74:77], v[136:139], v[32:47]
	ds_read_b64_tr_b16 v[136:137], v175 offset:0x2600
	ds_read_b64_tr_b16 v[138:139], v175 offset:0x2e00
	v_mfma_f32_32x32x16_bf16 v[32:47], v[120:123], v[140:143], v[32:47]
	ds_read_b64_tr_b16 v[140:141], v175 offset:0x3600
	ds_read_b64_tr_b16 v[142:143], v175 offset:0x3e00
	s_waitcnt lgkmcnt(0)
	v_mfma_f32_32x32x16_bf16 v[48:63], v[64:67], v[124:127], v[48:63]
	v_mfma_f32_32x32x16_bf16 v[48:63], v[68:71], v[132:135], v[48:63]
	v_mfma_f32_32x32x16_bf16 v[48:63], v[74:77], v[136:139], v[48:63]
	v_mfma_f32_32x32x16_bf16 v[48:63], v[120:123], v[140:143], v[48:63]
	s_setprio 0
	v_readlane_b32 s4, v255, 21
	v_readlane_b32 s5, v255, 22
	s_andn2_b64 vcc, exec, s[4:5]
	s_cbranch_vccnz .LBB0_1128
	v_add_u32_e32 v64, 0xffffff40, v173
	s_mov_b32 s0, 0x100000
	v_cmp_gt_u32_e32 vcc, s0, v64
	v_add_u32_e32 v64, 0xffffff20, v173
	s_nop 0
	v_cndmask_b32_e32 v96, v196, v96, vcc
	v_cmp_gt_u32_e32 vcc, s0, v64
	v_add_u32_e32 v64, 0xffffff3f, v173
	s_nop 0
	v_cndmask_b32_e32 v80, v196, v80, vcc
	v_cmp_gt_u32_e32 vcc, s0, v64
	v_add_u32_e32 v64, 0xffffff1f, v173
	s_nop 0
	v_cndmask_b32_e32 v97, v196, v97, vcc
	v_cmp_gt_u32_e32 vcc, s0, v64
	v_add_u32_e32 v64, 0xffffff3e, v173
	s_nop 0
	v_cndmask_b32_e32 v81, v196, v81, vcc
	v_cmp_gt_u32_e32 vcc, s0, v64
	v_add_u32_e32 v64, 0xffffff1e, v173
	s_nop 0
	v_cndmask_b32_e32 v98, v196, v98, vcc
	v_cmp_gt_u32_e32 vcc, s0, v64
	v_add_u32_e32 v64, 0xffffff3d, v173
	s_nop 0
	v_cndmask_b32_e32 v82, v196, v82, vcc
	v_cmp_gt_u32_e32 vcc, s0, v64
	v_add_u32_e32 v64, 0xffffff1d, v173
	s_nop 0
	v_cndmask_b32_e32 v99, v196, v99, vcc
	v_cmp_gt_u32_e32 vcc, s0, v64
	v_add_u32_e32 v64, 0xffffff38, v173
	s_nop 0
	v_cndmask_b32_e32 v83, v196, v83, vcc
	v_cmp_gt_u32_e32 vcc, s0, v64
	v_add_u32_e32 v64, 0xffffff18, v173
	s_nop 0
	v_cndmask_b32_e32 v100, v196, v100, vcc
	v_cmp_gt_u32_e32 vcc, s0, v64
	v_add_u32_e32 v64, 0xffffff37, v173
	s_nop 0
	v_cndmask_b32_e32 v84, v196, v84, vcc
	v_cmp_gt_u32_e32 vcc, s0, v64
	v_add_u32_e32 v64, 0xffffff17, v173
	s_nop 0
	v_cndmask_b32_e32 v101, v196, v101, vcc
	v_cmp_gt_u32_e32 vcc, s0, v64
	v_add_u32_e32 v64, 0xffffff36, v173
	s_nop 0
	v_cndmask_b32_e32 v85, v196, v85, vcc
	v_cmp_gt_u32_e32 vcc, s0, v64
	v_add_u32_e32 v64, 0xffffff16, v173
	s_nop 0
	v_cndmask_b32_e32 v102, v196, v102, vcc
	v_cmp_gt_u32_e32 vcc, s0, v64
	v_add_u32_e32 v64, 0xffffff35, v173
	s_nop 0
	v_cndmask_b32_e32 v86, v196, v86, vcc
	v_cmp_gt_u32_e32 vcc, s0, v64
	v_add_u32_e32 v64, 0xffffff15, v173
	s_nop 0
	v_cndmask_b32_e32 v103, v196, v103, vcc
	v_cmp_gt_u32_e32 vcc, s0, v64
	v_add_u32_e32 v64, 0xffffff30, v173
	s_nop 0
	v_cndmask_b32_e32 v87, v196, v87, vcc
	v_cmp_gt_u32_e32 vcc, s0, v64
	v_add_u32_e32 v64, 0xffffff10, v173
	s_nop 0
	v_cndmask_b32_e32 v104, v196, v104, vcc
	v_cmp_gt_u32_e32 vcc, s0, v64
	v_add_u32_e32 v64, 0xffffff2f, v173
	s_nop 0
	v_cndmask_b32_e32 v88, v196, v88, vcc
	v_cmp_gt_u32_e32 vcc, s0, v64
	v_add_u32_e32 v64, 0xffffff0f, v173
	s_nop 0
	v_cndmask_b32_e32 v105, v196, v105, vcc
	v_cmp_gt_u32_e32 vcc, s0, v64
	v_add_u32_e32 v64, 0xffffff2e, v173
	s_nop 0
	v_cndmask_b32_e32 v89, v196, v89, vcc
	v_cmp_gt_u32_e32 vcc, s0, v64
	v_add_u32_e32 v64, 0xffffff0e, v173
	s_nop 0
	v_cndmask_b32_e32 v106, v196, v106, vcc
	v_cmp_gt_u32_e32 vcc, s0, v64
	v_add_u32_e32 v64, 0xffffff2d, v173
	s_nop 0
	v_cndmask_b32_e32 v90, v196, v90, vcc
	v_cmp_gt_u32_e32 vcc, s0, v64
	v_add_u32_e32 v64, 0xffffff0d, v173
	s_nop 0
	v_cndmask_b32_e32 v107, v196, v107, vcc
	v_cmp_gt_u32_e32 vcc, s0, v64
	v_add_u32_e32 v64, 0xffffff28, v173
	s_nop 0
	v_cndmask_b32_e32 v91, v196, v91, vcc
	v_cmp_gt_u32_e32 vcc, s0, v64
	v_add_u32_e32 v64, 0xffffff08, v173
	s_nop 0
	v_cndmask_b32_e32 v108, v196, v108, vcc
	v_cmp_gt_u32_e32 vcc, s0, v64
	v_add_u32_e32 v64, 0xffffff27, v173
	s_nop 0
	v_cndmask_b32_e32 v92, v196, v92, vcc
	v_cmp_gt_u32_e32 vcc, s0, v64
	v_add_u32_e32 v64, 0xffffff07, v173
	s_nop 0
	v_cndmask_b32_e32 v109, v196, v109, vcc
	v_cmp_gt_u32_e32 vcc, s0, v64
	v_add_u32_e32 v64, 0xffffff26, v173
	s_nop 0
	v_cndmask_b32_e32 v93, v196, v93, vcc
	v_cmp_gt_u32_e32 vcc, s0, v64
	v_add_u32_e32 v64, 0xffffff06, v173
	s_nop 0
	v_cndmask_b32_e32 v110, v196, v110, vcc
	v_cmp_gt_u32_e32 vcc, s0, v64
	v_add_u32_e32 v64, 0xffffff25, v173
	s_nop 0
	v_cndmask_b32_e32 v94, v196, v94, vcc
	v_cmp_gt_u32_e32 vcc, s0, v64
	v_add_u32_e32 v64, 0xffffff05, v173
	s_nop 0
	v_cndmask_b32_e32 v111, v196, v111, vcc
	v_cmp_gt_u32_e32 vcc, s0, v64
	s_nop 1
	v_cndmask_b32_e32 v95, v196, v95, vcc

.LBB0_1135:
	s_or_b64 exec, exec, s[4:5]
	s_waitcnt lgkmcnt(0)
	ds_read_b128 v[76:79], v183
	ds_read_b128 v[72:75], v183 offset:32
	s_or_b64 s[4:5], s[50:51], s[70:71]
	s_lshl_b64 s[4:5], s[4:5], 12
	s_add_u32 s0, s19, s4
	s_waitcnt lgkmcnt(1)
	v_rcp_f32_e32 v76, v76
	s_addc_u32 s3, s28, s5
	s_lshl_b32 s1, s1, 8
	s_add_u32 s0, s0, s1
	v_mul_f32_e32 v0, v0, v76
	s_addc_u32 s1, s3, 0
	ds_read_b128 v[68:71], v183 offset:64
	ds_read_b128 v[64:67], v183 offset:96
	ds_bpermute_b32 v84, v170, v0
	s_add_u32 s0, s0, s8
	s_addc_u32 s1, s1, s9
	v_and_b32_e32 v80, 1, v165
	v_lshlrev_b32_e32 v130, 1, v171
	v_ashrrev_i32_e32 v165, 31, v164
	v_cmp_eq_u32_e32 vcc, 0, v80
	v_lshl_add_u64 v[80:81], s[0:1], 0, v[130:131]
	v_lshlrev_b64 v[82:83], 12, v[164:165]
	v_lshl_add_u64 v[82:83], v[80:81], 0, v[82:83]
	s_and_saveexec_b64 s[4:5], vcc
	s_cbranch_execz .LBB0_1137
	s_waitcnt lgkmcnt(0)
	v_cvt_pk_bf16_f32 v0, v0, v84
	global_store_dword v[82:83], v0, off offset:3072
.LBB0_1137:
	s_or_b64 exec, exec, s[4:5]
	v_mul_f32_e32 v0, v16, v76
	ds_bpermute_b32 v16, v170, v0
	s_and_saveexec_b64 s[4:5], vcc
	s_cbranch_execz .LBB0_1139
	s_waitcnt lgkmcnt(0)
	v_cvt_pk_bf16_f32 v0, v0, v16
	global_store_dword v[82:83], v0, off offset:3136
.LBB0_1139:
	s_or_b64 exec, exec, s[4:5]
	v_mul_f32_e32 v0, v32, v76
	s_waitcnt lgkmcnt(0)
	ds_bpermute_b32 v16, v170, v0
	s_and_saveexec_b64 s[4:5], vcc
	s_cbranch_execz .LBB0_1141
	s_waitcnt lgkmcnt(0)
	v_cvt_pk_bf16_f32 v0, v0, v16
	global_store_dword v[82:83], v0, off offset:3200
.LBB0_1141:
	s_or_b64 exec, exec, s[4:5]
	v_mul_f32_e32 v0, v48, v76
	s_waitcnt lgkmcnt(0)
	ds_bpermute_b32 v16, v170, v0
	s_and_saveexec_b64 s[4:5], vcc
	s_cbranch_execz .LBB0_1143
	s_waitcnt lgkmcnt(0)
	v_cvt_pk_bf16_f32 v0, v0, v16
	global_store_dword v[82:83], v0, off offset:3264
.LBB0_1143:
	s_or_b64 exec, exec, s[4:5]
	v_rcp_f32_e32 v0, v77
	v_or_b32_e32 v76, 1, v164
	v_ashrrev_i32_e32 v77, 31, v76
	v_lshlrev_b64 v[76:77], 12, v[76:77]
	v_mul_f32_e32 v1, v1, v0
	s_waitcnt lgkmcnt(0)
	ds_bpermute_b32 v16, v170, v1
	v_lshl_add_u64 v[76:77], v[80:81], 0, v[76:77]
	s_and_saveexec_b64 s[4:5], vcc
	s_cbranch_execz .LBB0_1145
	s_waitcnt lgkmcnt(0)
	v_cvt_pk_bf16_f32 v1, v1, v16
	global_store_dword v[76:77], v1, off offset:3072
.LBB0_1145:
	s_or_b64 exec, exec, s[4:5]
	v_mul_f32_e32 v1, v17, v0
	s_waitcnt lgkmcnt(0)
	ds_bpermute_b32 v16, v170, v1
	s_and_saveexec_b64 s[4:5], vcc
	s_cbranch_execz .LBB0_1147
	s_waitcnt lgkmcnt(0)
	v_cvt_pk_bf16_f32 v1, v1, v16
	global_store_dword v[76:77], v1, off offset:3136
.LBB0_1147:
	s_or_b64 exec, exec, s[4:5]
	v_mul_f32_e32 v1, v33, v0
	s_waitcnt lgkmcnt(0)
	ds_bpermute_b32 v16, v170, v1
	s_and_saveexec_b64 s[4:5], vcc
	s_cbranch_execz .LBB0_1149
	s_waitcnt lgkmcnt(0)
	v_cvt_pk_bf16_f32 v1, v1, v16
	global_store_dword v[76:77], v1, off offset:3200
.LBB0_1149:
	s_or_b64 exec, exec, s[4:5]
	v_mul_f32_e32 v0, v49, v0
	ds_bpermute_b32 v1, v170, v0
	s_and_saveexec_b64 s[4:5], vcc
	s_cbranch_execz .LBB0_1151
	s_waitcnt lgkmcnt(0)
	v_cvt_pk_bf16_f32 v0, v0, v1
	global_store_dword v[76:77], v0, off offset:3264
.LBB0_1151:
	s_or_b64 exec, exec, s[4:5]
	s_waitcnt lgkmcnt(0)
	v_rcp_f32_e32 v16, v78
	v_or_b32_e32 v0, 2, v164
	v_ashrrev_i32_e32 v1, 31, v0
	v_lshlrev_b64 v[0:1], 12, v[0:1]
	v_mul_f32_e32 v2, v2, v16
	ds_bpermute_b32 v17, v170, v2
	v_lshl_add_u64 v[0:1], v[80:81], 0, v[0:1]
	s_and_saveexec_b64 s[4:5], vcc
	s_cbranch_execz .LBB0_1153
	s_waitcnt lgkmcnt(0)
	v_cvt_pk_bf16_f32 v2, v2, v17
	global_store_dword v[0:1], v2, off offset:3072
.LBB0_1153:
	s_or_b64 exec, exec, s[4:5]
	v_mul_f32_e32 v2, v18, v16
	s_waitcnt lgkmcnt(0)
	ds_bpermute_b32 v17, v170, v2
	s_and_saveexec_b64 s[4:5], vcc
	s_cbranch_execz .LBB0_1155
	s_waitcnt lgkmcnt(0)
	v_cvt_pk_bf16_f32 v2, v2, v17
	global_store_dword v[0:1], v2, off offset:3136
.LBB0_1155:
	s_or_b64 exec, exec, s[4:5]
	v_mul_f32_e32 v2, v34, v16
	s_waitcnt lgkmcnt(0)
	ds_bpermute_b32 v17, v170, v2
	s_and_saveexec_b64 s[4:5], vcc
	s_cbranch_execz .LBB0_1157
	s_waitcnt lgkmcnt(0)
	v_cvt_pk_bf16_f32 v2, v2, v17
	global_store_dword v[0:1], v2, off offset:3200
.LBB0_1157:
	s_or_b64 exec, exec, s[4:5]
	v_mul_f32_e32 v2, v50, v16
	ds_bpermute_b32 v16, v170, v2
	s_and_saveexec_b64 s[4:5], vcc
	s_cbranch_execz .LBB0_1159
	s_waitcnt lgkmcnt(0)
	v_cvt_pk_bf16_f32 v2, v2, v16
	global_store_dword v[0:1], v2, off offset:3264
.LBB0_1159:
	s_or_b64 exec, exec, s[4:5]
	v_rcp_f32_e32 v2, v79
	v_or_b32_e32 v0, 3, v164
	v_ashrrev_i32_e32 v1, 31, v0
	v_lshlrev_b64 v[0:1], 12, v[0:1]
	v_mul_f32_e32 v3, v3, v2
	s_waitcnt lgkmcnt(0)
	ds_bpermute_b32 v16, v170, v3
	v_lshl_add_u64 v[0:1], v[80:81], 0, v[0:1]
	s_and_saveexec_b64 s[4:5], vcc
	s_cbranch_execz .LBB0_1161
	s_waitcnt lgkmcnt(0)
	v_cvt_pk_bf16_f32 v3, v3, v16
	global_store_dword v[0:1], v3, off offset:3072
.LBB0_1161:
	s_or_b64 exec, exec, s[4:5]
	v_mul_f32_e32 v3, v19, v2
	s_waitcnt lgkmcnt(0)
	ds_bpermute_b32 v16, v170, v3
	s_and_saveexec_b64 s[4:5], vcc
	s_cbranch_execz .LBB0_1163
	s_waitcnt lgkmcnt(0)
	v_cvt_pk_bf16_f32 v3, v3, v16
	global_store_dword v[0:1], v3, off offset:3136
.LBB0_1163:
	s_or_b64 exec, exec, s[4:5]
	v_mul_f32_e32 v3, v35, v2
	s_waitcnt lgkmcnt(0)
	ds_bpermute_b32 v16, v170, v3
	s_and_saveexec_b64 s[4:5], vcc
	s_cbranch_execz .LBB0_1165
	s_waitcnt lgkmcnt(0)
	v_cvt_pk_bf16_f32 v3, v3, v16
	global_store_dword v[0:1], v3, off offset:3200
.LBB0_1165:
	s_or_b64 exec, exec, s[4:5]
	v_mul_f32_e32 v2, v51, v2
	ds_bpermute_b32 v3, v170, v2
	s_and_saveexec_b64 s[4:5], vcc
	s_cbranch_execz .LBB0_1167
	s_waitcnt lgkmcnt(0)
	v_cvt_pk_bf16_f32 v2, v2, v3
	global_store_dword v[0:1], v2, off offset:3264
.LBB0_1167:
	s_or_b64 exec, exec, s[4:5]
	v_rcp_f32_e32 v2, v72
	v_lshlrev_b64 v[0:1], 12, v[164:165]
	v_lshl_add_u64 v[0:1], v[80:81], 0, v[0:1]
	v_lshl_add_u64 v[0:1], v[0:1], 0, s[34:35]
	s_waitcnt lgkmcnt(0)
	v_mul_f32_e32 v3, v4, v2
	ds_bpermute_b32 v4, v170, v3
	s_and_saveexec_b64 s[4:5], vcc
	s_cbranch_execz .LBB0_1169
	s_waitcnt lgkmcnt(0)
	v_cvt_pk_bf16_f32 v3, v3, v4
	global_store_dword v[0:1], v3, off offset:3072
.LBB0_1169:
	s_or_b64 exec, exec, s[4:5]
	v_mul_f32_e32 v3, v20, v2
	s_waitcnt lgkmcnt(0)
	ds_bpermute_b32 v4, v170, v3
	s_and_saveexec_b64 s[4:5], vcc
	s_cbranch_execz .LBB0_1171
	s_waitcnt lgkmcnt(0)
	v_cvt_pk_bf16_f32 v3, v3, v4
	global_store_dword v[0:1], v3, off offset:3136
.LBB0_1171:
	s_or_b64 exec, exec, s[4:5]
	v_mul_f32_e32 v3, v36, v2
	s_waitcnt lgkmcnt(0)
	ds_bpermute_b32 v4, v170, v3
	s_and_saveexec_b64 s[4:5], vcc
	s_cbranch_execz .LBB0_1173
	s_waitcnt lgkmcnt(0)
	v_cvt_pk_bf16_f32 v3, v3, v4
	global_store_dword v[0:1], v3, off offset:3200
.LBB0_1173:
	s_or_b64 exec, exec, s[4:5]
	v_mul_f32_e32 v2, v52, v2
	ds_bpermute_b32 v3, v170, v2
	s_and_saveexec_b64 s[4:5], vcc
	s_cbranch_execz .LBB0_1175
	s_waitcnt lgkmcnt(0)
	v_cvt_pk_bf16_f32 v2, v2, v3
	global_store_dword v[0:1], v2, off offset:3264
.LBB0_1175:
	s_or_b64 exec, exec, s[4:5]
	v_rcp_f32_e32 v2, v73
	v_lshlrev_b64 v[0:1], 12, v[164:165]
	v_lshl_add_u64 v[0:1], v[80:81], 0, v[0:1]
	v_lshl_add_u64 v[0:1], v[0:1], 0, s[48:49]
	s_waitcnt lgkmcnt(0)
	v_mul_f32_e32 v3, v5, v2
	ds_bpermute_b32 v4, v170, v3
	s_and_saveexec_b64 s[4:5], vcc
	s_cbranch_execz .LBB0_1177
	s_waitcnt lgkmcnt(0)
	v_cvt_pk_bf16_f32 v3, v3, v4
	global_store_dword v[0:1], v3, off offset:3072
.LBB0_1177:
	s_or_b64 exec, exec, s[4:5]
	v_mul_f32_e32 v3, v21, v2
	s_waitcnt lgkmcnt(0)
	ds_bpermute_b32 v4, v170, v3
	s_and_saveexec_b64 s[4:5], vcc
	s_cbranch_execz .LBB0_1179
	s_waitcnt lgkmcnt(0)
	v_cvt_pk_bf16_f32 v3, v3, v4
	global_store_dword v[0:1], v3, off offset:3136
.LBB0_1179:
	s_or_b64 exec, exec, s[4:5]
	v_mul_f32_e32 v3, v37, v2
	s_waitcnt lgkmcnt(0)
	ds_bpermute_b32 v4, v170, v3
	s_and_saveexec_b64 s[4:5], vcc
	s_cbranch_execz .LBB0_1181
	s_waitcnt lgkmcnt(0)
	v_cvt_pk_bf16_f32 v3, v3, v4
	global_store_dword v[0:1], v3, off offset:3200
.LBB0_1181:
	s_or_b64 exec, exec, s[4:5]
	v_mul_f32_e32 v2, v53, v2
	ds_bpermute_b32 v3, v170, v2
	s_and_saveexec_b64 s[4:5], vcc
	s_cbranch_execz .LBB0_1183
	s_waitcnt lgkmcnt(0)
	v_cvt_pk_bf16_f32 v2, v2, v3
	global_store_dword v[0:1], v2, off offset:3264
.LBB0_1183:
	s_or_b64 exec, exec, s[4:5]
	v_rcp_f32_e32 v2, v74
	v_lshlrev_b64 v[0:1], 12, v[164:165]
	v_lshl_add_u64 v[0:1], v[80:81], 0, v[0:1]
	v_lshl_add_u64 v[0:1], v[0:1], 0, s[54:55]
	s_waitcnt lgkmcnt(0)
	v_mul_f32_e32 v3, v6, v2
	ds_bpermute_b32 v4, v170, v3
	s_and_saveexec_b64 s[4:5], vcc
	s_cbranch_execz .LBB0_1185
	s_waitcnt lgkmcnt(0)
	v_cvt_pk_bf16_f32 v3, v3, v4
	global_store_dword v[0:1], v3, off offset:3072
.LBB0_1185:
	s_or_b64 exec, exec, s[4:5]
	v_mul_f32_e32 v3, v22, v2
	s_waitcnt lgkmcnt(0)
	ds_bpermute_b32 v4, v170, v3
	s_and_saveexec_b64 s[4:5], vcc
	s_cbranch_execz .LBB0_1187
	s_waitcnt lgkmcnt(0)
	v_cvt_pk_bf16_f32 v3, v3, v4
	global_store_dword v[0:1], v3, off offset:3136
.LBB0_1187:
	s_or_b64 exec, exec, s[4:5]
	v_mul_f32_e32 v3, v38, v2
	s_waitcnt lgkmcnt(0)
	ds_bpermute_b32 v4, v170, v3
	s_and_saveexec_b64 s[4:5], vcc
	s_cbranch_execz .LBB0_1189
	s_waitcnt lgkmcnt(0)
	v_cvt_pk_bf16_f32 v3, v3, v4
	global_store_dword v[0:1], v3, off offset:3200
.LBB0_1189:
	s_or_b64 exec, exec, s[4:5]
	v_mul_f32_e32 v2, v54, v2
	ds_bpermute_b32 v3, v170, v2
	s_and_saveexec_b64 s[4:5], vcc
	s_cbranch_execz .LBB0_1191
	s_waitcnt lgkmcnt(0)
	v_cvt_pk_bf16_f32 v2, v2, v3
	global_store_dword v[0:1], v2, off offset:3264
.LBB0_1191:
	s_or_b64 exec, exec, s[4:5]
	v_rcp_f32_e32 v2, v75
	v_lshlrev_b64 v[0:1], 12, v[164:165]
	v_lshl_add_u64 v[0:1], v[80:81], 0, v[0:1]
	v_lshl_add_u64 v[0:1], v[0:1], 0, s[40:41]
	s_waitcnt lgkmcnt(0)
	v_mul_f32_e32 v3, v7, v2
	ds_bpermute_b32 v4, v170, v3
	s_and_saveexec_b64 s[4:5], vcc
	s_cbranch_execz .LBB0_1193
	s_waitcnt lgkmcnt(0)
	v_cvt_pk_bf16_f32 v3, v3, v4
	global_store_dword v[0:1], v3, off offset:3072
.LBB0_1193:
	s_or_b64 exec, exec, s[4:5]
	v_mul_f32_e32 v3, v23, v2
	s_waitcnt lgkmcnt(0)
	ds_bpermute_b32 v4, v170, v3
	s_and_saveexec_b64 s[4:5], vcc
	s_cbranch_execz .LBB0_1195
	s_waitcnt lgkmcnt(0)
	v_cvt_pk_bf16_f32 v3, v3, v4
	global_store_dword v[0:1], v3, off offset:3136
.LBB0_1195:
	s_or_b64 exec, exec, s[4:5]
	v_mul_f32_e32 v3, v39, v2
	s_waitcnt lgkmcnt(0)
	ds_bpermute_b32 v4, v170, v3
	s_and_saveexec_b64 s[4:5], vcc
	s_cbranch_execz .LBB0_1197
	s_waitcnt lgkmcnt(0)
	v_cvt_pk_bf16_f32 v3, v3, v4
	global_store_dword v[0:1], v3, off offset:3200
.LBB0_1197:
	s_or_b64 exec, exec, s[4:5]
	v_mul_f32_e32 v2, v55, v2
	ds_bpermute_b32 v3, v170, v2
	s_and_saveexec_b64 s[4:5], vcc
	s_cbranch_execz .LBB0_1199
	s_waitcnt lgkmcnt(0)
	v_cvt_pk_bf16_f32 v2, v2, v3
	global_store_dword v[0:1], v2, off offset:3264
.LBB0_1199:
	s_or_b64 exec, exec, s[4:5]
	v_rcp_f32_e32 v2, v68
	v_lshlrev_b64 v[0:1], 12, v[164:165]
	v_lshl_add_u64 v[0:1], v[80:81], 0, v[0:1]
	s_mov_b64 s[0:1], 0x10000
	s_waitcnt lgkmcnt(0)
	v_mul_f32_e32 v3, v8, v2
	ds_bpermute_b32 v4, v170, v3
	v_lshl_add_u64 v[0:1], v[0:1], 0, s[0:1]
	s_and_saveexec_b64 s[4:5], vcc
	s_cbranch_execz .LBB0_1201
	s_waitcnt lgkmcnt(0)
	v_cvt_pk_bf16_f32 v3, v3, v4
	global_store_dword v[0:1], v3, off offset:3072
.LBB0_1201:
	s_or_b64 exec, exec, s[4:5]
	v_mul_f32_e32 v3, v24, v2
	s_waitcnt lgkmcnt(0)
	ds_bpermute_b32 v4, v170, v3
	s_and_saveexec_b64 s[4:5], vcc
	s_cbranch_execz .LBB0_1203
	s_waitcnt lgkmcnt(0)
	v_cvt_pk_bf16_f32 v3, v3, v4
	global_store_dword v[0:1], v3, off offset:3136
.LBB0_1203:
	s_or_b64 exec, exec, s[4:5]
	v_mul_f32_e32 v3, v40, v2
	s_waitcnt lgkmcnt(0)
	ds_bpermute_b32 v4, v170, v3
	s_and_saveexec_b64 s[4:5], vcc
	s_cbranch_execz .LBB0_1205
	s_waitcnt lgkmcnt(0)
	v_cvt_pk_bf16_f32 v3, v3, v4
	global_store_dword v[0:1], v3, off offset:3200
.LBB0_1205:
	s_or_b64 exec, exec, s[4:5]
	v_mul_f32_e32 v2, v56, v2
	ds_bpermute_b32 v3, v170, v2
	s_and_saveexec_b64 s[4:5], vcc
	s_cbranch_execz .LBB0_1207
	s_waitcnt lgkmcnt(0)
	v_cvt_pk_bf16_f32 v2, v2, v3
	global_store_dword v[0:1], v2, off offset:3264
.LBB0_1207:
	s_or_b64 exec, exec, s[4:5]
	v_rcp_f32_e32 v2, v69
	v_lshlrev_b64 v[0:1], 12, v[164:165]
	v_lshl_add_u64 v[0:1], v[80:81], 0, v[0:1]
	s_mov_b64 s[0:1], 0x11000
	s_waitcnt lgkmcnt(0)
	v_mul_f32_e32 v3, v9, v2
	ds_bpermute_b32 v4, v170, v3
	v_lshl_add_u64 v[0:1], v[0:1], 0, s[0:1]
	s_and_saveexec_b64 s[4:5], vcc
	s_cbranch_execz .LBB0_1209
	s_waitcnt lgkmcnt(0)
	v_cvt_pk_bf16_f32 v3, v3, v4
	global_store_dword v[0:1], v3, off offset:3072
.LBB0_1209:
	s_or_b64 exec, exec, s[4:5]
	v_mul_f32_e32 v3, v25, v2
	s_waitcnt lgkmcnt(0)
	ds_bpermute_b32 v4, v170, v3
	s_and_saveexec_b64 s[4:5], vcc
	s_cbranch_execz .LBB0_1211
	s_waitcnt lgkmcnt(0)
	v_cvt_pk_bf16_f32 v3, v3, v4
	global_store_dword v[0:1], v3, off offset:3136
.LBB0_1211:
	s_or_b64 exec, exec, s[4:5]
	v_mul_f32_e32 v3, v41, v2
	s_waitcnt lgkmcnt(0)
	ds_bpermute_b32 v4, v170, v3
	s_and_saveexec_b64 s[4:5], vcc
	s_cbranch_execz .LBB0_1213
	s_waitcnt lgkmcnt(0)
	v_cvt_pk_bf16_f32 v3, v3, v4
	global_store_dword v[0:1], v3, off offset:3200
.LBB0_1213:
	s_or_b64 exec, exec, s[4:5]
	v_mul_f32_e32 v2, v57, v2
	ds_bpermute_b32 v3, v170, v2
	s_and_saveexec_b64 s[4:5], vcc
	s_cbranch_execz .LBB0_1215
	s_waitcnt lgkmcnt(0)
	v_cvt_pk_bf16_f32 v2, v2, v3
	global_store_dword v[0:1], v2, off offset:3264
.LBB0_1215:
	s_or_b64 exec, exec, s[4:5]
	v_rcp_f32_e32 v2, v70
	v_lshlrev_b64 v[0:1], 12, v[164:165]
	v_lshl_add_u64 v[0:1], v[80:81], 0, v[0:1]
	v_lshl_add_u64 v[0:1], v[0:1], 0, s[56:57]
	s_waitcnt lgkmcnt(0)
	v_mul_f32_e32 v3, v10, v2
	ds_bpermute_b32 v4, v170, v3
	s_and_saveexec_b64 s[4:5], vcc
	s_cbranch_execz .LBB0_1217
	s_waitcnt lgkmcnt(0)
	v_cvt_pk_bf16_f32 v3, v3, v4
	global_store_dword v[0:1], v3, off offset:3072
.LBB0_1217:
	s_or_b64 exec, exec, s[4:5]
	v_mul_f32_e32 v3, v26, v2
	s_waitcnt lgkmcnt(0)
	ds_bpermute_b32 v4, v170, v3
	s_and_saveexec_b64 s[4:5], vcc
	s_cbranch_execz .LBB0_1219
	s_waitcnt lgkmcnt(0)
	v_cvt_pk_bf16_f32 v3, v3, v4
	global_store_dword v[0:1], v3, off offset:3136
.LBB0_1219:
	s_or_b64 exec, exec, s[4:5]
	v_mul_f32_e32 v3, v42, v2
	s_waitcnt lgkmcnt(0)
	ds_bpermute_b32 v4, v170, v3
	s_and_saveexec_b64 s[4:5], vcc
	s_cbranch_execz .LBB0_1221
	s_waitcnt lgkmcnt(0)
	v_cvt_pk_bf16_f32 v3, v3, v4
	global_store_dword v[0:1], v3, off offset:3200
.LBB0_1221:
	s_or_b64 exec, exec, s[4:5]
	v_mul_f32_e32 v2, v58, v2
	ds_bpermute_b32 v3, v170, v2
	s_and_saveexec_b64 s[4:5], vcc
	s_cbranch_execz .LBB0_1223
	s_waitcnt lgkmcnt(0)
	v_cvt_pk_bf16_f32 v2, v2, v3
	global_store_dword v[0:1], v2, off offset:3264
.LBB0_1223:
	s_or_b64 exec, exec, s[4:5]
	v_rcp_f32_e32 v2, v71
	v_lshlrev_b64 v[0:1], 12, v[164:165]
	v_lshl_add_u64 v[0:1], v[80:81], 0, v[0:1]
	s_mov_b64 s[0:1], 0x13000
	s_waitcnt lgkmcnt(0)
	v_mul_f32_e32 v3, v11, v2
	ds_bpermute_b32 v4, v170, v3
	v_lshl_add_u64 v[0:1], v[0:1], 0, s[0:1]
	s_and_saveexec_b64 s[4:5], vcc
	s_cbranch_execz .LBB0_1225
	s_waitcnt lgkmcnt(0)
	v_cvt_pk_bf16_f32 v3, v3, v4
	global_store_dword v[0:1], v3, off offset:3072
.LBB0_1225:
	s_or_b64 exec, exec, s[4:5]
	v_mul_f32_e32 v3, v27, v2
	s_waitcnt lgkmcnt(0)
	ds_bpermute_b32 v4, v170, v3
	s_and_saveexec_b64 s[4:5], vcc
	s_cbranch_execz .LBB0_1227
	s_waitcnt lgkmcnt(0)
	v_cvt_pk_bf16_f32 v3, v3, v4
	global_store_dword v[0:1], v3, off offset:3136
.LBB0_1227:
	s_or_b64 exec, exec, s[4:5]
	v_mul_f32_e32 v3, v43, v2
	s_waitcnt lgkmcnt(0)
	ds_bpermute_b32 v4, v170, v3
	s_and_saveexec_b64 s[4:5], vcc
	s_cbranch_execz .LBB0_1229
	s_waitcnt lgkmcnt(0)
	v_cvt_pk_bf16_f32 v3, v3, v4
	global_store_dword v[0:1], v3, off offset:3200
.LBB0_1229:
	s_or_b64 exec, exec, s[4:5]
	v_mul_f32_e32 v2, v59, v2
	ds_bpermute_b32 v3, v170, v2
	s_and_saveexec_b64 s[4:5], vcc
	s_cbranch_execz .LBB0_1231
	s_waitcnt lgkmcnt(0)
	v_cvt_pk_bf16_f32 v2, v2, v3
	global_store_dword v[0:1], v2, off offset:3264
.LBB0_1231:
	s_or_b64 exec, exec, s[4:5]
	v_rcp_f32_e32 v2, v64
	v_lshlrev_b64 v[0:1], 12, v[164:165]
	v_lshl_add_u64 v[0:1], v[80:81], 0, v[0:1]
	s_mov_b64 s[0:1], 0x18000
	s_waitcnt lgkmcnt(0)
	v_mul_f32_e32 v3, v12, v2
	ds_bpermute_b32 v4, v170, v3
	v_lshl_add_u64 v[0:1], v[0:1], 0, s[0:1]
	s_and_saveexec_b64 s[4:5], vcc
	s_cbranch_execz .LBB0_1233
	s_waitcnt lgkmcnt(0)
	v_cvt_pk_bf16_f32 v3, v3, v4
	global_store_dword v[0:1], v3, off offset:3072
.LBB0_1233:
	s_or_b64 exec, exec, s[4:5]
	v_mul_f32_e32 v3, v28, v2
	s_waitcnt lgkmcnt(0)
	ds_bpermute_b32 v4, v170, v3
	s_and_saveexec_b64 s[4:5], vcc
	s_cbranch_execz .LBB0_1235
	s_waitcnt lgkmcnt(0)
	v_cvt_pk_bf16_f32 v3, v3, v4
	global_store_dword v[0:1], v3, off offset:3136
.LBB0_1235:
	s_or_b64 exec, exec, s[4:5]
	v_mul_f32_e32 v3, v44, v2
	s_waitcnt lgkmcnt(0)
	ds_bpermute_b32 v4, v170, v3
	s_and_saveexec_b64 s[4:5], vcc
	s_cbranch_execz .LBB0_1237
	s_waitcnt lgkmcnt(0)
	v_cvt_pk_bf16_f32 v3, v3, v4
	global_store_dword v[0:1], v3, off offset:3200
.LBB0_1237:
	s_or_b64 exec, exec, s[4:5]
	v_mul_f32_e32 v2, v60, v2
	ds_bpermute_b32 v3, v170, v2
	s_and_saveexec_b64 s[4:5], vcc
	s_cbranch_execz .LBB0_1239
	s_waitcnt lgkmcnt(0)
	v_cvt_pk_bf16_f32 v2, v2, v3
	global_store_dword v[0:1], v2, off offset:3264
.LBB0_1239:
	s_or_b64 exec, exec, s[4:5]
	v_rcp_f32_e32 v2, v65
	v_lshlrev_b64 v[0:1], 12, v[164:165]
	v_lshl_add_u64 v[0:1], v[80:81], 0, v[0:1]
	s_mov_b64 s[0:1], 0x19000
	s_waitcnt lgkmcnt(0)
	v_mul_f32_e32 v3, v13, v2
	ds_bpermute_b32 v4, v170, v3
	v_lshl_add_u64 v[0:1], v[0:1], 0, s[0:1]
	s_and_saveexec_b64 s[4:5], vcc
	s_cbranch_execz .LBB0_1241
	s_waitcnt lgkmcnt(0)
	v_cvt_pk_bf16_f32 v3, v3, v4
	global_store_dword v[0:1], v3, off offset:3072
.LBB0_1241:
	s_or_b64 exec, exec, s[4:5]
	v_mul_f32_e32 v3, v29, v2
	s_waitcnt lgkmcnt(0)
	ds_bpermute_b32 v4, v170, v3
	s_and_saveexec_b64 s[4:5], vcc
	s_cbranch_execz .LBB0_1243
	s_waitcnt lgkmcnt(0)
	v_cvt_pk_bf16_f32 v3, v3, v4
	global_store_dword v[0:1], v3, off offset:3136
.LBB0_1243:
	s_or_b64 exec, exec, s[4:5]
	v_mul_f32_e32 v3, v45, v2
	s_waitcnt lgkmcnt(0)
	ds_bpermute_b32 v4, v170, v3
	s_and_saveexec_b64 s[4:5], vcc
	s_cbranch_execz .LBB0_1245
	s_waitcnt lgkmcnt(0)
	v_cvt_pk_bf16_f32 v3, v3, v4
	global_store_dword v[0:1], v3, off offset:3200
.LBB0_1245:
	s_or_b64 exec, exec, s[4:5]
	v_mul_f32_e32 v2, v61, v2
	ds_bpermute_b32 v3, v170, v2
	s_and_saveexec_b64 s[4:5], vcc
	s_cbranch_execz .LBB0_1247
	s_waitcnt lgkmcnt(0)
	v_cvt_pk_bf16_f32 v2, v2, v3
	global_store_dword v[0:1], v2, off offset:3264
.LBB0_1247:
	s_or_b64 exec, exec, s[4:5]
	v_rcp_f32_e32 v2, v66
	v_lshlrev_b64 v[0:1], 12, v[164:165]
	v_lshl_add_u64 v[0:1], v[80:81], 0, v[0:1]
	v_lshl_add_u64 v[0:1], v[0:1], 0, s[66:67]
	s_waitcnt lgkmcnt(0)
	v_mul_f32_e32 v3, v14, v2
	ds_bpermute_b32 v4, v170, v3
	s_and_saveexec_b64 s[4:5], vcc
	s_cbranch_execz .LBB0_1249
	s_waitcnt lgkmcnt(0)
	v_cvt_pk_bf16_f32 v3, v3, v4
	global_store_dword v[0:1], v3, off offset:3072
.LBB0_1249:
	s_or_b64 exec, exec, s[4:5]
	v_mul_f32_e32 v3, v30, v2
	s_waitcnt lgkmcnt(0)
	ds_bpermute_b32 v4, v170, v3
	s_and_saveexec_b64 s[4:5], vcc
	s_cbranch_execz .LBB0_1251
	s_waitcnt lgkmcnt(0)
	v_cvt_pk_bf16_f32 v3, v3, v4
	global_store_dword v[0:1], v3, off offset:3136
.LBB0_1251:
	s_or_b64 exec, exec, s[4:5]
	v_mul_f32_e32 v3, v46, v2
	s_waitcnt lgkmcnt(0)
	ds_bpermute_b32 v4, v170, v3
	s_and_saveexec_b64 s[4:5], vcc
	s_cbranch_execz .LBB0_1253
	s_waitcnt lgkmcnt(0)
	v_cvt_pk_bf16_f32 v3, v3, v4
	global_store_dword v[0:1], v3, off offset:3200
.LBB0_1253:
	s_or_b64 exec, exec, s[4:5]
	v_mul_f32_e32 v2, v62, v2
	ds_bpermute_b32 v3, v170, v2
	s_and_saveexec_b64 s[4:5], vcc
	s_cbranch_execz .LBB0_1255
	s_waitcnt lgkmcnt(0)
	v_cvt_pk_bf16_f32 v2, v2, v3
	global_store_dword v[0:1], v2, off offset:3264
.LBB0_1255:
	s_or_b64 exec, exec, s[4:5]
	v_rcp_f32_e32 v2, v67
	v_lshlrev_b64 v[0:1], 12, v[164:165]
	v_lshl_add_u64 v[0:1], v[80:81], 0, v[0:1]
	v_lshl_add_u64 v[0:1], v[0:1], 0, s[68:69]
	s_waitcnt lgkmcnt(0)
	v_mul_f32_e32 v3, v15, v2
	ds_bpermute_b32 v4, v170, v3
	s_and_saveexec_b64 s[4:5], vcc
	s_cbranch_execz .LBB0_1257
	s_waitcnt lgkmcnt(0)
	v_cvt_pk_bf16_f32 v3, v3, v4
	global_store_dword v[0:1], v3, off offset:3072
.LBB0_1257:
	s_or_b64 exec, exec, s[4:5]
	v_mul_f32_e32 v3, v31, v2
	s_waitcnt lgkmcnt(0)
	ds_bpermute_b32 v4, v170, v3
	s_and_saveexec_b64 s[4:5], vcc
	s_cbranch_execz .LBB0_1259
	s_waitcnt lgkmcnt(0)
	v_cvt_pk_bf16_f32 v3, v3, v4
	global_store_dword v[0:1], v3, off offset:3136
.LBB0_1259:
	s_or_b64 exec, exec, s[4:5]
	v_mul_f32_e32 v3, v47, v2
	s_waitcnt lgkmcnt(0)
	ds_bpermute_b32 v4, v170, v3
	s_and_saveexec_b64 s[4:5], vcc
	s_cbranch_execz .LBB0_1261
	s_waitcnt lgkmcnt(0)
	v_cvt_pk_bf16_f32 v3, v3, v4
	global_store_dword v[0:1], v3, off offset:3200
.LBB0_1261:
	s_or_b64 exec, exec, s[4:5]
	v_mul_f32_e32 v2, v63, v2
	ds_bpermute_b32 v3, v170, v2
	s_and_saveexec_b64 s[4:5], vcc
	s_cbranch_execz .LBB0_837
	s_waitcnt lgkmcnt(0)
	v_cvt_pk_bf16_f32 v2, v2, v3
	global_store_dword v[0:1], v2, off offset:3264
	s_branch .LBB0_837

.LBB0_1273:
	global_load_dword v47, v[0:1], off sc1
	global_load_dword v32, v[2:3], off sc1
	global_load_dword v33, v[4:5], off sc1
	global_load_dword v34, v[6:7], off sc1
	global_load_dword v35, v[8:9], off sc1
	global_load_dword v36, v[10:11], off sc1
	global_load_dword v37, v[12:13], off sc1
	global_load_dword v38, v[14:15], off sc1
	global_load_dword v39, v[16:17], off sc1
	global_load_dword v40, v[18:19], off sc1
	global_load_dword v41, v[20:21], off sc1
	global_load_dword v42, v[22:23], off sc1
	global_load_dword v43, v[24:25], off sc1
	global_load_dword v44, v[26:27], off sc1
	global_load_dword v45, v[28:29], off sc1
	global_load_dword v46, v[30:31], off sc1
	s_or_b64 s[16:17], s[16:17], exec
	s_or_b64 s[12:13], s[12:13], exec
	s_waitcnt vmcnt(0) lgkmcnt(0)
	v_add_u32_e32 v48, v32, v47
	v_add_u32_e32 v48, v48, v33
	v_add_u32_e32 v48, v48, v34
	v_add_u32_e32 v48, v48, v35
	v_add_u32_e32 v48, v48, v36
	v_add_u32_e32 v48, v48, v37
	v_add_u32_e32 v48, v48, v38
	v_add_u32_e32 v48, v48, v39
	v_add_u32_e32 v48, v48, v40
	v_add_u32_e32 v48, v48, v41
	v_add_u32_e32 v48, v48, v42
	v_add_u32_e32 v48, v48, v43
	v_add_u32_e32 v48, v48, v44
	v_add_u32_e32 v48, v48, v45
	v_add_u32_e32 v48, v48, v46
	v_cmp_ne_u32_e32 vcc, s1, v48
	s_and_saveexec_b64 s[18:19], vcc
	s_cbranch_execz .LBB0_1272
	s_and_b32 s3, s2, 0xff
	s_mov_b64 s[20:21], -1
	s_cmp_eq_u32 s3, 0
	s_mov_b64 s[24:25], -1
	s_mov_b64 s[22:23], -1
	s_sleep 1
	s_cbranch_scc1 .LBB0_1276
	s_and_saveexec_b64 s[26:27], s[24:25]
	s_cbranch_execz .LBB0_1271
	s_branch .LBB0_1279
.LBB0_1276:
	v_mov_b64_e32 v[48:49], s[6:7]
	global_load_dword v48, v[48:49], off sc1
	s_mov_b64 s[24:25], 0
	s_waitcnt vmcnt(0) lgkmcnt(0)
	v_cmp_eq_u32_e32 vcc, 0, v48
	s_and_saveexec_b64 s[26:27], vcc
	s_cmp_lt_u32 s2, 0x40001
	s_cselect_b64 s[14:15], -1, 0
	s_xor_b64 s[22:23], exec, -1
	s_and_b64 s[24:25], s[14:15], exec
	s_or_b64 exec, exec, s[26:27]
	s_and_saveexec_b64 s[26:27], s[24:25]
	s_cbranch_execz .LBB0_1271

.LBB0_1283:
	s_lshl_b32 s0, s0, 8
	s_add_u32 s0, s4, s0
	s_addc_u32 s2, s5, 0
	v_mov_b32_e32 v1, s0
	v_add_co_u32_e32 v4, vcc, 0x101000, v1
	v_mov_b32_e32 v1, s2
	s_nop 0
	v_addc_co_u32_e32 v5, vcc, 0, v1, vcc
	v_mov_b32_e32 v1, 1
	global_atomic_add v1, v[4:5], v1, off offset:1024 sc0
	v_cvt_f32_u32_e32 v3, v2
	v_sub_u32_e32 v4, 0, v2
	s_add_u32 s1, s0, 0x100000
	s_addc_u32 s0, s2, 0
	v_rcp_iflag_f32_e32 v3, v3
	s_nop 0
	v_mul_f32_e32 v3, 0x4f7ffffe, v3
	v_cvt_u32_f32_e32 v3, v3
	v_mul_lo_u32 v4, v4, v3
	v_mul_hi_u32 v4, v3, v4
	v_add_u32_e32 v3, v3, v4
	s_waitcnt vmcnt(0) lgkmcnt(0)
	v_mul_hi_u32 v3, v1, v3
	v_mul_lo_u32 v5, v3, v2
	v_add_u32_e32 v4, 1, v1
	v_sub_u32_e32 v1, v1, v5
	v_add_u32_e32 v6, 1, v3
	v_cmp_ge_u32_e32 vcc, v1, v2
	v_sub_u32_e32 v5, v1, v2
	s_nop 0
	v_cndmask_b32_e32 v3, v3, v6, vcc
	v_cndmask_b32_e32 v1, v1, v5, vcc
	v_add_u32_e32 v5, 1, v3
	v_cmp_ge_u32_e32 vcc, v1, v2
	s_nop 1
	v_cndmask_b32_e32 v1, v3, v5, vcc
	v_mad_u64_u32 v[2:3], s[2:3], v2, v1, v[2:3]
	v_cmp_ne_u32_e32 vcc, v4, v2
	s_and_saveexec_b64 s[2:3], vcc
	s_xor_b64 s[6:7], exec, s[2:3]
	s_cbranch_execz .LBB0_1296
	v_mov_b32_e32 v0, s1
	v_add_co_u32_e32 v2, vcc, 0x2000, v0
	v_mov_b32_e32 v0, s0
	s_nop 0
	v_addc_co_u32_e32 v3, vcc, 0, v0, vcc
	global_load_dword v0, v[2:3], off offset:1024 sc1
	s_add_u32 s12, s1, 0x2400
	s_addc_u32 s13, s0, 0
	s_waitcnt vmcnt(0) lgkmcnt(0)
	v_cmp_eq_u32_e32 vcc, v0, v1
	s_and_saveexec_b64 s[8:9], vcc
	s_cbranch_execz .LBB0_1295
	s_add_u32 s10, s4, 0x100200
	s_addc_u32 s11, s5, 0
	s_mov_b32 s2, 1
	s_mov_b64 s[16:17], 0
	s_branch .LBB0_1287

.LBB0_1287:
	s_and_b32 s3, s2, 0xff
	s_mov_b64 s[22:23], -1
	s_cmp_lg_u32 s3, 0
	s_mov_b64 s[24:25], -1
	s_sleep 1
	s_cbranch_scc1 .LBB0_1291
	v_mov_b64_e32 v[2:3], s[10:11]
	global_load_dword v0, v[2:3], off sc1
	s_mov_b64 s[24:25], 0
	s_mov_b64 s[26:27], -1
	s_waitcnt vmcnt(0) lgkmcnt(0)
	v_cmp_eq_u32_e32 vcc, 0, v0
	s_and_saveexec_b64 s[28:29], vcc
	s_cmp_lt_u32 s2, 0x40001
	s_cselect_b64 s[14:15], -1, 0
	s_xor_b64 s[26:27], exec, -1
	s_and_b64 s[24:25], s[14:15], exec
	s_or_b64 exec, exec, s[28:29]
.LBB0_1291:
	s_andn2_b64 s[14:15], s[20:21], exec
	s_and_b64 s[20:21], s[26:27], exec
	s_or_b64 s[20:21], s[14:15], s[20:21]
	s_and_saveexec_b64 s[26:27], s[24:25]
	s_cbranch_execz .LBB0_1286
	v_mov_b64_e32 v[2:3], s[12:13]
	global_load_dword v0, v[2:3], off sc1
	s_add_i32 s2, s2, 1
	s_or_b64 s[20:21], s[20:21], exec
	s_waitcnt vmcnt(0) lgkmcnt(0)
	v_cmp_ne_u32_e32 vcc, v0, v1
	s_orn2_b64 s[22:23], vcc, exec
	s_branch .LBB0_1286
.LBB0_1293:
	s_or_b64 exec, exec, s[16:17]
	s_xor_b64 s[2:3], s[18:19], -1
	s_and_saveexec_b64 s[12:13], s[2:3]
	s_xor_b64 s[12:13], exec, s[12:13]
	s_cbranch_execz .LBB0_1295
	v_mov_b32_e32 v2, 1
	v_mov_b64_e32 v[0:1], s[10:11]
	global_atomic_add v[0:1], v2, off

.LBB0_1296:
	s_andn2_saveexec_b64 s[2:3], s[6:7]
	s_cbranch_execz .LBB0_1312
	v_mov_b32_e32 v1, s4
	v_add_co_u32_e32 v2, vcc, 0x103000, v1
	v_mov_b32_e32 v1, s5
	buffer_wbl2 sc1
	s_waitcnt vmcnt(0)
	v_addc_co_u32_e32 v3, vcc, 0, v1, vcc
	v_mov_b32_e32 v1, 1
	global_atomic_add v1, v[2:3], v1, off offset:1024 sc0
	v_cvt_f32_u32_e32 v2, v0
	v_sub_u32_e32 v3, 0, v0
	s_add_u32 s6, s4, 0x103500
	s_addc_u32 s7, s5, 0
	v_rcp_iflag_f32_e32 v2, v2
	s_mov_b64 s[10:11], -1
	v_mul_f32_e32 v2, 0x4f7ffffe, v2
	v_cvt_u32_f32_e32 v2, v2
	v_mul_lo_u32 v3, v3, v2
	v_mul_hi_u32 v3, v2, v3
	v_add_u32_e32 v2, v2, v3
	s_waitcnt vmcnt(0) lgkmcnt(0)
	v_mul_hi_u32 v2, v1, v2
	v_mul_lo_u32 v4, v2, v0
	v_add_u32_e32 v3, 1, v1
	v_sub_u32_e32 v1, v1, v4
	v_add_u32_e32 v5, 1, v2
	v_cmp_ge_u32_e32 vcc, v1, v0
	v_sub_u32_e32 v4, v1, v0
	s_nop 0
	v_cndmask_b32_e32 v2, v2, v5, vcc
	v_cndmask_b32_e32 v1, v1, v4, vcc
	v_add_u32_e32 v4, 1, v2
	v_cmp_ge_u32_e32 vcc, v1, v0
	s_nop 1
	v_cndmask_b32_e32 v2, v2, v4, vcc
	v_mad_u64_u32 v[0:1], s[2:3], v0, v2, v[0:1]
	v_cmp_ne_u32_e32 vcc, v3, v0
	v_mov_b64_e32 v[0:1], s[6:7]
	s_and_saveexec_b64 s[8:9], vcc
	s_cbranch_execz .LBB0_1309
	v_mov_b64_e32 v[0:1], s[6:7]
	global_load_dword v0, v[0:1], off sc1
	s_mov_b64 s[16:17], 0
	s_waitcnt vmcnt(0) lgkmcnt(0)
	v_cmp_eq_u32_e32 vcc, v0, v2
	s_and_saveexec_b64 s[12:13], vcc
	s_cbranch_execz .LBB0_1308
	s_add_u32 s10, s4, 0x100200
	s_addc_u32 s11, s5, 0
	s_mov_b32 s2, 1
	s_mov_b64 s[4:5], 0
	s_branch .LBB0_1301

.LBB0_1303:
	v_mov_b64_e32 v[0:1], s[10:11]
	global_load_dword v0, v[0:1], off sc1
	s_mov_b64 s[20:21], 0
	s_mov_b64 s[18:19], -1
	s_waitcnt vmcnt(0) lgkmcnt(0)
	v_cmp_eq_u32_e32 vcc, 0, v0
	s_and_saveexec_b64 s[22:23], vcc
	s_cmp_lt_u32 s2, 0x40001
	s_cselect_b64 s[14:15], -1, 0
	s_xor_b64 s[18:19], exec, -1
	s_and_b64 s[20:21], s[14:15], exec
	s_or_b64 exec, exec, s[22:23]
	s_mov_b64 s[22:23], -1
	s_and_saveexec_b64 s[24:25], s[20:21]
	s_cbranch_execz .LBB0_1300
.LBB0_1306:
	v_mov_b64_e32 v[0:1], s[6:7]
	global_load_dword v0, v[0:1], off sc1
	s_add_i32 s2, s2, 1
	s_or_b64 s[18:19], s[18:19], exec
	s_waitcnt vmcnt(0) lgkmcnt(0)
	v_cmp_ne_u32_e32 vcc, v0, v2
	s_orn2_b64 s[22:23], vcc, exec
	s_branch .LBB0_1300

.LBB0_1311:
	s_or_b64 exec, exec, s[4:5]
	v_mov_b32_e32 v0, s1
	v_add_co_u32_e32 v0, vcc, 0x2000, v0
	v_mov_b32_e32 v1, s0
	s_nop 0
	v_addc_co_u32_e32 v1, vcc, 0, v1, vcc
	v_mov_b32_e32 v2, 1
	s_waitcnt vmcnt(0) lgkmcnt(0)
	buffer_inv sc1
	global_atomic_add v[0:1], v2, off offset:1024
	s_waitcnt vmcnt(0)

.LBB0_1335:
	v_lshl_add_u32 v168, s30, 8, v188
	v_lshl_add_u32 v172, s28, 8, v186
	v_ashrrev_i32_e32 v169, 31, v168
	v_lshlrev_b64 v[202:203], 1, v[168:169]
	v_ashrrev_i32_e32 v173, 31, v172
	v_lshl_add_u64 v[170:171], s[12:13], 0, v[202:203]
	v_lshlrev_b64 v[204:205], 12, v[172:173]
	v_lshl_add_u64 v[128:129], v[170:171], 0, v[204:205]
	global_load_dwordx4 v[194:197], v[128:129], off
	global_load_dwordx4 v[198:201], v[128:129], off offset:256
	v_or_b32_e32 v182, 16, v172
	v_or_b32_e32 v178, 32, v172
	v_or_b32_e32 v174, 48, v172
	v_ashrrev_i32_e32 v183, 31, v182
	v_ashrrev_i32_e32 v179, 31, v178
	v_ashrrev_i32_e32 v175, 31, v174
	v_lshlrev_b64 v[184:185], 12, v[182:183]
	v_lshlrev_b64 v[180:181], 12, v[178:179]
	v_lshlrev_b64 v[176:177], 12, v[174:175]
	v_lshl_add_u64 v[128:129], v[170:171], 0, v[184:185]
	v_lshl_add_u64 v[130:131], v[170:171], 0, v[180:181]
	v_lshl_add_u64 v[206:207], v[170:171], 0, v[176:177]
	global_load_dwordx4 v[148:151], v[128:129], off
	global_load_dwordx4 v[144:147], v[128:129], off offset:256
	global_load_dwordx4 v[140:143], v[130:131], off
	global_load_dwordx4 v[136:139], v[130:131], off offset:256
	global_load_dwordx4 v[132:135], v[206:207], off
	s_nop 0
	global_load_dwordx4 v[128:131], v[206:207], off offset:256
	v_and_b32_e32 v206, 64, v192
	v_xor_b32_e32 v193, 16, v192
	v_add_u32_e32 v206, 64, v206
	v_xor_b32_e32 v207, 32, v192
	v_cmp_lt_i32_e32 vcc, v193, v206
	v_lshl_add_u64 v[204:205], s[16:17], 0, v[204:205]
	v_lshl_add_u64 v[202:203], v[204:205], 0, v[202:203]
	v_cndmask_b32_e32 v193, v192, v193, vcc
	v_cmp_lt_i32_e32 vcc, v207, v206
	v_lshlrev_b32_e32 v193, 2, v193
	s_waitcnt vmcnt(0) lgkmcnt(0)
	v_lshlrev_b32_e32 v204, 16, v194
	v_cndmask_b32_e32 v212, v192, v207, vcc
	v_and_b32_e32 v205, 0xffff0000, v194
	v_lshlrev_b32_e32 v194, 16, v195
	v_and_b32_e32 v195, 0xffff0000, v195
	v_lshlrev_b32_e32 v206, 16, v196
	v_and_b32_e32 v207, 0xffff0000, v196
	v_lshlrev_b32_e32 v196, 16, v197
	v_and_b32_e32 v197, 0xffff0000, v197
	v_lshlrev_b32_e32 v208, 16, v198
	v_and_b32_e32 v209, 0xffff0000, v198
	v_lshlrev_b32_e32 v198, 16, v199
	v_and_b32_e32 v199, 0xffff0000, v199
	v_lshlrev_b32_e32 v210, 16, v200
	v_and_b32_e32 v211, 0xffff0000, v200
	v_lshlrev_b32_e32 v200, 16, v201
	v_and_b32_e32 v201, 0xffff0000, v201
	v_pk_add_f32 v[126:127], v[126:127], v[194:195]
	v_pk_add_f32 v[124:125], v[124:125], v[204:205]
	v_pk_add_f32 v[122:123], v[122:123], v[196:197]
	v_pk_add_f32 v[120:121], v[120:121], v[206:207]
	v_pk_add_f32 v[118:119], v[118:119], v[198:199]
	v_pk_add_f32 v[116:117], v[116:117], v[208:209]
	v_pk_add_f32 v[194:195], v[114:115], v[200:201]
	v_pk_add_f32 v[196:197], v[112:113], v[210:211]
	v_cvt_pk_bf16_f32 v112, v124, v125
	v_cvt_pk_bf16_f32 v113, v126, v127
	v_mul_f32_e32 v114, v125, v125
	v_mul_f32_e32 v115, v127, v127
	v_mul_f32_e32 v125, v121, v121
	v_mul_f32_e32 v127, v123, v123
	v_mul_f32_e32 v198, v117, v117
	v_mul_f32_e32 v199, v119, v119
	v_mul_f32_e32 v200, v197, v197
	v_mul_f32_e32 v201, v195, v195
	v_fmac_f32_e32 v114, v124, v124
	v_fmac_f32_e32 v115, v126, v126
	v_fmac_f32_e32 v125, v120, v120
	v_fmac_f32_e32 v127, v122, v122
	v_fmac_f32_e32 v198, v116, v116
	v_fmac_f32_e32 v199, v118, v118
	v_fmac_f32_e32 v200, v196, v196
	v_fmac_f32_e32 v201, v194, v194
	v_add_f32_e32 v114, v114, v115
	v_add_f32_e32 v115, v125, v127
	v_add_f32_e32 v124, v198, v199
	v_add_f32_e32 v125, v200, v201
	v_add_f32_e32 v114, v114, v115
	v_add_f32_e32 v115, v124, v125
	v_add_f32_e32 v124, v114, v115
	ds_bpermute_b32 v125, v193, v124
	v_cvt_pk_bf16_f32 v114, v120, v121
	v_cvt_pk_bf16_f32 v115, v122, v123
	global_store_dwordx4 v[202:203], v[112:115], off
	v_cvt_pk_bf16_f32 v116, v116, v117
	v_cvt_pk_bf16_f32 v117, v118, v119
	v_cvt_pk_bf16_f32 v118, v196, v197
	v_cvt_pk_bf16_f32 v119, v194, v195
	global_store_dwordx4 v[202:203], v[116:119], off offset:256
	s_waitcnt lgkmcnt(0)
	v_add_f32_e32 v113, v124, v125
	v_lshlrev_b32_e32 v112, 2, v212
	ds_bpermute_b32 v114, v112, v113
	s_and_saveexec_b64 s[4:5], s[6:7]
	s_cbranch_execz .LBB0_1337
	s_waitcnt lgkmcnt(0)
	v_add_f32_e32 v113, v113, v114
	v_lshl_add_u64 v[114:115], v[172:173], 2, s[10:11]
	global_atomic_add_f32 v[114:115], v113, off
.LBB0_1337:
	s_or_b64 exec, exec, s[4:5]
	s_waitcnt lgkmcnt(0)
	v_lshlrev_b32_e32 v114, 16, v148
	v_and_b32_e32 v115, 0xffff0000, v148
	v_lshlrev_b32_e32 v116, 16, v149
	v_and_b32_e32 v117, 0xffff0000, v149
	v_lshlrev_b32_e32 v118, 16, v150
	v_and_b32_e32 v119, 0xffff0000, v150
	v_pk_add_f32 v[108:109], v[108:109], v[114:115]
	v_pk_add_f32 v[110:111], v[110:111], v[116:117]
	v_pk_add_f32 v[116:117], v[104:105], v[118:119]
	v_cvt_pk_bf16_f32 v104, v108, v109
	v_mul_f32_e32 v109, v109, v109
	v_lshlrev_b32_e32 v120, 16, v151
	v_and_b32_e32 v121, 0xffff0000, v151
	v_fmac_f32_e32 v109, v108, v108
	v_mul_f32_e32 v108, v111, v111
	v_pk_add_f32 v[114:115], v[106:107], v[120:121]
	v_fmac_f32_e32 v108, v110, v110
	v_cvt_pk_bf16_f32 v105, v110, v111
	v_add_f32_e32 v108, v109, v108
	v_mul_f32_e32 v109, v117, v117
	v_mul_f32_e32 v110, v115, v115
	v_fmac_f32_e32 v109, v116, v116
	v_fmac_f32_e32 v110, v114, v114
	v_add_f32_e32 v109, v109, v110
	v_add_f32_e32 v113, v108, v109
	v_lshlrev_b32_e32 v108, 16, v144
	v_and_b32_e32 v109, 0xffff0000, v144
	v_lshlrev_b32_e32 v110, 16, v145
	v_and_b32_e32 v111, 0xffff0000, v145
	v_cvt_pk_bf16_f32 v106, v116, v117
	v_cvt_pk_bf16_f32 v107, v114, v115
	v_lshlrev_b32_e32 v114, 16, v146
	v_and_b32_e32 v115, 0xffff0000, v146
	v_pk_add_f32 v[102:103], v[102:103], v[110:111]
	v_pk_add_f32 v[100:101], v[100:101], v[108:109]
	v_lshlrev_b32_e32 v116, 16, v147
	v_and_b32_e32 v117, 0xffff0000, v147
	v_pk_add_f32 v[110:111], v[96:97], v[114:115]
	v_mul_f32_e32 v96, v101, v101
	v_mul_f32_e32 v97, v103, v103
	v_pk_add_f32 v[108:109], v[98:99], v[116:117]
	v_fmac_f32_e32 v96, v100, v100
	v_fmac_f32_e32 v97, v102, v102
	v_add_f32_e32 v96, v96, v97
	v_mul_f32_e32 v97, v111, v111
	v_mul_f32_e32 v98, v109, v109
	v_fmac_f32_e32 v97, v110, v110
	v_fmac_f32_e32 v98, v108, v108
	v_add_f32_e32 v97, v97, v98
	v_add_f32_e32 v96, v96, v97
	v_add_f32_e32 v99, v113, v96
	ds_bpermute_b32 v113, v193, v99
	v_lshl_add_u64 v[96:97], s[16:17], 0, v[184:185]
	v_lshl_add_u64 v[114:115], v[168:169], 1, v[96:97]
	global_store_dwordx4 v[114:115], v[104:107], off
	v_cvt_pk_bf16_f32 v98, v100, v101
	s_waitcnt lgkmcnt(0)
	v_add_f32_e32 v96, v99, v113
	ds_bpermute_b32 v97, v112, v96
	v_cvt_pk_bf16_f32 v99, v102, v103
	v_cvt_pk_bf16_f32 v100, v110, v111
	v_cvt_pk_bf16_f32 v101, v108, v109
	global_store_dwordx4 v[114:115], v[98:101], off offset:256
	s_and_saveexec_b64 s[4:5], s[6:7]
	s_cbranch_execz .LBB0_1339
	s_waitcnt lgkmcnt(0)
	v_add_f32_e32 v98, v96, v97
	v_lshl_add_u64 v[96:97], v[182:183], 2, s[10:11]
	global_atomic_add_f32 v[96:97], v98, off
.LBB0_1339:
	s_or_b64 exec, exec, s[4:5]
	v_lshlrev_b32_e32 v96, 16, v140
	s_waitcnt lgkmcnt(0)
	v_and_b32_e32 v97, 0xffff0000, v140
	v_lshlrev_b32_e32 v98, 16, v141
	v_and_b32_e32 v99, 0xffff0000, v141
	v_lshlrev_b32_e32 v100, 16, v142
	v_and_b32_e32 v101, 0xffff0000, v142
	v_pk_add_f32 v[92:93], v[92:93], v[96:97]
	v_pk_add_f32 v[94:95], v[94:95], v[98:99]
	v_pk_add_f32 v[98:99], v[88:89], v[100:101]
	v_cvt_pk_bf16_f32 v88, v92, v93
	v_mul_f32_e32 v93, v93, v93
	v_lshlrev_b32_e32 v102, 16, v143
	v_and_b32_e32 v103, 0xffff0000, v143
	v_fmac_f32_e32 v93, v92, v92
	v_mul_f32_e32 v92, v95, v95
	v_pk_add_f32 v[96:97], v[90:91], v[102:103]
	v_fmac_f32_e32 v92, v94, v94
	v_cvt_pk_bf16_f32 v89, v94, v95
	v_add_f32_e32 v92, v93, v92
	v_mul_f32_e32 v93, v99, v99
	v_mul_f32_e32 v94, v97, v97
	v_fmac_f32_e32 v93, v98, v98
	v_fmac_f32_e32 v94, v96, v96
	v_add_f32_e32 v93, v93, v94
	v_add_f32_e32 v100, v92, v93
	v_lshlrev_b32_e32 v92, 16, v136
	v_and_b32_e32 v93, 0xffff0000, v136
	v_lshlrev_b32_e32 v94, 16, v137
	v_and_b32_e32 v95, 0xffff0000, v137
	v_cvt_pk_bf16_f32 v90, v98, v99
	v_cvt_pk_bf16_f32 v91, v96, v97
	v_lshlrev_b32_e32 v96, 16, v138
	v_and_b32_e32 v97, 0xffff0000, v138
	v_pk_add_f32 v[86:87], v[86:87], v[94:95]
	v_pk_add_f32 v[84:85], v[84:85], v[92:93]
	v_lshlrev_b32_e32 v98, 16, v139
	v_and_b32_e32 v99, 0xffff0000, v139
	v_pk_add_f32 v[94:95], v[80:81], v[96:97]
	v_mul_f32_e32 v80, v85, v85
	v_mul_f32_e32 v81, v87, v87
	v_pk_add_f32 v[92:93], v[82:83], v[98:99]
	v_fmac_f32_e32 v80, v84, v84
	v_fmac_f32_e32 v81, v86, v86
	v_add_f32_e32 v80, v80, v81
	v_mul_f32_e32 v81, v95, v95
	v_mul_f32_e32 v82, v93, v93
	v_fmac_f32_e32 v81, v94, v94
	v_fmac_f32_e32 v82, v92, v92
	v_add_f32_e32 v81, v81, v82
	v_add_f32_e32 v80, v80, v81
	v_add_f32_e32 v83, v100, v80
	ds_bpermute_b32 v98, v193, v83
	v_lshl_add_u64 v[80:81], s[16:17], 0, v[180:181]
	v_lshl_add_u64 v[96:97], v[168:169], 1, v[80:81]
	global_store_dwordx4 v[96:97], v[88:91], off
	v_cvt_pk_bf16_f32 v82, v84, v85
	s_waitcnt lgkmcnt(0)
	v_add_f32_e32 v80, v83, v98
	ds_bpermute_b32 v81, v112, v80
	v_cvt_pk_bf16_f32 v83, v86, v87
	v_cvt_pk_bf16_f32 v84, v94, v95
	v_cvt_pk_bf16_f32 v85, v92, v93
	global_store_dwordx4 v[96:97], v[82:85], off offset:256
	s_and_saveexec_b64 s[4:5], s[6:7]
	s_cbranch_execz .LBB0_1341
	s_waitcnt lgkmcnt(0)
	v_add_f32_e32 v82, v80, v81
	v_lshl_add_u64 v[80:81], v[178:179], 2, s[10:11]
	global_atomic_add_f32 v[80:81], v82, off
.LBB0_1341:
	s_or_b64 exec, exec, s[4:5]
	v_lshlrev_b32_e32 v80, 16, v132
	s_waitcnt lgkmcnt(0)
	v_and_b32_e32 v81, 0xffff0000, v132
	v_lshlrev_b32_e32 v82, 16, v133
	v_and_b32_e32 v83, 0xffff0000, v133
	v_lshlrev_b32_e32 v84, 16, v134
	v_and_b32_e32 v85, 0xffff0000, v134
	v_pk_add_f32 v[76:77], v[76:77], v[80:81]
	v_pk_add_f32 v[78:79], v[78:79], v[82:83]
	v_pk_add_f32 v[82:83], v[72:73], v[84:85]
	v_cvt_pk_bf16_f32 v72, v76, v77
	v_mul_f32_e32 v77, v77, v77
	v_lshlrev_b32_e32 v86, 16, v135
	v_and_b32_e32 v87, 0xffff0000, v135
	v_fmac_f32_e32 v77, v76, v76
	v_mul_f32_e32 v76, v79, v79
	v_pk_add_f32 v[80:81], v[74:75], v[86:87]
	v_fmac_f32_e32 v76, v78, v78
	v_cvt_pk_bf16_f32 v73, v78, v79
	v_add_f32_e32 v76, v77, v76
	v_mul_f32_e32 v77, v83, v83
	v_mul_f32_e32 v78, v81, v81
	v_fmac_f32_e32 v77, v82, v82
	v_fmac_f32_e32 v78, v80, v80
	v_add_f32_e32 v77, v77, v78
	v_add_f32_e32 v84, v76, v77
	v_lshlrev_b32_e32 v76, 16, v128
	v_and_b32_e32 v77, 0xffff0000, v128
	v_lshlrev_b32_e32 v78, 16, v129
	v_and_b32_e32 v79, 0xffff0000, v129
	v_cvt_pk_bf16_f32 v74, v82, v83
	v_cvt_pk_bf16_f32 v75, v80, v81
	v_lshlrev_b32_e32 v80, 16, v130
	v_and_b32_e32 v81, 0xffff0000, v130
	v_pk_add_f32 v[70:71], v[70:71], v[78:79]
	v_pk_add_f32 v[68:69], v[68:69], v[76:77]
	v_lshlrev_b32_e32 v82, 16, v131
	v_and_b32_e32 v83, 0xffff0000, v131
	v_pk_add_f32 v[78:79], v[64:65], v[80:81]
	v_mul_f32_e32 v64, v69, v69
	v_mul_f32_e32 v65, v71, v71
	v_pk_add_f32 v[76:77], v[66:67], v[82:83]
	v_fmac_f32_e32 v64, v68, v68
	v_fmac_f32_e32 v65, v70, v70
	v_add_f32_e32 v64, v64, v65
	v_mul_f32_e32 v65, v79, v79
	v_mul_f32_e32 v66, v77, v77
	v_fmac_f32_e32 v65, v78, v78
	v_fmac_f32_e32 v66, v76, v76
	v_add_f32_e32 v65, v65, v66
	v_add_f32_e32 v64, v64, v65
	v_add_f32_e32 v67, v84, v64
	ds_bpermute_b32 v82, v193, v67
	v_lshl_add_u64 v[64:65], s[16:17], 0, v[176:177]
	v_lshl_add_u64 v[80:81], v[168:169], 1, v[64:65]
	global_store_dwordx4 v[80:81], v[72:75], off
	v_cvt_pk_bf16_f32 v66, v68, v69
	s_waitcnt lgkmcnt(0)
	v_add_f32_e32 v64, v67, v82
	ds_bpermute_b32 v65, v112, v64
	v_cvt_pk_bf16_f32 v67, v70, v71
	v_cvt_pk_bf16_f32 v68, v78, v79
	v_cvt_pk_bf16_f32 v69, v76, v77
	global_store_dwordx4 v[80:81], v[66:69], off offset:256
	s_and_saveexec_b64 s[4:5], s[6:7]
	s_cbranch_execz .LBB0_1343
	s_waitcnt lgkmcnt(0)
	v_add_f32_e32 v66, v64, v65
	v_lshl_add_u64 v[64:65], v[174:175], 2, s[10:11]
	global_atomic_add_f32 v[64:65], v66, off
.LBB0_1343:
	s_or_b64 exec, exec, s[4:5]
	v_add_u32_e32 v100, 0x80, v172
	v_ashrrev_i32_e32 v101, 31, v100
	v_lshlrev_b64 v[110:111], 12, v[100:101]
	s_waitcnt lgkmcnt(0)
	v_lshl_add_u64 v[64:65], v[170:171], 0, v[110:111]
	global_load_dwordx4 v[102:105], v[64:65], off
	global_load_dwordx4 v[106:109], v[64:65], off offset:256
	v_add_u32_e32 v96, 0x90, v172
	v_add_u32_e32 v92, 0xa0, v172
	v_add_u32_e32 v88, 0xb0, v172
	v_ashrrev_i32_e32 v97, 31, v96
	v_ashrrev_i32_e32 v93, 31, v92
	v_ashrrev_i32_e32 v89, 31, v88
	v_lshlrev_b64 v[98:99], 12, v[96:97]
	v_lshlrev_b64 v[94:95], 12, v[92:93]
	v_lshlrev_b64 v[90:91], 12, v[88:89]
	v_lshl_add_u64 v[64:65], v[170:171], 0, v[98:99]
	v_lshl_add_u64 v[66:67], v[170:171], 0, v[94:95]
	v_lshl_add_u64 v[114:115], v[170:171], 0, v[90:91]
	global_load_dwordx4 v[84:87], v[64:65], off
	global_load_dwordx4 v[80:83], v[64:65], off offset:256
	global_load_dwordx4 v[76:79], v[66:67], off
	global_load_dwordx4 v[72:75], v[66:67], off offset:256
	global_load_dwordx4 v[68:71], v[114:115], off
	s_nop 0
	global_load_dwordx4 v[64:67], v[114:115], off offset:256
	s_waitcnt vmcnt(0) lgkmcnt(0)
	v_lshlrev_b32_e32 v114, 16, v102
	v_and_b32_e32 v115, 0xffff0000, v102
	v_lshlrev_b32_e32 v102, 16, v103
	v_and_b32_e32 v103, 0xffff0000, v103
	v_lshlrev_b32_e32 v116, 16, v104
	v_and_b32_e32 v117, 0xffff0000, v104
	v_lshlrev_b32_e32 v104, 16, v105
	v_and_b32_e32 v105, 0xffff0000, v105
	v_lshlrev_b32_e32 v118, 16, v106
	v_and_b32_e32 v119, 0xffff0000, v106
	v_lshlrev_b32_e32 v106, 16, v107
	v_and_b32_e32 v107, 0xffff0000, v107
	v_lshlrev_b32_e32 v120, 16, v108
	v_and_b32_e32 v121, 0xffff0000, v108
	v_lshlrev_b32_e32 v108, 16, v109
	v_and_b32_e32 v109, 0xffff0000, v109
	v_pk_add_f32 v[62:63], v[62:63], v[102:103]
	v_pk_add_f32 v[60:61], v[60:61], v[114:115]
	v_pk_add_f32 v[58:59], v[58:59], v[104:105]
	v_pk_add_f32 v[56:57], v[56:57], v[116:117]
	v_pk_add_f32 v[54:55], v[54:55], v[106:107]
	v_pk_add_f32 v[52:53], v[52:53], v[118:119]
	v_pk_add_f32 v[102:103], v[50:51], v[108:109]
	v_pk_add_f32 v[104:105], v[48:49], v[120:121]
	v_cvt_pk_bf16_f32 v48, v60, v61
	v_cvt_pk_bf16_f32 v49, v62, v63
	v_cvt_pk_bf16_f32 v50, v56, v57
	v_cvt_pk_bf16_f32 v51, v58, v59
	v_mul_f32_e32 v61, v61, v61
	v_mul_f32_e32 v63, v63, v63
	v_mul_f32_e32 v57, v57, v57
	v_mul_f32_e32 v59, v59, v59
	v_mul_f32_e32 v106, v53, v53
	v_mul_f32_e32 v107, v55, v55
	v_mul_f32_e32 v108, v105, v105
	v_mul_f32_e32 v109, v103, v103
	v_fmac_f32_e32 v61, v60, v60
	v_fmac_f32_e32 v63, v62, v62
	v_fmac_f32_e32 v57, v56, v56
	v_fmac_f32_e32 v59, v58, v58
	v_fmac_f32_e32 v106, v52, v52
	v_fmac_f32_e32 v107, v54, v54
	v_fmac_f32_e32 v108, v104, v104
	v_fmac_f32_e32 v109, v102, v102
	v_add_f32_e32 v56, v61, v63
	v_add_f32_e32 v57, v57, v59
	v_add_f32_e32 v58, v106, v107
	v_add_f32_e32 v59, v108, v109
	v_add_f32_e32 v56, v56, v57
	v_add_f32_e32 v57, v58, v59
	v_add_f32_e32 v58, v56, v57
	ds_bpermute_b32 v59, v193, v58
	v_lshl_add_u64 v[56:57], s[16:17], 0, v[110:111]
	v_lshl_add_u64 v[56:57], v[168:169], 1, v[56:57]
	global_store_dwordx4 v[56:57], v[48:51], off
	s_waitcnt lgkmcnt(0)
	s_nop 0
	v_add_f32_e32 v48, v58, v59
	ds_bpermute_b32 v49, v112, v48
	v_cvt_pk_bf16_f32 v50, v52, v53
	v_cvt_pk_bf16_f32 v51, v54, v55
	v_cvt_pk_bf16_f32 v52, v104, v105
	v_cvt_pk_bf16_f32 v53, v102, v103
	global_store_dwordx4 v[56:57], v[50:53], off offset:256
	s_and_saveexec_b64 s[4:5], s[6:7]
	s_cbranch_execz .LBB0_1345
	s_waitcnt lgkmcnt(0)
	v_add_f32_e32 v50, v48, v49
	v_lshl_add_u64 v[48:49], v[100:101], 2, s[10:11]
	global_atomic_add_f32 v[48:49], v50, off
.LBB0_1345:
	s_or_b64 exec, exec, s[4:5]
	v_lshlrev_b32_e32 v48, 16, v84
	s_waitcnt lgkmcnt(0)
	v_and_b32_e32 v49, 0xffff0000, v84
	v_lshlrev_b32_e32 v50, 16, v85
	v_and_b32_e32 v51, 0xffff0000, v85
	v_lshlrev_b32_e32 v52, 16, v86
	v_and_b32_e32 v53, 0xffff0000, v86
	v_pk_add_f32 v[44:45], v[44:45], v[48:49]
	v_pk_add_f32 v[46:47], v[46:47], v[50:51]
	v_pk_add_f32 v[50:51], v[40:41], v[52:53]
	v_cvt_pk_bf16_f32 v40, v44, v45
	v_mul_f32_e32 v45, v45, v45
	v_lshlrev_b32_e32 v54, 16, v87
	v_and_b32_e32 v55, 0xffff0000, v87
	v_fmac_f32_e32 v45, v44, v44
	v_mul_f32_e32 v44, v47, v47
	v_pk_add_f32 v[48:49], v[42:43], v[54:55]
	v_fmac_f32_e32 v44, v46, v46
	v_cvt_pk_bf16_f32 v41, v46, v47
	v_add_f32_e32 v44, v45, v44
	v_mul_f32_e32 v45, v51, v51
	v_mul_f32_e32 v46, v49, v49
	v_fmac_f32_e32 v45, v50, v50
	v_fmac_f32_e32 v46, v48, v48
	v_add_f32_e32 v45, v45, v46
	v_add_f32_e32 v52, v44, v45
	v_lshlrev_b32_e32 v44, 16, v80
	v_and_b32_e32 v45, 0xffff0000, v80
	v_lshlrev_b32_e32 v46, 16, v81
	v_and_b32_e32 v47, 0xffff0000, v81
	v_cvt_pk_bf16_f32 v42, v50, v51
	v_cvt_pk_bf16_f32 v43, v48, v49
	v_lshlrev_b32_e32 v48, 16, v82
	v_and_b32_e32 v49, 0xffff0000, v82
	v_pk_add_f32 v[38:39], v[38:39], v[46:47]
	v_pk_add_f32 v[36:37], v[36:37], v[44:45]
	v_lshlrev_b32_e32 v50, 16, v83
	v_and_b32_e32 v51, 0xffff0000, v83
	v_pk_add_f32 v[46:47], v[32:33], v[48:49]
	v_mul_f32_e32 v32, v37, v37
	v_mul_f32_e32 v33, v39, v39
	v_pk_add_f32 v[44:45], v[34:35], v[50:51]
	v_fmac_f32_e32 v32, v36, v36
	v_fmac_f32_e32 v33, v38, v38
	v_add_f32_e32 v32, v32, v33
	v_mul_f32_e32 v33, v47, v47
	v_mul_f32_e32 v34, v45, v45
	v_fmac_f32_e32 v33, v46, v46
	v_fmac_f32_e32 v34, v44, v44
	v_add_f32_e32 v33, v33, v34
	v_add_f32_e32 v32, v32, v33
	v_add_f32_e32 v35, v52, v32
	ds_bpermute_b32 v50, v193, v35
	v_lshl_add_u64 v[32:33], s[16:17], 0, v[98:99]
	v_lshl_add_u64 v[48:49], v[168:169], 1, v[32:33]
	global_store_dwordx4 v[48:49], v[40:43], off
	v_cvt_pk_bf16_f32 v34, v36, v37
	s_waitcnt lgkmcnt(0)
	v_add_f32_e32 v32, v35, v50
	ds_bpermute_b32 v33, v112, v32
	v_cvt_pk_bf16_f32 v35, v38, v39
	v_cvt_pk_bf16_f32 v36, v46, v47
	v_cvt_pk_bf16_f32 v37, v44, v45
	global_store_dwordx4 v[48:49], v[34:37], off offset:256
	s_and_saveexec_b64 s[4:5], s[6:7]
	s_cbranch_execz .LBB0_1347
	s_waitcnt lgkmcnt(0)
	v_add_f32_e32 v34, v32, v33
	v_lshl_add_u64 v[32:33], v[96:97], 2, s[10:11]
	global_atomic_add_f32 v[32:33], v34, off
.LBB0_1347:
	s_or_b64 exec, exec, s[4:5]
	v_lshlrev_b32_e32 v32, 16, v76
	s_waitcnt lgkmcnt(0)
	v_and_b32_e32 v33, 0xffff0000, v76
	v_lshlrev_b32_e32 v34, 16, v77
	v_and_b32_e32 v35, 0xffff0000, v77
	v_lshlrev_b32_e32 v36, 16, v78
	v_and_b32_e32 v37, 0xffff0000, v78
	v_pk_add_f32 v[28:29], v[28:29], v[32:33]
	v_pk_add_f32 v[30:31], v[30:31], v[34:35]
	v_pk_add_f32 v[34:35], v[24:25], v[36:37]
	v_cvt_pk_bf16_f32 v24, v28, v29
	v_mul_f32_e32 v29, v29, v29
	v_lshlrev_b32_e32 v38, 16, v79
	v_and_b32_e32 v39, 0xffff0000, v79
	v_fmac_f32_e32 v29, v28, v28
	v_mul_f32_e32 v28, v31, v31
	v_pk_add_f32 v[32:33], v[26:27], v[38:39]
	v_fmac_f32_e32 v28, v30, v30
	v_cvt_pk_bf16_f32 v25, v30, v31
	v_add_f32_e32 v28, v29, v28
	v_mul_f32_e32 v29, v35, v35
	v_mul_f32_e32 v30, v33, v33
	v_fmac_f32_e32 v29, v34, v34
	v_fmac_f32_e32 v30, v32, v32
	v_add_f32_e32 v29, v29, v30
	v_add_f32_e32 v36, v28, v29
	v_lshlrev_b32_e32 v28, 16, v72
	v_and_b32_e32 v29, 0xffff0000, v72
	v_lshlrev_b32_e32 v30, 16, v73
	v_and_b32_e32 v31, 0xffff0000, v73
	v_cvt_pk_bf16_f32 v26, v34, v35
	v_cvt_pk_bf16_f32 v27, v32, v33
	v_lshlrev_b32_e32 v32, 16, v74
	v_and_b32_e32 v33, 0xffff0000, v74
	v_pk_add_f32 v[22:23], v[22:23], v[30:31]
	v_pk_add_f32 v[20:21], v[20:21], v[28:29]
	v_lshlrev_b32_e32 v34, 16, v75
	v_and_b32_e32 v35, 0xffff0000, v75
	v_pk_add_f32 v[30:31], v[16:17], v[32:33]
	v_mul_f32_e32 v16, v21, v21
	v_mul_f32_e32 v17, v23, v23
	v_pk_add_f32 v[28:29], v[18:19], v[34:35]
	v_fmac_f32_e32 v16, v20, v20
	v_fmac_f32_e32 v17, v22, v22
	v_add_f32_e32 v16, v16, v17
	v_mul_f32_e32 v17, v31, v31
	v_mul_f32_e32 v18, v29, v29
	v_fmac_f32_e32 v17, v30, v30
	v_fmac_f32_e32 v18, v28, v28
	v_add_f32_e32 v17, v17, v18
	v_add_f32_e32 v16, v16, v17
	v_add_f32_e32 v19, v36, v16
	ds_bpermute_b32 v34, v193, v19
	v_lshl_add_u64 v[16:17], s[16:17], 0, v[94:95]
	v_lshl_add_u64 v[32:33], v[168:169], 1, v[16:17]
	global_store_dwordx4 v[32:33], v[24:27], off
	v_cvt_pk_bf16_f32 v18, v20, v21
	s_waitcnt lgkmcnt(0)
	v_add_f32_e32 v16, v19, v34
	ds_bpermute_b32 v17, v112, v16
	v_cvt_pk_bf16_f32 v19, v22, v23
	v_cvt_pk_bf16_f32 v20, v30, v31
	v_cvt_pk_bf16_f32 v21, v28, v29
	global_store_dwordx4 v[32:33], v[18:21], off offset:256
	s_and_saveexec_b64 s[4:5], s[6:7]
	s_cbranch_execz .LBB0_1349
	s_waitcnt lgkmcnt(0)
	v_add_f32_e32 v18, v16, v17
	v_lshl_add_u64 v[16:17], v[92:93], 2, s[10:11]
	global_atomic_add_f32 v[16:17], v18, off
.LBB0_1349:
	s_or_b64 exec, exec, s[4:5]
	v_lshlrev_b32_e32 v16, 16, v68
	s_waitcnt lgkmcnt(0)
	v_and_b32_e32 v17, 0xffff0000, v68
	v_lshlrev_b32_e32 v18, 16, v69
	v_and_b32_e32 v19, 0xffff0000, v69
	v_lshlrev_b32_e32 v20, 16, v70
	v_and_b32_e32 v21, 0xffff0000, v70
	v_pk_add_f32 v[12:13], v[12:13], v[16:17]
	v_pk_add_f32 v[14:15], v[14:15], v[18:19]
	v_pk_add_f32 v[18:19], v[8:9], v[20:21]
	v_cvt_pk_bf16_f32 v8, v12, v13
	v_mul_f32_e32 v13, v13, v13
	v_lshlrev_b32_e32 v22, 16, v71
	v_and_b32_e32 v23, 0xffff0000, v71
	v_fmac_f32_e32 v13, v12, v12
	v_mul_f32_e32 v12, v15, v15
	v_pk_add_f32 v[16:17], v[10:11], v[22:23]
	v_fmac_f32_e32 v12, v14, v14
	v_cvt_pk_bf16_f32 v9, v14, v15
	v_add_f32_e32 v12, v13, v12
	v_mul_f32_e32 v13, v19, v19
	v_mul_f32_e32 v14, v17, v17
	v_fmac_f32_e32 v13, v18, v18
	v_fmac_f32_e32 v14, v16, v16
	v_add_f32_e32 v13, v13, v14
	v_add_f32_e32 v20, v12, v13
	v_lshlrev_b32_e32 v12, 16, v64
	v_and_b32_e32 v13, 0xffff0000, v64
	v_lshlrev_b32_e32 v14, 16, v65
	v_and_b32_e32 v15, 0xffff0000, v65
	v_cvt_pk_bf16_f32 v10, v18, v19
	v_cvt_pk_bf16_f32 v11, v16, v17
	v_lshlrev_b32_e32 v16, 16, v66
	v_and_b32_e32 v17, 0xffff0000, v66
	v_pk_add_f32 v[6:7], v[6:7], v[14:15]
	v_pk_add_f32 v[4:5], v[4:5], v[12:13]
	v_lshlrev_b32_e32 v18, 16, v67
	v_and_b32_e32 v19, 0xffff0000, v67
	v_pk_add_f32 v[14:15], v[0:1], v[16:17]
	v_mul_f32_e32 v0, v5, v5
	v_mul_f32_e32 v1, v7, v7
	v_pk_add_f32 v[12:13], v[2:3], v[18:19]
	v_fmac_f32_e32 v0, v4, v4
	v_fmac_f32_e32 v1, v6, v6
	v_add_f32_e32 v0, v0, v1
	v_mul_f32_e32 v1, v15, v15
	v_mul_f32_e32 v2, v13, v13
	v_fmac_f32_e32 v1, v14, v14
	v_fmac_f32_e32 v2, v12, v12
	v_add_f32_e32 v1, v1, v2
	v_add_f32_e32 v0, v0, v1
	v_add_f32_e32 v3, v20, v0
	ds_bpermute_b32 v18, v193, v3
	v_lshl_add_u64 v[0:1], s[16:17], 0, v[90:91]
	v_lshl_add_u64 v[16:17], v[168:169], 1, v[0:1]
	global_store_dwordx4 v[16:17], v[8:11], off
	v_cvt_pk_bf16_f32 v2, v4, v5
	s_waitcnt lgkmcnt(0)
	v_add_f32_e32 v0, v3, v18
	ds_bpermute_b32 v1, v112, v0
	v_cvt_pk_bf16_f32 v3, v6, v7
	v_cvt_pk_bf16_f32 v4, v14, v15
	v_cvt_pk_bf16_f32 v5, v12, v13
	global_store_dwordx4 v[16:17], v[2:5], off offset:256
	s_and_saveexec_b64 s[4:5], s[6:7]
	s_cbranch_execz .LBB0_1351
	s_waitcnt lgkmcnt(0)
	v_add_f32_e32 v2, v0, v1
	v_lshl_add_u64 v[0:1], v[88:89], 2, s[10:11]
	global_atomic_add_f32 v[0:1], v2, off

.LBB0_1413:
	v_lshl_add_u32 v144, s8, 8, v152
	v_ashrrev_i32_e32 v145, 31, v144
	v_lshl_add_u64 v[150:151], v[144:145], 2, s[10:11]
	global_load_dword v145, v[150:151], off
	v_lshl_add_u32 v146, s9, 7, v154
	v_or_b32_e32 v162, 16, v144
	v_mov_b64_e32 v[148:149], s[12:13]
	v_ashrrev_i32_e32 v147, 31, v146
	v_mad_i64_i32 v[160:161], s[4:5], v144, s42, v[148:149]
	v_lshlrev_b64 v[146:147], 1, v[146:147]
	v_lshl_add_u64 v[160:161], v[160:161], 0, v[146:147]
	s_waitcnt vmcnt(0) lgkmcnt(0)
	v_fmamk_f32 v145, v145, 0x3a000000, v158
	v_mul_f32_e32 v163, 0x4f800000, v145
	v_cmp_gt_f32_e32 vcc, s41, v145
	s_nop 1
	v_cndmask_b32_e32 v145, v145, v163, vcc
	v_sqrt_f32_e32 v164, v145
	v_ashrrev_i32_e32 v163, 31, v162
	v_add_u32_e32 v165, -1, v164
	v_add_u32_e32 v166, 1, v164
	v_fma_f32 v167, -v165, v164, v145
	v_fma_f32 v168, -v166, v164, v145
	v_cmp_ge_f32_e64 s[8:9], 0, v167
	s_nop 1
	v_cndmask_b32_e64 v164, v164, v165, s[8:9]
	v_cmp_lt_f32_e64 s[8:9], 0, v168
	s_nop 1
	v_cndmask_b32_e64 v164, v164, v166, s[8:9]
	v_mul_f32_e32 v165, 0x37800000, v164
	v_cndmask_b32_e32 v164, v164, v165, vcc
	v_cmp_class_f32_e32 vcc, v145, v159
	s_nop 1
	v_cndmask_b32_e32 v145, v164, v145, vcc
	v_div_scale_f32 v166, s[4:5], v145, v145, 1.0
	v_rcp_f32_e32 v167, v166
	v_lshl_add_u64 v[164:165], v[162:163], 2, s[10:11]
	v_div_scale_f32 v163, vcc, 1.0, v145, 1.0
	v_fma_f32 v168, -v166, v167, 1.0
	v_fmac_f32_e32 v167, v168, v167
	v_mul_f32_e32 v168, v163, v167
	v_fma_f32 v169, -v166, v168, v163
	v_fmac_f32_e32 v168, v169, v167
	v_fma_f32 v163, -v166, v168, v163
	v_div_fmas_f32 v163, v163, v167, v168
	v_div_fixup_f32 v166, v163, v145, 1.0
	v_pk_mul_f32 v[126:127], v[126:127], v[166:167] op_sel_hi:[1,0]
	v_pk_mul_f32 v[124:125], v[124:125], v[166:167] op_sel_hi:[1,0]
	v_pk_mul_f32 v[122:123], v[122:123], v[166:167] op_sel_hi:[1,0]
	v_pk_mul_f32 v[120:121], v[120:121], v[166:167] op_sel_hi:[1,0]
	v_pk_mul_f32 v[116:117], v[116:117], v[166:167] op_sel_hi:[1,0]
	v_pk_mul_f32 v[118:119], v[118:119], v[166:167] op_sel_hi:[1,0]
	v_pk_mul_f32 v[112:113], v[112:113], v[166:167] op_sel_hi:[1,0]
	v_pk_mul_f32 v[114:115], v[114:115], v[166:167] op_sel_hi:[1,0]
	v_pk_mul_f32 v[166:167], v[124:125], s[18:19] op_sel_hi:[1,0]
	v_pk_mul_f32 v[118:119], v[126:127], v[118:119]
	v_pk_mul_f32 v[116:117], v[124:125], v[116:117]
	v_pk_mul_f32 v[124:125], v[126:127], s[18:19] op_sel_hi:[1,0]
	v_pk_mul_f32 v[126:127], v[120:121], s[18:19] op_sel_hi:[1,0]
	v_pk_mul_f32 v[112:113], v[120:121], v[112:113]
	v_pk_mul_f32 v[120:121], v[122:123], s[18:19] op_sel_hi:[1,0]
	v_pk_mul_f32 v[114:115], v[122:123], v[114:115]
	v_exp_f32_e32 v122, v166
	v_exp_f32_e32 v123, v167
	v_exp_f32_e32 v124, v124
	v_exp_f32_e32 v125, v125
	v_exp_f32_e32 v126, v126
	v_exp_f32_e32 v127, v127
	v_exp_f32_e32 v120, v120
	v_exp_f32_e32 v121, v121
	v_pk_add_f32 v[122:123], v[122:123], 1.0 op_sel_hi:[1,0]
	v_pk_add_f32 v[124:125], v[124:125], 1.0 op_sel_hi:[1,0]
	v_pk_add_f32 v[126:127], v[126:127], 1.0 op_sel_hi:[1,0]
	v_pk_add_f32 v[120:121], v[120:121], 1.0 op_sel_hi:[1,0]
	v_rcp_f32_e32 v122, v122
	v_rcp_f32_e32 v123, v123
	v_rcp_f32_e32 v124, v124
	v_rcp_f32_e32 v125, v125
	v_rcp_f32_e32 v126, v126
	v_rcp_f32_e32 v127, v127
	v_rcp_f32_e32 v120, v120
	v_rcp_f32_e32 v121, v121
	v_pk_mul_f32 v[116:117], v[116:117], v[122:123]
	v_pk_mul_f32 v[118:119], v[118:119], v[124:125]
	v_pk_mul_f32 v[122:123], v[112:113], v[126:127]
	v_pk_mul_f32 v[120:121], v[114:115], v[120:121]
	v_cvt_pk_bf16_f32 v112, v116, v117
	v_cvt_pk_bf16_f32 v113, v118, v119
	v_cvt_pk_bf16_f32 v114, v122, v123
	s_nop 0
	v_cvt_pk_bf16_f32 v115, v120, v121
	global_store_dwordx4 v[160:161], v[112:115], off
	global_load_dword v113, v[164:165], off
	s_nop 0
	v_or_b32_e32 v112, 32, v144
	s_waitcnt vmcnt(0) lgkmcnt(0)
	v_fmamk_f32 v113, v113, 0x3a000000, v158
	v_mul_f32_e32 v114, 0x4f800000, v113
	v_cmp_gt_f32_e32 vcc, s41, v113
	s_nop 1
	v_cndmask_b32_e32 v116, v113, v114, vcc
	v_sqrt_f32_e32 v117, v116
	v_ashrrev_i32_e32 v113, 31, v112
	v_mad_i64_i32 v[114:115], s[4:5], v162, s42, v[148:149]
	v_add_u32_e32 v118, -1, v117
	v_add_u32_e32 v119, 1, v117
	v_fma_f32 v120, -v118, v117, v116
	v_fma_f32 v121, -v119, v117, v116
	v_cmp_ge_f32_e64 s[8:9], 0, v120
	v_lshl_add_u64 v[114:115], v[114:115], 0, v[146:147]
	s_nop 0
	v_cndmask_b32_e64 v117, v117, v118, s[8:9]
	v_cmp_lt_f32_e64 s[8:9], 0, v121
	s_nop 1
	v_cndmask_b32_e64 v117, v117, v119, s[8:9]
	v_mul_f32_e32 v118, 0x37800000, v117
	v_cndmask_b32_e32 v117, v117, v118, vcc
	v_cmp_class_f32_e32 vcc, v116, v159
	s_nop 1
	v_cndmask_b32_e32 v118, v117, v116, vcc
	v_div_scale_f32 v119, s[4:5], v118, v118, 1.0
	v_rcp_f32_e32 v120, v119
	v_lshl_add_u64 v[116:117], v[112:113], 2, s[10:11]
	v_div_scale_f32 v113, vcc, 1.0, v118, 1.0
	v_fma_f32 v121, -v119, v120, 1.0
	v_fmac_f32_e32 v120, v121, v120
	v_mul_f32_e32 v121, v113, v120
	v_fma_f32 v122, -v119, v121, v113
	v_fmac_f32_e32 v121, v122, v120
	v_fma_f32 v113, -v119, v121, v113
	v_div_fmas_f32 v113, v113, v120, v121
	v_div_fixup_f32 v118, v113, v118, 1.0
	v_pk_mul_f32 v[110:111], v[110:111], v[118:119] op_sel_hi:[1,0]
	v_pk_mul_f32 v[108:109], v[108:109], v[118:119] op_sel_hi:[1,0]
	v_pk_mul_f32 v[106:107], v[106:107], v[118:119] op_sel_hi:[1,0]
	v_pk_mul_f32 v[104:105], v[104:105], v[118:119] op_sel_hi:[1,0]
	v_pk_mul_f32 v[100:101], v[100:101], v[118:119] op_sel_hi:[1,0]
	v_pk_mul_f32 v[102:103], v[102:103], v[118:119] op_sel_hi:[1,0]
	v_pk_mul_f32 v[96:97], v[96:97], v[118:119] op_sel_hi:[1,0]
	v_pk_mul_f32 v[98:99], v[98:99], v[118:119] op_sel_hi:[1,0]
	v_pk_mul_f32 v[118:119], v[108:109], s[18:19] op_sel_hi:[1,0]
	v_pk_mul_f32 v[102:103], v[110:111], v[102:103]
	v_pk_mul_f32 v[100:101], v[108:109], v[100:101]
	v_pk_mul_f32 v[108:109], v[110:111], s[18:19] op_sel_hi:[1,0]
	v_pk_mul_f32 v[110:111], v[104:105], s[18:19] op_sel_hi:[1,0]
	v_pk_mul_f32 v[96:97], v[104:105], v[96:97]
	v_pk_mul_f32 v[104:105], v[106:107], s[18:19] op_sel_hi:[1,0]
	v_pk_mul_f32 v[98:99], v[106:107], v[98:99]
	v_exp_f32_e32 v106, v118
	v_exp_f32_e32 v107, v119
	v_exp_f32_e32 v108, v108
	v_exp_f32_e32 v109, v109
	v_exp_f32_e32 v110, v110
	v_exp_f32_e32 v111, v111
	v_exp_f32_e32 v104, v104
	v_exp_f32_e32 v105, v105
	v_pk_add_f32 v[106:107], v[106:107], 1.0 op_sel_hi:[1,0]
	v_pk_add_f32 v[108:109], v[108:109], 1.0 op_sel_hi:[1,0]
	v_pk_add_f32 v[110:111], v[110:111], 1.0 op_sel_hi:[1,0]
	v_pk_add_f32 v[104:105], v[104:105], 1.0 op_sel_hi:[1,0]
	v_rcp_f32_e32 v106, v106
	v_rcp_f32_e32 v107, v107
	v_rcp_f32_e32 v108, v108
	v_rcp_f32_e32 v109, v109
	v_rcp_f32_e32 v110, v110
	v_rcp_f32_e32 v111, v111
	v_rcp_f32_e32 v104, v104
	v_rcp_f32_e32 v105, v105
	v_pk_mul_f32 v[100:101], v[100:101], v[106:107]
	v_pk_mul_f32 v[102:103], v[102:103], v[108:109]
	v_pk_mul_f32 v[106:107], v[96:97], v[110:111]
	v_pk_mul_f32 v[104:105], v[98:99], v[104:105]
	v_cvt_pk_bf16_f32 v96, v100, v101
	v_cvt_pk_bf16_f32 v97, v102, v103
	v_cvt_pk_bf16_f32 v98, v106, v107
	s_nop 0
	v_cvt_pk_bf16_f32 v99, v104, v105
	global_store_dwordx4 v[114:115], v[96:99], off
	global_load_dword v97, v[116:117], off
	s_nop 0
	v_or_b32_e32 v96, 48, v144
	s_waitcnt vmcnt(0) lgkmcnt(0)
	v_fmamk_f32 v97, v97, 0x3a000000, v158
	v_mul_f32_e32 v98, 0x4f800000, v97
	v_cmp_gt_f32_e32 vcc, s41, v97
	s_nop 1
	v_cndmask_b32_e32 v100, v97, v98, vcc
	v_sqrt_f32_e32 v101, v100
	v_ashrrev_i32_e32 v97, 31, v96
	v_mad_i64_i32 v[98:99], s[4:5], v112, s42, v[148:149]
	v_add_u32_e32 v102, -1, v101
	v_add_u32_e32 v103, 1, v101
	v_fma_f32 v104, -v102, v101, v100
	v_fma_f32 v105, -v103, v101, v100
	v_cmp_ge_f32_e64 s[8:9], 0, v104
	v_lshl_add_u64 v[98:99], v[98:99], 0, v[146:147]
	s_nop 0
	v_cndmask_b32_e64 v101, v101, v102, s[8:9]
	v_cmp_lt_f32_e64 s[8:9], 0, v105
	s_nop 1
	v_cndmask_b32_e64 v101, v101, v103, s[8:9]
	v_mul_f32_e32 v102, 0x37800000, v101
	v_cndmask_b32_e32 v101, v101, v102, vcc
	v_cmp_class_f32_e32 vcc, v100, v159
	s_nop 1
	v_cndmask_b32_e32 v102, v101, v100, vcc
	v_div_scale_f32 v103, s[4:5], v102, v102, 1.0
	v_rcp_f32_e32 v104, v103
	v_lshl_add_u64 v[100:101], v[96:97], 2, s[10:11]
	v_div_scale_f32 v97, vcc, 1.0, v102, 1.0
	v_fma_f32 v105, -v103, v104, 1.0
	v_fmac_f32_e32 v104, v105, v104
	v_mul_f32_e32 v105, v97, v104
	v_fma_f32 v106, -v103, v105, v97
	v_fmac_f32_e32 v105, v106, v104
	v_fma_f32 v97, -v103, v105, v97
	v_div_fmas_f32 v97, v97, v104, v105
	v_div_fixup_f32 v102, v97, v102, 1.0
	v_pk_mul_f32 v[94:95], v[94:95], v[102:103] op_sel_hi:[1,0]
	v_pk_mul_f32 v[92:93], v[92:93], v[102:103] op_sel_hi:[1,0]
	v_pk_mul_f32 v[90:91], v[90:91], v[102:103] op_sel_hi:[1,0]
	v_pk_mul_f32 v[88:89], v[88:89], v[102:103] op_sel_hi:[1,0]
	v_pk_mul_f32 v[84:85], v[84:85], v[102:103] op_sel_hi:[1,0]
	v_pk_mul_f32 v[86:87], v[86:87], v[102:103] op_sel_hi:[1,0]
	v_pk_mul_f32 v[80:81], v[80:81], v[102:103] op_sel_hi:[1,0]
	v_pk_mul_f32 v[82:83], v[82:83], v[102:103] op_sel_hi:[1,0]
	v_pk_mul_f32 v[102:103], v[92:93], s[18:19] op_sel_hi:[1,0]
	v_pk_mul_f32 v[86:87], v[94:95], v[86:87]
	v_pk_mul_f32 v[84:85], v[92:93], v[84:85]
	v_pk_mul_f32 v[92:93], v[94:95], s[18:19] op_sel_hi:[1,0]
	v_pk_mul_f32 v[94:95], v[88:89], s[18:19] op_sel_hi:[1,0]
	v_pk_mul_f32 v[80:81], v[88:89], v[80:81]
	v_pk_mul_f32 v[88:89], v[90:91], s[18:19] op_sel_hi:[1,0]
	v_pk_mul_f32 v[82:83], v[90:91], v[82:83]
	v_exp_f32_e32 v90, v102
	v_exp_f32_e32 v91, v103
	v_exp_f32_e32 v92, v92
	v_exp_f32_e32 v93, v93
	v_exp_f32_e32 v94, v94
	v_exp_f32_e32 v95, v95
	v_exp_f32_e32 v88, v88
	v_exp_f32_e32 v89, v89
	v_pk_add_f32 v[90:91], v[90:91], 1.0 op_sel_hi:[1,0]
	v_pk_add_f32 v[92:93], v[92:93], 1.0 op_sel_hi:[1,0]
	v_pk_add_f32 v[94:95], v[94:95], 1.0 op_sel_hi:[1,0]
	v_pk_add_f32 v[88:89], v[88:89], 1.0 op_sel_hi:[1,0]
	v_rcp_f32_e32 v90, v90
	v_rcp_f32_e32 v91, v91
	v_rcp_f32_e32 v92, v92
	v_rcp_f32_e32 v93, v93
	v_rcp_f32_e32 v94, v94
	v_rcp_f32_e32 v95, v95
	v_rcp_f32_e32 v88, v88
	v_rcp_f32_e32 v89, v89
	v_pk_mul_f32 v[84:85], v[84:85], v[90:91]
	v_pk_mul_f32 v[86:87], v[86:87], v[92:93]
	v_pk_mul_f32 v[90:91], v[80:81], v[94:95]
	v_pk_mul_f32 v[88:89], v[82:83], v[88:89]
	v_cvt_pk_bf16_f32 v80, v84, v85
	v_cvt_pk_bf16_f32 v81, v86, v87
	v_cvt_pk_bf16_f32 v82, v90, v91
	s_nop 0
	v_cvt_pk_bf16_f32 v83, v88, v89
	global_store_dwordx4 v[98:99], v[80:83], off
	global_load_dword v80, v[100:101], off
	s_waitcnt vmcnt(0) lgkmcnt(0)
	v_fmamk_f32 v80, v80, 0x3a000000, v158
	v_mul_f32_e32 v81, 0x4f800000, v80
	v_cmp_gt_f32_e32 vcc, s41, v80
	s_nop 1
	v_cndmask_b32_e32 v82, v80, v81, vcc
	v_sqrt_f32_e32 v83, v82
	v_mad_i64_i32 v[80:81], s[4:5], v96, s42, v[148:149]
	v_lshl_add_u64 v[80:81], v[80:81], 0, v[146:147]
	v_add_u32_e32 v84, -1, v83
	v_add_u32_e32 v85, 1, v83
	v_fma_f32 v86, -v84, v83, v82
	v_fma_f32 v87, -v85, v83, v82
	v_cmp_ge_f32_e64 s[8:9], 0, v86
	s_nop 1
	v_cndmask_b32_e64 v83, v83, v84, s[8:9]
	v_cmp_lt_f32_e64 s[8:9], 0, v87
	s_nop 1
	v_cndmask_b32_e64 v83, v83, v85, s[8:9]
	v_mul_f32_e32 v84, 0x37800000, v83
	v_cndmask_b32_e32 v83, v83, v84, vcc
	v_cmp_class_f32_e32 vcc, v82, v159
	s_nop 1
	v_cndmask_b32_e32 v82, v83, v82, vcc
	v_div_scale_f32 v83, s[4:5], v82, v82, 1.0
	v_rcp_f32_e32 v84, v83
	v_div_scale_f32 v85, vcc, 1.0, v82, 1.0
	v_fma_f32 v86, -v83, v84, 1.0
	v_fmac_f32_e32 v84, v86, v84
	v_mul_f32_e32 v86, v85, v84
	v_fma_f32 v87, -v83, v86, v85
	v_fmac_f32_e32 v86, v87, v84
	v_fma_f32 v83, -v83, v86, v85
	v_div_fmas_f32 v83, v83, v84, v86
	v_div_fixup_f32 v82, v83, v82, 1.0
	v_pk_mul_f32 v[78:79], v[78:79], v[82:83] op_sel_hi:[1,0]
	v_pk_mul_f32 v[76:77], v[76:77], v[82:83] op_sel_hi:[1,0]
	v_pk_mul_f32 v[74:75], v[74:75], v[82:83] op_sel_hi:[1,0]
	v_pk_mul_f32 v[72:73], v[72:73], v[82:83] op_sel_hi:[1,0]
	v_pk_mul_f32 v[68:69], v[68:69], v[82:83] op_sel_hi:[1,0]
	v_pk_mul_f32 v[70:71], v[70:71], v[82:83] op_sel_hi:[1,0]
	v_pk_mul_f32 v[64:65], v[64:65], v[82:83] op_sel_hi:[1,0]
	v_pk_mul_f32 v[66:67], v[66:67], v[82:83] op_sel_hi:[1,0]
	v_pk_mul_f32 v[82:83], v[76:77], s[18:19] op_sel_hi:[1,0]
	v_pk_mul_f32 v[70:71], v[78:79], v[70:71]
	v_pk_mul_f32 v[68:69], v[76:77], v[68:69]
	v_pk_mul_f32 v[76:77], v[78:79], s[18:19] op_sel_hi:[1,0]
	v_pk_mul_f32 v[78:79], v[72:73], s[18:19] op_sel_hi:[1,0]
	v_pk_mul_f32 v[64:65], v[72:73], v[64:65]
	v_pk_mul_f32 v[72:73], v[74:75], s[18:19] op_sel_hi:[1,0]
	v_pk_mul_f32 v[66:67], v[74:75], v[66:67]
	v_exp_f32_e32 v74, v82
	v_exp_f32_e32 v75, v83
	v_exp_f32_e32 v76, v76
	v_exp_f32_e32 v77, v77
	v_exp_f32_e32 v78, v78
	v_exp_f32_e32 v79, v79
	v_exp_f32_e32 v72, v72
	v_exp_f32_e32 v73, v73
	v_pk_add_f32 v[74:75], v[74:75], 1.0 op_sel_hi:[1,0]
	v_pk_add_f32 v[76:77], v[76:77], 1.0 op_sel_hi:[1,0]
	v_pk_add_f32 v[78:79], v[78:79], 1.0 op_sel_hi:[1,0]
	v_pk_add_f32 v[72:73], v[72:73], 1.0 op_sel_hi:[1,0]
	v_rcp_f32_e32 v74, v74
	v_rcp_f32_e32 v75, v75
	v_rcp_f32_e32 v76, v76
	v_rcp_f32_e32 v77, v77
	v_rcp_f32_e32 v78, v78
	v_rcp_f32_e32 v79, v79
	v_rcp_f32_e32 v72, v72
	v_rcp_f32_e32 v73, v73
	v_pk_mul_f32 v[68:69], v[68:69], v[74:75]
	v_pk_mul_f32 v[70:71], v[70:71], v[76:77]
	v_pk_mul_f32 v[74:75], v[64:65], v[78:79]
	v_pk_mul_f32 v[72:73], v[66:67], v[72:73]
	v_cvt_pk_bf16_f32 v64, v68, v69
	v_cvt_pk_bf16_f32 v65, v70, v71
	v_cvt_pk_bf16_f32 v66, v74, v75
	s_nop 0
	v_cvt_pk_bf16_f32 v67, v72, v73
	global_store_dwordx4 v[80:81], v[64:67], off
	global_load_dword v64, v[150:151], off offset:512
	s_waitcnt vmcnt(0) lgkmcnt(0)
	v_fmamk_f32 v64, v64, 0x3a000000, v158
	v_mul_f32_e32 v65, 0x4f800000, v64
	v_cmp_gt_f32_e32 vcc, s41, v64
	s_nop 1
	v_cndmask_b32_e32 v66, v64, v65, vcc
	v_sqrt_f32_e32 v67, v66
	v_add_u32_e32 v64, 0x80, v144
	v_mad_i64_i32 v[64:65], s[4:5], v64, s42, v[148:149]
	v_add_u32_e32 v68, -1, v67
	v_add_u32_e32 v69, 1, v67
	v_fma_f32 v70, -v68, v67, v66
	v_fma_f32 v71, -v69, v67, v66
	v_cmp_ge_f32_e64 s[8:9], 0, v70
	v_lshl_add_u64 v[64:65], v[64:65], 0, v[146:147]
	s_nop 0
	v_cndmask_b32_e64 v67, v67, v68, s[8:9]
	v_cmp_lt_f32_e64 s[8:9], 0, v71
	s_nop 1
	v_cndmask_b32_e64 v67, v67, v69, s[8:9]
	v_mul_f32_e32 v68, 0x37800000, v67
	v_cndmask_b32_e32 v67, v67, v68, vcc
	v_cmp_class_f32_e32 vcc, v66, v159
	s_nop 1
	v_cndmask_b32_e32 v66, v67, v66, vcc
	v_div_scale_f32 v67, s[4:5], v66, v66, 1.0
	v_rcp_f32_e32 v68, v67
	v_div_scale_f32 v69, vcc, 1.0, v66, 1.0
	v_fma_f32 v70, -v67, v68, 1.0
	v_fmac_f32_e32 v68, v70, v68
	v_mul_f32_e32 v70, v69, v68
	v_fma_f32 v71, -v67, v70, v69
	v_fmac_f32_e32 v70, v71, v68
	v_fma_f32 v67, -v67, v70, v69
	v_div_fmas_f32 v67, v67, v68, v70
	v_div_fixup_f32 v66, v67, v66, 1.0
	v_pk_mul_f32 v[62:63], v[62:63], v[66:67] op_sel_hi:[1,0]
	v_pk_mul_f32 v[60:61], v[60:61], v[66:67] op_sel_hi:[1,0]
	v_pk_mul_f32 v[58:59], v[58:59], v[66:67] op_sel_hi:[1,0]
	v_pk_mul_f32 v[56:57], v[56:57], v[66:67] op_sel_hi:[1,0]
	v_pk_mul_f32 v[52:53], v[52:53], v[66:67] op_sel_hi:[1,0]
	v_pk_mul_f32 v[54:55], v[54:55], v[66:67] op_sel_hi:[1,0]
	v_pk_mul_f32 v[48:49], v[48:49], v[66:67] op_sel_hi:[1,0]
	v_pk_mul_f32 v[50:51], v[50:51], v[66:67] op_sel_hi:[1,0]
	v_pk_mul_f32 v[66:67], v[60:61], s[18:19] op_sel_hi:[1,0]
	v_pk_mul_f32 v[54:55], v[62:63], v[54:55]
	v_pk_mul_f32 v[52:53], v[60:61], v[52:53]
	v_pk_mul_f32 v[60:61], v[62:63], s[18:19] op_sel_hi:[1,0]
	v_pk_mul_f32 v[62:63], v[56:57], s[18:19] op_sel_hi:[1,0]
	v_pk_mul_f32 v[48:49], v[56:57], v[48:49]
	v_pk_mul_f32 v[56:57], v[58:59], s[18:19] op_sel_hi:[1,0]
	v_pk_mul_f32 v[50:51], v[58:59], v[50:51]
	v_exp_f32_e32 v58, v66
	v_exp_f32_e32 v59, v67
	v_exp_f32_e32 v60, v60
	v_exp_f32_e32 v61, v61
	v_exp_f32_e32 v62, v62
	v_exp_f32_e32 v63, v63
	v_exp_f32_e32 v56, v56
	v_exp_f32_e32 v57, v57
	v_pk_add_f32 v[58:59], v[58:59], 1.0 op_sel_hi:[1,0]
	v_pk_add_f32 v[60:61], v[60:61], 1.0 op_sel_hi:[1,0]
	v_pk_add_f32 v[62:63], v[62:63], 1.0 op_sel_hi:[1,0]
	v_pk_add_f32 v[56:57], v[56:57], 1.0 op_sel_hi:[1,0]
	v_rcp_f32_e32 v58, v58
	v_rcp_f32_e32 v59, v59
	v_rcp_f32_e32 v60, v60
	v_rcp_f32_e32 v61, v61
	v_rcp_f32_e32 v62, v62
	v_rcp_f32_e32 v63, v63
	v_rcp_f32_e32 v56, v56
	v_rcp_f32_e32 v57, v57
	v_pk_mul_f32 v[52:53], v[52:53], v[58:59]
	v_pk_mul_f32 v[54:55], v[54:55], v[60:61]
	v_pk_mul_f32 v[58:59], v[48:49], v[62:63]
	v_pk_mul_f32 v[56:57], v[50:51], v[56:57]
	v_cvt_pk_bf16_f32 v48, v52, v53
	v_cvt_pk_bf16_f32 v49, v54, v55
	v_cvt_pk_bf16_f32 v50, v58, v59
	s_nop 0
	v_cvt_pk_bf16_f32 v51, v56, v57
	global_store_dwordx4 v[64:65], v[48:51], off
	global_load_dword v48, v[150:151], off offset:576
	s_waitcnt vmcnt(0) lgkmcnt(0)
	v_fmamk_f32 v48, v48, 0x3a000000, v158
	v_mul_f32_e32 v49, 0x4f800000, v48
	v_cmp_gt_f32_e32 vcc, s41, v48
	s_nop 1
	v_cndmask_b32_e32 v50, v48, v49, vcc
	v_sqrt_f32_e32 v51, v50
	v_add_u32_e32 v48, 0x90, v144
	v_mad_i64_i32 v[48:49], s[4:5], v48, s42, v[148:149]
	v_add_u32_e32 v52, -1, v51
	v_add_u32_e32 v53, 1, v51
	v_fma_f32 v54, -v52, v51, v50
	v_fma_f32 v55, -v53, v51, v50
	v_cmp_ge_f32_e64 s[8:9], 0, v54
	v_lshl_add_u64 v[48:49], v[48:49], 0, v[146:147]
	s_nop 0
	v_cndmask_b32_e64 v51, v51, v52, s[8:9]
	v_cmp_lt_f32_e64 s[8:9], 0, v55
	s_nop 1
	v_cndmask_b32_e64 v51, v51, v53, s[8:9]
	v_mul_f32_e32 v52, 0x37800000, v51
	v_cndmask_b32_e32 v51, v51, v52, vcc
	v_cmp_class_f32_e32 vcc, v50, v159
	s_nop 1
	v_cndmask_b32_e32 v50, v51, v50, vcc
	v_div_scale_f32 v51, s[4:5], v50, v50, 1.0
	v_rcp_f32_e32 v52, v51
	v_div_scale_f32 v53, vcc, 1.0, v50, 1.0
	v_fma_f32 v54, -v51, v52, 1.0
	v_fmac_f32_e32 v52, v54, v52
	v_mul_f32_e32 v54, v53, v52
	v_fma_f32 v55, -v51, v54, v53
	v_fmac_f32_e32 v54, v55, v52
	v_fma_f32 v51, -v51, v54, v53
	v_div_fmas_f32 v51, v51, v52, v54
	v_div_fixup_f32 v50, v51, v50, 1.0
	v_pk_mul_f32 v[46:47], v[46:47], v[50:51] op_sel_hi:[1,0]
	v_pk_mul_f32 v[44:45], v[44:45], v[50:51] op_sel_hi:[1,0]
	v_pk_mul_f32 v[42:43], v[42:43], v[50:51] op_sel_hi:[1,0]
	v_pk_mul_f32 v[40:41], v[40:41], v[50:51] op_sel_hi:[1,0]
	v_pk_mul_f32 v[36:37], v[36:37], v[50:51] op_sel_hi:[1,0]
	v_pk_mul_f32 v[38:39], v[38:39], v[50:51] op_sel_hi:[1,0]
	v_pk_mul_f32 v[32:33], v[32:33], v[50:51] op_sel_hi:[1,0]
	v_pk_mul_f32 v[34:35], v[34:35], v[50:51] op_sel_hi:[1,0]
	v_pk_mul_f32 v[50:51], v[44:45], s[18:19] op_sel_hi:[1,0]
	v_pk_mul_f32 v[38:39], v[46:47], v[38:39]
	v_pk_mul_f32 v[36:37], v[44:45], v[36:37]
	v_pk_mul_f32 v[44:45], v[46:47], s[18:19] op_sel_hi:[1,0]
	v_pk_mul_f32 v[46:47], v[40:41], s[18:19] op_sel_hi:[1,0]
	v_pk_mul_f32 v[32:33], v[40:41], v[32:33]
	v_pk_mul_f32 v[40:41], v[42:43], s[18:19] op_sel_hi:[1,0]
	v_pk_mul_f32 v[34:35], v[42:43], v[34:35]
	v_exp_f32_e32 v42, v50
	v_exp_f32_e32 v43, v51
	v_exp_f32_e32 v44, v44
	v_exp_f32_e32 v45, v45
	v_exp_f32_e32 v46, v46
	v_exp_f32_e32 v47, v47
	v_exp_f32_e32 v40, v40
	v_exp_f32_e32 v41, v41
	v_pk_add_f32 v[42:43], v[42:43], 1.0 op_sel_hi:[1,0]
	v_pk_add_f32 v[44:45], v[44:45], 1.0 op_sel_hi:[1,0]
	v_pk_add_f32 v[46:47], v[46:47], 1.0 op_sel_hi:[1,0]
	v_pk_add_f32 v[40:41], v[40:41], 1.0 op_sel_hi:[1,0]
	v_rcp_f32_e32 v42, v42
	v_rcp_f32_e32 v43, v43
	v_rcp_f32_e32 v44, v44
	v_rcp_f32_e32 v45, v45
	v_rcp_f32_e32 v46, v46
	v_rcp_f32_e32 v47, v47
	v_rcp_f32_e32 v40, v40
	v_rcp_f32_e32 v41, v41
	v_pk_mul_f32 v[36:37], v[36:37], v[42:43]
	v_pk_mul_f32 v[38:39], v[38:39], v[44:45]
	v_pk_mul_f32 v[42:43], v[32:33], v[46:47]
	v_pk_mul_f32 v[40:41], v[34:35], v[40:41]
	v_cvt_pk_bf16_f32 v32, v36, v37
	v_cvt_pk_bf16_f32 v33, v38, v39
	v_cvt_pk_bf16_f32 v34, v42, v43
	s_nop 0
	v_cvt_pk_bf16_f32 v35, v40, v41
	global_store_dwordx4 v[48:49], v[32:35], off
	global_load_dword v32, v[150:151], off offset:640
	s_waitcnt vmcnt(0) lgkmcnt(0)
	v_fmamk_f32 v32, v32, 0x3a000000, v158
	v_mul_f32_e32 v33, 0x4f800000, v32
	v_cmp_gt_f32_e32 vcc, s41, v32
	s_nop 1
	v_cndmask_b32_e32 v34, v32, v33, vcc
	v_sqrt_f32_e32 v35, v34
	v_add_u32_e32 v32, 0xa0, v144
	v_mad_i64_i32 v[32:33], s[4:5], v32, s42, v[148:149]
	v_add_u32_e32 v36, -1, v35
	v_add_u32_e32 v37, 1, v35
	v_fma_f32 v38, -v36, v35, v34
	v_fma_f32 v39, -v37, v35, v34
	v_cmp_ge_f32_e64 s[8:9], 0, v38
	v_lshl_add_u64 v[32:33], v[32:33], 0, v[146:147]
	s_nop 0
	v_cndmask_b32_e64 v35, v35, v36, s[8:9]
	v_cmp_lt_f32_e64 s[8:9], 0, v39
	s_nop 1
	v_cndmask_b32_e64 v35, v35, v37, s[8:9]
	v_mul_f32_e32 v36, 0x37800000, v35
	v_cndmask_b32_e32 v35, v35, v36, vcc
	v_cmp_class_f32_e32 vcc, v34, v159
	s_nop 1
	v_cndmask_b32_e32 v34, v35, v34, vcc
	v_div_scale_f32 v35, s[4:5], v34, v34, 1.0
	v_rcp_f32_e32 v36, v35
	v_div_scale_f32 v37, vcc, 1.0, v34, 1.0
	v_fma_f32 v38, -v35, v36, 1.0
	v_fmac_f32_e32 v36, v38, v36
	v_mul_f32_e32 v38, v37, v36
	v_fma_f32 v39, -v35, v38, v37
	v_fmac_f32_e32 v38, v39, v36
	v_fma_f32 v35, -v35, v38, v37
	v_div_fmas_f32 v35, v35, v36, v38
	v_div_fixup_f32 v34, v35, v34, 1.0
	v_pk_mul_f32 v[30:31], v[30:31], v[34:35] op_sel_hi:[1,0]
	v_pk_mul_f32 v[28:29], v[28:29], v[34:35] op_sel_hi:[1,0]
	v_pk_mul_f32 v[26:27], v[26:27], v[34:35] op_sel_hi:[1,0]
	v_pk_mul_f32 v[24:25], v[24:25], v[34:35] op_sel_hi:[1,0]
	v_pk_mul_f32 v[20:21], v[20:21], v[34:35] op_sel_hi:[1,0]
	v_pk_mul_f32 v[22:23], v[22:23], v[34:35] op_sel_hi:[1,0]
	v_pk_mul_f32 v[16:17], v[16:17], v[34:35] op_sel_hi:[1,0]
	v_pk_mul_f32 v[18:19], v[18:19], v[34:35] op_sel_hi:[1,0]
	v_pk_mul_f32 v[34:35], v[28:29], s[18:19] op_sel_hi:[1,0]
	v_pk_mul_f32 v[22:23], v[30:31], v[22:23]
	v_pk_mul_f32 v[20:21], v[28:29], v[20:21]
	v_pk_mul_f32 v[28:29], v[30:31], s[18:19] op_sel_hi:[1,0]
	v_pk_mul_f32 v[30:31], v[24:25], s[18:19] op_sel_hi:[1,0]
	v_pk_mul_f32 v[16:17], v[24:25], v[16:17]
	v_pk_mul_f32 v[24:25], v[26:27], s[18:19] op_sel_hi:[1,0]
	v_pk_mul_f32 v[18:19], v[26:27], v[18:19]
	v_exp_f32_e32 v26, v34
	v_exp_f32_e32 v27, v35
	v_exp_f32_e32 v28, v28
	v_exp_f32_e32 v29, v29
	v_exp_f32_e32 v30, v30
	v_exp_f32_e32 v31, v31
	v_exp_f32_e32 v24, v24
	v_exp_f32_e32 v25, v25
	v_pk_add_f32 v[26:27], v[26:27], 1.0 op_sel_hi:[1,0]
	v_pk_add_f32 v[28:29], v[28:29], 1.0 op_sel_hi:[1,0]
	v_pk_add_f32 v[30:31], v[30:31], 1.0 op_sel_hi:[1,0]
	v_pk_add_f32 v[24:25], v[24:25], 1.0 op_sel_hi:[1,0]
	v_rcp_f32_e32 v26, v26
	v_rcp_f32_e32 v27, v27
	v_rcp_f32_e32 v28, v28
	v_rcp_f32_e32 v29, v29
	v_rcp_f32_e32 v30, v30
	v_rcp_f32_e32 v31, v31
	v_rcp_f32_e32 v24, v24
	v_rcp_f32_e32 v25, v25
	v_pk_mul_f32 v[20:21], v[20:21], v[26:27]
	v_pk_mul_f32 v[22:23], v[22:23], v[28:29]
	v_pk_mul_f32 v[26:27], v[16:17], v[30:31]
	v_pk_mul_f32 v[24:25], v[18:19], v[24:25]
	v_cvt_pk_bf16_f32 v16, v20, v21
	v_cvt_pk_bf16_f32 v17, v22, v23
	v_cvt_pk_bf16_f32 v18, v26, v27
	s_nop 0
	v_cvt_pk_bf16_f32 v19, v24, v25
	global_store_dwordx4 v[32:33], v[16:19], off
	global_load_dword v16, v[150:151], off offset:704
	s_nop 0
	v_add_u32_e32 v17, 0xb0, v144
	s_waitcnt vmcnt(0) lgkmcnt(0)
	v_fmamk_f32 v16, v16, 0x3a000000, v158
	v_mul_f32_e32 v18, 0x4f800000, v16
	v_cmp_gt_f32_e32 vcc, s41, v16
	s_nop 1
	v_cndmask_b32_e32 v18, v16, v18, vcc
	v_sqrt_f32_e32 v19, v18
	v_mad_i64_i32 v[16:17], s[4:5], v17, s42, v[148:149]
	v_lshl_add_u64 v[16:17], v[16:17], 0, v[146:147]
	v_add_u32_e32 v20, -1, v19
	v_add_u32_e32 v21, 1, v19
	v_fma_f32 v22, -v20, v19, v18
	v_fma_f32 v23, -v21, v19, v18
	v_cmp_ge_f32_e64 s[8:9], 0, v22
	s_nop 1
	v_cndmask_b32_e64 v19, v19, v20, s[8:9]
	v_cmp_lt_f32_e64 s[8:9], 0, v23
	s_nop 1
	v_cndmask_b32_e64 v19, v19, v21, s[8:9]
	v_mul_f32_e32 v20, 0x37800000, v19
	v_cndmask_b32_e32 v19, v19, v20, vcc
	v_cmp_class_f32_e32 vcc, v18, v159
	s_nop 1
	v_cndmask_b32_e32 v18, v19, v18, vcc
	v_div_scale_f32 v19, s[4:5], v18, v18, 1.0
	v_rcp_f32_e32 v20, v19
	v_div_scale_f32 v21, vcc, 1.0, v18, 1.0
	s_mov_b64 s[4:5], -1
	v_fma_f32 v22, -v19, v20, 1.0
	v_fmac_f32_e32 v20, v22, v20
	v_mul_f32_e32 v22, v21, v20
	v_fma_f32 v23, -v19, v22, v21
	v_fmac_f32_e32 v22, v23, v20
	v_fma_f32 v19, -v19, v22, v21
	v_div_fmas_f32 v19, v19, v20, v22
	v_div_fixup_f32 v18, v19, v18, 1.0
	v_pk_mul_f32 v[14:15], v[14:15], v[18:19] op_sel_hi:[1,0]
	v_pk_mul_f32 v[12:13], v[12:13], v[18:19] op_sel_hi:[1,0]
	v_pk_mul_f32 v[10:11], v[10:11], v[18:19] op_sel_hi:[1,0]
	v_pk_mul_f32 v[8:9], v[8:9], v[18:19] op_sel_hi:[1,0]
	v_pk_mul_f32 v[4:5], v[4:5], v[18:19] op_sel_hi:[1,0]
	v_pk_mul_f32 v[6:7], v[6:7], v[18:19] op_sel_hi:[1,0]
	v_pk_mul_f32 v[0:1], v[0:1], v[18:19] op_sel_hi:[1,0]
	v_pk_mul_f32 v[2:3], v[2:3], v[18:19] op_sel_hi:[1,0]
	v_pk_mul_f32 v[18:19], v[12:13], s[18:19] op_sel_hi:[1,0]
	v_pk_mul_f32 v[6:7], v[14:15], v[6:7]
	v_pk_mul_f32 v[4:5], v[12:13], v[4:5]
	v_pk_mul_f32 v[12:13], v[14:15], s[18:19] op_sel_hi:[1,0]
	v_pk_mul_f32 v[14:15], v[8:9], s[18:19] op_sel_hi:[1,0]
	v_pk_mul_f32 v[0:1], v[8:9], v[0:1]
	v_pk_mul_f32 v[8:9], v[10:11], s[18:19] op_sel_hi:[1,0]
	v_pk_mul_f32 v[2:3], v[10:11], v[2:3]
	v_exp_f32_e32 v10, v18
	v_exp_f32_e32 v11, v19
	v_exp_f32_e32 v12, v12
	v_exp_f32_e32 v13, v13
	v_exp_f32_e32 v14, v14
	v_exp_f32_e32 v15, v15
	v_exp_f32_e32 v8, v8
	v_exp_f32_e32 v9, v9
	v_pk_add_f32 v[10:11], v[10:11], 1.0 op_sel_hi:[1,0]
	v_pk_add_f32 v[12:13], v[12:13], 1.0 op_sel_hi:[1,0]
	v_pk_add_f32 v[14:15], v[14:15], 1.0 op_sel_hi:[1,0]
	v_pk_add_f32 v[8:9], v[8:9], 1.0 op_sel_hi:[1,0]
	v_rcp_f32_e32 v10, v10
	v_rcp_f32_e32 v11, v11
	v_rcp_f32_e32 v12, v12
	v_rcp_f32_e32 v13, v13
	v_rcp_f32_e32 v14, v14
	v_rcp_f32_e32 v15, v15
	v_rcp_f32_e32 v8, v8
	v_rcp_f32_e32 v9, v9
	s_andn2_b64 vcc, exec, s[6:7]
	v_pk_mul_f32 v[4:5], v[4:5], v[10:11]
	v_pk_mul_f32 v[6:7], v[6:7], v[12:13]
	v_pk_mul_f32 v[10:11], v[0:1], v[14:15]
	v_pk_mul_f32 v[8:9], v[2:3], v[8:9]
	v_cvt_pk_bf16_f32 v0, v4, v5
	v_cvt_pk_bf16_f32 v1, v6, v7
	v_cvt_pk_bf16_f32 v2, v10, v11
	s_nop 0
	v_cvt_pk_bf16_f32 v3, v8, v9
	global_store_dwordx4 v[16:17], v[0:3], off
	s_cbranch_vccnz .LBB0_1406
	s_and_b64 vcc, exec, s[60:61]
	s_cbranch_vccnz .LBB0_1405
	s_barrier
	s_branch .LBB0_1405

.LBB0_1423:
	global_load_dword v47, v[0:1], off sc1
	global_load_dword v32, v[2:3], off sc1
	global_load_dword v33, v[4:5], off sc1
	global_load_dword v34, v[6:7], off sc1
	global_load_dword v35, v[8:9], off sc1
	global_load_dword v36, v[10:11], off sc1
	global_load_dword v37, v[12:13], off sc1
	global_load_dword v38, v[14:15], off sc1
	global_load_dword v39, v[16:17], off sc1
	global_load_dword v40, v[18:19], off sc1
	global_load_dword v41, v[20:21], off sc1
	global_load_dword v42, v[22:23], off sc1
	global_load_dword v43, v[24:25], off sc1
	global_load_dword v44, v[26:27], off sc1
	global_load_dword v45, v[28:29], off sc1
	global_load_dword v46, v[30:31], off sc1
	s_or_b64 s[14:15], s[14:15], exec
	s_or_b64 s[12:13], s[12:13], exec
	s_waitcnt vmcnt(0) lgkmcnt(0)
	v_add_u32_e32 v48, v32, v47
	v_add_u32_e32 v48, v48, v33
	v_add_u32_e32 v48, v48, v34
	v_add_u32_e32 v48, v48, v35
	v_add_u32_e32 v48, v48, v36
	v_add_u32_e32 v48, v48, v37
	v_add_u32_e32 v48, v48, v38
	v_add_u32_e32 v48, v48, v39
	v_add_u32_e32 v48, v48, v40
	v_add_u32_e32 v48, v48, v41
	v_add_u32_e32 v48, v48, v42
	v_add_u32_e32 v48, v48, v43
	v_add_u32_e32 v48, v48, v44
	v_add_u32_e32 v48, v48, v45
	v_add_u32_e32 v48, v48, v46
	v_cmp_ne_u32_e32 vcc, s1, v48
	s_and_saveexec_b64 s[16:17], vcc
	s_cbranch_execz .LBB0_1422
	s_and_b32 s3, s2, 0xff
	s_mov_b64 s[18:19], -1
	s_cmp_eq_u32 s3, 0
	s_mov_b64 s[22:23], -1
	s_mov_b64 s[20:21], -1
	s_sleep 1
	s_cbranch_scc1 .LBB0_1426
	s_and_saveexec_b64 s[24:25], s[22:23]
	s_cbranch_execz .LBB0_1421
	s_branch .LBB0_1429
.LBB0_1426:
	v_mov_b64_e32 v[48:49], s[6:7]
	global_load_dword v48, v[48:49], off sc1
	s_mov_b64 s[22:23], 0
	s_waitcnt vmcnt(0) lgkmcnt(0)
	v_cmp_eq_u32_e32 vcc, 0, v48
	s_and_saveexec_b64 s[24:25], vcc
	s_cmp_lt_u32 s2, 0x40001
	s_cselect_b64 s[22:23], -1, 0
	s_xor_b64 s[20:21], exec, -1
	s_and_b64 s[22:23], s[22:23], exec
	s_or_b64 exec, exec, s[24:25]
	s_and_saveexec_b64 s[24:25], s[22:23]
	s_cbranch_execz .LBB0_1421

.LBB0_1433:
	s_lshl_b32 s0, s0, 8
	s_add_u32 s0, s4, s0
	s_addc_u32 s2, s5, 0
	v_mov_b32_e32 v1, s0
	v_add_co_u32_e32 v4, vcc, 0x101000, v1
	v_mov_b32_e32 v1, s2
	s_nop 0
	v_addc_co_u32_e32 v5, vcc, 0, v1, vcc
	v_mov_b32_e32 v1, 1
	global_atomic_add v1, v[4:5], v1, off offset:1024 sc0
	v_cvt_f32_u32_e32 v3, v2
	v_sub_u32_e32 v4, 0, v2
	s_add_u32 s1, s0, 0x100000
	s_addc_u32 s0, s2, 0
	v_rcp_iflag_f32_e32 v3, v3
	s_nop 0
	v_mul_f32_e32 v3, 0x4f7ffffe, v3
	v_cvt_u32_f32_e32 v3, v3
	v_mul_lo_u32 v4, v4, v3
	v_mul_hi_u32 v4, v3, v4
	v_add_u32_e32 v3, v3, v4
	s_waitcnt vmcnt(0) lgkmcnt(0)
	v_mul_hi_u32 v3, v1, v3
	v_mul_lo_u32 v5, v3, v2
	v_add_u32_e32 v4, 1, v1
	v_sub_u32_e32 v1, v1, v5
	v_add_u32_e32 v6, 1, v3
	v_cmp_ge_u32_e32 vcc, v1, v2
	v_sub_u32_e32 v5, v1, v2
	s_nop 0
	v_cndmask_b32_e32 v3, v3, v6, vcc
	v_cndmask_b32_e32 v1, v1, v5, vcc
	v_add_u32_e32 v5, 1, v3
	v_cmp_ge_u32_e32 vcc, v1, v2
	s_nop 1
	v_cndmask_b32_e32 v1, v3, v5, vcc
	v_mad_u64_u32 v[2:3], s[2:3], v2, v1, v[2:3]
	v_cmp_ne_u32_e32 vcc, v4, v2
	s_and_saveexec_b64 s[2:3], vcc
	s_xor_b64 s[6:7], exec, s[2:3]
	s_cbranch_execz .LBB0_1446
	v_mov_b32_e32 v0, s1
	v_add_co_u32_e32 v2, vcc, 0x2000, v0
	v_mov_b32_e32 v0, s0
	s_nop 0
	v_addc_co_u32_e32 v3, vcc, 0, v0, vcc
	global_load_dword v0, v[2:3], off offset:1024 sc1
	s_add_u32 s12, s1, 0x2400
	s_addc_u32 s13, s0, 0
	s_waitcnt vmcnt(0) lgkmcnt(0)
	v_cmp_eq_u32_e32 vcc, v0, v1
	s_and_saveexec_b64 s[8:9], vcc
	s_cbranch_execz .LBB0_1445
	s_add_u32 s10, s4, 0x100200
	s_addc_u32 s11, s5, 0
	s_mov_b32 s2, 1
	s_mov_b64 s[14:15], 0
	s_branch .LBB0_1437

.LBB0_1437:
	s_and_b32 s3, s2, 0xff
	s_mov_b64 s[20:21], -1
	s_cmp_lg_u32 s3, 0
	s_mov_b64 s[22:23], -1
	s_sleep 1
	s_cbranch_scc1 .LBB0_1441
	v_mov_b64_e32 v[2:3], s[10:11]
	global_load_dword v0, v[2:3], off sc1
	s_mov_b64 s[22:23], 0
	s_mov_b64 s[24:25], -1
	s_waitcnt vmcnt(0) lgkmcnt(0)
	v_cmp_eq_u32_e32 vcc, 0, v0
	s_and_saveexec_b64 s[26:27], vcc
	s_cmp_lt_u32 s2, 0x40001
	s_cselect_b64 s[22:23], -1, 0
	s_xor_b64 s[24:25], exec, -1
	s_and_b64 s[22:23], s[22:23], exec
	s_or_b64 exec, exec, s[26:27]
.LBB0_1441:
	s_andn2_b64 s[18:19], s[18:19], exec
	s_and_b64 s[24:25], s[24:25], exec
	s_or_b64 s[18:19], s[18:19], s[24:25]
	s_and_saveexec_b64 s[24:25], s[22:23]
	s_cbranch_execz .LBB0_1436
	v_mov_b64_e32 v[2:3], s[12:13]
	global_load_dword v0, v[2:3], off sc1
	s_add_i32 s2, s2, 1
	s_or_b64 s[18:19], s[18:19], exec
	s_waitcnt vmcnt(0) lgkmcnt(0)
	v_cmp_ne_u32_e32 vcc, v0, v1
	s_orn2_b64 s[20:21], vcc, exec
	s_branch .LBB0_1436
.LBB0_1443:
	s_or_b64 exec, exec, s[14:15]
	s_xor_b64 s[2:3], s[16:17], -1
	s_and_saveexec_b64 s[12:13], s[2:3]
	s_xor_b64 s[12:13], exec, s[12:13]
	s_cbranch_execz .LBB0_1445
	v_mov_b32_e32 v2, 1
	v_mov_b64_e32 v[0:1], s[10:11]
	global_atomic_add v[0:1], v2, off

.LBB0_1446:
	s_andn2_saveexec_b64 s[2:3], s[6:7]
	s_cbranch_execz .LBB0_1462
	v_mov_b32_e32 v1, s4
	v_add_co_u32_e32 v2, vcc, 0x103000, v1
	v_mov_b32_e32 v1, s5
	buffer_wbl2 sc1
	s_waitcnt vmcnt(0)
	v_addc_co_u32_e32 v3, vcc, 0, v1, vcc
	v_mov_b32_e32 v1, 1
	global_atomic_add v1, v[2:3], v1, off offset:1024 sc0
	v_cvt_f32_u32_e32 v2, v0
	v_sub_u32_e32 v3, 0, v0
	s_add_u32 s6, s4, 0x103500
	s_addc_u32 s7, s5, 0
	v_rcp_iflag_f32_e32 v2, v2
	s_mov_b64 s[10:11], -1
	v_mul_f32_e32 v2, 0x4f7ffffe, v2
	v_cvt_u32_f32_e32 v2, v2
	v_mul_lo_u32 v3, v3, v2
	v_mul_hi_u32 v3, v2, v3
	v_add_u32_e32 v2, v2, v3
	s_waitcnt vmcnt(0) lgkmcnt(0)
	v_mul_hi_u32 v2, v1, v2
	v_mul_lo_u32 v4, v2, v0
	v_add_u32_e32 v3, 1, v1
	v_sub_u32_e32 v1, v1, v4
	v_add_u32_e32 v5, 1, v2
	v_cmp_ge_u32_e32 vcc, v1, v0
	v_sub_u32_e32 v4, v1, v0
	s_nop 0
	v_cndmask_b32_e32 v2, v2, v5, vcc
	v_cndmask_b32_e32 v1, v1, v4, vcc
	v_add_u32_e32 v4, 1, v2
	v_cmp_ge_u32_e32 vcc, v1, v0
	s_nop 1
	v_cndmask_b32_e32 v2, v2, v4, vcc
	v_mad_u64_u32 v[0:1], s[2:3], v0, v2, v[0:1]
	v_cmp_ne_u32_e32 vcc, v3, v0
	v_mov_b64_e32 v[0:1], s[6:7]
	s_and_saveexec_b64 s[8:9], vcc
	s_cbranch_execz .LBB0_1459
	v_mov_b64_e32 v[0:1], s[6:7]
	global_load_dword v0, v[0:1], off sc1
	s_mov_b64 s[14:15], 0
	s_waitcnt vmcnt(0) lgkmcnt(0)
	v_cmp_eq_u32_e32 vcc, v0, v2
	s_and_saveexec_b64 s[12:13], vcc
	s_cbranch_execz .LBB0_1458
	s_add_u32 s10, s4, 0x100200
	s_addc_u32 s11, s5, 0
	s_mov_b32 s2, 1
	s_mov_b64 s[4:5], 0
	s_branch .LBB0_1451

.LBB0_1453:
	v_mov_b64_e32 v[0:1], s[10:11]
	global_load_dword v0, v[0:1], off sc1
	s_mov_b64 s[18:19], 0
	s_mov_b64 s[16:17], -1
	s_waitcnt vmcnt(0) lgkmcnt(0)
	v_cmp_eq_u32_e32 vcc, 0, v0
	s_and_saveexec_b64 s[20:21], vcc
	s_cmp_lt_u32 s2, 0x40001
	s_cselect_b64 s[18:19], -1, 0
	s_xor_b64 s[16:17], exec, -1
	s_and_b64 s[18:19], s[18:19], exec
	s_or_b64 exec, exec, s[20:21]
	s_mov_b64 s[20:21], -1
	s_and_saveexec_b64 s[22:23], s[18:19]
	s_cbranch_execz .LBB0_1450
.LBB0_1456:
	v_mov_b64_e32 v[0:1], s[6:7]
	global_load_dword v0, v[0:1], off sc1
	s_add_i32 s2, s2, 1
	s_or_b64 s[16:17], s[16:17], exec
	s_waitcnt vmcnt(0) lgkmcnt(0)
	v_cmp_ne_u32_e32 vcc, v0, v2
	s_orn2_b64 s[20:21], vcc, exec
	s_branch .LBB0_1450

.LBB0_1487:
	v_lshl_add_u32 v148, s35, 8, v152
	v_lshl_add_u32 v144, s36, 8, v154
	v_ashrrev_i32_e32 v145, 31, v144
	v_ashrrev_i32_e32 v149, 31, v148
	v_lshl_add_u64 v[146:147], v[144:145], 1, s[8:9]
	v_lshlrev_b64 v[150:151], 12, v[148:149]
	v_or_b32_e32 v182, 16, v148
	v_lshl_add_u64 v[150:151], v[146:147], 0, v[150:151]
	v_ashrrev_i32_e32 v183, 31, v182
	global_load_dwordx4 v[158:161], v[150:151], off
	global_load_dwordx4 v[162:165], v[150:151], off offset:256
	v_lshlrev_b64 v[150:151], 12, v[182:183]
	v_or_b32_e32 v190, 32, v148
	v_lshl_add_u64 v[150:151], v[146:147], 0, v[150:151]
	v_ashrrev_i32_e32 v191, 31, v190
	global_load_dwordx4 v[166:169], v[150:151], off
	global_load_dwordx4 v[170:173], v[150:151], off offset:256
	v_lshlrev_b64 v[150:151], 12, v[190:191]
	v_lshl_add_u64 v[178:179], v[146:147], 0, v[150:151]
	global_load_dwordx4 v[174:177], v[178:179], off
	v_or_b32_e32 v150, 48, v148
	global_load_dwordx4 v[178:181], v[178:179], off offset:256
	v_ashrrev_i32_e32 v151, 31, v150
	v_lshlrev_b64 v[186:187], 12, v[150:151]
	v_lshl_add_u64 v[144:145], v[144:145], 2, s[52:53]
	v_lshlrev_b64 v[184:185], 13, v[148:149]
	v_lshlrev_b64 v[182:183], 13, v[182:183]
	v_lshl_add_u64 v[186:187], v[146:147], 0, v[186:187]
	v_lshl_add_u64 v[192:193], v[144:145], 0, v[184:185]
	v_lshl_add_u64 v[194:195], v[144:145], 0, v[182:183]
	global_load_dwordx4 v[182:185], v[186:187], off
	s_nop 0
	global_load_dwordx4 v[186:189], v[186:187], off offset:256
	s_and_b64 vcc, exec, s[6:7]
	s_mov_b64 s[6:7], -1
	s_waitcnt vmcnt(0) lgkmcnt(0)
	v_lshlrev_b32_e32 v196, 16, v158
	v_and_b32_e32 v197, 0xffff0000, v158
	v_lshlrev_b32_e32 v158, 16, v159
	v_and_b32_e32 v159, 0xffff0000, v159
	v_lshlrev_b32_e32 v198, 16, v160
	v_and_b32_e32 v199, 0xffff0000, v160
	v_lshlrev_b32_e32 v160, 16, v161
	v_and_b32_e32 v161, 0xffff0000, v161
	v_lshlrev_b32_e32 v200, 16, v162
	v_and_b32_e32 v201, 0xffff0000, v162
	v_lshlrev_b32_e32 v162, 16, v163
	v_and_b32_e32 v163, 0xffff0000, v163
	v_lshlrev_b32_e32 v202, 16, v164
	v_and_b32_e32 v203, 0xffff0000, v164
	v_lshlrev_b32_e32 v164, 16, v165
	v_and_b32_e32 v165, 0xffff0000, v165
	v_pk_fma_f32 v[126:127], v[126:127], 0.5, v[158:159] op_sel_hi:[1,0,1]
	v_pk_fma_f32 v[122:123], v[122:123], 0.5, v[160:161] op_sel_hi:[1,0,1]
	v_pk_fma_f32 v[118:119], v[118:119], 0.5, v[162:163] op_sel_hi:[1,0,1]
	v_pk_fma_f32 v[114:115], v[114:115], 0.5, v[164:165] op_sel_hi:[1,0,1]
	v_lshlrev_b32_e32 v158, 16, v166
	v_and_b32_e32 v159, 0xffff0000, v166
	v_lshlrev_b32_e32 v160, 16, v167
	v_and_b32_e32 v161, 0xffff0000, v167
	v_lshlrev_b32_e32 v162, 16, v168
	v_and_b32_e32 v163, 0xffff0000, v168
	v_lshlrev_b32_e32 v164, 16, v169
	v_and_b32_e32 v165, 0xffff0000, v169
	v_lshlrev_b32_e32 v166, 16, v170
	v_and_b32_e32 v167, 0xffff0000, v170
	v_lshlrev_b32_e32 v168, 16, v171
	v_and_b32_e32 v169, 0xffff0000, v171
	v_lshlrev_b32_e32 v170, 16, v172
	v_and_b32_e32 v171, 0xffff0000, v172
	v_lshlrev_b32_e32 v172, 16, v173
	v_and_b32_e32 v173, 0xffff0000, v173
	v_pk_fma_f32 v[124:125], v[124:125], 0.5, v[196:197] op_sel_hi:[1,0,1]
	v_pk_fma_f32 v[110:111], v[110:111], 0.5, v[160:161] op_sel_hi:[1,0,1]
	v_pk_fma_f32 v[108:109], v[108:109], 0.5, v[158:159] op_sel_hi:[1,0,1]
	v_pk_fma_f32 v[104:105], v[104:105], 0.5, v[162:163] op_sel_hi:[1,0,1]
	v_pk_fma_f32 v[102:103], v[102:103], 0.5, v[168:169] op_sel_hi:[1,0,1]
	v_pk_fma_f32 v[100:101], v[100:101], 0.5, v[166:167] op_sel_hi:[1,0,1]
	v_pk_fma_f32 v[98:99], v[98:99], 0.5, v[172:173] op_sel_hi:[1,0,1]
	v_pk_fma_f32 v[96:97], v[96:97], 0.5, v[170:171] op_sel_hi:[1,0,1]
	v_pk_fma_f32 v[120:121], v[120:121], 0.5, v[198:199] op_sel_hi:[1,0,1]
	v_pk_fma_f32 v[116:117], v[116:117], 0.5, v[200:201] op_sel_hi:[1,0,1]
	v_pk_fma_f32 v[112:113], v[112:113], 0.5, v[202:203] op_sel_hi:[1,0,1]
	global_store_dwordx4 v[192:193], v[124:127], off
	global_store_dwordx4 v[192:193], v[120:123], off offset:16
	global_store_dwordx4 v[192:193], v[116:119], off offset:512
	global_store_dwordx4 v[192:193], v[112:115], off offset:528
	v_pk_fma_f32 v[106:107], v[106:107], 0.5, v[164:165] op_sel_hi:[1,0,1]
	global_store_dwordx4 v[194:195], v[108:111], off
	global_store_dwordx4 v[194:195], v[104:107], off offset:16
	global_store_dwordx4 v[194:195], v[100:103], off offset:512
	global_store_dwordx4 v[194:195], v[96:99], off offset:528
	v_lshlrev_b32_e32 v104, 16, v177
	v_lshlrev_b32_e32 v100, 16, v175
	v_lshlrev_b64 v[96:97], 13, v[190:191]
	v_lshlrev_b32_e32 v98, 16, v174
	v_and_b32_e32 v99, 0xffff0000, v174
	v_and_b32_e32 v101, 0xffff0000, v175
	v_lshlrev_b32_e32 v102, 16, v176
	v_and_b32_e32 v103, 0xffff0000, v176
	v_and_b32_e32 v105, 0xffff0000, v177
	v_lshl_add_u64 v[96:97], v[144:145], 0, v[96:97]
	v_pk_fma_f32 v[94:95], v[94:95], 0.5, v[100:101] op_sel_hi:[1,0,1]
	v_pk_fma_f32 v[92:93], v[92:93], 0.5, v[98:99] op_sel_hi:[1,0,1]
	v_pk_fma_f32 v[90:91], v[90:91], 0.5, v[104:105] op_sel_hi:[1,0,1]
	v_pk_fma_f32 v[88:89], v[88:89], 0.5, v[102:103] op_sel_hi:[1,0,1]
	global_store_dwordx4 v[96:97], v[92:95], off
	global_store_dwordx4 v[96:97], v[88:91], off offset:16
	v_add_u32_e32 v98, 0x90, v148
	v_lshlrev_b32_e32 v92, 16, v180
	v_lshlrev_b32_e32 v88, 16, v178
	v_and_b32_e32 v89, 0xffff0000, v178
	v_lshlrev_b32_e32 v90, 16, v179
	v_and_b32_e32 v91, 0xffff0000, v179
	v_and_b32_e32 v93, 0xffff0000, v180
	v_lshlrev_b32_e32 v94, 16, v181
	v_and_b32_e32 v95, 0xffff0000, v181
	v_pk_fma_f32 v[86:87], v[86:87], 0.5, v[90:91] op_sel_hi:[1,0,1]
	v_pk_fma_f32 v[84:85], v[84:85], 0.5, v[88:89] op_sel_hi:[1,0,1]
	v_pk_fma_f32 v[76:77], v[76:77], 0.5, v[92:93] op_sel_hi:[1,0,1]
	v_pk_fma_f32 v[78:79], v[78:79], 0.5, v[94:95] op_sel_hi:[1,0,1]
	global_store_dwordx4 v[96:97], v[84:87], off offset:512
	global_store_dwordx4 v[96:97], v[76:79], off offset:528
	v_lshlrev_b32_e32 v88, 16, v185
	v_lshlrev_b32_e32 v86, 16, v184
	v_lshlrev_b64 v[76:77], 13, v[150:151]
	v_lshl_add_u64 v[84:85], v[144:145], 0, v[76:77]
	v_lshlrev_b32_e32 v76, 16, v182
	v_and_b32_e32 v77, 0xffff0000, v182
	v_lshlrev_b32_e32 v78, 16, v183
	v_and_b32_e32 v79, 0xffff0000, v183
	v_and_b32_e32 v87, 0xffff0000, v184
	v_and_b32_e32 v89, 0xffff0000, v185
	v_pk_fma_f32 v[78:79], v[82:83], 0.5, v[78:79] op_sel_hi:[1,0,1]
	v_pk_fma_f32 v[76:77], v[80:81], 0.5, v[76:77] op_sel_hi:[1,0,1]
	v_pk_fma_f32 v[74:75], v[74:75], 0.5, v[88:89] op_sel_hi:[1,0,1]
	v_pk_fma_f32 v[72:73], v[72:73], 0.5, v[86:87] op_sel_hi:[1,0,1]
	global_store_dwordx4 v[84:85], v[76:79], off
	global_store_dwordx4 v[84:85], v[72:75], off offset:16
	v_add_u32_e32 v96, 0x80, v148
	v_lshlrev_b32_e32 v76, 16, v188
	v_lshlrev_b32_e32 v72, 16, v186
	v_and_b32_e32 v73, 0xffff0000, v186
	v_lshlrev_b32_e32 v74, 16, v187
	v_and_b32_e32 v75, 0xffff0000, v187
	v_and_b32_e32 v77, 0xffff0000, v188
	v_lshlrev_b32_e32 v78, 16, v189
	v_and_b32_e32 v79, 0xffff0000, v189
	v_pk_fma_f32 v[70:71], v[70:71], 0.5, v[74:75] op_sel_hi:[1,0,1]
	v_pk_fma_f32 v[68:69], v[68:69], 0.5, v[72:73] op_sel_hi:[1,0,1]
	v_pk_fma_f32 v[64:65], v[64:65], 0.5, v[76:77] op_sel_hi:[1,0,1]
	v_ashrrev_i32_e32 v97, 31, v96
	v_pk_fma_f32 v[66:67], v[66:67], 0.5, v[78:79] op_sel_hi:[1,0,1]
	global_store_dwordx4 v[84:85], v[68:71], off offset:512
	global_store_dwordx4 v[84:85], v[64:67], off offset:528
	v_ashrrev_i32_e32 v99, 31, v98
	v_add_u32_e32 v100, 0xa0, v148
	v_lshlrev_b64 v[64:65], 12, v[96:97]
	v_lshl_add_u64 v[64:65], v[146:147], 0, v[64:65]
	global_load_dwordx4 v[68:71], v[64:65], off
	global_load_dwordx4 v[72:75], v[64:65], off offset:256
	v_lshlrev_b64 v[64:65], 12, v[98:99]
	v_lshl_add_u64 v[64:65], v[146:147], 0, v[64:65]
	global_load_dwordx4 v[76:79], v[64:65], off
	global_load_dwordx4 v[80:83], v[64:65], off offset:256
	v_ashrrev_i32_e32 v101, 31, v100
	v_lshlrev_b64 v[64:65], 12, v[100:101]
	v_lshl_add_u64 v[64:65], v[146:147], 0, v[64:65]
	global_load_dwordx4 v[84:87], v[64:65], off
	global_load_dwordx4 v[88:91], v[64:65], off offset:256
	v_add_u32_e32 v102, 0xb0, v148
	v_ashrrev_i32_e32 v103, 31, v102
	v_lshlrev_b64 v[64:65], 12, v[102:103]
	v_lshl_add_u64 v[64:65], v[146:147], 0, v[64:65]
	global_load_dwordx4 v[92:95], v[64:65], off
	s_nop 0
	global_load_dwordx4 v[64:67], v[64:65], off offset:256
	v_lshlrev_b64 v[96:97], 13, v[96:97]
	v_lshl_add_u64 v[96:97], v[144:145], 0, v[96:97]
	s_waitcnt vmcnt(0) lgkmcnt(0)
	v_lshlrev_b32_e32 v104, 16, v68
	v_and_b32_e32 v105, 0xffff0000, v68
	v_lshlrev_b32_e32 v68, 16, v69
	v_and_b32_e32 v69, 0xffff0000, v69
	v_lshlrev_b32_e32 v106, 16, v70
	v_and_b32_e32 v107, 0xffff0000, v70
	v_lshlrev_b32_e32 v70, 16, v71
	v_and_b32_e32 v71, 0xffff0000, v71
	v_pk_fma_f32 v[62:63], v[62:63], 0.5, v[68:69] op_sel_hi:[1,0,1]
	v_pk_fma_f32 v[60:61], v[60:61], 0.5, v[104:105] op_sel_hi:[1,0,1]
	v_pk_fma_f32 v[58:59], v[58:59], 0.5, v[70:71] op_sel_hi:[1,0,1]
	v_pk_fma_f32 v[56:57], v[56:57], 0.5, v[106:107] op_sel_hi:[1,0,1]
	global_store_dwordx4 v[96:97], v[60:63], off
	global_store_dwordx4 v[96:97], v[56:59], off offset:16
	s_nop 0
	v_lshlrev_b32_e32 v60, 16, v74
	v_lshlrev_b32_e32 v56, 16, v72
	v_and_b32_e32 v57, 0xffff0000, v72
	v_lshlrev_b32_e32 v58, 16, v73
	v_and_b32_e32 v59, 0xffff0000, v73
	v_and_b32_e32 v61, 0xffff0000, v74
	v_lshlrev_b32_e32 v62, 16, v75
	v_and_b32_e32 v63, 0xffff0000, v75
	v_pk_fma_f32 v[54:55], v[54:55], 0.5, v[58:59] op_sel_hi:[1,0,1]
	v_pk_fma_f32 v[52:53], v[52:53], 0.5, v[56:57] op_sel_hi:[1,0,1]
	v_pk_fma_f32 v[44:45], v[44:45], 0.5, v[60:61] op_sel_hi:[1,0,1]
	v_pk_fma_f32 v[46:47], v[46:47], 0.5, v[62:63] op_sel_hi:[1,0,1]
	global_store_dwordx4 v[96:97], v[52:55], off offset:512
	global_store_dwordx4 v[96:97], v[44:47], off offset:528
	v_lshlrev_b32_e32 v56, 16, v79
	v_lshlrev_b32_e32 v54, 16, v78
	v_lshlrev_b64 v[44:45], 13, v[98:99]
	v_lshl_add_u64 v[52:53], v[144:145], 0, v[44:45]
	v_lshlrev_b32_e32 v44, 16, v76
	v_and_b32_e32 v45, 0xffff0000, v76
	v_lshlrev_b32_e32 v46, 16, v77
	v_and_b32_e32 v47, 0xffff0000, v77
	v_and_b32_e32 v55, 0xffff0000, v78
	v_and_b32_e32 v57, 0xffff0000, v79
	v_pk_fma_f32 v[46:47], v[50:51], 0.5, v[46:47] op_sel_hi:[1,0,1]
	v_pk_fma_f32 v[44:45], v[48:49], 0.5, v[44:45] op_sel_hi:[1,0,1]
	v_pk_fma_f32 v[42:43], v[42:43], 0.5, v[56:57] op_sel_hi:[1,0,1]
	v_pk_fma_f32 v[40:41], v[40:41], 0.5, v[54:55] op_sel_hi:[1,0,1]
	global_store_dwordx4 v[52:53], v[44:47], off
	global_store_dwordx4 v[52:53], v[40:43], off offset:16
	s_nop 0
	v_lshlrev_b32_e32 v44, 16, v82
	v_lshlrev_b32_e32 v40, 16, v80
	v_and_b32_e32 v41, 0xffff0000, v80
	v_lshlrev_b32_e32 v42, 16, v81
	v_and_b32_e32 v43, 0xffff0000, v81
	v_and_b32_e32 v45, 0xffff0000, v82
	v_lshlrev_b32_e32 v46, 16, v83
	v_and_b32_e32 v47, 0xffff0000, v83
	v_pk_fma_f32 v[38:39], v[38:39], 0.5, v[42:43] op_sel_hi:[1,0,1]
	v_pk_fma_f32 v[36:37], v[36:37], 0.5, v[40:41] op_sel_hi:[1,0,1]
	v_pk_fma_f32 v[28:29], v[28:29], 0.5, v[44:45] op_sel_hi:[1,0,1]
	v_pk_fma_f32 v[30:31], v[30:31], 0.5, v[46:47] op_sel_hi:[1,0,1]
	global_store_dwordx4 v[52:53], v[36:39], off offset:512
	global_store_dwordx4 v[52:53], v[28:31], off offset:528
	v_lshlrev_b32_e32 v40, 16, v87
	v_lshlrev_b32_e32 v38, 16, v86
	v_lshlrev_b64 v[28:29], 13, v[100:101]
	v_lshl_add_u64 v[36:37], v[144:145], 0, v[28:29]
	v_lshlrev_b32_e32 v28, 16, v84
	v_and_b32_e32 v29, 0xffff0000, v84
	v_lshlrev_b32_e32 v30, 16, v85
	v_and_b32_e32 v31, 0xffff0000, v85
	v_and_b32_e32 v39, 0xffff0000, v86
	v_and_b32_e32 v41, 0xffff0000, v87
	v_pk_fma_f32 v[30:31], v[34:35], 0.5, v[30:31] op_sel_hi:[1,0,1]
	v_pk_fma_f32 v[28:29], v[32:33], 0.5, v[28:29] op_sel_hi:[1,0,1]
	v_pk_fma_f32 v[26:27], v[26:27], 0.5, v[40:41] op_sel_hi:[1,0,1]
	v_pk_fma_f32 v[24:25], v[24:25], 0.5, v[38:39] op_sel_hi:[1,0,1]
	global_store_dwordx4 v[36:37], v[28:31], off
	global_store_dwordx4 v[36:37], v[24:27], off offset:16
	s_nop 0
	v_lshlrev_b32_e32 v28, 16, v90
	v_lshlrev_b32_e32 v24, 16, v88
	v_and_b32_e32 v25, 0xffff0000, v88
	v_lshlrev_b32_e32 v26, 16, v89
	v_and_b32_e32 v27, 0xffff0000, v89
	v_and_b32_e32 v29, 0xffff0000, v90
	v_lshlrev_b32_e32 v30, 16, v91
	v_and_b32_e32 v31, 0xffff0000, v91
	v_pk_fma_f32 v[22:23], v[22:23], 0.5, v[26:27] op_sel_hi:[1,0,1]
	v_pk_fma_f32 v[20:21], v[20:21], 0.5, v[24:25] op_sel_hi:[1,0,1]
	v_pk_fma_f32 v[12:13], v[12:13], 0.5, v[28:29] op_sel_hi:[1,0,1]
	v_pk_fma_f32 v[14:15], v[14:15], 0.5, v[30:31] op_sel_hi:[1,0,1]
	global_store_dwordx4 v[36:37], v[20:23], off offset:512
	global_store_dwordx4 v[36:37], v[12:15], off offset:528
	v_lshlrev_b32_e32 v24, 16, v95
	v_lshlrev_b32_e32 v22, 16, v94
	v_lshlrev_b64 v[12:13], 13, v[102:103]
	v_lshl_add_u64 v[20:21], v[144:145], 0, v[12:13]
	v_lshlrev_b32_e32 v12, 16, v92
	v_and_b32_e32 v13, 0xffff0000, v92
	v_lshlrev_b32_e32 v14, 16, v93
	v_and_b32_e32 v15, 0xffff0000, v93
	v_and_b32_e32 v23, 0xffff0000, v94
	v_and_b32_e32 v25, 0xffff0000, v95
	v_pk_fma_f32 v[14:15], v[18:19], 0.5, v[14:15] op_sel_hi:[1,0,1]
	v_pk_fma_f32 v[12:13], v[16:17], 0.5, v[12:13] op_sel_hi:[1,0,1]
	v_pk_fma_f32 v[10:11], v[10:11], 0.5, v[24:25] op_sel_hi:[1,0,1]
	v_pk_fma_f32 v[8:9], v[8:9], 0.5, v[22:23] op_sel_hi:[1,0,1]
	global_store_dwordx4 v[20:21], v[12:15], off
	global_store_dwordx4 v[20:21], v[8:11], off offset:16
	s_nop 0
	v_lshlrev_b32_e32 v12, 16, v66
	v_lshlrev_b32_e32 v8, 16, v64
	v_and_b32_e32 v9, 0xffff0000, v64
	v_lshlrev_b32_e32 v10, 16, v65
	v_and_b32_e32 v11, 0xffff0000, v65
	v_and_b32_e32 v13, 0xffff0000, v66
	v_lshlrev_b32_e32 v14, 16, v67
	v_and_b32_e32 v15, 0xffff0000, v67
	v_pk_fma_f32 v[6:7], v[6:7], 0.5, v[10:11] op_sel_hi:[1,0,1]
	v_pk_fma_f32 v[4:5], v[4:5], 0.5, v[8:9] op_sel_hi:[1,0,1]
	v_pk_fma_f32 v[2:3], v[2:3], 0.5, v[14:15] op_sel_hi:[1,0,1]
	v_pk_fma_f32 v[0:1], v[0:1], 0.5, v[12:13] op_sel_hi:[1,0,1]
	global_store_dwordx4 v[20:21], v[4:7], off offset:512
	global_store_dwordx4 v[20:21], v[0:3], off offset:528
	s_cbranch_vccnz .LBB0_1472
	s_and_b64 vcc, exec, s[60:61]
	s_cbranch_vccnz .LBB0_1471
	s_barrier
	s_branch .LBB0_1471
